# same as previous best but the never-taken fallback GEMM loops are left exactly as the baseline has them (only executed paths edited)
# speedup vs baseline: 1.0143x; 1.0032x over previous
; #define MFMA(a, b, c) __builtin_amdgcn_mfma_f32_32x32x16_bf16((a), (b), (c), 0, 0, 0)
; template <int TM, int TN>
; DI void gemm_mainloop(const u16* __restrict__ A, long lda, const u16* __restrict__ Bt, long ldb, int K, char* smem,
;                       f32x16 (&acc)[TM][TN]) {
;     ...
;   const int nk = K / 64;
;   const int lrow = tid >> 3, lch = (tid & 7) * 8;
;   const u16* gA = A + (long)lrow * lda + lch;
;   const u16* gB = Bt + (long)lrow * ldb + lch;
;   const int soff = lrow * LD + lch;
;     ...
;   GEMM_GLOAD(0)
;   __syncthreads();
;   GEMM_SSTORE(0)
;   if (nk > 1) GEMM_GLOAD(64)
;   __syncthreads();
;   for (int kt = 0; kt < nk; kt++) {
;     const int buf = kt & 1;
;     const u16* cA = sA + buf * BM * LD + (wm * 32 * TM + r) * LD + h * 8;
;     const u16* cB = sB + buf * BN * LD + (wn * 32 * TN + r) * LD + h * 8;
;     bf16x8 af[TM], bfr[TN];
; #pragma unroll
;     for (int tm = 0; tm < TM; tm++) af[tm] = *(const bf16x8*)(cA + tm * 32 * LD);
; #pragma unroll
;     for (int tn = 0; tn < TN; tn++) bfr[tn] = *(const bf16x8*)(cB + tn * 32 * LD);
;     if (kt + 1 < nk) GEMM_SSTORE(buf ^ 1)
;     __builtin_amdgcn_sched_barrier(0);
;     __builtin_amdgcn_s_setprio(1);
; #pragma unroll
;     for (int tm = 0; tm < TM; tm++)
; #pragma unroll
;       for (int tn = 0; tn < TN; tn++) acc[tm][tn] = MFMA(af[tm], bfr[tn], acc[tm][tn]);
; #pragma unroll
;     for (int tm = 0; tm < TM; tm++) af[tm] = *(const bf16x8*)(cA + tm * 32 * LD + 16);
; #pragma unroll
;     for (int tn = 0; tn < TN; tn++) bfr[tn] = *(const bf16x8*)(cB + tn * 32 * LD + 16);
; #pragma unroll
;     for (int tm = 0; tm < TM; tm++)
; #pragma unroll
;       for (int tn = 0; tn < TN; tn++) acc[tm][tn] = MFMA(af[tm], bfr[tn], acc[tm][tn]);
;     __builtin_amdgcn_sched_group_barrier(0x8, 4, 0);
;     if (kt + 2 < nk) GEMM_GLOAD((kt + 2) * 64)
; #pragma unroll
;     for (int ks = 2; ks < 4; ks++) {
; #pragma unroll
;       for (int tm = 0; tm < TM; tm++) af[tm] = *(const bf16x8*)(cA + tm * 32 * LD + ks * 16);
; #pragma unroll
;       for (int tn = 0; tn < TN; tn++) bfr[tn] = *(const bf16x8*)(cB + tn * 32 * LD + ks * 16);
; #pragma unroll
;       for (int tm = 0; tm < TM; tm++)
; #pragma unroll
;         for (int tn = 0; tn < TN; tn++) acc[tm][tn] = MFMA(af[tm], bfr[tn], acc[tm][tn]);
;     }
.LBB0_131:
	s_mul_hi_i32 s4, s30, 0x66666667
	s_lshr_b32 s5, s4, 31
	s_ashr_i32 s4, s4, 3
	s_add_i32 s5, s4, s5
	s_mul_i32 s4, s5, 20
	s_sub_i32 s4, s30, s4
	s_lshl_b32 s31, s5, 7
	s_mul_i32 s5, s5, 0x44000
	s_mul_hi_i32 s17, s31, 0x880
	s_add_u32 s16, s8, s5
	v_mov_b32_e32 v1, v0
	s_addc_u32 s17, s9, s17
	s_mul_i32 s5, s4, 0x44000
	v_lshlrev_b32_e32 v2, 3, v1
	v_ashrrev_i32_e32 v68, 3, v1
	v_and_b32_e32 v69, 56, v2
	v_mov_b64_e32 v[2:3], s[16:17]
	v_mad_i64_i32 v[2:3], s[16:17], v68, s3, v[2:3]
	v_lshlrev_b32_e32 v66, 1, v69
	v_lshl_add_u64 v[72:73], v[2:3], 0, v[66:67]
	s_ashr_i32 s19, s5, 31
	v_add_co_u32_e32 v70, vcc, s21, v72
	s_add_u32 s18, s10, s5
	s_nop 0
	v_addc_co_u32_e32 v71, vcc, 0, v73, vcc
	s_addc_u32 s19, s11, s19
	v_add_co_u32_e32 v74, vcc, s22, v72
	v_mov_b64_e32 v[2:3], s[18:19]
	s_nop 0
	v_addc_co_u32_e32 v75, vcc, 0, v73, vcc
	v_mad_i64_i32 v[18:19], s[16:17], v68, s3, v[2:3]
	v_add_co_u32_e32 v78, vcc, s23, v72
	v_lshl_add_u64 v[76:77], v[18:19], 0, v[66:67]
	s_nop 0
	v_addc_co_u32_e32 v79, vcc, 0, v73, vcc
	v_add_co_u32_e32 v80, vcc, s21, v76
	global_load_dwordx4 v[2:5], v[72:73], off
	s_nop 0
	v_addc_co_u32_e32 v81, vcc, 0, v77, vcc
	v_add_co_u32_e32 v82, vcc, s22, v76
	global_load_dwordx4 v[6:9], v[70:71], off
	s_nop 0
	v_addc_co_u32_e32 v83, vcc, 0, v77, vcc
	v_add_co_u32_e32 v84, vcc, s23, v76
	global_load_dwordx4 v[10:13], v[74:75], off
	s_nop 0
	v_addc_co_u32_e32 v85, vcc, 0, v77, vcc
	global_load_dwordx4 v[14:17], v[78:79], off
	global_load_dwordx4 v[18:21], v[76:77], off
	global_load_dwordx4 v[22:25], v[80:81], off
	global_load_dwordx4 v[26:29], v[82:83], off
	global_load_dwordx4 v[30:33], v[84:85], off
	s_barrier
	global_load_dwordx4 v[34:37], v[72:73], off offset:128
	global_load_dwordx4 v[38:41], v[70:71], off offset:128
	global_load_dwordx4 v[42:45], v[74:75], off offset:128
	global_load_dwordx4 v[46:49], v[78:79], off offset:128
	global_load_dwordx4 v[50:53], v[76:77], off offset:128
	global_load_dwordx4 v[54:57], v[80:81], off offset:128
	global_load_dwordx4 v[58:61], v[82:83], off offset:128
	global_load_dwordx4 v[62:65], v[84:85], off offset:128
	v_and_b32_e32 v66, 31, v1
	v_lshrrev_b32_e32 v86, 1, v1
	v_and_b32_e32 v1, 0x5f, v1
	v_mul_lo_u32 v68, v68, s20
	v_and_or_b32 v87, v86, s24, v66
	v_and_b32_e32 v86, 16, v86
	v_add_lshl_u32 v66, v68, v69, 1
	v_mad_u64_u32 v[68:69], s[16:17], v87, s25, v[86:87]
	v_mad_u32_u24 v1, v1, s25, v86
	v_add_u32_e32 v69, 0x9000, v66
	s_waitcnt vmcnt(15)
	ds_write_b128 v66, v[2:5]
	s_waitcnt vmcnt(14)
	ds_write_b128 v66, v[6:9] offset:4608
	s_waitcnt vmcnt(13)
	ds_write_b128 v66, v[10:13] offset:9216
	s_waitcnt vmcnt(12)
	ds_write_b128 v66, v[14:17] offset:13824
	s_waitcnt vmcnt(11)
	ds_write_b128 v66, v[18:21] offset:36864
	s_waitcnt vmcnt(10)
	ds_write_b128 v66, v[22:25] offset:41472
	s_waitcnt vmcnt(9)
	ds_write_b128 v66, v[26:29] offset:46080
	s_waitcnt vmcnt(8)
	ds_write_b128 v66, v[30:33] offset:50688
	s_waitcnt lgkmcnt(0)
	s_barrier
	ds_read_b128 v[2:5], v68
	ds_read_b128 v[18:21], v68 offset:4608
	ds_read_b128 v[6:9], v1 offset:36864
	ds_read_b128 v[22:25], v1 offset:41472
	s_waitcnt vmcnt(7)
	ds_write_b128 v66, v[34:37] offset:18432
	s_waitcnt vmcnt(6)
	ds_write_b128 v66, v[38:41] offset:23040
	s_waitcnt vmcnt(5)
	ds_write_b128 v66, v[42:45] offset:27648
	s_waitcnt vmcnt(4)
	ds_write_b128 v66, v[46:49] offset:32256
	s_waitcnt vmcnt(3)
	ds_write_b128 v66, v[50:53] offset:55296
	s_waitcnt vmcnt(2)
	ds_write_b128 v66, v[54:57] offset:59904
	s_waitcnt vmcnt(1)
	ds_write_b128 v66, v[58:61] offset:64512
	s_waitcnt vmcnt(0)
	ds_write_b128 v69, v[62:65] offset:32256
	s_setprio 1
	ds_read_b128 v[86:89], v68 offset:32
	s_waitcnt lgkmcnt(10)
	v_mfma_f32_32x32x16_bf16 v[34:49], v[2:5], v[6:9], 0
	ds_read_b128 v[90:93], v1 offset:36896
	ds_read_b128 v[94:97], v1 offset:41504
	ds_read_b128 v[98:101], v68 offset:4704
	global_load_dwordx4 v[102:105], v[70:71], off offset:256
	global_load_dwordx4 v[106:109], v[74:75], off offset:256
	global_load_dwordx4 v[110:113], v[78:79], off offset:256
	global_load_dwordx4 v[114:117], v[84:85], off offset:256
	s_waitcnt lgkmcnt(12)
	v_mfma_f32_32x32x16_bf16 v[50:65], v[2:5], v[22:25], 0
	global_load_dwordx4 v[118:121], v[82:83], off offset:256
	global_load_dwordx4 v[122:125], v[80:81], off offset:256
	s_waitcnt lgkmcnt(2)
	v_mfma_f32_32x32x16_bf16 v[34:49], v[86:89], v[90:93], v[34:49]
	s_waitcnt lgkmcnt(1)
	v_mfma_f32_32x32x16_bf16 v[50:65], v[86:89], v[94:97], v[50:65]
	ds_read_b128 v[86:89], v68 offset:4640
	v_mfma_f32_32x32x16_bf16 v[2:17], v[18:21], v[6:9], 0
	v_mfma_f32_32x32x16_bf16 v[18:33], v[18:21], v[22:25], 0
	s_waitcnt lgkmcnt(0)
	v_mfma_f32_32x32x16_bf16 v[2:17], v[86:89], v[90:93], v[2:17]
	ds_read_b128 v[90:93], v1 offset:36928
	v_mfma_f32_32x32x16_bf16 v[18:33], v[86:89], v[94:97], v[18:33]
	ds_read_b128 v[86:89], v68 offset:64
	ds_read_b128 v[94:97], v1 offset:41536
	s_waitcnt lgkmcnt(1)
	v_mfma_f32_32x32x16_bf16 v[34:49], v[86:89], v[90:93], v[34:49]
	s_waitcnt lgkmcnt(0)
	v_mfma_f32_32x32x16_bf16 v[50:65], v[86:89], v[94:97], v[50:65]
	ds_read_b128 v[86:89], v68 offset:4672
	s_waitcnt lgkmcnt(0)
	v_mfma_f32_32x32x16_bf16 v[2:17], v[86:89], v[90:93], v[2:17]
	ds_read_b128 v[90:93], v1 offset:36960
	v_mfma_f32_32x32x16_bf16 v[18:33], v[86:89], v[94:97], v[18:33]
	ds_read_b128 v[86:89], v68 offset:96
	ds_read_b128 v[94:97], v1 offset:41568
	s_waitcnt lgkmcnt(1)
	v_mfma_f32_32x32x16_bf16 v[34:49], v[86:89], v[90:93], v[34:49]
	s_waitcnt lgkmcnt(0)
	v_mfma_f32_32x32x16_bf16 v[50:65], v[86:89], v[94:97], v[50:65]
	global_load_dwordx4 v[86:89], v[72:73], off offset:256
	v_mfma_f32_32x32x16_bf16 v[2:17], v[98:101], v[90:93], v[2:17]
	global_load_dwordx4 v[90:93], v[76:77], off offset:256
	v_mfma_f32_32x32x16_bf16 v[18:33], v[98:101], v[94:97], v[18:33]
	s_setprio 0
	s_barrier
; #define MFMA(a, b, c) __builtin_amdgcn_mfma_f32_32x32x16_bf16((a), (b), (c), 0, 0, 0)
; template <int TM, int TN>
; DI void gemm_mainloop(const u16* __restrict__ A, long lda, const u16* __restrict__ Bt, long ldb, int K, char* smem,
;                       f32x16 (&acc)[TM][TN]) {
;     ...
;   for (int kt = 0; kt < nk; kt++) {
;     const int buf = kt & 1;
;     const u16* cA = sA + buf * BM * LD + (wm * 32 * TM + r) * LD + h * 8;
;     const u16* cB = sB + buf * BN * LD + (wn * 32 * TN + r) * LD + h * 8;
;     bf16x8 af[TM], bfr[TN];
; #pragma unroll
;     for (int tm = 0; tm < TM; tm++) af[tm] = *(const bf16x8*)(cA + tm * 32 * LD);
; #pragma unroll
;     for (int tn = 0; tn < TN; tn++) bfr[tn] = *(const bf16x8*)(cB + tn * 32 * LD);
;     if (kt + 1 < nk) GEMM_SSTORE(buf ^ 1)
;     __builtin_amdgcn_sched_barrier(0);
;     __builtin_amdgcn_s_setprio(1);
; #pragma unroll
;     for (int tm = 0; tm < TM; tm++)
; #pragma unroll
;       for (int tn = 0; tn < TN; tn++) acc[tm][tn] = MFMA(af[tm], bfr[tn], acc[tm][tn]);
; #pragma unroll
;     for (int tm = 0; tm < TM; tm++) af[tm] = *(const bf16x8*)(cA + tm * 32 * LD + 16);
; #pragma unroll
;     for (int tn = 0; tn < TN; tn++) bfr[tn] = *(const bf16x8*)(cB + tn * 32 * LD + 16);
; #pragma unroll
;     for (int tm = 0; tm < TM; tm++)
; #pragma unroll
;       for (int tn = 0; tn < TN; tn++) acc[tm][tn] = MFMA(af[tm], bfr[tn], acc[tm][tn]);
;     __builtin_amdgcn_sched_group_barrier(0x8, 4, 0);
;     if (kt + 2 < nk) GEMM_GLOAD((kt + 2) * 64)
; #pragma unroll
;     for (int ks = 2; ks < 4; ks++) {
; #pragma unroll
;       for (int tm = 0; tm < TM; tm++) af[tm] = *(const bf16x8*)(cA + tm * 32 * LD + ks * 16);
; #pragma unroll
;       for (int tn = 0; tn < TN; tn++) bfr[tn] = *(const bf16x8*)(cB + tn * 32 * LD + ks * 16);
; #pragma unroll
;       for (int tm = 0; tm < TM; tm++)
; #pragma unroll
;         for (int tn = 0; tn < TN; tn++) acc[tm][tn] = MFMA(af[tm], bfr[tn], acc[tm][tn]);
;     }
	ds_read_b128 v[94:97], v68 offset:18432
	ds_read_b128 v[98:101], v68 offset:23040
	ds_read_b128 v[126:129], v1 offset:55296
	ds_read_b128 v[130:133], v1 offset:59904
	s_waitcnt vmcnt(1)
	ds_write_b128 v66, v[86:89]
	ds_write_b128 v66, v[102:105] offset:4608
	ds_write_b128 v66, v[106:109] offset:9216
	ds_write_b128 v66, v[110:113] offset:13824
	s_waitcnt vmcnt(0)
	ds_write_b128 v66, v[90:93] offset:36864
	ds_write_b128 v66, v[122:125] offset:41472
	ds_write_b128 v66, v[118:121] offset:46080
	ds_write_b128 v66, v[114:117] offset:50688
	s_setprio 1
	ds_read_b128 v[86:89], v68 offset:18464
	s_waitcnt lgkmcnt(10)
	v_mfma_f32_32x32x16_bf16 v[34:49], v[94:97], v[126:129], v[34:49]
	ds_read_b128 v[90:93], v1 offset:55328
	global_load_dwordx4 v[102:105], v[70:71], off offset:384
	global_load_dwordx4 v[106:109], v[74:75], off offset:384
	global_load_dwordx4 v[110:113], v[78:79], off offset:384
	global_load_dwordx4 v[114:117], v[84:85], off offset:384
	global_load_dwordx4 v[118:121], v[82:83], off offset:384
	global_load_dwordx4 v[122:125], v[80:81], off offset:384
	s_waitcnt lgkmcnt(10)
	v_mfma_f32_32x32x16_bf16 v[50:65], v[94:97], v[130:133], v[50:65]
	ds_read_b128 v[94:97], v1 offset:59936
	s_waitcnt lgkmcnt(1)
	v_mfma_f32_32x32x16_bf16 v[34:49], v[86:89], v[90:93], v[34:49]
	s_waitcnt lgkmcnt(0)
	v_mfma_f32_32x32x16_bf16 v[50:65], v[86:89], v[94:97], v[50:65]
	ds_read_b128 v[86:89], v68 offset:23072
	v_mfma_f32_32x32x16_bf16 v[2:17], v[98:101], v[126:129], v[2:17]
	v_mfma_f32_32x32x16_bf16 v[18:33], v[98:101], v[130:133], v[18:33]
	ds_read_b128 v[98:101], v68 offset:23136
	s_waitcnt lgkmcnt(1)
	v_mfma_f32_32x32x16_bf16 v[2:17], v[86:89], v[90:93], v[2:17]
	ds_read_b128 v[90:93], v1 offset:55360
	v_mfma_f32_32x32x16_bf16 v[18:33], v[86:89], v[94:97], v[18:33]
	ds_read_b128 v[86:89], v68 offset:18496
	ds_read_b128 v[94:97], v1 offset:59968
	s_waitcnt lgkmcnt(1)
	v_mfma_f32_32x32x16_bf16 v[34:49], v[86:89], v[90:93], v[34:49]
	s_waitcnt lgkmcnt(0)
	v_mfma_f32_32x32x16_bf16 v[50:65], v[86:89], v[94:97], v[50:65]
	ds_read_b128 v[86:89], v68 offset:23104
	s_waitcnt lgkmcnt(0)
	v_mfma_f32_32x32x16_bf16 v[2:17], v[86:89], v[90:93], v[2:17]
	ds_read_b128 v[90:93], v1 offset:55392
	v_mfma_f32_32x32x16_bf16 v[18:33], v[86:89], v[94:97], v[18:33]
	ds_read_b128 v[86:89], v68 offset:18528
	ds_read_b128 v[94:97], v1 offset:60000
	s_waitcnt lgkmcnt(1)
	v_mfma_f32_32x32x16_bf16 v[34:49], v[86:89], v[90:93], v[34:49]
	s_waitcnt lgkmcnt(0)
	v_mfma_f32_32x32x16_bf16 v[50:65], v[86:89], v[94:97], v[50:65]
	global_load_dwordx4 v[86:89], v[72:73], off offset:384
	v_mfma_f32_32x32x16_bf16 v[2:17], v[98:101], v[90:93], v[2:17]
	global_load_dwordx4 v[90:93], v[76:77], off offset:384
	v_mfma_f32_32x32x16_bf16 v[18:33], v[98:101], v[94:97], v[18:33]
	s_setprio 0
	s_barrier
	ds_read_b128 v[94:97], v68
	ds_read_b128 v[98:101], v68 offset:4608
	ds_read_b128 v[126:129], v1 offset:36864
	ds_read_b128 v[130:133], v1 offset:41472
	s_waitcnt vmcnt(1)
	ds_write_b128 v66, v[86:89] offset:18432
	ds_write_b128 v66, v[102:105] offset:23040
	ds_write_b128 v66, v[106:109] offset:27648
	ds_write_b128 v66, v[110:113] offset:32256
	s_waitcnt vmcnt(0)
	ds_write_b128 v66, v[90:93] offset:55296
	ds_write_b128 v66, v[122:125] offset:59904
	ds_write_b128 v66, v[118:121] offset:64512
	ds_write_b128 v69, v[114:117] offset:32256
	s_setprio 1
	ds_read_b128 v[86:89], v68 offset:32
	s_waitcnt lgkmcnt(10)
	v_mfma_f32_32x32x16_bf16 v[34:49], v[94:97], v[126:129], v[34:49]
	ds_read_b128 v[90:93], v1 offset:36896
	global_load_dwordx4 v[102:105], v[70:71], off offset:512
	global_load_dwordx4 v[106:109], v[74:75], off offset:512
	global_load_dwordx4 v[110:113], v[78:79], off offset:512
	global_load_dwordx4 v[114:117], v[84:85], off offset:512
	global_load_dwordx4 v[118:121], v[82:83], off offset:512
	global_load_dwordx4 v[122:125], v[80:81], off offset:512
	s_waitcnt lgkmcnt(10)
	v_mfma_f32_32x32x16_bf16 v[50:65], v[94:97], v[130:133], v[50:65]
	ds_read_b128 v[94:97], v1 offset:41504
	s_waitcnt lgkmcnt(1)
	v_mfma_f32_32x32x16_bf16 v[34:49], v[86:89], v[90:93], v[34:49]
	s_waitcnt lgkmcnt(0)
	v_mfma_f32_32x32x16_bf16 v[50:65], v[86:89], v[94:97], v[50:65]
	ds_read_b128 v[86:89], v68 offset:4640
	v_mfma_f32_32x32x16_bf16 v[2:17], v[98:101], v[126:129], v[2:17]
	v_mfma_f32_32x32x16_bf16 v[18:33], v[98:101], v[130:133], v[18:33]
	ds_read_b128 v[98:101], v68 offset:4704
	s_waitcnt lgkmcnt(1)
	v_mfma_f32_32x32x16_bf16 v[2:17], v[86:89], v[90:93], v[2:17]
	ds_read_b128 v[90:93], v1 offset:36928
	v_mfma_f32_32x32x16_bf16 v[18:33], v[86:89], v[94:97], v[18:33]
	ds_read_b128 v[86:89], v68 offset:64
	ds_read_b128 v[94:97], v1 offset:41536
	s_waitcnt lgkmcnt(1)
	v_mfma_f32_32x32x16_bf16 v[34:49], v[86:89], v[90:93], v[34:49]
	s_waitcnt lgkmcnt(0)
	v_mfma_f32_32x32x16_bf16 v[50:65], v[86:89], v[94:97], v[50:65]
	ds_read_b128 v[86:89], v68 offset:4672
	s_waitcnt lgkmcnt(0)
	v_mfma_f32_32x32x16_bf16 v[2:17], v[86:89], v[90:93], v[2:17]
	ds_read_b128 v[90:93], v1 offset:36960
	v_mfma_f32_32x32x16_bf16 v[18:33], v[86:89], v[94:97], v[18:33]
	ds_read_b128 v[86:89], v68 offset:96
	ds_read_b128 v[94:97], v1 offset:41568
	s_waitcnt lgkmcnt(1)
	v_mfma_f32_32x32x16_bf16 v[34:49], v[86:89], v[90:93], v[34:49]
	s_waitcnt lgkmcnt(0)
	v_mfma_f32_32x32x16_bf16 v[50:65], v[86:89], v[94:97], v[50:65]
	global_load_dwordx4 v[86:89], v[72:73], off offset:512
	v_mfma_f32_32x32x16_bf16 v[2:17], v[98:101], v[90:93], v[2:17]
	global_load_dwordx4 v[90:93], v[76:77], off offset:512
	v_mfma_f32_32x32x16_bf16 v[18:33], v[98:101], v[94:97], v[18:33]
	s_setprio 0
	s_barrier
; #define MFMA(a, b, c) __builtin_amdgcn_mfma_f32_32x32x16_bf16((a), (b), (c), 0, 0, 0)
; template <int TM, int TN>
; DI void gemm_mainloop(const u16* __restrict__ A, long lda, const u16* __restrict__ Bt, long ldb, int K, char* smem,
;                       f32x16 (&acc)[TM][TN]) {
;     ...
;   for (int kt = 0; kt < nk; kt++) {
;     const int buf = kt & 1;
;     const u16* cA = sA + buf * BM * LD + (wm * 32 * TM + r) * LD + h * 8;
;     const u16* cB = sB + buf * BN * LD + (wn * 32 * TN + r) * LD + h * 8;
;     bf16x8 af[TM], bfr[TN];
; #pragma unroll
;     for (int tm = 0; tm < TM; tm++) af[tm] = *(const bf16x8*)(cA + tm * 32 * LD);
; #pragma unroll
;     for (int tn = 0; tn < TN; tn++) bfr[tn] = *(const bf16x8*)(cB + tn * 32 * LD);
;     if (kt + 1 < nk) GEMM_SSTORE(buf ^ 1)
;     __builtin_amdgcn_sched_barrier(0);
;     __builtin_amdgcn_s_setprio(1);
; #pragma unroll
;     for (int tm = 0; tm < TM; tm++)
; #pragma unroll
;       for (int tn = 0; tn < TN; tn++) acc[tm][tn] = MFMA(af[tm], bfr[tn], acc[tm][tn]);
; #pragma unroll
;     for (int tm = 0; tm < TM; tm++) af[tm] = *(const bf16x8*)(cA + tm * 32 * LD + 16);
; #pragma unroll
;     for (int tn = 0; tn < TN; tn++) bfr[tn] = *(const bf16x8*)(cB + tn * 32 * LD + 16);
; #pragma unroll
;     for (int tm = 0; tm < TM; tm++)
; #pragma unroll
;       for (int tn = 0; tn < TN; tn++) acc[tm][tn] = MFMA(af[tm], bfr[tn], acc[tm][tn]);
;     __builtin_amdgcn_sched_group_barrier(0x8, 4, 0);
;     if (kt + 2 < nk) GEMM_GLOAD((kt + 2) * 64)
; #pragma unroll
;     for (int ks = 2; ks < 4; ks++) {
; #pragma unroll
;       for (int tm = 0; tm < TM; tm++) af[tm] = *(const bf16x8*)(cA + tm * 32 * LD + ks * 16);
; #pragma unroll
;       for (int tn = 0; tn < TN; tn++) bfr[tn] = *(const bf16x8*)(cB + tn * 32 * LD + ks * 16);
; #pragma unroll
;       for (int tm = 0; tm < TM; tm++)
; #pragma unroll
;         for (int tn = 0; tn < TN; tn++) acc[tm][tn] = MFMA(af[tm], bfr[tn], acc[tm][tn]);
;     }
	ds_read_b128 v[94:97], v68 offset:18432
	ds_read_b128 v[98:101], v68 offset:23040
	ds_read_b128 v[126:129], v1 offset:55296
	ds_read_b128 v[130:133], v1 offset:59904
	s_waitcnt vmcnt(1)
	ds_write_b128 v66, v[86:89]
	ds_write_b128 v66, v[102:105] offset:4608
	ds_write_b128 v66, v[106:109] offset:9216
	ds_write_b128 v66, v[110:113] offset:13824
	s_waitcnt vmcnt(0)
	ds_write_b128 v66, v[90:93] offset:36864
	ds_write_b128 v66, v[122:125] offset:41472
	ds_write_b128 v66, v[118:121] offset:46080
	ds_write_b128 v66, v[114:117] offset:50688
	s_setprio 1
	ds_read_b128 v[86:89], v68 offset:18464
	s_waitcnt lgkmcnt(10)
	v_mfma_f32_32x32x16_bf16 v[34:49], v[94:97], v[126:129], v[34:49]
	ds_read_b128 v[90:93], v1 offset:55328
	global_load_dwordx4 v[102:105], v[70:71], off offset:640
	global_load_dwordx4 v[106:109], v[74:75], off offset:640
	global_load_dwordx4 v[110:113], v[78:79], off offset:640
	global_load_dwordx4 v[114:117], v[84:85], off offset:640
	global_load_dwordx4 v[118:121], v[82:83], off offset:640
	global_load_dwordx4 v[122:125], v[80:81], off offset:640
	s_waitcnt lgkmcnt(10)
	v_mfma_f32_32x32x16_bf16 v[50:65], v[94:97], v[130:133], v[50:65]
	ds_read_b128 v[94:97], v1 offset:59936
	s_waitcnt lgkmcnt(1)
	v_mfma_f32_32x32x16_bf16 v[34:49], v[86:89], v[90:93], v[34:49]
	s_waitcnt lgkmcnt(0)
	v_mfma_f32_32x32x16_bf16 v[50:65], v[86:89], v[94:97], v[50:65]
	ds_read_b128 v[86:89], v68 offset:23072
	v_mfma_f32_32x32x16_bf16 v[2:17], v[98:101], v[126:129], v[2:17]
	v_mfma_f32_32x32x16_bf16 v[18:33], v[98:101], v[130:133], v[18:33]
	ds_read_b128 v[98:101], v68 offset:23136
	s_waitcnt lgkmcnt(1)
	v_mfma_f32_32x32x16_bf16 v[2:17], v[86:89], v[90:93], v[2:17]
	ds_read_b128 v[90:93], v1 offset:55360
	v_mfma_f32_32x32x16_bf16 v[18:33], v[86:89], v[94:97], v[18:33]
	ds_read_b128 v[86:89], v68 offset:18496
	ds_read_b128 v[94:97], v1 offset:59968
	s_waitcnt lgkmcnt(1)
	v_mfma_f32_32x32x16_bf16 v[34:49], v[86:89], v[90:93], v[34:49]
	s_waitcnt lgkmcnt(0)
	v_mfma_f32_32x32x16_bf16 v[50:65], v[86:89], v[94:97], v[50:65]
	ds_read_b128 v[86:89], v68 offset:23104
	s_waitcnt lgkmcnt(0)
	v_mfma_f32_32x32x16_bf16 v[2:17], v[86:89], v[90:93], v[2:17]
	ds_read_b128 v[90:93], v1 offset:55392
	v_mfma_f32_32x32x16_bf16 v[18:33], v[86:89], v[94:97], v[18:33]
	ds_read_b128 v[86:89], v68 offset:18528
	ds_read_b128 v[94:97], v1 offset:60000
	s_waitcnt lgkmcnt(1)
	v_mfma_f32_32x32x16_bf16 v[34:49], v[86:89], v[90:93], v[34:49]
	s_waitcnt lgkmcnt(0)
	v_mfma_f32_32x32x16_bf16 v[50:65], v[86:89], v[94:97], v[50:65]
	global_load_dwordx4 v[86:89], v[72:73], off offset:640
	v_mfma_f32_32x32x16_bf16 v[2:17], v[98:101], v[90:93], v[2:17]
	global_load_dwordx4 v[90:93], v[76:77], off offset:640
	v_mfma_f32_32x32x16_bf16 v[18:33], v[98:101], v[94:97], v[18:33]
	s_setprio 0
	s_barrier
	ds_read_b128 v[94:97], v68
	ds_read_b128 v[98:101], v68 offset:4608
	ds_read_b128 v[126:129], v1 offset:36864
	ds_read_b128 v[130:133], v1 offset:41472
	s_waitcnt vmcnt(1)
	ds_write_b128 v66, v[86:89] offset:18432
	ds_write_b128 v66, v[102:105] offset:23040
	ds_write_b128 v66, v[106:109] offset:27648
	ds_write_b128 v66, v[110:113] offset:32256
	s_waitcnt vmcnt(0)
	ds_write_b128 v66, v[90:93] offset:55296
	ds_write_b128 v66, v[122:125] offset:59904
	ds_write_b128 v66, v[118:121] offset:64512
	ds_write_b128 v69, v[114:117] offset:32256
	s_setprio 1
	ds_read_b128 v[86:89], v68 offset:32
	s_waitcnt lgkmcnt(10)
	v_mfma_f32_32x32x16_bf16 v[34:49], v[94:97], v[126:129], v[34:49]
	ds_read_b128 v[90:93], v1 offset:36896
	global_load_dwordx4 v[102:105], v[70:71], off offset:768
	global_load_dwordx4 v[106:109], v[74:75], off offset:768
	global_load_dwordx4 v[110:113], v[78:79], off offset:768
	global_load_dwordx4 v[114:117], v[84:85], off offset:768
	global_load_dwordx4 v[118:121], v[82:83], off offset:768
	global_load_dwordx4 v[122:125], v[80:81], off offset:768
	s_waitcnt lgkmcnt(10)
	v_mfma_f32_32x32x16_bf16 v[50:65], v[94:97], v[130:133], v[50:65]
	ds_read_b128 v[94:97], v1 offset:41504
	s_waitcnt lgkmcnt(1)
	v_mfma_f32_32x32x16_bf16 v[34:49], v[86:89], v[90:93], v[34:49]
	s_waitcnt lgkmcnt(0)
	v_mfma_f32_32x32x16_bf16 v[50:65], v[86:89], v[94:97], v[50:65]
	ds_read_b128 v[86:89], v68 offset:4640
	v_mfma_f32_32x32x16_bf16 v[2:17], v[98:101], v[126:129], v[2:17]
	v_mfma_f32_32x32x16_bf16 v[18:33], v[98:101], v[130:133], v[18:33]
	ds_read_b128 v[98:101], v68 offset:4704
	s_waitcnt lgkmcnt(1)
	v_mfma_f32_32x32x16_bf16 v[2:17], v[86:89], v[90:93], v[2:17]
	ds_read_b128 v[90:93], v1 offset:36928
	v_mfma_f32_32x32x16_bf16 v[18:33], v[86:89], v[94:97], v[18:33]
	ds_read_b128 v[86:89], v68 offset:64
	ds_read_b128 v[94:97], v1 offset:41536
	s_waitcnt lgkmcnt(1)
	v_mfma_f32_32x32x16_bf16 v[34:49], v[86:89], v[90:93], v[34:49]
	s_waitcnt lgkmcnt(0)
	v_mfma_f32_32x32x16_bf16 v[50:65], v[86:89], v[94:97], v[50:65]
	ds_read_b128 v[86:89], v68 offset:4672
	s_waitcnt lgkmcnt(0)
	v_mfma_f32_32x32x16_bf16 v[2:17], v[86:89], v[90:93], v[2:17]
	ds_read_b128 v[90:93], v1 offset:36960
	v_mfma_f32_32x32x16_bf16 v[18:33], v[86:89], v[94:97], v[18:33]
	ds_read_b128 v[86:89], v68 offset:96
	ds_read_b128 v[94:97], v1 offset:41568
	s_waitcnt lgkmcnt(1)
	v_mfma_f32_32x32x16_bf16 v[34:49], v[86:89], v[90:93], v[34:49]
	s_waitcnt lgkmcnt(0)
	v_mfma_f32_32x32x16_bf16 v[50:65], v[86:89], v[94:97], v[50:65]
	global_load_dwordx4 v[86:89], v[72:73], off offset:768
	v_mfma_f32_32x32x16_bf16 v[2:17], v[98:101], v[90:93], v[2:17]
	global_load_dwordx4 v[90:93], v[76:77], off offset:768
	v_mfma_f32_32x32x16_bf16 v[18:33], v[98:101], v[94:97], v[18:33]
	s_setprio 0
	s_barrier
; #define MFMA(a, b, c) __builtin_amdgcn_mfma_f32_32x32x16_bf16((a), (b), (c), 0, 0, 0)
; template <int TM, int TN>
; DI void gemm_mainloop(const u16* __restrict__ A, long lda, const u16* __restrict__ Bt, long ldb, int K, char* smem,
;                       f32x16 (&acc)[TM][TN]) {
;     ...
;   for (int kt = 0; kt < nk; kt++) {
;     const int buf = kt & 1;
;     const u16* cA = sA + buf * BM * LD + (wm * 32 * TM + r) * LD + h * 8;
;     const u16* cB = sB + buf * BN * LD + (wn * 32 * TN + r) * LD + h * 8;
;     bf16x8 af[TM], bfr[TN];
; #pragma unroll
;     for (int tm = 0; tm < TM; tm++) af[tm] = *(const bf16x8*)(cA + tm * 32 * LD);
; #pragma unroll
;     for (int tn = 0; tn < TN; tn++) bfr[tn] = *(const bf16x8*)(cB + tn * 32 * LD);
;     if (kt + 1 < nk) GEMM_SSTORE(buf ^ 1)
;     __builtin_amdgcn_sched_barrier(0);
;     __builtin_amdgcn_s_setprio(1);
; #pragma unroll
;     for (int tm = 0; tm < TM; tm++)
; #pragma unroll
;       for (int tn = 0; tn < TN; tn++) acc[tm][tn] = MFMA(af[tm], bfr[tn], acc[tm][tn]);
; #pragma unroll
;     for (int tm = 0; tm < TM; tm++) af[tm] = *(const bf16x8*)(cA + tm * 32 * LD + 16);
; #pragma unroll
;     for (int tn = 0; tn < TN; tn++) bfr[tn] = *(const bf16x8*)(cB + tn * 32 * LD + 16);
; #pragma unroll
;     for (int tm = 0; tm < TM; tm++)
; #pragma unroll
;       for (int tn = 0; tn < TN; tn++) acc[tm][tn] = MFMA(af[tm], bfr[tn], acc[tm][tn]);
;     __builtin_amdgcn_sched_group_barrier(0x8, 4, 0);
;     if (kt + 2 < nk) GEMM_GLOAD((kt + 2) * 64)
; #pragma unroll
;     for (int ks = 2; ks < 4; ks++) {
; #pragma unroll
;       for (int tm = 0; tm < TM; tm++) af[tm] = *(const bf16x8*)(cA + tm * 32 * LD + ks * 16);
; #pragma unroll
;       for (int tn = 0; tn < TN; tn++) bfr[tn] = *(const bf16x8*)(cB + tn * 32 * LD + ks * 16);
; #pragma unroll
;       for (int tm = 0; tm < TM; tm++)
; #pragma unroll
;         for (int tn = 0; tn < TN; tn++) acc[tm][tn] = MFMA(af[tm], bfr[tn], acc[tm][tn]);
;     }
	ds_read_b128 v[94:97], v68 offset:18432
	ds_read_b128 v[98:101], v68 offset:23040
	ds_read_b128 v[126:129], v1 offset:55296
	ds_read_b128 v[130:133], v1 offset:59904
	s_waitcnt vmcnt(1)
	ds_write_b128 v66, v[86:89]
	ds_write_b128 v66, v[102:105] offset:4608
	ds_write_b128 v66, v[106:109] offset:9216
	ds_write_b128 v66, v[110:113] offset:13824
	s_waitcnt vmcnt(0)
	ds_write_b128 v66, v[90:93] offset:36864
	ds_write_b128 v66, v[122:125] offset:41472
	ds_write_b128 v66, v[118:121] offset:46080
	ds_write_b128 v66, v[114:117] offset:50688
	s_setprio 1
	ds_read_b128 v[86:89], v68 offset:18464
	s_waitcnt lgkmcnt(10)
	v_mfma_f32_32x32x16_bf16 v[34:49], v[94:97], v[126:129], v[34:49]
	ds_read_b128 v[90:93], v1 offset:55328
	global_load_dwordx4 v[102:105], v[70:71], off offset:896
	global_load_dwordx4 v[106:109], v[74:75], off offset:896
	global_load_dwordx4 v[110:113], v[78:79], off offset:896
	global_load_dwordx4 v[114:117], v[84:85], off offset:896
	global_load_dwordx4 v[118:121], v[82:83], off offset:896
	global_load_dwordx4 v[122:125], v[80:81], off offset:896
	s_waitcnt lgkmcnt(10)
	v_mfma_f32_32x32x16_bf16 v[50:65], v[94:97], v[130:133], v[50:65]
	ds_read_b128 v[94:97], v1 offset:59936
	s_waitcnt lgkmcnt(1)
	v_mfma_f32_32x32x16_bf16 v[34:49], v[86:89], v[90:93], v[34:49]
	s_waitcnt lgkmcnt(0)
	v_mfma_f32_32x32x16_bf16 v[50:65], v[86:89], v[94:97], v[50:65]
	ds_read_b128 v[86:89], v68 offset:23072
	v_mfma_f32_32x32x16_bf16 v[2:17], v[98:101], v[126:129], v[2:17]
	v_mfma_f32_32x32x16_bf16 v[18:33], v[98:101], v[130:133], v[18:33]
	ds_read_b128 v[98:101], v68 offset:23136
	s_waitcnt lgkmcnt(1)
	v_mfma_f32_32x32x16_bf16 v[2:17], v[86:89], v[90:93], v[2:17]
	ds_read_b128 v[90:93], v1 offset:55360
	v_mfma_f32_32x32x16_bf16 v[18:33], v[86:89], v[94:97], v[18:33]
	ds_read_b128 v[86:89], v68 offset:18496
	ds_read_b128 v[94:97], v1 offset:59968
	s_waitcnt lgkmcnt(1)
	v_mfma_f32_32x32x16_bf16 v[34:49], v[86:89], v[90:93], v[34:49]
	s_waitcnt lgkmcnt(0)
	v_mfma_f32_32x32x16_bf16 v[50:65], v[86:89], v[94:97], v[50:65]
	ds_read_b128 v[86:89], v68 offset:23104
	s_waitcnt lgkmcnt(0)
	v_mfma_f32_32x32x16_bf16 v[2:17], v[86:89], v[90:93], v[2:17]
	ds_read_b128 v[90:93], v1 offset:55392
	v_mfma_f32_32x32x16_bf16 v[18:33], v[86:89], v[94:97], v[18:33]
	ds_read_b128 v[86:89], v68 offset:18528
	ds_read_b128 v[94:97], v1 offset:60000
	s_waitcnt lgkmcnt(1)
	v_mfma_f32_32x32x16_bf16 v[34:49], v[86:89], v[90:93], v[34:49]
	s_waitcnt lgkmcnt(0)
	v_mfma_f32_32x32x16_bf16 v[50:65], v[86:89], v[94:97], v[50:65]
	global_load_dwordx4 v[86:89], v[72:73], off offset:896
	v_mfma_f32_32x32x16_bf16 v[2:17], v[98:101], v[90:93], v[2:17]
	global_load_dwordx4 v[90:93], v[76:77], off offset:896
	v_mfma_f32_32x32x16_bf16 v[18:33], v[98:101], v[94:97], v[18:33]
	s_setprio 0
	s_barrier
	ds_read_b128 v[94:97], v68
	ds_read_b128 v[98:101], v68 offset:4608
	ds_read_b128 v[126:129], v1 offset:36864
	ds_read_b128 v[130:133], v1 offset:41472
	s_waitcnt vmcnt(1)
	ds_write_b128 v66, v[86:89] offset:18432
	ds_write_b128 v66, v[102:105] offset:23040
	ds_write_b128 v66, v[106:109] offset:27648
	ds_write_b128 v66, v[110:113] offset:32256
	s_waitcnt vmcnt(0)
	ds_write_b128 v66, v[90:93] offset:55296
	ds_write_b128 v66, v[122:125] offset:59904
	ds_write_b128 v66, v[118:121] offset:64512
	ds_write_b128 v69, v[114:117] offset:32256
	s_setprio 1
	ds_read_b128 v[86:89], v68 offset:32
	s_waitcnt lgkmcnt(10)
	v_mfma_f32_32x32x16_bf16 v[34:49], v[94:97], v[126:129], v[34:49]
	ds_read_b128 v[90:93], v1 offset:36896
	global_load_dwordx4 v[102:105], v[70:71], off offset:1024
	global_load_dwordx4 v[106:109], v[74:75], off offset:1024
	global_load_dwordx4 v[110:113], v[78:79], off offset:1024
	global_load_dwordx4 v[114:117], v[84:85], off offset:1024
	global_load_dwordx4 v[118:121], v[82:83], off offset:1024
	global_load_dwordx4 v[122:125], v[80:81], off offset:1024
	s_waitcnt lgkmcnt(10)
	v_mfma_f32_32x32x16_bf16 v[50:65], v[94:97], v[130:133], v[50:65]
	ds_read_b128 v[94:97], v1 offset:41504
	s_waitcnt lgkmcnt(1)
	v_mfma_f32_32x32x16_bf16 v[34:49], v[86:89], v[90:93], v[34:49]
	s_waitcnt lgkmcnt(0)
	v_mfma_f32_32x32x16_bf16 v[50:65], v[86:89], v[94:97], v[50:65]
	ds_read_b128 v[86:89], v68 offset:4640
	v_mfma_f32_32x32x16_bf16 v[2:17], v[98:101], v[126:129], v[2:17]
	v_mfma_f32_32x32x16_bf16 v[18:33], v[98:101], v[130:133], v[18:33]
	ds_read_b128 v[98:101], v68 offset:4704
	s_waitcnt lgkmcnt(1)
	v_mfma_f32_32x32x16_bf16 v[2:17], v[86:89], v[90:93], v[2:17]
	ds_read_b128 v[90:93], v1 offset:36928
	v_mfma_f32_32x32x16_bf16 v[18:33], v[86:89], v[94:97], v[18:33]
	ds_read_b128 v[86:89], v68 offset:64
	ds_read_b128 v[94:97], v1 offset:41536
	s_waitcnt lgkmcnt(1)
	v_mfma_f32_32x32x16_bf16 v[34:49], v[86:89], v[90:93], v[34:49]
	s_waitcnt lgkmcnt(0)
	v_mfma_f32_32x32x16_bf16 v[50:65], v[86:89], v[94:97], v[50:65]
	ds_read_b128 v[86:89], v68 offset:4672
	s_waitcnt lgkmcnt(0)
	v_mfma_f32_32x32x16_bf16 v[2:17], v[86:89], v[90:93], v[2:17]
	ds_read_b128 v[90:93], v1 offset:36960
	v_mfma_f32_32x32x16_bf16 v[18:33], v[86:89], v[94:97], v[18:33]
	ds_read_b128 v[86:89], v68 offset:96
	ds_read_b128 v[94:97], v1 offset:41568
	s_waitcnt lgkmcnt(1)
	v_mfma_f32_32x32x16_bf16 v[34:49], v[86:89], v[90:93], v[34:49]
	s_waitcnt lgkmcnt(0)
	v_mfma_f32_32x32x16_bf16 v[50:65], v[86:89], v[94:97], v[50:65]
	global_load_dwordx4 v[86:89], v[72:73], off offset:1024
	v_mfma_f32_32x32x16_bf16 v[2:17], v[98:101], v[90:93], v[2:17]
	global_load_dwordx4 v[90:93], v[76:77], off offset:1024
	v_mfma_f32_32x32x16_bf16 v[18:33], v[98:101], v[94:97], v[18:33]
	s_setprio 0
	s_barrier
; #define MFMA(a, b, c) __builtin_amdgcn_mfma_f32_32x32x16_bf16((a), (b), (c), 0, 0, 0)
; template <int TM, int TN>
; DI void gemm_mainloop(const u16* __restrict__ A, long lda, const u16* __restrict__ Bt, long ldb, int K, char* smem,
;                       f32x16 (&acc)[TM][TN]) {
;     ...
;   for (int kt = 0; kt < nk; kt++) {
;     const int buf = kt & 1;
;     const u16* cA = sA + buf * BM * LD + (wm * 32 * TM + r) * LD + h * 8;
;     const u16* cB = sB + buf * BN * LD + (wn * 32 * TN + r) * LD + h * 8;
;     bf16x8 af[TM], bfr[TN];
; #pragma unroll
;     for (int tm = 0; tm < TM; tm++) af[tm] = *(const bf16x8*)(cA + tm * 32 * LD);
; #pragma unroll
;     for (int tn = 0; tn < TN; tn++) bfr[tn] = *(const bf16x8*)(cB + tn * 32 * LD);
;     if (kt + 1 < nk) GEMM_SSTORE(buf ^ 1)
;     __builtin_amdgcn_sched_barrier(0);
;     __builtin_amdgcn_s_setprio(1);
; #pragma unroll
;     for (int tm = 0; tm < TM; tm++)
; #pragma unroll
;       for (int tn = 0; tn < TN; tn++) acc[tm][tn] = MFMA(af[tm], bfr[tn], acc[tm][tn]);
; #pragma unroll
;     for (int tm = 0; tm < TM; tm++) af[tm] = *(const bf16x8*)(cA + tm * 32 * LD + 16);
; #pragma unroll
;     for (int tn = 0; tn < TN; tn++) bfr[tn] = *(const bf16x8*)(cB + tn * 32 * LD + 16);
; #pragma unroll
;     for (int tm = 0; tm < TM; tm++)
; #pragma unroll
;       for (int tn = 0; tn < TN; tn++) acc[tm][tn] = MFMA(af[tm], bfr[tn], acc[tm][tn]);
;     __builtin_amdgcn_sched_group_barrier(0x8, 4, 0);
;     if (kt + 2 < nk) GEMM_GLOAD((kt + 2) * 64)
; #pragma unroll
;     for (int ks = 2; ks < 4; ks++) {
; #pragma unroll
;       for (int tm = 0; tm < TM; tm++) af[tm] = *(const bf16x8*)(cA + tm * 32 * LD + ks * 16);
; #pragma unroll
;       for (int tn = 0; tn < TN; tn++) bfr[tn] = *(const bf16x8*)(cB + tn * 32 * LD + ks * 16);
; #pragma unroll
;       for (int tm = 0; tm < TM; tm++)
; #pragma unroll
;         for (int tn = 0; tn < TN; tn++) acc[tm][tn] = MFMA(af[tm], bfr[tn], acc[tm][tn]);
;     }
	ds_read_b128 v[94:97], v68 offset:18432
	ds_read_b128 v[98:101], v68 offset:23040
	ds_read_b128 v[126:129], v1 offset:55296
	ds_read_b128 v[130:133], v1 offset:59904
	s_waitcnt vmcnt(1)
	ds_write_b128 v66, v[86:89]
	ds_write_b128 v66, v[102:105] offset:4608
	ds_write_b128 v66, v[106:109] offset:9216
	ds_write_b128 v66, v[110:113] offset:13824
	s_waitcnt vmcnt(0)
	ds_write_b128 v66, v[90:93] offset:36864
	ds_write_b128 v66, v[122:125] offset:41472
	ds_write_b128 v66, v[118:121] offset:46080
	ds_write_b128 v66, v[114:117] offset:50688
	s_setprio 1
	ds_read_b128 v[86:89], v68 offset:18464
	s_waitcnt lgkmcnt(10)
	v_mfma_f32_32x32x16_bf16 v[34:49], v[94:97], v[126:129], v[34:49]
	ds_read_b128 v[90:93], v1 offset:55328
	global_load_dwordx4 v[102:105], v[70:71], off offset:1152
	global_load_dwordx4 v[106:109], v[74:75], off offset:1152
	global_load_dwordx4 v[110:113], v[78:79], off offset:1152
	global_load_dwordx4 v[114:117], v[84:85], off offset:1152
	global_load_dwordx4 v[118:121], v[82:83], off offset:1152
	global_load_dwordx4 v[122:125], v[80:81], off offset:1152
	s_waitcnt lgkmcnt(10)
	v_mfma_f32_32x32x16_bf16 v[50:65], v[94:97], v[130:133], v[50:65]
	ds_read_b128 v[94:97], v1 offset:59936
	s_waitcnt lgkmcnt(1)
	v_mfma_f32_32x32x16_bf16 v[34:49], v[86:89], v[90:93], v[34:49]
	s_waitcnt lgkmcnt(0)
	v_mfma_f32_32x32x16_bf16 v[50:65], v[86:89], v[94:97], v[50:65]
	ds_read_b128 v[86:89], v68 offset:23072
	v_mfma_f32_32x32x16_bf16 v[2:17], v[98:101], v[126:129], v[2:17]
	v_mfma_f32_32x32x16_bf16 v[18:33], v[98:101], v[130:133], v[18:33]
	ds_read_b128 v[98:101], v68 offset:23136
	s_waitcnt lgkmcnt(1)
	v_mfma_f32_32x32x16_bf16 v[2:17], v[86:89], v[90:93], v[2:17]
	ds_read_b128 v[90:93], v1 offset:55360
	v_mfma_f32_32x32x16_bf16 v[18:33], v[86:89], v[94:97], v[18:33]
	ds_read_b128 v[86:89], v68 offset:18496
	ds_read_b128 v[94:97], v1 offset:59968
	s_waitcnt lgkmcnt(1)
	v_mfma_f32_32x32x16_bf16 v[34:49], v[86:89], v[90:93], v[34:49]
	s_waitcnt lgkmcnt(0)
	v_mfma_f32_32x32x16_bf16 v[50:65], v[86:89], v[94:97], v[50:65]
	ds_read_b128 v[86:89], v68 offset:23104
	s_waitcnt lgkmcnt(0)
	v_mfma_f32_32x32x16_bf16 v[2:17], v[86:89], v[90:93], v[2:17]
	ds_read_b128 v[90:93], v1 offset:55392
	v_mfma_f32_32x32x16_bf16 v[18:33], v[86:89], v[94:97], v[18:33]
	ds_read_b128 v[86:89], v68 offset:18528
	ds_read_b128 v[94:97], v1 offset:60000
	s_waitcnt lgkmcnt(1)
	v_mfma_f32_32x32x16_bf16 v[34:49], v[86:89], v[90:93], v[34:49]
	s_waitcnt lgkmcnt(0)
	v_mfma_f32_32x32x16_bf16 v[50:65], v[86:89], v[94:97], v[50:65]
	global_load_dwordx4 v[86:89], v[72:73], off offset:1152
	v_mfma_f32_32x32x16_bf16 v[2:17], v[98:101], v[90:93], v[2:17]
	global_load_dwordx4 v[90:93], v[76:77], off offset:1152
	v_mfma_f32_32x32x16_bf16 v[18:33], v[98:101], v[94:97], v[18:33]
	s_setprio 0
	s_barrier
	ds_read_b128 v[94:97], v68
	ds_read_b128 v[98:101], v68 offset:4608
	ds_read_b128 v[126:129], v1 offset:36864
	ds_read_b128 v[130:133], v1 offset:41472
	s_waitcnt vmcnt(1)
	ds_write_b128 v66, v[86:89] offset:18432
	ds_write_b128 v66, v[102:105] offset:23040
	ds_write_b128 v66, v[106:109] offset:27648
	ds_write_b128 v66, v[110:113] offset:32256
	s_waitcnt vmcnt(0)
	ds_write_b128 v66, v[90:93] offset:55296
	ds_write_b128 v66, v[122:125] offset:59904
	ds_write_b128 v66, v[118:121] offset:64512
	ds_write_b128 v69, v[114:117] offset:32256
	s_setprio 1
	ds_read_b128 v[86:89], v68 offset:32
	s_waitcnt lgkmcnt(10)
	v_mfma_f32_32x32x16_bf16 v[34:49], v[94:97], v[126:129], v[34:49]
	ds_read_b128 v[90:93], v1 offset:36896
	global_load_dwordx4 v[102:105], v[70:71], off offset:1280
	global_load_dwordx4 v[106:109], v[74:75], off offset:1280
	global_load_dwordx4 v[110:113], v[78:79], off offset:1280
	global_load_dwordx4 v[114:117], v[84:85], off offset:1280
	global_load_dwordx4 v[118:121], v[82:83], off offset:1280
	global_load_dwordx4 v[122:125], v[80:81], off offset:1280
	s_waitcnt lgkmcnt(10)
	v_mfma_f32_32x32x16_bf16 v[50:65], v[94:97], v[130:133], v[50:65]
	ds_read_b128 v[94:97], v1 offset:41504
	s_waitcnt lgkmcnt(1)
	v_mfma_f32_32x32x16_bf16 v[34:49], v[86:89], v[90:93], v[34:49]
	s_waitcnt lgkmcnt(0)
	v_mfma_f32_32x32x16_bf16 v[50:65], v[86:89], v[94:97], v[50:65]
	ds_read_b128 v[86:89], v68 offset:4640
	v_mfma_f32_32x32x16_bf16 v[2:17], v[98:101], v[126:129], v[2:17]
	v_mfma_f32_32x32x16_bf16 v[18:33], v[98:101], v[130:133], v[18:33]
	ds_read_b128 v[98:101], v68 offset:4704
	s_waitcnt lgkmcnt(1)
	v_mfma_f32_32x32x16_bf16 v[2:17], v[86:89], v[90:93], v[2:17]
	ds_read_b128 v[90:93], v1 offset:36928
	v_mfma_f32_32x32x16_bf16 v[18:33], v[86:89], v[94:97], v[18:33]
	ds_read_b128 v[86:89], v68 offset:64
	ds_read_b128 v[94:97], v1 offset:41536
	s_waitcnt lgkmcnt(1)
	v_mfma_f32_32x32x16_bf16 v[34:49], v[86:89], v[90:93], v[34:49]
	s_waitcnt lgkmcnt(0)
	v_mfma_f32_32x32x16_bf16 v[50:65], v[86:89], v[94:97], v[50:65]
	ds_read_b128 v[86:89], v68 offset:4672
	s_waitcnt lgkmcnt(0)
	v_mfma_f32_32x32x16_bf16 v[2:17], v[86:89], v[90:93], v[2:17]
	ds_read_b128 v[90:93], v1 offset:36960
	v_mfma_f32_32x32x16_bf16 v[18:33], v[86:89], v[94:97], v[18:33]
	ds_read_b128 v[86:89], v68 offset:96
	ds_read_b128 v[94:97], v1 offset:41568
	s_waitcnt lgkmcnt(1)
	v_mfma_f32_32x32x16_bf16 v[34:49], v[86:89], v[90:93], v[34:49]
	s_waitcnt lgkmcnt(0)
	v_mfma_f32_32x32x16_bf16 v[50:65], v[86:89], v[94:97], v[50:65]
	global_load_dwordx4 v[86:89], v[72:73], off offset:1280
	v_mfma_f32_32x32x16_bf16 v[2:17], v[98:101], v[90:93], v[2:17]
	global_load_dwordx4 v[90:93], v[76:77], off offset:1280
	v_mfma_f32_32x32x16_bf16 v[18:33], v[98:101], v[94:97], v[18:33]
	s_setprio 0
	s_barrier
; #define MFMA(a, b, c) __builtin_amdgcn_mfma_f32_32x32x16_bf16((a), (b), (c), 0, 0, 0)
; template <int TM, int TN>
; DI void gemm_mainloop(const u16* __restrict__ A, long lda, const u16* __restrict__ Bt, long ldb, int K, char* smem,
;                       f32x16 (&acc)[TM][TN]) {
;     ...
;   for (int kt = 0; kt < nk; kt++) {
;     const int buf = kt & 1;
;     const u16* cA = sA + buf * BM * LD + (wm * 32 * TM + r) * LD + h * 8;
;     const u16* cB = sB + buf * BN * LD + (wn * 32 * TN + r) * LD + h * 8;
;     bf16x8 af[TM], bfr[TN];
; #pragma unroll
;     for (int tm = 0; tm < TM; tm++) af[tm] = *(const bf16x8*)(cA + tm * 32 * LD);
; #pragma unroll
;     for (int tn = 0; tn < TN; tn++) bfr[tn] = *(const bf16x8*)(cB + tn * 32 * LD);
;     if (kt + 1 < nk) GEMM_SSTORE(buf ^ 1)
;     __builtin_amdgcn_sched_barrier(0);
;     __builtin_amdgcn_s_setprio(1);
; #pragma unroll
;     for (int tm = 0; tm < TM; tm++)
; #pragma unroll
;       for (int tn = 0; tn < TN; tn++) acc[tm][tn] = MFMA(af[tm], bfr[tn], acc[tm][tn]);
; #pragma unroll
;     for (int tm = 0; tm < TM; tm++) af[tm] = *(const bf16x8*)(cA + tm * 32 * LD + 16);
; #pragma unroll
;     for (int tn = 0; tn < TN; tn++) bfr[tn] = *(const bf16x8*)(cB + tn * 32 * LD + 16);
; #pragma unroll
;     for (int tm = 0; tm < TM; tm++)
; #pragma unroll
;       for (int tn = 0; tn < TN; tn++) acc[tm][tn] = MFMA(af[tm], bfr[tn], acc[tm][tn]);
;     __builtin_amdgcn_sched_group_barrier(0x8, 4, 0);
;     if (kt + 2 < nk) GEMM_GLOAD((kt + 2) * 64)
; #pragma unroll
;     for (int ks = 2; ks < 4; ks++) {
; #pragma unroll
;       for (int tm = 0; tm < TM; tm++) af[tm] = *(const bf16x8*)(cA + tm * 32 * LD + ks * 16);
; #pragma unroll
;       for (int tn = 0; tn < TN; tn++) bfr[tn] = *(const bf16x8*)(cB + tn * 32 * LD + ks * 16);
; #pragma unroll
;       for (int tm = 0; tm < TM; tm++)
; #pragma unroll
;         for (int tn = 0; tn < TN; tn++) acc[tm][tn] = MFMA(af[tm], bfr[tn], acc[tm][tn]);
;     }
	ds_read_b128 v[94:97], v68 offset:18432
	ds_read_b128 v[98:101], v68 offset:23040
	ds_read_b128 v[126:129], v1 offset:55296
	ds_read_b128 v[130:133], v1 offset:59904
	s_waitcnt vmcnt(1)
	ds_write_b128 v66, v[86:89]
	ds_write_b128 v66, v[102:105] offset:4608
	ds_write_b128 v66, v[106:109] offset:9216
	ds_write_b128 v66, v[110:113] offset:13824
	s_waitcnt vmcnt(0)
	ds_write_b128 v66, v[90:93] offset:36864
	ds_write_b128 v66, v[122:125] offset:41472
	ds_write_b128 v66, v[118:121] offset:46080
	ds_write_b128 v66, v[114:117] offset:50688
	s_setprio 1
	ds_read_b128 v[86:89], v68 offset:18464
	s_waitcnt lgkmcnt(10)
	v_mfma_f32_32x32x16_bf16 v[34:49], v[94:97], v[126:129], v[34:49]
	ds_read_b128 v[90:93], v1 offset:55328
	global_load_dwordx4 v[102:105], v[70:71], off offset:1408
	global_load_dwordx4 v[106:109], v[74:75], off offset:1408
	global_load_dwordx4 v[110:113], v[78:79], off offset:1408
	global_load_dwordx4 v[114:117], v[84:85], off offset:1408
	global_load_dwordx4 v[118:121], v[82:83], off offset:1408
	global_load_dwordx4 v[122:125], v[80:81], off offset:1408
	s_waitcnt lgkmcnt(10)
	v_mfma_f32_32x32x16_bf16 v[50:65], v[94:97], v[130:133], v[50:65]
	ds_read_b128 v[94:97], v1 offset:59936
	s_waitcnt lgkmcnt(1)
	v_mfma_f32_32x32x16_bf16 v[34:49], v[86:89], v[90:93], v[34:49]
	s_waitcnt lgkmcnt(0)
	v_mfma_f32_32x32x16_bf16 v[50:65], v[86:89], v[94:97], v[50:65]
	ds_read_b128 v[86:89], v68 offset:23072
	v_mfma_f32_32x32x16_bf16 v[2:17], v[98:101], v[126:129], v[2:17]
	v_mfma_f32_32x32x16_bf16 v[18:33], v[98:101], v[130:133], v[18:33]
	ds_read_b128 v[98:101], v68 offset:23136
	s_waitcnt lgkmcnt(1)
	v_mfma_f32_32x32x16_bf16 v[2:17], v[86:89], v[90:93], v[2:17]
	ds_read_b128 v[90:93], v1 offset:55360
	v_mfma_f32_32x32x16_bf16 v[18:33], v[86:89], v[94:97], v[18:33]
	ds_read_b128 v[86:89], v68 offset:18496
	ds_read_b128 v[94:97], v1 offset:59968
	s_waitcnt lgkmcnt(1)
	v_mfma_f32_32x32x16_bf16 v[34:49], v[86:89], v[90:93], v[34:49]
	s_waitcnt lgkmcnt(0)
	v_mfma_f32_32x32x16_bf16 v[50:65], v[86:89], v[94:97], v[50:65]
	ds_read_b128 v[86:89], v68 offset:23104
	s_waitcnt lgkmcnt(0)
	v_mfma_f32_32x32x16_bf16 v[2:17], v[86:89], v[90:93], v[2:17]
	ds_read_b128 v[90:93], v1 offset:55392
	v_mfma_f32_32x32x16_bf16 v[18:33], v[86:89], v[94:97], v[18:33]
	ds_read_b128 v[86:89], v68 offset:18528
	ds_read_b128 v[94:97], v1 offset:60000
	s_waitcnt lgkmcnt(1)
	v_mfma_f32_32x32x16_bf16 v[34:49], v[86:89], v[90:93], v[34:49]
	s_waitcnt lgkmcnt(0)
	v_mfma_f32_32x32x16_bf16 v[50:65], v[86:89], v[94:97], v[50:65]
	global_load_dwordx4 v[86:89], v[72:73], off offset:1408
	v_mfma_f32_32x32x16_bf16 v[2:17], v[98:101], v[90:93], v[2:17]
	global_load_dwordx4 v[90:93], v[76:77], off offset:1408
	v_mfma_f32_32x32x16_bf16 v[18:33], v[98:101], v[94:97], v[18:33]
	s_setprio 0
	s_barrier
	ds_read_b128 v[94:97], v68
	ds_read_b128 v[98:101], v68 offset:4608
	ds_read_b128 v[126:129], v1 offset:36864
	ds_read_b128 v[130:133], v1 offset:41472
	s_waitcnt vmcnt(1)
	ds_write_b128 v66, v[86:89] offset:18432
	ds_write_b128 v66, v[102:105] offset:23040
	ds_write_b128 v66, v[106:109] offset:27648
	ds_write_b128 v66, v[110:113] offset:32256
	s_waitcnt vmcnt(0)
	ds_write_b128 v66, v[90:93] offset:55296
	ds_write_b128 v66, v[122:125] offset:59904
	ds_write_b128 v66, v[118:121] offset:64512
	ds_write_b128 v69, v[114:117] offset:32256
	s_setprio 1
	ds_read_b128 v[86:89], v68 offset:32
	s_waitcnt lgkmcnt(10)
	v_mfma_f32_32x32x16_bf16 v[34:49], v[94:97], v[126:129], v[34:49]
	ds_read_b128 v[90:93], v1 offset:36896
	global_load_dwordx4 v[102:105], v[70:71], off offset:1536
	global_load_dwordx4 v[106:109], v[74:75], off offset:1536
	global_load_dwordx4 v[110:113], v[78:79], off offset:1536
	global_load_dwordx4 v[114:117], v[84:85], off offset:1536
	global_load_dwordx4 v[118:121], v[82:83], off offset:1536
	global_load_dwordx4 v[122:125], v[80:81], off offset:1536
	s_waitcnt lgkmcnt(10)
	v_mfma_f32_32x32x16_bf16 v[50:65], v[94:97], v[130:133], v[50:65]
	ds_read_b128 v[94:97], v1 offset:41504
	s_waitcnt lgkmcnt(1)
	v_mfma_f32_32x32x16_bf16 v[34:49], v[86:89], v[90:93], v[34:49]
	s_waitcnt lgkmcnt(0)
	v_mfma_f32_32x32x16_bf16 v[50:65], v[86:89], v[94:97], v[50:65]
	ds_read_b128 v[86:89], v68 offset:4640
	v_mfma_f32_32x32x16_bf16 v[2:17], v[98:101], v[126:129], v[2:17]
	v_mfma_f32_32x32x16_bf16 v[18:33], v[98:101], v[130:133], v[18:33]
	ds_read_b128 v[98:101], v68 offset:4704
	s_waitcnt lgkmcnt(1)
	v_mfma_f32_32x32x16_bf16 v[2:17], v[86:89], v[90:93], v[2:17]
	ds_read_b128 v[90:93], v1 offset:36928
	v_mfma_f32_32x32x16_bf16 v[18:33], v[86:89], v[94:97], v[18:33]
	ds_read_b128 v[86:89], v68 offset:64
	ds_read_b128 v[94:97], v1 offset:41536
	s_waitcnt lgkmcnt(1)
	v_mfma_f32_32x32x16_bf16 v[34:49], v[86:89], v[90:93], v[34:49]
	s_waitcnt lgkmcnt(0)
	v_mfma_f32_32x32x16_bf16 v[50:65], v[86:89], v[94:97], v[50:65]
	ds_read_b128 v[86:89], v68 offset:4672
	s_waitcnt lgkmcnt(0)
	v_mfma_f32_32x32x16_bf16 v[2:17], v[86:89], v[90:93], v[2:17]
	ds_read_b128 v[90:93], v1 offset:36960
	v_mfma_f32_32x32x16_bf16 v[18:33], v[86:89], v[94:97], v[18:33]
	ds_read_b128 v[86:89], v68 offset:96
	ds_read_b128 v[94:97], v1 offset:41568
	s_waitcnt lgkmcnt(1)
	v_mfma_f32_32x32x16_bf16 v[34:49], v[86:89], v[90:93], v[34:49]
	s_waitcnt lgkmcnt(0)
	v_mfma_f32_32x32x16_bf16 v[50:65], v[86:89], v[94:97], v[50:65]
	global_load_dwordx4 v[86:89], v[72:73], off offset:1536
	v_mfma_f32_32x32x16_bf16 v[2:17], v[98:101], v[90:93], v[2:17]
	global_load_dwordx4 v[90:93], v[76:77], off offset:1536
	v_mfma_f32_32x32x16_bf16 v[18:33], v[98:101], v[94:97], v[18:33]
	s_setprio 0
	s_barrier
; #define MFMA(a, b, c) __builtin_amdgcn_mfma_f32_32x32x16_bf16((a), (b), (c), 0, 0, 0)
; template <int TM, int TN>
; DI void gemm_mainloop(const u16* __restrict__ A, long lda, const u16* __restrict__ Bt, long ldb, int K, char* smem,
;                       f32x16 (&acc)[TM][TN]) {
;     ...
;   for (int kt = 0; kt < nk; kt++) {
;     const int buf = kt & 1;
;     const u16* cA = sA + buf * BM * LD + (wm * 32 * TM + r) * LD + h * 8;
;     const u16* cB = sB + buf * BN * LD + (wn * 32 * TN + r) * LD + h * 8;
;     bf16x8 af[TM], bfr[TN];
; #pragma unroll
;     for (int tm = 0; tm < TM; tm++) af[tm] = *(const bf16x8*)(cA + tm * 32 * LD);
; #pragma unroll
;     for (int tn = 0; tn < TN; tn++) bfr[tn] = *(const bf16x8*)(cB + tn * 32 * LD);
;     if (kt + 1 < nk) GEMM_SSTORE(buf ^ 1)
;     __builtin_amdgcn_sched_barrier(0);
;     __builtin_amdgcn_s_setprio(1);
; #pragma unroll
;     for (int tm = 0; tm < TM; tm++)
; #pragma unroll
;       for (int tn = 0; tn < TN; tn++) acc[tm][tn] = MFMA(af[tm], bfr[tn], acc[tm][tn]);
; #pragma unroll
;     for (int tm = 0; tm < TM; tm++) af[tm] = *(const bf16x8*)(cA + tm * 32 * LD + 16);
; #pragma unroll
;     for (int tn = 0; tn < TN; tn++) bfr[tn] = *(const bf16x8*)(cB + tn * 32 * LD + 16);
; #pragma unroll
;     for (int tm = 0; tm < TM; tm++)
; #pragma unroll
;       for (int tn = 0; tn < TN; tn++) acc[tm][tn] = MFMA(af[tm], bfr[tn], acc[tm][tn]);
;     __builtin_amdgcn_sched_group_barrier(0x8, 4, 0);
;     if (kt + 2 < nk) GEMM_GLOAD((kt + 2) * 64)
; #pragma unroll
;     for (int ks = 2; ks < 4; ks++) {
; #pragma unroll
;       for (int tm = 0; tm < TM; tm++) af[tm] = *(const bf16x8*)(cA + tm * 32 * LD + ks * 16);
; #pragma unroll
;       for (int tn = 0; tn < TN; tn++) bfr[tn] = *(const bf16x8*)(cB + tn * 32 * LD + ks * 16);
; #pragma unroll
;       for (int tm = 0; tm < TM; tm++)
; #pragma unroll
;         for (int tn = 0; tn < TN; tn++) acc[tm][tn] = MFMA(af[tm], bfr[tn], acc[tm][tn]);
;     }
	ds_read_b128 v[94:97], v68 offset:18432
	ds_read_b128 v[98:101], v68 offset:23040
	ds_read_b128 v[126:129], v1 offset:55296
	ds_read_b128 v[130:133], v1 offset:59904
	s_waitcnt vmcnt(1)
	ds_write_b128 v66, v[86:89]
	ds_write_b128 v66, v[102:105] offset:4608
	ds_write_b128 v66, v[106:109] offset:9216
	ds_write_b128 v66, v[110:113] offset:13824
	s_waitcnt vmcnt(0)
	ds_write_b128 v66, v[90:93] offset:36864
	ds_write_b128 v66, v[122:125] offset:41472
	ds_write_b128 v66, v[118:121] offset:46080
	ds_write_b128 v66, v[114:117] offset:50688
	s_setprio 1
	ds_read_b128 v[86:89], v68 offset:18464
	s_waitcnt lgkmcnt(10)
	v_mfma_f32_32x32x16_bf16 v[34:49], v[94:97], v[126:129], v[34:49]
	ds_read_b128 v[90:93], v1 offset:55328
	global_load_dwordx4 v[102:105], v[70:71], off offset:1664
	global_load_dwordx4 v[106:109], v[74:75], off offset:1664
	global_load_dwordx4 v[110:113], v[78:79], off offset:1664
	global_load_dwordx4 v[114:117], v[84:85], off offset:1664
	global_load_dwordx4 v[118:121], v[82:83], off offset:1664
	global_load_dwordx4 v[122:125], v[80:81], off offset:1664
	s_waitcnt lgkmcnt(10)
	v_mfma_f32_32x32x16_bf16 v[50:65], v[94:97], v[130:133], v[50:65]
	ds_read_b128 v[94:97], v1 offset:59936
	s_waitcnt lgkmcnt(1)
	v_mfma_f32_32x32x16_bf16 v[34:49], v[86:89], v[90:93], v[34:49]
	s_waitcnt lgkmcnt(0)
	v_mfma_f32_32x32x16_bf16 v[50:65], v[86:89], v[94:97], v[50:65]
	ds_read_b128 v[86:89], v68 offset:23072
	v_mfma_f32_32x32x16_bf16 v[2:17], v[98:101], v[126:129], v[2:17]
	v_mfma_f32_32x32x16_bf16 v[18:33], v[98:101], v[130:133], v[18:33]
	ds_read_b128 v[98:101], v68 offset:23136
	s_waitcnt lgkmcnt(1)
	v_mfma_f32_32x32x16_bf16 v[2:17], v[86:89], v[90:93], v[2:17]
	ds_read_b128 v[90:93], v1 offset:55360
	v_mfma_f32_32x32x16_bf16 v[18:33], v[86:89], v[94:97], v[18:33]
	ds_read_b128 v[86:89], v68 offset:18496
	ds_read_b128 v[94:97], v1 offset:59968
	s_waitcnt lgkmcnt(1)
	v_mfma_f32_32x32x16_bf16 v[34:49], v[86:89], v[90:93], v[34:49]
	s_waitcnt lgkmcnt(0)
	v_mfma_f32_32x32x16_bf16 v[50:65], v[86:89], v[94:97], v[50:65]
	ds_read_b128 v[86:89], v68 offset:23104
	s_waitcnt lgkmcnt(0)
	v_mfma_f32_32x32x16_bf16 v[2:17], v[86:89], v[90:93], v[2:17]
	ds_read_b128 v[90:93], v1 offset:55392
	v_mfma_f32_32x32x16_bf16 v[18:33], v[86:89], v[94:97], v[18:33]
	ds_read_b128 v[86:89], v68 offset:18528
	ds_read_b128 v[94:97], v1 offset:60000
	s_waitcnt lgkmcnt(1)
	v_mfma_f32_32x32x16_bf16 v[34:49], v[86:89], v[90:93], v[34:49]
	s_waitcnt lgkmcnt(0)
	v_mfma_f32_32x32x16_bf16 v[50:65], v[86:89], v[94:97], v[50:65]
	global_load_dwordx4 v[86:89], v[72:73], off offset:1664
	v_mfma_f32_32x32x16_bf16 v[2:17], v[98:101], v[90:93], v[2:17]
	global_load_dwordx4 v[90:93], v[76:77], off offset:1664
	v_mfma_f32_32x32x16_bf16 v[18:33], v[98:101], v[94:97], v[18:33]
	s_setprio 0
	s_barrier
	ds_read_b128 v[94:97], v68
	ds_read_b128 v[98:101], v68 offset:4608
	ds_read_b128 v[126:129], v1 offset:36864
	ds_read_b128 v[130:133], v1 offset:41472
	s_waitcnt vmcnt(1)
	ds_write_b128 v66, v[86:89] offset:18432
	ds_write_b128 v66, v[102:105] offset:23040
	ds_write_b128 v66, v[106:109] offset:27648
	ds_write_b128 v66, v[110:113] offset:32256
	s_waitcnt vmcnt(0)
	ds_write_b128 v66, v[90:93] offset:55296
	ds_write_b128 v66, v[122:125] offset:59904
	ds_write_b128 v66, v[118:121] offset:64512
	ds_write_b128 v69, v[114:117] offset:32256
	s_setprio 1
	ds_read_b128 v[86:89], v68 offset:32
	s_waitcnt lgkmcnt(10)
	v_mfma_f32_32x32x16_bf16 v[34:49], v[94:97], v[126:129], v[34:49]
	ds_read_b128 v[90:93], v1 offset:36896
	global_load_dwordx4 v[102:105], v[70:71], off offset:1792
	global_load_dwordx4 v[106:109], v[74:75], off offset:1792
	global_load_dwordx4 v[110:113], v[78:79], off offset:1792
	global_load_dwordx4 v[114:117], v[84:85], off offset:1792
	global_load_dwordx4 v[118:121], v[82:83], off offset:1792
	global_load_dwordx4 v[122:125], v[80:81], off offset:1792
	s_waitcnt lgkmcnt(10)
	v_mfma_f32_32x32x16_bf16 v[50:65], v[94:97], v[130:133], v[50:65]
	ds_read_b128 v[94:97], v1 offset:41504
	s_waitcnt lgkmcnt(1)
	v_mfma_f32_32x32x16_bf16 v[34:49], v[86:89], v[90:93], v[34:49]
	s_waitcnt lgkmcnt(0)
	v_mfma_f32_32x32x16_bf16 v[50:65], v[86:89], v[94:97], v[50:65]
	ds_read_b128 v[86:89], v68 offset:4640
	v_mfma_f32_32x32x16_bf16 v[2:17], v[98:101], v[126:129], v[2:17]
	v_mfma_f32_32x32x16_bf16 v[18:33], v[98:101], v[130:133], v[18:33]
	ds_read_b128 v[98:101], v68 offset:4704
	s_waitcnt lgkmcnt(1)
	v_mfma_f32_32x32x16_bf16 v[2:17], v[86:89], v[90:93], v[2:17]
	ds_read_b128 v[90:93], v1 offset:36928
	v_mfma_f32_32x32x16_bf16 v[18:33], v[86:89], v[94:97], v[18:33]
	ds_read_b128 v[86:89], v68 offset:64
	ds_read_b128 v[94:97], v1 offset:41536
	s_waitcnt lgkmcnt(1)
	v_mfma_f32_32x32x16_bf16 v[34:49], v[86:89], v[90:93], v[34:49]
	s_waitcnt lgkmcnt(0)
	v_mfma_f32_32x32x16_bf16 v[50:65], v[86:89], v[94:97], v[50:65]
	ds_read_b128 v[86:89], v68 offset:4672
	s_waitcnt lgkmcnt(0)
	v_mfma_f32_32x32x16_bf16 v[2:17], v[86:89], v[90:93], v[2:17]
	ds_read_b128 v[90:93], v1 offset:36960
	v_mfma_f32_32x32x16_bf16 v[18:33], v[86:89], v[94:97], v[18:33]
	ds_read_b128 v[86:89], v68 offset:96
	ds_read_b128 v[94:97], v1 offset:41568
	s_waitcnt lgkmcnt(1)
	v_mfma_f32_32x32x16_bf16 v[34:49], v[86:89], v[90:93], v[34:49]
	s_waitcnt lgkmcnt(0)
	v_mfma_f32_32x32x16_bf16 v[50:65], v[86:89], v[94:97], v[50:65]
	global_load_dwordx4 v[86:89], v[72:73], off offset:1792
	v_mfma_f32_32x32x16_bf16 v[2:17], v[98:101], v[90:93], v[2:17]
	global_load_dwordx4 v[90:93], v[76:77], off offset:1792
	v_mfma_f32_32x32x16_bf16 v[18:33], v[98:101], v[94:97], v[18:33]
	s_setprio 0
	s_barrier
; #define MFMA(a, b, c) __builtin_amdgcn_mfma_f32_32x32x16_bf16((a), (b), (c), 0, 0, 0)
; template <int TM, int TN>
; DI void gemm_mainloop(const u16* __restrict__ A, long lda, const u16* __restrict__ Bt, long ldb, int K, char* smem,
;                       f32x16 (&acc)[TM][TN]) {
;     ...
;   for (int kt = 0; kt < nk; kt++) {
;     const int buf = kt & 1;
;     const u16* cA = sA + buf * BM * LD + (wm * 32 * TM + r) * LD + h * 8;
;     const u16* cB = sB + buf * BN * LD + (wn * 32 * TN + r) * LD + h * 8;
;     bf16x8 af[TM], bfr[TN];
; #pragma unroll
;     for (int tm = 0; tm < TM; tm++) af[tm] = *(const bf16x8*)(cA + tm * 32 * LD);
; #pragma unroll
;     for (int tn = 0; tn < TN; tn++) bfr[tn] = *(const bf16x8*)(cB + tn * 32 * LD);
;     if (kt + 1 < nk) GEMM_SSTORE(buf ^ 1)
;     __builtin_amdgcn_sched_barrier(0);
;     __builtin_amdgcn_s_setprio(1);
; #pragma unroll
;     for (int tm = 0; tm < TM; tm++)
; #pragma unroll
;       for (int tn = 0; tn < TN; tn++) acc[tm][tn] = MFMA(af[tm], bfr[tn], acc[tm][tn]);
; #pragma unroll
;     for (int tm = 0; tm < TM; tm++) af[tm] = *(const bf16x8*)(cA + tm * 32 * LD + 16);
; #pragma unroll
;     for (int tn = 0; tn < TN; tn++) bfr[tn] = *(const bf16x8*)(cB + tn * 32 * LD + 16);
; #pragma unroll
;     for (int tm = 0; tm < TM; tm++)
; #pragma unroll
;       for (int tn = 0; tn < TN; tn++) acc[tm][tn] = MFMA(af[tm], bfr[tn], acc[tm][tn]);
;     __builtin_amdgcn_sched_group_barrier(0x8, 4, 0);
;     if (kt + 2 < nk) GEMM_GLOAD((kt + 2) * 64)
; #pragma unroll
;     for (int ks = 2; ks < 4; ks++) {
; #pragma unroll
;       for (int tm = 0; tm < TM; tm++) af[tm] = *(const bf16x8*)(cA + tm * 32 * LD + ks * 16);
; #pragma unroll
;       for (int tn = 0; tn < TN; tn++) bfr[tn] = *(const bf16x8*)(cB + tn * 32 * LD + ks * 16);
; #pragma unroll
;       for (int tm = 0; tm < TM; tm++)
; #pragma unroll
;         for (int tn = 0; tn < TN; tn++) acc[tm][tn] = MFMA(af[tm], bfr[tn], acc[tm][tn]);
;     }
	ds_read_b128 v[94:97], v68 offset:18432
	ds_read_b128 v[98:101], v68 offset:23040
	ds_read_b128 v[126:129], v1 offset:55296
	ds_read_b128 v[130:133], v1 offset:59904
	s_waitcnt vmcnt(1)
	ds_write_b128 v66, v[86:89]
	ds_write_b128 v66, v[102:105] offset:4608
	ds_write_b128 v66, v[106:109] offset:9216
	ds_write_b128 v66, v[110:113] offset:13824
	s_waitcnt vmcnt(0)
	ds_write_b128 v66, v[90:93] offset:36864
	ds_write_b128 v66, v[122:125] offset:41472
	ds_write_b128 v66, v[118:121] offset:46080
	ds_write_b128 v66, v[114:117] offset:50688
	s_setprio 1
	ds_read_b128 v[86:89], v68 offset:18464
	s_waitcnt lgkmcnt(10)
	v_mfma_f32_32x32x16_bf16 v[34:49], v[94:97], v[126:129], v[34:49]
	ds_read_b128 v[90:93], v1 offset:55328
	global_load_dwordx4 v[102:105], v[70:71], off offset:1920
	global_load_dwordx4 v[106:109], v[74:75], off offset:1920
	global_load_dwordx4 v[110:113], v[78:79], off offset:1920
	global_load_dwordx4 v[114:117], v[84:85], off offset:1920
	global_load_dwordx4 v[118:121], v[82:83], off offset:1920
	global_load_dwordx4 v[122:125], v[80:81], off offset:1920
	s_waitcnt lgkmcnt(10)
	v_mfma_f32_32x32x16_bf16 v[50:65], v[94:97], v[130:133], v[50:65]
	ds_read_b128 v[94:97], v1 offset:59936
	s_waitcnt lgkmcnt(1)
	v_mfma_f32_32x32x16_bf16 v[34:49], v[86:89], v[90:93], v[34:49]
	s_waitcnt lgkmcnt(0)
	v_mfma_f32_32x32x16_bf16 v[50:65], v[86:89], v[94:97], v[50:65]
	ds_read_b128 v[86:89], v68 offset:23072
	v_mfma_f32_32x32x16_bf16 v[2:17], v[98:101], v[126:129], v[2:17]
	v_mfma_f32_32x32x16_bf16 v[18:33], v[98:101], v[130:133], v[18:33]
	ds_read_b128 v[98:101], v68 offset:23136
	s_waitcnt lgkmcnt(1)
	v_mfma_f32_32x32x16_bf16 v[2:17], v[86:89], v[90:93], v[2:17]
	ds_read_b128 v[90:93], v1 offset:55360
	v_mfma_f32_32x32x16_bf16 v[18:33], v[86:89], v[94:97], v[18:33]
	ds_read_b128 v[86:89], v68 offset:18496
	ds_read_b128 v[94:97], v1 offset:59968
	s_waitcnt lgkmcnt(1)
	v_mfma_f32_32x32x16_bf16 v[34:49], v[86:89], v[90:93], v[34:49]
	s_waitcnt lgkmcnt(0)
	v_mfma_f32_32x32x16_bf16 v[50:65], v[86:89], v[94:97], v[50:65]
	ds_read_b128 v[86:89], v68 offset:23104
	s_waitcnt lgkmcnt(0)
	v_mfma_f32_32x32x16_bf16 v[2:17], v[86:89], v[90:93], v[2:17]
	ds_read_b128 v[90:93], v1 offset:55392
	v_mfma_f32_32x32x16_bf16 v[18:33], v[86:89], v[94:97], v[18:33]
	ds_read_b128 v[86:89], v68 offset:18528
	ds_read_b128 v[94:97], v1 offset:60000
	s_waitcnt lgkmcnt(1)
	v_mfma_f32_32x32x16_bf16 v[34:49], v[86:89], v[90:93], v[34:49]
	s_waitcnt lgkmcnt(0)
	v_mfma_f32_32x32x16_bf16 v[50:65], v[86:89], v[94:97], v[50:65]
	global_load_dwordx4 v[86:89], v[72:73], off offset:1920
	s_nop 0
	global_load_dwordx4 v[70:73], v[76:77], off offset:1920
	v_mfma_f32_32x32x16_bf16 v[2:17], v[98:101], v[90:93], v[2:17]
	v_mfma_f32_32x32x16_bf16 v[18:33], v[98:101], v[94:97], v[18:33]
	s_setprio 0
	s_barrier
	ds_read_b128 v[74:77], v68
	ds_read_b128 v[78:81], v68 offset:4608
	ds_read_b128 v[82:85], v1 offset:36864
	ds_read_b128 v[90:93], v1 offset:41472
	s_waitcnt vmcnt(1)
	ds_write_b128 v66, v[86:89] offset:18432
	ds_write_b128 v66, v[102:105] offset:23040
	ds_write_b128 v66, v[106:109] offset:27648
	ds_write_b128 v66, v[110:113] offset:32256
	s_waitcnt vmcnt(0)
	ds_write_b128 v66, v[70:73] offset:55296
	ds_write_b128 v66, v[122:125] offset:59904
	ds_write_b128 v66, v[118:121] offset:64512
	ds_write_b128 v69, v[114:117] offset:32256
	s_setprio 1
	ds_read_b128 v[70:73], v68 offset:32
	s_waitcnt lgkmcnt(10)
	v_mfma_f32_32x32x16_bf16 v[34:49], v[74:77], v[82:85], v[34:49]
	s_waitcnt lgkmcnt(9)
	v_mfma_f32_32x32x16_bf16 v[50:65], v[74:77], v[90:93], v[50:65]
	ds_read_b128 v[74:77], v1 offset:36896
	v_mfma_f32_32x32x16_bf16 v[2:17], v[78:81], v[82:85], v[2:17]
	v_mfma_f32_32x32x16_bf16 v[18:33], v[78:81], v[90:93], v[18:33]
	ds_read_b128 v[78:81], v1 offset:41504
	s_waitcnt lgkmcnt(1)
	v_mfma_f32_32x32x16_bf16 v[34:49], v[70:73], v[74:77], v[34:49]
	s_waitcnt lgkmcnt(0)
	v_mfma_f32_32x32x16_bf16 v[50:65], v[70:73], v[78:81], v[50:65]
	ds_read_b128 v[70:73], v68 offset:4640
	s_waitcnt lgkmcnt(0)
	v_mfma_f32_32x32x16_bf16 v[2:17], v[70:73], v[74:77], v[2:17]
	ds_read_b128 v[74:77], v1 offset:36928
	v_mfma_f32_32x32x16_bf16 v[18:33], v[70:73], v[78:81], v[18:33]
	ds_read_b128 v[70:73], v68 offset:64
	ds_read_b128 v[78:81], v1 offset:41536
	s_waitcnt lgkmcnt(1)
	v_mfma_f32_32x32x16_bf16 v[34:49], v[70:73], v[74:77], v[34:49]
	s_waitcnt lgkmcnt(0)
	v_mfma_f32_32x32x16_bf16 v[50:65], v[70:73], v[78:81], v[50:65]
	ds_read_b128 v[70:73], v68 offset:4672
	s_waitcnt lgkmcnt(0)
	v_mfma_f32_32x32x16_bf16 v[2:17], v[70:73], v[74:77], v[2:17]
	ds_read_b128 v[74:77], v1 offset:36960
	v_mfma_f32_32x32x16_bf16 v[18:33], v[70:73], v[78:81], v[18:33]
	ds_read_b128 v[70:73], v68 offset:96
	ds_read_b128 v[78:81], v1 offset:41568
	s_waitcnt lgkmcnt(1)
	v_mfma_f32_32x32x16_bf16 v[34:49], v[70:73], v[74:77], v[34:49]
	s_waitcnt lgkmcnt(0)
	v_mfma_f32_32x32x16_bf16 v[50:65], v[70:73], v[78:81], v[50:65]
	ds_read_b128 v[70:73], v68 offset:4704
	s_waitcnt lgkmcnt(0)
	v_mfma_f32_32x32x16_bf16 v[2:17], v[70:73], v[74:77], v[2:17]
	v_mfma_f32_32x32x16_bf16 v[18:33], v[70:73], v[78:81], v[18:33]
	s_setprio 0
	s_barrier
; #define MFMA(a, b, c) __builtin_amdgcn_mfma_f32_32x32x16_bf16((a), (b), (c), 0, 0, 0)
; DI int crow(int i, int h) { return (i & 3) + 8 * (i >> 2) + 4 * h; }
; template <int TM, int TN>
; DI void gemm_mainloop(const u16* __restrict__ A, long lda, const u16* __restrict__ Bt, long ldb, int K, char* smem,
;                       f32x16 (&acc)[TM][TN]) {
;     ...
;     for (int tm = 0; tm < TM; tm++) af[tm] = *(const bf16x8*)(cA + tm * 32 * LD + 16);
; #pragma unroll
;     for (int tn = 0; tn < TN; tn++) bfr[tn] = *(const bf16x8*)(cB + tn * 32 * LD + 16);
; #pragma unroll
;     for (int tm = 0; tm < TM; tm++)
; #pragma unroll
;       for (int tn = 0; tn < TN; tn++) acc[tm][tn] = MFMA(af[tm], bfr[tn], acc[tm][tn]);
;     __builtin_amdgcn_sched_group_barrier(0x8, 4, 0);
;     if (kt + 2 < nk) GEMM_GLOAD((kt + 2) * 64)
; #pragma unroll
;     for (int ks = 2; ks < 4; ks++) {
; #pragma unroll
;       for (int tm = 0; tm < TM; tm++) af[tm] = *(const bf16x8*)(cA + tm * 32 * LD + ks * 16);
; #pragma unroll
;       for (int tn = 0; tn < TN; tn++) bfr[tn] = *(const bf16x8*)(cB + tn * 32 * LD + ks * 16);
; #pragma unroll
;       for (int tm = 0; tm < TM; tm++)
; #pragma unroll
;         for (int tn = 0; tn < TN; tn++) acc[tm][tn] = MFMA(af[tm], bfr[tn], acc[tm][tn]);
;     }
; template <int TM, int TN, class Epi>
; DI void gemm_tile(const u16* A, long lda, const u16* Bt, long ldb, int K, int m0, int n0, char* smem, const Epi& epi) {
;     ...
; #pragma unroll
;   for (int tm = 0; tm < TM; tm++)
; #pragma unroll
;     for (int tn = 0; tn < TN; tn++)
; #pragma unroll
;       for (int i = 0; i < 16; i++)
;         Ct[(wm * 32 * TM + tm * 32 + crow(i, h)) * LDC + wn * 32 * TN + tn * 32 + r] = acc[tm][tn][i];
;   __syncthreads();
;   epi(Ct, LDC, m0, n0, tid, BM);
	ds_read_b128 v[70:73], v68 offset:18432
	ds_read_b128 v[74:77], v68 offset:23040
	ds_read_b128 v[78:81], v1 offset:55296
	ds_read_b128 v[82:85], v1 offset:59904
	s_setprio 1
	s_waitcnt lgkmcnt(1)
	v_mfma_f32_32x32x16_bf16 v[34:49], v[70:73], v[78:81], v[34:49]
	s_waitcnt lgkmcnt(0)
	v_mfma_f32_32x32x16_bf16 v[50:65], v[70:73], v[82:85], v[50:65]
	ds_read_b128 v[70:73], v68 offset:18464
	v_mfma_f32_32x32x16_bf16 v[2:17], v[74:77], v[78:81], v[2:17]
	ds_read_b128 v[78:81], v1 offset:59936
	v_mfma_f32_32x32x16_bf16 v[18:33], v[74:77], v[82:85], v[18:33]
	ds_read_b128 v[74:77], v1 offset:55328
	s_waitcnt lgkmcnt(0)
	v_mfma_f32_32x32x16_bf16 v[34:49], v[70:73], v[74:77], v[34:49]
	v_mfma_f32_32x32x16_bf16 v[50:65], v[70:73], v[78:81], v[50:65]
	ds_read_b128 v[70:73], v68 offset:23072
	s_waitcnt lgkmcnt(0)
	v_mfma_f32_32x32x16_bf16 v[2:17], v[70:73], v[74:77], v[2:17]
	ds_read_b128 v[74:77], v1 offset:55360
	v_mfma_f32_32x32x16_bf16 v[18:33], v[70:73], v[78:81], v[18:33]
	ds_read_b128 v[70:73], v68 offset:18496
	ds_read_b128 v[78:81], v1 offset:59968
	s_waitcnt lgkmcnt(1)
	v_mfma_f32_32x32x16_bf16 v[34:49], v[70:73], v[74:77], v[34:49]
	s_waitcnt lgkmcnt(0)
	v_mfma_f32_32x32x16_bf16 v[50:65], v[70:73], v[78:81], v[50:65]
	ds_read_b128 v[70:73], v68 offset:23104
	s_waitcnt lgkmcnt(0)
	v_mfma_f32_32x32x16_bf16 v[2:17], v[70:73], v[74:77], v[2:17]
	ds_read_b128 v[74:77], v1 offset:55392
	v_mfma_f32_32x32x16_bf16 v[18:33], v[70:73], v[78:81], v[18:33]
	ds_read_b128 v[70:73], v68 offset:18528
	ds_read_b128 v[78:81], v1 offset:60000
	s_waitcnt lgkmcnt(1)
	v_mfma_f32_32x32x16_bf16 v[34:49], v[70:73], v[74:77], v[34:49]
	s_waitcnt lgkmcnt(0)
	v_mfma_f32_32x32x16_bf16 v[50:65], v[70:73], v[78:81], v[50:65]
	ds_read_b128 v[68:71], v68 offset:23136
	s_waitcnt lgkmcnt(0)
	v_mfma_f32_32x32x16_bf16 v[2:17], v[68:71], v[74:77], v[2:17]
	v_mfma_f32_32x32x16_bf16 v[18:33], v[68:71], v[78:81], v[18:33]
	s_setprio 0
	v_mov_b32_e32 v1, v0
	s_barrier
	s_mov_b32 s36, 0
	v_lshrrev_b32_e32 v66, 1, v1
	v_and_b32_e32 v66, 0xfffffc0, v66
	v_lshrrev_b32_e32 v68, 3, v1
	v_and_or_b32 v66, v68, 4, v66
	v_and_b32_e32 v68, 0x5f, v1
	v_mul_lo_u32 v66, v66, s26
	v_lshl_add_u32 v66, v68, 2, v66
	ds_write2_b32 v66, v34, v50 offset1:32
	v_add_u32_e32 v34, 0x400, v66
	ds_write2_b32 v34, v36, v52 offset0:8 offset1:40
	ds_write2_b32 v34, v37, v53 offset0:140 offset1:172
	v_add_u32_e32 v34, 0x1000, v66
	ds_write2_b32 v34, v38, v54 offset0:32 offset1:64
	ds_write2_b32 v34, v39, v55 offset0:164 offset1:196
	v_add_u32_e32 v34, 0x1400, v66
	ds_write2_b32 v34, v40, v56 offset0:40 offset1:72
	ds_write2_b32 v34, v41, v57 offset0:172 offset1:204
	v_add_u32_e32 v34, 0x2000, v66
	ds_write2_b32 v34, v42, v58 offset0:64 offset1:96
	ds_write2_b32 v34, v43, v59 offset0:196 offset1:228
	v_add_u32_e32 v34, 0x2400, v66
	ds_write2_b32 v34, v44, v60 offset0:72 offset1:104
	ds_write2_b32 v34, v45, v61 offset0:204 offset1:236
	v_add_u32_e32 v34, 0x3000, v66
	ds_write2_b32 v34, v46, v62 offset0:96 offset1:128
	v_add_u32_e32 v34, 0x3200, v66
	ds_write2_b32 v34, v47, v63 offset0:100 offset1:132
	v_add_u32_e32 v34, 0x3400, v66
	ds_write2_b32 v34, v48, v64 offset0:104 offset1:136
	v_add_u32_e32 v34, 0x3600, v66
	ds_write2_b32 v34, v49, v65 offset0:108 offset1:140
	v_add_u32_e32 v34, 0x4000, v66
	ds_write2_b32 v34, v2, v18 offset0:128 offset1:160
	v_add_u32_e32 v2, 0x4400, v66
	ds_write2_b32 v2, v3, v19 offset0:4 offset1:36
	ds_write2_b32 v2, v4, v20 offset0:136 offset1:168
	v_add_u32_e32 v2, 0x4800, v66
	ds_write2_b32 v2, v5, v21 offset0:12 offset1:44
	v_add_u32_e32 v2, 0x5000, v66
	ds_write2_b32 v2, v6, v22 offset0:160 offset1:192
	v_add_u32_e32 v2, 0x5400, v66
	ds_write2_b32 v2, v7, v23 offset0:36 offset1:68
	ds_write2_b32 v2, v8, v24 offset0:168 offset1:200
	v_add_u32_e32 v2, 0x5800, v66
	ds_write2_b32 v2, v9, v25 offset0:44 offset1:76
	v_add_u32_e32 v2, 0x6000, v66
	ds_write2_b32 v2, v10, v26 offset0:192 offset1:224
	v_add_u32_e32 v2, 0x6400, v66
	ds_write2_b32 v2, v11, v27 offset0:68 offset1:100
	ds_write2_b32 v2, v12, v28 offset0:200 offset1:232
	v_add_u32_e32 v2, 0x6800, v66
	ds_write2_b32 v2, v13, v29 offset0:76 offset1:108
	v_add_u32_e32 v2, 0x7200, v66
	ds_write2_b32 v2, v14, v30 offset0:96 offset1:128
	v_add_u32_e32 v2, 0x7400, v66
	ds_write2_b32 v2, v15, v31 offset0:100 offset1:132
	v_add_u32_e32 v2, 0x7600, v66
	ds_write2_b32 v2, v16, v32 offset0:104 offset1:136
	v_add_u32_e32 v2, 0x7800, v66
	ds_write2_b32 v2, v17, v33 offset0:108 offset1:140
	v_lshlrev_b32_e32 v2, 3, v1
	v_and_b32_e32 v3, 0x78, v2
	v_lshl_or_b32 v2, s4, 7, v3
	v_lshlrev_b32_e32 v10, 2, v3
	v_ashrrev_i32_e32 v3, 31, v2
	v_cmp_eq_u32_e32 vcc, s27, v2
	v_cmp_gt_i32_e64 s[4:5], s28, v2
	v_lshl_add_u64 v[12:13], v[2:3], 1, s[6:7]
	ds_write2_b32 v66, v35, v51 offset0:132 offset1:164
	s_waitcnt lgkmcnt(0)
	s_barrier
	s_branch .LBB0_133

; #define MFMA(a, b, c) __builtin_amdgcn_mfma_f32_32x32x16_bf16((a), (b), (c), 0, 0, 0)
; template <int TM, int TN>
; DI void gemm_mainloop(const u16* __restrict__ A, long lda, const u16* __restrict__ Bt, long ldb, int K, char* smem,
;                       f32x16 (&acc)[TM][TN]) {
;     ...
;   const int nk = K / 64;
;   const int lrow = tid >> 3, lch = (tid & 7) * 8;
;   const u16* gA = A + (long)lrow * lda + lch;
;   const u16* gB = Bt + (long)lrow * ldb + lch;
;   const int soff = lrow * LD + lch;
;     ...
;   GEMM_GLOAD(0)
;   __syncthreads();
;   GEMM_SSTORE(0)
;   if (nk > 1) GEMM_GLOAD(64)
;   __syncthreads();
;   for (int kt = 0; kt < nk; kt++) {
;     const int buf = kt & 1;
;     const u16* cA = sA + buf * BM * LD + (wm * 32 * TM + r) * LD + h * 8;
;     const u16* cB = sB + buf * BN * LD + (wn * 32 * TN + r) * LD + h * 8;
;     bf16x8 af[TM], bfr[TN];
; #pragma unroll
;     for (int tm = 0; tm < TM; tm++) af[tm] = *(const bf16x8*)(cA + tm * 32 * LD);
; #pragma unroll
;     for (int tn = 0; tn < TN; tn++) bfr[tn] = *(const bf16x8*)(cB + tn * 32 * LD);
;     if (kt + 1 < nk) GEMM_SSTORE(buf ^ 1)
;     __builtin_amdgcn_sched_barrier(0);
;     __builtin_amdgcn_s_setprio(1);
; #pragma unroll
;     for (int tm = 0; tm < TM; tm++)
; #pragma unroll
;       for (int tn = 0; tn < TN; tn++) acc[tm][tn] = MFMA(af[tm], bfr[tn], acc[tm][tn]);
; #pragma unroll
;     for (int tm = 0; tm < TM; tm++) af[tm] = *(const bf16x8*)(cA + tm * 32 * LD + 16);
; #pragma unroll
;     for (int tn = 0; tn < TN; tn++) bfr[tn] = *(const bf16x8*)(cB + tn * 32 * LD + 16);
; #pragma unroll
;     for (int tm = 0; tm < TM; tm++)
; #pragma unroll
;       for (int tn = 0; tn < TN; tn++) acc[tm][tn] = MFMA(af[tm], bfr[tn], acc[tm][tn]);
;     __builtin_amdgcn_sched_group_barrier(0x8, 4, 0);
;     if (kt + 2 < nk) GEMM_GLOAD((kt + 2) * 64)
; #pragma unroll
;     for (int ks = 2; ks < 4; ks++) {
; #pragma unroll
;       for (int tm = 0; tm < TM; tm++) af[tm] = *(const bf16x8*)(cA + tm * 32 * LD + ks * 16);
; #pragma unroll
;       for (int tn = 0; tn < TN; tn++) bfr[tn] = *(const bf16x8*)(cB + tn * 32 * LD + ks * 16);
; #pragma unroll
;       for (int tm = 0; tm < TM; tm++)
; #pragma unroll
;         for (int tn = 0; tn < TN; tn++) acc[tm][tn] = MFMA(af[tm], bfr[tn], acc[tm][tn]);
;     }
.LBB0_1064:
	s_ashr_i32 s4, s24, 31
	s_lshr_b32 s4, s4, 29
	s_add_i32 s4, s24, s4
	s_and_b32 s5, s4, -8
	s_lshl_b32 s4, s4, 4
	s_and_b32 s25, s4, 0xffffff80
	s_sub_i32 s10, s24, s5
	s_mul_i32 s4, s25, 0x880
	s_mul_hi_i32 s5, s25, 0x880
	s_add_u32 s4, s8, s4
	v_mov_b32_e32 v1, v0
	s_addc_u32 s5, s9, s5
	s_mul_i32 s11, s10, 0x44000
	v_lshlrev_b32_e32 v2, 3, v1
	v_ashrrev_i32_e32 v68, 3, v1
	v_and_b32_e32 v69, 56, v2
	v_mov_b64_e32 v[2:3], s[4:5]
	v_mad_i64_i32 v[2:3], s[4:5], v68, s14, v[2:3]
	v_lshlrev_b32_e32 v66, 1, v69
	v_lshl_add_u64 v[72:73], v[2:3], 0, v[66:67]
	s_ashr_i32 s27, s11, 31
	v_add_co_u32_e32 v70, vcc, s17, v72
	s_add_u32 s26, s3, s11
	s_nop 0
	v_addc_co_u32_e32 v71, vcc, 0, v73, vcc
	s_addc_u32 s27, s16, s27
	v_add_co_u32_e32 v74, vcc, s18, v72
	v_mov_b64_e32 v[2:3], s[26:27]
	s_nop 0
	v_addc_co_u32_e32 v75, vcc, 0, v73, vcc
	v_mad_i64_i32 v[18:19], s[4:5], v68, s14, v[2:3]
	v_add_co_u32_e32 v78, vcc, s19, v72
	v_lshl_add_u64 v[76:77], v[18:19], 0, v[66:67]
	s_nop 0
	v_addc_co_u32_e32 v79, vcc, 0, v73, vcc
	v_add_co_u32_e32 v80, vcc, s17, v76
	global_load_dwordx4 v[2:5], v[72:73], off
	s_nop 0
	v_addc_co_u32_e32 v81, vcc, 0, v77, vcc
	v_add_co_u32_e32 v82, vcc, s18, v76
	global_load_dwordx4 v[6:9], v[70:71], off
	s_nop 0
	v_addc_co_u32_e32 v83, vcc, 0, v77, vcc
	v_add_co_u32_e32 v84, vcc, s19, v76
	global_load_dwordx4 v[10:13], v[74:75], off
	s_nop 0
	v_addc_co_u32_e32 v85, vcc, 0, v77, vcc
	global_load_dwordx4 v[14:17], v[78:79], off
	global_load_dwordx4 v[18:21], v[76:77], off
	global_load_dwordx4 v[22:25], v[80:81], off
	global_load_dwordx4 v[26:29], v[82:83], off
	global_load_dwordx4 v[30:33], v[84:85], off
	s_barrier
	global_load_dwordx4 v[34:37], v[72:73], off offset:128
	global_load_dwordx4 v[38:41], v[70:71], off offset:128
	global_load_dwordx4 v[42:45], v[74:75], off offset:128
	global_load_dwordx4 v[46:49], v[78:79], off offset:128
	global_load_dwordx4 v[50:53], v[76:77], off offset:128
	global_load_dwordx4 v[54:57], v[80:81], off offset:128
	global_load_dwordx4 v[58:61], v[82:83], off offset:128
	global_load_dwordx4 v[62:65], v[84:85], off offset:128
	v_and_b32_e32 v66, 31, v1
	v_lshrrev_b32_e32 v86, 1, v1
	v_mul_lo_u32 v68, v68, s15
	v_and_or_b32 v87, v86, s20, v66
	v_and_b32_e32 v86, 16, v86
	v_and_b32_e32 v1, 0x5f, v1
	v_add_lshl_u32 v66, v68, v69, 1
	v_mad_u64_u32 v[68:69], s[4:5], v87, s21, v[86:87]
	v_mad_u32_u24 v1, v1, s21, v86
	v_add_u32_e32 v69, 0x9000, v66
	s_waitcnt vmcnt(15)
	ds_write_b128 v66, v[2:5]
	s_waitcnt vmcnt(14)
	ds_write_b128 v66, v[6:9] offset:4608
	s_waitcnt vmcnt(13)
	ds_write_b128 v66, v[10:13] offset:9216
	s_waitcnt vmcnt(12)
	ds_write_b128 v66, v[14:17] offset:13824
	s_waitcnt vmcnt(11)
	ds_write_b128 v66, v[18:21] offset:36864
	s_waitcnt vmcnt(10)
	ds_write_b128 v66, v[22:25] offset:41472
	s_waitcnt vmcnt(9)
	ds_write_b128 v66, v[26:29] offset:46080
	s_waitcnt vmcnt(8)
	ds_write_b128 v66, v[30:33] offset:50688
	s_waitcnt lgkmcnt(0)
	s_barrier
	ds_read_b128 v[2:5], v68
	ds_read_b128 v[18:21], v68 offset:4608
	ds_read_b128 v[6:9], v1 offset:36864
	ds_read_b128 v[22:25], v1 offset:41472
	s_waitcnt vmcnt(7)
	ds_write_b128 v66, v[34:37] offset:18432
	s_waitcnt vmcnt(6)
	ds_write_b128 v66, v[38:41] offset:23040
	s_waitcnt vmcnt(5)
	ds_write_b128 v66, v[42:45] offset:27648
	s_waitcnt vmcnt(4)
	ds_write_b128 v66, v[46:49] offset:32256
	s_waitcnt vmcnt(3)
	ds_write_b128 v66, v[50:53] offset:55296
	s_waitcnt vmcnt(2)
	ds_write_b128 v66, v[54:57] offset:59904
	s_waitcnt vmcnt(1)
	ds_write_b128 v66, v[58:61] offset:64512
	s_waitcnt vmcnt(0)
	ds_write_b128 v69, v[62:65] offset:32256
	s_setprio 1
	ds_read_b128 v[86:89], v68 offset:32
	s_waitcnt lgkmcnt(10)
	v_mfma_f32_32x32x16_bf16 v[34:49], v[2:5], v[6:9], 0
	ds_read_b128 v[90:93], v1 offset:36896
	ds_read_b128 v[94:97], v1 offset:41504
	ds_read_b128 v[98:101], v68 offset:4704
	global_load_dwordx4 v[102:105], v[70:71], off offset:256
	global_load_dwordx4 v[106:109], v[74:75], off offset:256
	global_load_dwordx4 v[110:113], v[78:79], off offset:256
	global_load_dwordx4 v[114:117], v[84:85], off offset:256
	s_waitcnt lgkmcnt(12)
	v_mfma_f32_32x32x16_bf16 v[50:65], v[2:5], v[22:25], 0
	global_load_dwordx4 v[118:121], v[82:83], off offset:256
	global_load_dwordx4 v[122:125], v[80:81], off offset:256
	s_waitcnt lgkmcnt(2)
	v_mfma_f32_32x32x16_bf16 v[34:49], v[86:89], v[90:93], v[34:49]
	s_waitcnt lgkmcnt(1)
	v_mfma_f32_32x32x16_bf16 v[50:65], v[86:89], v[94:97], v[50:65]
	ds_read_b128 v[86:89], v68 offset:4640
	v_mfma_f32_32x32x16_bf16 v[2:17], v[18:21], v[6:9], 0
	v_mfma_f32_32x32x16_bf16 v[18:33], v[18:21], v[22:25], 0
	s_waitcnt lgkmcnt(0)
	v_mfma_f32_32x32x16_bf16 v[2:17], v[86:89], v[90:93], v[2:17]
	ds_read_b128 v[90:93], v1 offset:36928
	v_mfma_f32_32x32x16_bf16 v[18:33], v[86:89], v[94:97], v[18:33]
	ds_read_b128 v[86:89], v68 offset:64
	ds_read_b128 v[94:97], v1 offset:41536
	s_waitcnt lgkmcnt(1)
	v_mfma_f32_32x32x16_bf16 v[34:49], v[86:89], v[90:93], v[34:49]
	s_waitcnt lgkmcnt(0)
	v_mfma_f32_32x32x16_bf16 v[50:65], v[86:89], v[94:97], v[50:65]
	ds_read_b128 v[86:89], v68 offset:4672
	s_waitcnt lgkmcnt(0)
	v_mfma_f32_32x32x16_bf16 v[2:17], v[86:89], v[90:93], v[2:17]
	ds_read_b128 v[90:93], v1 offset:36960
	v_mfma_f32_32x32x16_bf16 v[18:33], v[86:89], v[94:97], v[18:33]
	ds_read_b128 v[86:89], v68 offset:96
	ds_read_b128 v[94:97], v1 offset:41568
	s_waitcnt lgkmcnt(1)
	v_mfma_f32_32x32x16_bf16 v[34:49], v[86:89], v[90:93], v[34:49]
	s_waitcnt lgkmcnt(0)
	v_mfma_f32_32x32x16_bf16 v[50:65], v[86:89], v[94:97], v[50:65]
	global_load_dwordx4 v[86:89], v[72:73], off offset:256
	v_mfma_f32_32x32x16_bf16 v[2:17], v[98:101], v[90:93], v[2:17]
	global_load_dwordx4 v[90:93], v[76:77], off offset:256
	v_mfma_f32_32x32x16_bf16 v[18:33], v[98:101], v[94:97], v[18:33]
	s_setprio 0
	s_barrier
; #define MFMA(a, b, c) __builtin_amdgcn_mfma_f32_32x32x16_bf16((a), (b), (c), 0, 0, 0)
; template <int TM, int TN>
; DI void gemm_mainloop(const u16* __restrict__ A, long lda, const u16* __restrict__ Bt, long ldb, int K, char* smem,
;                       f32x16 (&acc)[TM][TN]) {
;     ...
;   for (int kt = 0; kt < nk; kt++) {
;     const int buf = kt & 1;
;     const u16* cA = sA + buf * BM * LD + (wm * 32 * TM + r) * LD + h * 8;
;     const u16* cB = sB + buf * BN * LD + (wn * 32 * TN + r) * LD + h * 8;
;     bf16x8 af[TM], bfr[TN];
; #pragma unroll
;     for (int tm = 0; tm < TM; tm++) af[tm] = *(const bf16x8*)(cA + tm * 32 * LD);
; #pragma unroll
;     for (int tn = 0; tn < TN; tn++) bfr[tn] = *(const bf16x8*)(cB + tn * 32 * LD);
;     if (kt + 1 < nk) GEMM_SSTORE(buf ^ 1)
;     __builtin_amdgcn_sched_barrier(0);
;     __builtin_amdgcn_s_setprio(1);
; #pragma unroll
;     for (int tm = 0; tm < TM; tm++)
; #pragma unroll
;       for (int tn = 0; tn < TN; tn++) acc[tm][tn] = MFMA(af[tm], bfr[tn], acc[tm][tn]);
; #pragma unroll
;     for (int tm = 0; tm < TM; tm++) af[tm] = *(const bf16x8*)(cA + tm * 32 * LD + 16);
; #pragma unroll
;     for (int tn = 0; tn < TN; tn++) bfr[tn] = *(const bf16x8*)(cB + tn * 32 * LD + 16);
; #pragma unroll
;     for (int tm = 0; tm < TM; tm++)
; #pragma unroll
;       for (int tn = 0; tn < TN; tn++) acc[tm][tn] = MFMA(af[tm], bfr[tn], acc[tm][tn]);
;     __builtin_amdgcn_sched_group_barrier(0x8, 4, 0);
;     if (kt + 2 < nk) GEMM_GLOAD((kt + 2) * 64)
; #pragma unroll
;     for (int ks = 2; ks < 4; ks++) {
; #pragma unroll
;       for (int tm = 0; tm < TM; tm++) af[tm] = *(const bf16x8*)(cA + tm * 32 * LD + ks * 16);
; #pragma unroll
;       for (int tn = 0; tn < TN; tn++) bfr[tn] = *(const bf16x8*)(cB + tn * 32 * LD + ks * 16);
; #pragma unroll
;       for (int tm = 0; tm < TM; tm++)
; #pragma unroll
;         for (int tn = 0; tn < TN; tn++) acc[tm][tn] = MFMA(af[tm], bfr[tn], acc[tm][tn]);
;     }
;     __builtin_amdgcn_s_setprio(0);
;     __syncthreads();
;   }
	ds_read_b128 v[94:97], v68 offset:18432
	ds_read_b128 v[98:101], v68 offset:23040
	ds_read_b128 v[126:129], v1 offset:55296
	ds_read_b128 v[130:133], v1 offset:59904
	s_waitcnt vmcnt(1)
	ds_write_b128 v66, v[86:89]
	ds_write_b128 v66, v[102:105] offset:4608
	ds_write_b128 v66, v[106:109] offset:9216
	ds_write_b128 v66, v[110:113] offset:13824
	s_waitcnt vmcnt(0)
	ds_write_b128 v66, v[90:93] offset:36864
	ds_write_b128 v66, v[122:125] offset:41472
	ds_write_b128 v66, v[118:121] offset:46080
	ds_write_b128 v66, v[114:117] offset:50688
	s_setprio 1
	ds_read_b128 v[86:89], v68 offset:18464
	s_waitcnt lgkmcnt(10)
	v_mfma_f32_32x32x16_bf16 v[34:49], v[94:97], v[126:129], v[34:49]
	ds_read_b128 v[90:93], v1 offset:55328
	global_load_dwordx4 v[102:105], v[70:71], off offset:384
	global_load_dwordx4 v[106:109], v[74:75], off offset:384
	global_load_dwordx4 v[110:113], v[78:79], off offset:384
	global_load_dwordx4 v[114:117], v[84:85], off offset:384
	global_load_dwordx4 v[118:121], v[82:83], off offset:384
	global_load_dwordx4 v[122:125], v[80:81], off offset:384
	s_waitcnt lgkmcnt(10)
	v_mfma_f32_32x32x16_bf16 v[50:65], v[94:97], v[130:133], v[50:65]
	ds_read_b128 v[94:97], v1 offset:59936
	s_waitcnt lgkmcnt(1)
	v_mfma_f32_32x32x16_bf16 v[34:49], v[86:89], v[90:93], v[34:49]
	s_waitcnt lgkmcnt(0)
	v_mfma_f32_32x32x16_bf16 v[50:65], v[86:89], v[94:97], v[50:65]
	ds_read_b128 v[86:89], v68 offset:23072
	v_mfma_f32_32x32x16_bf16 v[2:17], v[98:101], v[126:129], v[2:17]
	v_mfma_f32_32x32x16_bf16 v[18:33], v[98:101], v[130:133], v[18:33]
	ds_read_b128 v[98:101], v68 offset:23136
	s_waitcnt lgkmcnt(1)
	v_mfma_f32_32x32x16_bf16 v[2:17], v[86:89], v[90:93], v[2:17]
	ds_read_b128 v[90:93], v1 offset:55360
	v_mfma_f32_32x32x16_bf16 v[18:33], v[86:89], v[94:97], v[18:33]
	ds_read_b128 v[86:89], v68 offset:18496
	ds_read_b128 v[94:97], v1 offset:59968
	s_waitcnt lgkmcnt(1)
	v_mfma_f32_32x32x16_bf16 v[34:49], v[86:89], v[90:93], v[34:49]
	s_waitcnt lgkmcnt(0)
	v_mfma_f32_32x32x16_bf16 v[50:65], v[86:89], v[94:97], v[50:65]
	ds_read_b128 v[86:89], v68 offset:23104
	s_waitcnt lgkmcnt(0)
	v_mfma_f32_32x32x16_bf16 v[2:17], v[86:89], v[90:93], v[2:17]
	ds_read_b128 v[90:93], v1 offset:55392
	v_mfma_f32_32x32x16_bf16 v[18:33], v[86:89], v[94:97], v[18:33]
	ds_read_b128 v[86:89], v68 offset:18528
	ds_read_b128 v[94:97], v1 offset:60000
	s_waitcnt lgkmcnt(1)
	v_mfma_f32_32x32x16_bf16 v[34:49], v[86:89], v[90:93], v[34:49]
	s_waitcnt lgkmcnt(0)
	v_mfma_f32_32x32x16_bf16 v[50:65], v[86:89], v[94:97], v[50:65]
	global_load_dwordx4 v[86:89], v[72:73], off offset:384
	v_mfma_f32_32x32x16_bf16 v[2:17], v[98:101], v[90:93], v[2:17]
	global_load_dwordx4 v[90:93], v[76:77], off offset:384
	v_mfma_f32_32x32x16_bf16 v[18:33], v[98:101], v[94:97], v[18:33]
	s_setprio 0
	s_barrier
	ds_read_b128 v[94:97], v68
	ds_read_b128 v[98:101], v68 offset:4608
	ds_read_b128 v[126:129], v1 offset:36864
	ds_read_b128 v[130:133], v1 offset:41472
	s_waitcnt vmcnt(1)
	ds_write_b128 v66, v[86:89] offset:18432
	ds_write_b128 v66, v[102:105] offset:23040
	ds_write_b128 v66, v[106:109] offset:27648
	ds_write_b128 v66, v[110:113] offset:32256
	s_waitcnt vmcnt(0)
	ds_write_b128 v66, v[90:93] offset:55296
	ds_write_b128 v66, v[122:125] offset:59904
	ds_write_b128 v66, v[118:121] offset:64512
	ds_write_b128 v69, v[114:117] offset:32256
	s_setprio 1
	ds_read_b128 v[86:89], v68 offset:32
	s_waitcnt lgkmcnt(10)
	v_mfma_f32_32x32x16_bf16 v[34:49], v[94:97], v[126:129], v[34:49]
	ds_read_b128 v[90:93], v1 offset:36896
	global_load_dwordx4 v[102:105], v[70:71], off offset:512
	global_load_dwordx4 v[106:109], v[74:75], off offset:512
	global_load_dwordx4 v[110:113], v[78:79], off offset:512
	global_load_dwordx4 v[114:117], v[84:85], off offset:512
	global_load_dwordx4 v[118:121], v[82:83], off offset:512
	global_load_dwordx4 v[122:125], v[80:81], off offset:512
	s_waitcnt lgkmcnt(10)
	v_mfma_f32_32x32x16_bf16 v[50:65], v[94:97], v[130:133], v[50:65]
	ds_read_b128 v[94:97], v1 offset:41504
	s_waitcnt lgkmcnt(1)
	v_mfma_f32_32x32x16_bf16 v[34:49], v[86:89], v[90:93], v[34:49]
	s_waitcnt lgkmcnt(0)
	v_mfma_f32_32x32x16_bf16 v[50:65], v[86:89], v[94:97], v[50:65]
	ds_read_b128 v[86:89], v68 offset:4640
	v_mfma_f32_32x32x16_bf16 v[2:17], v[98:101], v[126:129], v[2:17]
	v_mfma_f32_32x32x16_bf16 v[18:33], v[98:101], v[130:133], v[18:33]
	ds_read_b128 v[98:101], v68 offset:4704
	s_waitcnt lgkmcnt(1)
	v_mfma_f32_32x32x16_bf16 v[2:17], v[86:89], v[90:93], v[2:17]
	ds_read_b128 v[90:93], v1 offset:36928
	v_mfma_f32_32x32x16_bf16 v[18:33], v[86:89], v[94:97], v[18:33]
	ds_read_b128 v[86:89], v68 offset:64
	ds_read_b128 v[94:97], v1 offset:41536
	s_waitcnt lgkmcnt(1)
	v_mfma_f32_32x32x16_bf16 v[34:49], v[86:89], v[90:93], v[34:49]
	s_waitcnt lgkmcnt(0)
	v_mfma_f32_32x32x16_bf16 v[50:65], v[86:89], v[94:97], v[50:65]
	ds_read_b128 v[86:89], v68 offset:4672
	s_waitcnt lgkmcnt(0)
	v_mfma_f32_32x32x16_bf16 v[2:17], v[86:89], v[90:93], v[2:17]
	ds_read_b128 v[90:93], v1 offset:36960
	v_mfma_f32_32x32x16_bf16 v[18:33], v[86:89], v[94:97], v[18:33]
	ds_read_b128 v[86:89], v68 offset:96
	ds_read_b128 v[94:97], v1 offset:41568
	s_waitcnt lgkmcnt(1)
	v_mfma_f32_32x32x16_bf16 v[34:49], v[86:89], v[90:93], v[34:49]
	s_waitcnt lgkmcnt(0)
	v_mfma_f32_32x32x16_bf16 v[50:65], v[86:89], v[94:97], v[50:65]
	global_load_dwordx4 v[86:89], v[72:73], off offset:512
	v_mfma_f32_32x32x16_bf16 v[2:17], v[98:101], v[90:93], v[2:17]
	global_load_dwordx4 v[90:93], v[76:77], off offset:512
	v_mfma_f32_32x32x16_bf16 v[18:33], v[98:101], v[94:97], v[18:33]
	s_setprio 0
	s_barrier
; #define MFMA(a, b, c) __builtin_amdgcn_mfma_f32_32x32x16_bf16((a), (b), (c), 0, 0, 0)
; template <int TM, int TN>
; DI void gemm_mainloop(const u16* __restrict__ A, long lda, const u16* __restrict__ Bt, long ldb, int K, char* smem,
;                       f32x16 (&acc)[TM][TN]) {
;     ...
;   for (int kt = 0; kt < nk; kt++) {
;     const int buf = kt & 1;
;     const u16* cA = sA + buf * BM * LD + (wm * 32 * TM + r) * LD + h * 8;
;     const u16* cB = sB + buf * BN * LD + (wn * 32 * TN + r) * LD + h * 8;
;     bf16x8 af[TM], bfr[TN];
; #pragma unroll
;     for (int tm = 0; tm < TM; tm++) af[tm] = *(const bf16x8*)(cA + tm * 32 * LD);
; #pragma unroll
;     for (int tn = 0; tn < TN; tn++) bfr[tn] = *(const bf16x8*)(cB + tn * 32 * LD);
;     if (kt + 1 < nk) GEMM_SSTORE(buf ^ 1)
;     __builtin_amdgcn_sched_barrier(0);
;     __builtin_amdgcn_s_setprio(1);
; #pragma unroll
;     for (int tm = 0; tm < TM; tm++)
; #pragma unroll
;       for (int tn = 0; tn < TN; tn++) acc[tm][tn] = MFMA(af[tm], bfr[tn], acc[tm][tn]);
; #pragma unroll
;     for (int tm = 0; tm < TM; tm++) af[tm] = *(const bf16x8*)(cA + tm * 32 * LD + 16);
; #pragma unroll
;     for (int tn = 0; tn < TN; tn++) bfr[tn] = *(const bf16x8*)(cB + tn * 32 * LD + 16);
; #pragma unroll
;     for (int tm = 0; tm < TM; tm++)
; #pragma unroll
;       for (int tn = 0; tn < TN; tn++) acc[tm][tn] = MFMA(af[tm], bfr[tn], acc[tm][tn]);
;     __builtin_amdgcn_sched_group_barrier(0x8, 4, 0);
;     if (kt + 2 < nk) GEMM_GLOAD((kt + 2) * 64)
; #pragma unroll
;     for (int ks = 2; ks < 4; ks++) {
; #pragma unroll
;       for (int tm = 0; tm < TM; tm++) af[tm] = *(const bf16x8*)(cA + tm * 32 * LD + ks * 16);
; #pragma unroll
;       for (int tn = 0; tn < TN; tn++) bfr[tn] = *(const bf16x8*)(cB + tn * 32 * LD + ks * 16);
; #pragma unroll
;       for (int tm = 0; tm < TM; tm++)
; #pragma unroll
;         for (int tn = 0; tn < TN; tn++) acc[tm][tn] = MFMA(af[tm], bfr[tn], acc[tm][tn]);
;     }
;     __builtin_amdgcn_s_setprio(0);
;     __syncthreads();
;   }
	ds_read_b128 v[94:97], v68 offset:18432
	ds_read_b128 v[98:101], v68 offset:23040
	ds_read_b128 v[126:129], v1 offset:55296
	ds_read_b128 v[130:133], v1 offset:59904
	s_waitcnt vmcnt(1)
	ds_write_b128 v66, v[86:89]
	ds_write_b128 v66, v[102:105] offset:4608
	ds_write_b128 v66, v[106:109] offset:9216
	ds_write_b128 v66, v[110:113] offset:13824
	s_waitcnt vmcnt(0)
	ds_write_b128 v66, v[90:93] offset:36864
	ds_write_b128 v66, v[122:125] offset:41472
	ds_write_b128 v66, v[118:121] offset:46080
	ds_write_b128 v66, v[114:117] offset:50688
	s_setprio 1
	ds_read_b128 v[86:89], v68 offset:18464
	s_waitcnt lgkmcnt(10)
	v_mfma_f32_32x32x16_bf16 v[34:49], v[94:97], v[126:129], v[34:49]
	ds_read_b128 v[90:93], v1 offset:55328
	global_load_dwordx4 v[102:105], v[70:71], off offset:640
	global_load_dwordx4 v[106:109], v[74:75], off offset:640
	global_load_dwordx4 v[110:113], v[78:79], off offset:640
	global_load_dwordx4 v[114:117], v[84:85], off offset:640
	global_load_dwordx4 v[118:121], v[82:83], off offset:640
	global_load_dwordx4 v[122:125], v[80:81], off offset:640
	s_waitcnt lgkmcnt(10)
	v_mfma_f32_32x32x16_bf16 v[50:65], v[94:97], v[130:133], v[50:65]
	ds_read_b128 v[94:97], v1 offset:59936
	s_waitcnt lgkmcnt(1)
	v_mfma_f32_32x32x16_bf16 v[34:49], v[86:89], v[90:93], v[34:49]
	s_waitcnt lgkmcnt(0)
	v_mfma_f32_32x32x16_bf16 v[50:65], v[86:89], v[94:97], v[50:65]
	ds_read_b128 v[86:89], v68 offset:23072
	v_mfma_f32_32x32x16_bf16 v[2:17], v[98:101], v[126:129], v[2:17]
	v_mfma_f32_32x32x16_bf16 v[18:33], v[98:101], v[130:133], v[18:33]
	ds_read_b128 v[98:101], v68 offset:23136
	s_waitcnt lgkmcnt(1)
	v_mfma_f32_32x32x16_bf16 v[2:17], v[86:89], v[90:93], v[2:17]
	ds_read_b128 v[90:93], v1 offset:55360
	v_mfma_f32_32x32x16_bf16 v[18:33], v[86:89], v[94:97], v[18:33]
	ds_read_b128 v[86:89], v68 offset:18496
	ds_read_b128 v[94:97], v1 offset:59968
	s_waitcnt lgkmcnt(1)
	v_mfma_f32_32x32x16_bf16 v[34:49], v[86:89], v[90:93], v[34:49]
	s_waitcnt lgkmcnt(0)
	v_mfma_f32_32x32x16_bf16 v[50:65], v[86:89], v[94:97], v[50:65]
	ds_read_b128 v[86:89], v68 offset:23104
	s_waitcnt lgkmcnt(0)
	v_mfma_f32_32x32x16_bf16 v[2:17], v[86:89], v[90:93], v[2:17]
	ds_read_b128 v[90:93], v1 offset:55392
	v_mfma_f32_32x32x16_bf16 v[18:33], v[86:89], v[94:97], v[18:33]
	ds_read_b128 v[86:89], v68 offset:18528
	ds_read_b128 v[94:97], v1 offset:60000
	s_waitcnt lgkmcnt(1)
	v_mfma_f32_32x32x16_bf16 v[34:49], v[86:89], v[90:93], v[34:49]
	s_waitcnt lgkmcnt(0)
	v_mfma_f32_32x32x16_bf16 v[50:65], v[86:89], v[94:97], v[50:65]
	global_load_dwordx4 v[86:89], v[72:73], off offset:640
	v_mfma_f32_32x32x16_bf16 v[2:17], v[98:101], v[90:93], v[2:17]
	global_load_dwordx4 v[90:93], v[76:77], off offset:640
	v_mfma_f32_32x32x16_bf16 v[18:33], v[98:101], v[94:97], v[18:33]
	s_setprio 0
	s_barrier
	ds_read_b128 v[94:97], v68
	ds_read_b128 v[98:101], v68 offset:4608
	ds_read_b128 v[126:129], v1 offset:36864
	ds_read_b128 v[130:133], v1 offset:41472
	s_waitcnt vmcnt(1)
	ds_write_b128 v66, v[86:89] offset:18432
	ds_write_b128 v66, v[102:105] offset:23040
	ds_write_b128 v66, v[106:109] offset:27648
	ds_write_b128 v66, v[110:113] offset:32256
	s_waitcnt vmcnt(0)
	ds_write_b128 v66, v[90:93] offset:55296
	ds_write_b128 v66, v[122:125] offset:59904
	ds_write_b128 v66, v[118:121] offset:64512
	ds_write_b128 v69, v[114:117] offset:32256
	s_setprio 1
	ds_read_b128 v[86:89], v68 offset:32
	s_waitcnt lgkmcnt(10)
	v_mfma_f32_32x32x16_bf16 v[34:49], v[94:97], v[126:129], v[34:49]
	ds_read_b128 v[90:93], v1 offset:36896
	global_load_dwordx4 v[102:105], v[70:71], off offset:768
	global_load_dwordx4 v[106:109], v[74:75], off offset:768
	global_load_dwordx4 v[110:113], v[78:79], off offset:768
	global_load_dwordx4 v[114:117], v[84:85], off offset:768
	global_load_dwordx4 v[118:121], v[82:83], off offset:768
	global_load_dwordx4 v[122:125], v[80:81], off offset:768
	s_waitcnt lgkmcnt(10)
	v_mfma_f32_32x32x16_bf16 v[50:65], v[94:97], v[130:133], v[50:65]
	ds_read_b128 v[94:97], v1 offset:41504
	s_waitcnt lgkmcnt(1)
	v_mfma_f32_32x32x16_bf16 v[34:49], v[86:89], v[90:93], v[34:49]
	s_waitcnt lgkmcnt(0)
	v_mfma_f32_32x32x16_bf16 v[50:65], v[86:89], v[94:97], v[50:65]
	ds_read_b128 v[86:89], v68 offset:4640
	v_mfma_f32_32x32x16_bf16 v[2:17], v[98:101], v[126:129], v[2:17]
	v_mfma_f32_32x32x16_bf16 v[18:33], v[98:101], v[130:133], v[18:33]
	ds_read_b128 v[98:101], v68 offset:4704
	s_waitcnt lgkmcnt(1)
	v_mfma_f32_32x32x16_bf16 v[2:17], v[86:89], v[90:93], v[2:17]
	ds_read_b128 v[90:93], v1 offset:36928
	v_mfma_f32_32x32x16_bf16 v[18:33], v[86:89], v[94:97], v[18:33]
	ds_read_b128 v[86:89], v68 offset:64
	ds_read_b128 v[94:97], v1 offset:41536
	s_waitcnt lgkmcnt(1)
	v_mfma_f32_32x32x16_bf16 v[34:49], v[86:89], v[90:93], v[34:49]
	s_waitcnt lgkmcnt(0)
	v_mfma_f32_32x32x16_bf16 v[50:65], v[86:89], v[94:97], v[50:65]
	ds_read_b128 v[86:89], v68 offset:4672
	s_waitcnt lgkmcnt(0)
	v_mfma_f32_32x32x16_bf16 v[2:17], v[86:89], v[90:93], v[2:17]
	ds_read_b128 v[90:93], v1 offset:36960
	v_mfma_f32_32x32x16_bf16 v[18:33], v[86:89], v[94:97], v[18:33]
	ds_read_b128 v[86:89], v68 offset:96
	ds_read_b128 v[94:97], v1 offset:41568
	s_waitcnt lgkmcnt(1)
	v_mfma_f32_32x32x16_bf16 v[34:49], v[86:89], v[90:93], v[34:49]
	s_waitcnt lgkmcnt(0)
	v_mfma_f32_32x32x16_bf16 v[50:65], v[86:89], v[94:97], v[50:65]
	global_load_dwordx4 v[86:89], v[72:73], off offset:768
	v_mfma_f32_32x32x16_bf16 v[2:17], v[98:101], v[90:93], v[2:17]
	global_load_dwordx4 v[90:93], v[76:77], off offset:768
	v_mfma_f32_32x32x16_bf16 v[18:33], v[98:101], v[94:97], v[18:33]
	s_setprio 0
	s_barrier
; #define MFMA(a, b, c) __builtin_amdgcn_mfma_f32_32x32x16_bf16((a), (b), (c), 0, 0, 0)
; template <int TM, int TN>
; DI void gemm_mainloop(const u16* __restrict__ A, long lda, const u16* __restrict__ Bt, long ldb, int K, char* smem,
;                       f32x16 (&acc)[TM][TN]) {
;     ...
;   for (int kt = 0; kt < nk; kt++) {
;     const int buf = kt & 1;
;     const u16* cA = sA + buf * BM * LD + (wm * 32 * TM + r) * LD + h * 8;
;     const u16* cB = sB + buf * BN * LD + (wn * 32 * TN + r) * LD + h * 8;
;     bf16x8 af[TM], bfr[TN];
; #pragma unroll
;     for (int tm = 0; tm < TM; tm++) af[tm] = *(const bf16x8*)(cA + tm * 32 * LD);
; #pragma unroll
;     for (int tn = 0; tn < TN; tn++) bfr[tn] = *(const bf16x8*)(cB + tn * 32 * LD);
;     if (kt + 1 < nk) GEMM_SSTORE(buf ^ 1)
;     __builtin_amdgcn_sched_barrier(0);
;     __builtin_amdgcn_s_setprio(1);
; #pragma unroll
;     for (int tm = 0; tm < TM; tm++)
; #pragma unroll
;       for (int tn = 0; tn < TN; tn++) acc[tm][tn] = MFMA(af[tm], bfr[tn], acc[tm][tn]);
; #pragma unroll
;     for (int tm = 0; tm < TM; tm++) af[tm] = *(const bf16x8*)(cA + tm * 32 * LD + 16);
; #pragma unroll
;     for (int tn = 0; tn < TN; tn++) bfr[tn] = *(const bf16x8*)(cB + tn * 32 * LD + 16);
; #pragma unroll
;     for (int tm = 0; tm < TM; tm++)
; #pragma unroll
;       for (int tn = 0; tn < TN; tn++) acc[tm][tn] = MFMA(af[tm], bfr[tn], acc[tm][tn]);
;     __builtin_amdgcn_sched_group_barrier(0x8, 4, 0);
;     if (kt + 2 < nk) GEMM_GLOAD((kt + 2) * 64)
; #pragma unroll
;     for (int ks = 2; ks < 4; ks++) {
; #pragma unroll
;       for (int tm = 0; tm < TM; tm++) af[tm] = *(const bf16x8*)(cA + tm * 32 * LD + ks * 16);
; #pragma unroll
;       for (int tn = 0; tn < TN; tn++) bfr[tn] = *(const bf16x8*)(cB + tn * 32 * LD + ks * 16);
; #pragma unroll
;       for (int tm = 0; tm < TM; tm++)
; #pragma unroll
;         for (int tn = 0; tn < TN; tn++) acc[tm][tn] = MFMA(af[tm], bfr[tn], acc[tm][tn]);
;     }
;     __builtin_amdgcn_s_setprio(0);
;     __syncthreads();
;   }
	ds_read_b128 v[94:97], v68 offset:18432
	ds_read_b128 v[98:101], v68 offset:23040
	ds_read_b128 v[126:129], v1 offset:55296
	ds_read_b128 v[130:133], v1 offset:59904
	s_waitcnt vmcnt(1)
	ds_write_b128 v66, v[86:89]
	ds_write_b128 v66, v[102:105] offset:4608
	ds_write_b128 v66, v[106:109] offset:9216
	ds_write_b128 v66, v[110:113] offset:13824
	s_waitcnt vmcnt(0)
	ds_write_b128 v66, v[90:93] offset:36864
	ds_write_b128 v66, v[122:125] offset:41472
	ds_write_b128 v66, v[118:121] offset:46080
	ds_write_b128 v66, v[114:117] offset:50688
	s_setprio 1
	ds_read_b128 v[86:89], v68 offset:18464
	s_waitcnt lgkmcnt(10)
	v_mfma_f32_32x32x16_bf16 v[34:49], v[94:97], v[126:129], v[34:49]
	ds_read_b128 v[90:93], v1 offset:55328
	global_load_dwordx4 v[102:105], v[70:71], off offset:896
	global_load_dwordx4 v[106:109], v[74:75], off offset:896
	global_load_dwordx4 v[110:113], v[78:79], off offset:896
	global_load_dwordx4 v[114:117], v[84:85], off offset:896
	global_load_dwordx4 v[118:121], v[82:83], off offset:896
	global_load_dwordx4 v[122:125], v[80:81], off offset:896
	s_waitcnt lgkmcnt(10)
	v_mfma_f32_32x32x16_bf16 v[50:65], v[94:97], v[130:133], v[50:65]
	ds_read_b128 v[94:97], v1 offset:59936
	s_waitcnt lgkmcnt(1)
	v_mfma_f32_32x32x16_bf16 v[34:49], v[86:89], v[90:93], v[34:49]
	s_waitcnt lgkmcnt(0)
	v_mfma_f32_32x32x16_bf16 v[50:65], v[86:89], v[94:97], v[50:65]
	ds_read_b128 v[86:89], v68 offset:23072
	v_mfma_f32_32x32x16_bf16 v[2:17], v[98:101], v[126:129], v[2:17]
	v_mfma_f32_32x32x16_bf16 v[18:33], v[98:101], v[130:133], v[18:33]
	ds_read_b128 v[98:101], v68 offset:23136
	s_waitcnt lgkmcnt(1)
	v_mfma_f32_32x32x16_bf16 v[2:17], v[86:89], v[90:93], v[2:17]
	ds_read_b128 v[90:93], v1 offset:55360
	v_mfma_f32_32x32x16_bf16 v[18:33], v[86:89], v[94:97], v[18:33]
	ds_read_b128 v[86:89], v68 offset:18496
	ds_read_b128 v[94:97], v1 offset:59968
	s_waitcnt lgkmcnt(1)
	v_mfma_f32_32x32x16_bf16 v[34:49], v[86:89], v[90:93], v[34:49]
	s_waitcnt lgkmcnt(0)
	v_mfma_f32_32x32x16_bf16 v[50:65], v[86:89], v[94:97], v[50:65]
	ds_read_b128 v[86:89], v68 offset:23104
	s_waitcnt lgkmcnt(0)
	v_mfma_f32_32x32x16_bf16 v[2:17], v[86:89], v[90:93], v[2:17]
	ds_read_b128 v[90:93], v1 offset:55392
	v_mfma_f32_32x32x16_bf16 v[18:33], v[86:89], v[94:97], v[18:33]
	ds_read_b128 v[86:89], v68 offset:18528
	ds_read_b128 v[94:97], v1 offset:60000
	s_waitcnt lgkmcnt(1)
	v_mfma_f32_32x32x16_bf16 v[34:49], v[86:89], v[90:93], v[34:49]
	s_waitcnt lgkmcnt(0)
	v_mfma_f32_32x32x16_bf16 v[50:65], v[86:89], v[94:97], v[50:65]
	global_load_dwordx4 v[86:89], v[72:73], off offset:896
	v_mfma_f32_32x32x16_bf16 v[2:17], v[98:101], v[90:93], v[2:17]
	global_load_dwordx4 v[90:93], v[76:77], off offset:896
	v_mfma_f32_32x32x16_bf16 v[18:33], v[98:101], v[94:97], v[18:33]
	s_setprio 0
	s_barrier
	ds_read_b128 v[94:97], v68
	ds_read_b128 v[98:101], v68 offset:4608
	ds_read_b128 v[126:129], v1 offset:36864
	ds_read_b128 v[130:133], v1 offset:41472
	s_waitcnt vmcnt(1)
	ds_write_b128 v66, v[86:89] offset:18432
	ds_write_b128 v66, v[102:105] offset:23040
	ds_write_b128 v66, v[106:109] offset:27648
	ds_write_b128 v66, v[110:113] offset:32256
	s_waitcnt vmcnt(0)
	ds_write_b128 v66, v[90:93] offset:55296
	ds_write_b128 v66, v[122:125] offset:59904
	ds_write_b128 v66, v[118:121] offset:64512
	ds_write_b128 v69, v[114:117] offset:32256
	s_setprio 1
	ds_read_b128 v[86:89], v68 offset:32
	s_waitcnt lgkmcnt(10)
	v_mfma_f32_32x32x16_bf16 v[34:49], v[94:97], v[126:129], v[34:49]
	ds_read_b128 v[90:93], v1 offset:36896
	global_load_dwordx4 v[102:105], v[70:71], off offset:1024
	global_load_dwordx4 v[106:109], v[74:75], off offset:1024
	global_load_dwordx4 v[110:113], v[78:79], off offset:1024
	global_load_dwordx4 v[114:117], v[84:85], off offset:1024
	global_load_dwordx4 v[118:121], v[82:83], off offset:1024
	global_load_dwordx4 v[122:125], v[80:81], off offset:1024
	s_waitcnt lgkmcnt(10)
	v_mfma_f32_32x32x16_bf16 v[50:65], v[94:97], v[130:133], v[50:65]
	ds_read_b128 v[94:97], v1 offset:41504
	s_waitcnt lgkmcnt(1)
	v_mfma_f32_32x32x16_bf16 v[34:49], v[86:89], v[90:93], v[34:49]
	s_waitcnt lgkmcnt(0)
	v_mfma_f32_32x32x16_bf16 v[50:65], v[86:89], v[94:97], v[50:65]
	ds_read_b128 v[86:89], v68 offset:4640
	v_mfma_f32_32x32x16_bf16 v[2:17], v[98:101], v[126:129], v[2:17]
	v_mfma_f32_32x32x16_bf16 v[18:33], v[98:101], v[130:133], v[18:33]
	ds_read_b128 v[98:101], v68 offset:4704
	s_waitcnt lgkmcnt(1)
	v_mfma_f32_32x32x16_bf16 v[2:17], v[86:89], v[90:93], v[2:17]
	ds_read_b128 v[90:93], v1 offset:36928
	v_mfma_f32_32x32x16_bf16 v[18:33], v[86:89], v[94:97], v[18:33]
	ds_read_b128 v[86:89], v68 offset:64
	ds_read_b128 v[94:97], v1 offset:41536
	s_waitcnt lgkmcnt(1)
	v_mfma_f32_32x32x16_bf16 v[34:49], v[86:89], v[90:93], v[34:49]
	s_waitcnt lgkmcnt(0)
	v_mfma_f32_32x32x16_bf16 v[50:65], v[86:89], v[94:97], v[50:65]
	ds_read_b128 v[86:89], v68 offset:4672
	s_waitcnt lgkmcnt(0)
	v_mfma_f32_32x32x16_bf16 v[2:17], v[86:89], v[90:93], v[2:17]
	ds_read_b128 v[90:93], v1 offset:36960
	v_mfma_f32_32x32x16_bf16 v[18:33], v[86:89], v[94:97], v[18:33]
	ds_read_b128 v[86:89], v68 offset:96
	ds_read_b128 v[94:97], v1 offset:41568
	s_waitcnt lgkmcnt(1)
	v_mfma_f32_32x32x16_bf16 v[34:49], v[86:89], v[90:93], v[34:49]
	s_waitcnt lgkmcnt(0)
	v_mfma_f32_32x32x16_bf16 v[50:65], v[86:89], v[94:97], v[50:65]
	global_load_dwordx4 v[86:89], v[72:73], off offset:1024
	v_mfma_f32_32x32x16_bf16 v[2:17], v[98:101], v[90:93], v[2:17]
	global_load_dwordx4 v[90:93], v[76:77], off offset:1024
	v_mfma_f32_32x32x16_bf16 v[18:33], v[98:101], v[94:97], v[18:33]
	s_setprio 0
	s_barrier
; #define MFMA(a, b, c) __builtin_amdgcn_mfma_f32_32x32x16_bf16((a), (b), (c), 0, 0, 0)
; template <int TM, int TN>
; DI void gemm_mainloop(const u16* __restrict__ A, long lda, const u16* __restrict__ Bt, long ldb, int K, char* smem,
;                       f32x16 (&acc)[TM][TN]) {
;     ...
;   for (int kt = 0; kt < nk; kt++) {
;     const int buf = kt & 1;
;     const u16* cA = sA + buf * BM * LD + (wm * 32 * TM + r) * LD + h * 8;
;     const u16* cB = sB + buf * BN * LD + (wn * 32 * TN + r) * LD + h * 8;
;     bf16x8 af[TM], bfr[TN];
; #pragma unroll
;     for (int tm = 0; tm < TM; tm++) af[tm] = *(const bf16x8*)(cA + tm * 32 * LD);
; #pragma unroll
;     for (int tn = 0; tn < TN; tn++) bfr[tn] = *(const bf16x8*)(cB + tn * 32 * LD);
;     if (kt + 1 < nk) GEMM_SSTORE(buf ^ 1)
;     __builtin_amdgcn_sched_barrier(0);
;     __builtin_amdgcn_s_setprio(1);
; #pragma unroll
;     for (int tm = 0; tm < TM; tm++)
; #pragma unroll
;       for (int tn = 0; tn < TN; tn++) acc[tm][tn] = MFMA(af[tm], bfr[tn], acc[tm][tn]);
; #pragma unroll
;     for (int tm = 0; tm < TM; tm++) af[tm] = *(const bf16x8*)(cA + tm * 32 * LD + 16);
; #pragma unroll
;     for (int tn = 0; tn < TN; tn++) bfr[tn] = *(const bf16x8*)(cB + tn * 32 * LD + 16);
; #pragma unroll
;     for (int tm = 0; tm < TM; tm++)
; #pragma unroll
;       for (int tn = 0; tn < TN; tn++) acc[tm][tn] = MFMA(af[tm], bfr[tn], acc[tm][tn]);
;     __builtin_amdgcn_sched_group_barrier(0x8, 4, 0);
;     if (kt + 2 < nk) GEMM_GLOAD((kt + 2) * 64)
; #pragma unroll
;     for (int ks = 2; ks < 4; ks++) {
; #pragma unroll
;       for (int tm = 0; tm < TM; tm++) af[tm] = *(const bf16x8*)(cA + tm * 32 * LD + ks * 16);
; #pragma unroll
;       for (int tn = 0; tn < TN; tn++) bfr[tn] = *(const bf16x8*)(cB + tn * 32 * LD + ks * 16);
; #pragma unroll
;       for (int tm = 0; tm < TM; tm++)
; #pragma unroll
;         for (int tn = 0; tn < TN; tn++) acc[tm][tn] = MFMA(af[tm], bfr[tn], acc[tm][tn]);
;     }
;     __builtin_amdgcn_s_setprio(0);
;     __syncthreads();
;   }
	ds_read_b128 v[94:97], v68 offset:18432
	ds_read_b128 v[98:101], v68 offset:23040
	ds_read_b128 v[126:129], v1 offset:55296
	ds_read_b128 v[130:133], v1 offset:59904
	s_waitcnt vmcnt(1)
	ds_write_b128 v66, v[86:89]
	ds_write_b128 v66, v[102:105] offset:4608
	ds_write_b128 v66, v[106:109] offset:9216
	ds_write_b128 v66, v[110:113] offset:13824
	s_waitcnt vmcnt(0)
	ds_write_b128 v66, v[90:93] offset:36864
	ds_write_b128 v66, v[122:125] offset:41472
	ds_write_b128 v66, v[118:121] offset:46080
	ds_write_b128 v66, v[114:117] offset:50688
	s_setprio 1
	ds_read_b128 v[86:89], v68 offset:18464
	s_waitcnt lgkmcnt(10)
	v_mfma_f32_32x32x16_bf16 v[34:49], v[94:97], v[126:129], v[34:49]
	ds_read_b128 v[90:93], v1 offset:55328
	global_load_dwordx4 v[102:105], v[70:71], off offset:1152
	global_load_dwordx4 v[106:109], v[74:75], off offset:1152
	global_load_dwordx4 v[110:113], v[78:79], off offset:1152
	global_load_dwordx4 v[114:117], v[84:85], off offset:1152
	global_load_dwordx4 v[118:121], v[82:83], off offset:1152
	global_load_dwordx4 v[122:125], v[80:81], off offset:1152
	s_waitcnt lgkmcnt(10)
	v_mfma_f32_32x32x16_bf16 v[50:65], v[94:97], v[130:133], v[50:65]
	ds_read_b128 v[94:97], v1 offset:59936
	s_waitcnt lgkmcnt(1)
	v_mfma_f32_32x32x16_bf16 v[34:49], v[86:89], v[90:93], v[34:49]
	s_waitcnt lgkmcnt(0)
	v_mfma_f32_32x32x16_bf16 v[50:65], v[86:89], v[94:97], v[50:65]
	ds_read_b128 v[86:89], v68 offset:23072
	v_mfma_f32_32x32x16_bf16 v[2:17], v[98:101], v[126:129], v[2:17]
	v_mfma_f32_32x32x16_bf16 v[18:33], v[98:101], v[130:133], v[18:33]
	ds_read_b128 v[98:101], v68 offset:23136
	s_waitcnt lgkmcnt(1)
	v_mfma_f32_32x32x16_bf16 v[2:17], v[86:89], v[90:93], v[2:17]
	ds_read_b128 v[90:93], v1 offset:55360
	v_mfma_f32_32x32x16_bf16 v[18:33], v[86:89], v[94:97], v[18:33]
	ds_read_b128 v[86:89], v68 offset:18496
	ds_read_b128 v[94:97], v1 offset:59968
	s_waitcnt lgkmcnt(1)
	v_mfma_f32_32x32x16_bf16 v[34:49], v[86:89], v[90:93], v[34:49]
	s_waitcnt lgkmcnt(0)
	v_mfma_f32_32x32x16_bf16 v[50:65], v[86:89], v[94:97], v[50:65]
	ds_read_b128 v[86:89], v68 offset:23104
	s_waitcnt lgkmcnt(0)
	v_mfma_f32_32x32x16_bf16 v[2:17], v[86:89], v[90:93], v[2:17]
	ds_read_b128 v[90:93], v1 offset:55392
	v_mfma_f32_32x32x16_bf16 v[18:33], v[86:89], v[94:97], v[18:33]
	ds_read_b128 v[86:89], v68 offset:18528
	ds_read_b128 v[94:97], v1 offset:60000
	s_waitcnt lgkmcnt(1)
	v_mfma_f32_32x32x16_bf16 v[34:49], v[86:89], v[90:93], v[34:49]
	s_waitcnt lgkmcnt(0)
	v_mfma_f32_32x32x16_bf16 v[50:65], v[86:89], v[94:97], v[50:65]
	global_load_dwordx4 v[86:89], v[72:73], off offset:1152
	v_mfma_f32_32x32x16_bf16 v[2:17], v[98:101], v[90:93], v[2:17]
	global_load_dwordx4 v[90:93], v[76:77], off offset:1152
	v_mfma_f32_32x32x16_bf16 v[18:33], v[98:101], v[94:97], v[18:33]
	s_setprio 0
	s_barrier
	ds_read_b128 v[94:97], v68
	ds_read_b128 v[98:101], v68 offset:4608
	ds_read_b128 v[126:129], v1 offset:36864
	ds_read_b128 v[130:133], v1 offset:41472
	s_waitcnt vmcnt(1)
	ds_write_b128 v66, v[86:89] offset:18432
	ds_write_b128 v66, v[102:105] offset:23040
	ds_write_b128 v66, v[106:109] offset:27648
	ds_write_b128 v66, v[110:113] offset:32256
	s_waitcnt vmcnt(0)
	ds_write_b128 v66, v[90:93] offset:55296
	ds_write_b128 v66, v[122:125] offset:59904
	ds_write_b128 v66, v[118:121] offset:64512
	ds_write_b128 v69, v[114:117] offset:32256
	s_setprio 1
	ds_read_b128 v[86:89], v68 offset:32
	s_waitcnt lgkmcnt(10)
	v_mfma_f32_32x32x16_bf16 v[34:49], v[94:97], v[126:129], v[34:49]
	ds_read_b128 v[90:93], v1 offset:36896
	global_load_dwordx4 v[102:105], v[70:71], off offset:1280
	global_load_dwordx4 v[106:109], v[74:75], off offset:1280
	global_load_dwordx4 v[110:113], v[78:79], off offset:1280
	global_load_dwordx4 v[114:117], v[84:85], off offset:1280
	global_load_dwordx4 v[118:121], v[82:83], off offset:1280
	global_load_dwordx4 v[122:125], v[80:81], off offset:1280
	s_waitcnt lgkmcnt(10)
	v_mfma_f32_32x32x16_bf16 v[50:65], v[94:97], v[130:133], v[50:65]
	ds_read_b128 v[94:97], v1 offset:41504
	s_waitcnt lgkmcnt(1)
	v_mfma_f32_32x32x16_bf16 v[34:49], v[86:89], v[90:93], v[34:49]
	s_waitcnt lgkmcnt(0)
	v_mfma_f32_32x32x16_bf16 v[50:65], v[86:89], v[94:97], v[50:65]
	ds_read_b128 v[86:89], v68 offset:4640
	v_mfma_f32_32x32x16_bf16 v[2:17], v[98:101], v[126:129], v[2:17]
	v_mfma_f32_32x32x16_bf16 v[18:33], v[98:101], v[130:133], v[18:33]
	ds_read_b128 v[98:101], v68 offset:4704
	s_waitcnt lgkmcnt(1)
	v_mfma_f32_32x32x16_bf16 v[2:17], v[86:89], v[90:93], v[2:17]
	ds_read_b128 v[90:93], v1 offset:36928
	v_mfma_f32_32x32x16_bf16 v[18:33], v[86:89], v[94:97], v[18:33]
	ds_read_b128 v[86:89], v68 offset:64
	ds_read_b128 v[94:97], v1 offset:41536
	s_waitcnt lgkmcnt(1)
	v_mfma_f32_32x32x16_bf16 v[34:49], v[86:89], v[90:93], v[34:49]
	s_waitcnt lgkmcnt(0)
	v_mfma_f32_32x32x16_bf16 v[50:65], v[86:89], v[94:97], v[50:65]
	ds_read_b128 v[86:89], v68 offset:4672
	s_waitcnt lgkmcnt(0)
	v_mfma_f32_32x32x16_bf16 v[2:17], v[86:89], v[90:93], v[2:17]
	ds_read_b128 v[90:93], v1 offset:36960
	v_mfma_f32_32x32x16_bf16 v[18:33], v[86:89], v[94:97], v[18:33]
	ds_read_b128 v[86:89], v68 offset:96
	ds_read_b128 v[94:97], v1 offset:41568
	s_waitcnt lgkmcnt(1)
	v_mfma_f32_32x32x16_bf16 v[34:49], v[86:89], v[90:93], v[34:49]
	s_waitcnt lgkmcnt(0)
	v_mfma_f32_32x32x16_bf16 v[50:65], v[86:89], v[94:97], v[50:65]
	global_load_dwordx4 v[86:89], v[72:73], off offset:1280
	v_mfma_f32_32x32x16_bf16 v[2:17], v[98:101], v[90:93], v[2:17]
	global_load_dwordx4 v[90:93], v[76:77], off offset:1280
	v_mfma_f32_32x32x16_bf16 v[18:33], v[98:101], v[94:97], v[18:33]
	s_setprio 0
	s_barrier
; #define MFMA(a, b, c) __builtin_amdgcn_mfma_f32_32x32x16_bf16((a), (b), (c), 0, 0, 0)
; template <int TM, int TN>
; DI void gemm_mainloop(const u16* __restrict__ A, long lda, const u16* __restrict__ Bt, long ldb, int K, char* smem,
;                       f32x16 (&acc)[TM][TN]) {
;     ...
;   for (int kt = 0; kt < nk; kt++) {
;     const int buf = kt & 1;
;     const u16* cA = sA + buf * BM * LD + (wm * 32 * TM + r) * LD + h * 8;
;     const u16* cB = sB + buf * BN * LD + (wn * 32 * TN + r) * LD + h * 8;
;     bf16x8 af[TM], bfr[TN];
; #pragma unroll
;     for (int tm = 0; tm < TM; tm++) af[tm] = *(const bf16x8*)(cA + tm * 32 * LD);
; #pragma unroll
;     for (int tn = 0; tn < TN; tn++) bfr[tn] = *(const bf16x8*)(cB + tn * 32 * LD);
;     if (kt + 1 < nk) GEMM_SSTORE(buf ^ 1)
;     __builtin_amdgcn_sched_barrier(0);
;     __builtin_amdgcn_s_setprio(1);
; #pragma unroll
;     for (int tm = 0; tm < TM; tm++)
; #pragma unroll
;       for (int tn = 0; tn < TN; tn++) acc[tm][tn] = MFMA(af[tm], bfr[tn], acc[tm][tn]);
; #pragma unroll
;     for (int tm = 0; tm < TM; tm++) af[tm] = *(const bf16x8*)(cA + tm * 32 * LD + 16);
; #pragma unroll
;     for (int tn = 0; tn < TN; tn++) bfr[tn] = *(const bf16x8*)(cB + tn * 32 * LD + 16);
; #pragma unroll
;     for (int tm = 0; tm < TM; tm++)
; #pragma unroll
;       for (int tn = 0; tn < TN; tn++) acc[tm][tn] = MFMA(af[tm], bfr[tn], acc[tm][tn]);
;     __builtin_amdgcn_sched_group_barrier(0x8, 4, 0);
;     if (kt + 2 < nk) GEMM_GLOAD((kt + 2) * 64)
; #pragma unroll
;     for (int ks = 2; ks < 4; ks++) {
; #pragma unroll
;       for (int tm = 0; tm < TM; tm++) af[tm] = *(const bf16x8*)(cA + tm * 32 * LD + ks * 16);
; #pragma unroll
;       for (int tn = 0; tn < TN; tn++) bfr[tn] = *(const bf16x8*)(cB + tn * 32 * LD + ks * 16);
; #pragma unroll
;       for (int tm = 0; tm < TM; tm++)
; #pragma unroll
;         for (int tn = 0; tn < TN; tn++) acc[tm][tn] = MFMA(af[tm], bfr[tn], acc[tm][tn]);
;     }
;     __builtin_amdgcn_s_setprio(0);
;     __syncthreads();
;   }
	ds_read_b128 v[94:97], v68 offset:18432
	ds_read_b128 v[98:101], v68 offset:23040
	ds_read_b128 v[126:129], v1 offset:55296
	ds_read_b128 v[130:133], v1 offset:59904
	s_waitcnt vmcnt(1)
	ds_write_b128 v66, v[86:89]
	ds_write_b128 v66, v[102:105] offset:4608
	ds_write_b128 v66, v[106:109] offset:9216
	ds_write_b128 v66, v[110:113] offset:13824
	s_waitcnt vmcnt(0)
	ds_write_b128 v66, v[90:93] offset:36864
	ds_write_b128 v66, v[122:125] offset:41472
	ds_write_b128 v66, v[118:121] offset:46080
	ds_write_b128 v66, v[114:117] offset:50688
	s_setprio 1
	ds_read_b128 v[86:89], v68 offset:18464
	s_waitcnt lgkmcnt(10)
	v_mfma_f32_32x32x16_bf16 v[34:49], v[94:97], v[126:129], v[34:49]
	ds_read_b128 v[90:93], v1 offset:55328
	global_load_dwordx4 v[102:105], v[70:71], off offset:1408
	global_load_dwordx4 v[106:109], v[74:75], off offset:1408
	global_load_dwordx4 v[110:113], v[78:79], off offset:1408
	global_load_dwordx4 v[114:117], v[84:85], off offset:1408
	global_load_dwordx4 v[118:121], v[82:83], off offset:1408
	global_load_dwordx4 v[122:125], v[80:81], off offset:1408
	s_waitcnt lgkmcnt(10)
	v_mfma_f32_32x32x16_bf16 v[50:65], v[94:97], v[130:133], v[50:65]
	ds_read_b128 v[94:97], v1 offset:59936
	s_waitcnt lgkmcnt(1)
	v_mfma_f32_32x32x16_bf16 v[34:49], v[86:89], v[90:93], v[34:49]
	s_waitcnt lgkmcnt(0)
	v_mfma_f32_32x32x16_bf16 v[50:65], v[86:89], v[94:97], v[50:65]
	ds_read_b128 v[86:89], v68 offset:23072
	v_mfma_f32_32x32x16_bf16 v[2:17], v[98:101], v[126:129], v[2:17]
	v_mfma_f32_32x32x16_bf16 v[18:33], v[98:101], v[130:133], v[18:33]
	ds_read_b128 v[98:101], v68 offset:23136
	s_waitcnt lgkmcnt(1)
	v_mfma_f32_32x32x16_bf16 v[2:17], v[86:89], v[90:93], v[2:17]
	ds_read_b128 v[90:93], v1 offset:55360
	v_mfma_f32_32x32x16_bf16 v[18:33], v[86:89], v[94:97], v[18:33]
	ds_read_b128 v[86:89], v68 offset:18496
	ds_read_b128 v[94:97], v1 offset:59968
	s_waitcnt lgkmcnt(1)
	v_mfma_f32_32x32x16_bf16 v[34:49], v[86:89], v[90:93], v[34:49]
	s_waitcnt lgkmcnt(0)
	v_mfma_f32_32x32x16_bf16 v[50:65], v[86:89], v[94:97], v[50:65]
	ds_read_b128 v[86:89], v68 offset:23104
	s_waitcnt lgkmcnt(0)
	v_mfma_f32_32x32x16_bf16 v[2:17], v[86:89], v[90:93], v[2:17]
	ds_read_b128 v[90:93], v1 offset:55392
	v_mfma_f32_32x32x16_bf16 v[18:33], v[86:89], v[94:97], v[18:33]
	ds_read_b128 v[86:89], v68 offset:18528
	ds_read_b128 v[94:97], v1 offset:60000
	s_waitcnt lgkmcnt(1)
	v_mfma_f32_32x32x16_bf16 v[34:49], v[86:89], v[90:93], v[34:49]
	s_waitcnt lgkmcnt(0)
	v_mfma_f32_32x32x16_bf16 v[50:65], v[86:89], v[94:97], v[50:65]
	global_load_dwordx4 v[86:89], v[72:73], off offset:1408
	v_mfma_f32_32x32x16_bf16 v[2:17], v[98:101], v[90:93], v[2:17]
	global_load_dwordx4 v[90:93], v[76:77], off offset:1408
	v_mfma_f32_32x32x16_bf16 v[18:33], v[98:101], v[94:97], v[18:33]
	s_setprio 0
	s_barrier
	ds_read_b128 v[94:97], v68
	ds_read_b128 v[98:101], v68 offset:4608
	ds_read_b128 v[126:129], v1 offset:36864
	ds_read_b128 v[130:133], v1 offset:41472
	s_waitcnt vmcnt(1)
	ds_write_b128 v66, v[86:89] offset:18432
	ds_write_b128 v66, v[102:105] offset:23040
	ds_write_b128 v66, v[106:109] offset:27648
	ds_write_b128 v66, v[110:113] offset:32256
	s_waitcnt vmcnt(0)
	ds_write_b128 v66, v[90:93] offset:55296
	ds_write_b128 v66, v[122:125] offset:59904
	ds_write_b128 v66, v[118:121] offset:64512
	ds_write_b128 v69, v[114:117] offset:32256
	s_setprio 1
	ds_read_b128 v[86:89], v68 offset:32
	s_waitcnt lgkmcnt(10)
	v_mfma_f32_32x32x16_bf16 v[34:49], v[94:97], v[126:129], v[34:49]
	ds_read_b128 v[90:93], v1 offset:36896
	global_load_dwordx4 v[102:105], v[70:71], off offset:1536
	global_load_dwordx4 v[106:109], v[74:75], off offset:1536
	global_load_dwordx4 v[110:113], v[78:79], off offset:1536
	global_load_dwordx4 v[114:117], v[84:85], off offset:1536
	global_load_dwordx4 v[118:121], v[82:83], off offset:1536
	global_load_dwordx4 v[122:125], v[80:81], off offset:1536
	s_waitcnt lgkmcnt(10)
	v_mfma_f32_32x32x16_bf16 v[50:65], v[94:97], v[130:133], v[50:65]
	ds_read_b128 v[94:97], v1 offset:41504
	s_waitcnt lgkmcnt(1)
	v_mfma_f32_32x32x16_bf16 v[34:49], v[86:89], v[90:93], v[34:49]
	s_waitcnt lgkmcnt(0)
	v_mfma_f32_32x32x16_bf16 v[50:65], v[86:89], v[94:97], v[50:65]
	ds_read_b128 v[86:89], v68 offset:4640
	v_mfma_f32_32x32x16_bf16 v[2:17], v[98:101], v[126:129], v[2:17]
	v_mfma_f32_32x32x16_bf16 v[18:33], v[98:101], v[130:133], v[18:33]
	ds_read_b128 v[98:101], v68 offset:4704
	s_waitcnt lgkmcnt(1)
	v_mfma_f32_32x32x16_bf16 v[2:17], v[86:89], v[90:93], v[2:17]
	ds_read_b128 v[90:93], v1 offset:36928
	v_mfma_f32_32x32x16_bf16 v[18:33], v[86:89], v[94:97], v[18:33]
	ds_read_b128 v[86:89], v68 offset:64
	ds_read_b128 v[94:97], v1 offset:41536
	s_waitcnt lgkmcnt(1)
	v_mfma_f32_32x32x16_bf16 v[34:49], v[86:89], v[90:93], v[34:49]
	s_waitcnt lgkmcnt(0)
	v_mfma_f32_32x32x16_bf16 v[50:65], v[86:89], v[94:97], v[50:65]
	ds_read_b128 v[86:89], v68 offset:4672
	s_waitcnt lgkmcnt(0)
	v_mfma_f32_32x32x16_bf16 v[2:17], v[86:89], v[90:93], v[2:17]
	ds_read_b128 v[90:93], v1 offset:36960
	v_mfma_f32_32x32x16_bf16 v[18:33], v[86:89], v[94:97], v[18:33]
	ds_read_b128 v[86:89], v68 offset:96
	ds_read_b128 v[94:97], v1 offset:41568
	s_waitcnt lgkmcnt(1)
	v_mfma_f32_32x32x16_bf16 v[34:49], v[86:89], v[90:93], v[34:49]
	s_waitcnt lgkmcnt(0)
	v_mfma_f32_32x32x16_bf16 v[50:65], v[86:89], v[94:97], v[50:65]
	global_load_dwordx4 v[86:89], v[72:73], off offset:1536
	v_mfma_f32_32x32x16_bf16 v[2:17], v[98:101], v[90:93], v[2:17]
	global_load_dwordx4 v[90:93], v[76:77], off offset:1536
	v_mfma_f32_32x32x16_bf16 v[18:33], v[98:101], v[94:97], v[18:33]
	s_setprio 0
	s_barrier
; #define MFMA(a, b, c) __builtin_amdgcn_mfma_f32_32x32x16_bf16((a), (b), (c), 0, 0, 0)
; template <int TM, int TN>
; DI void gemm_mainloop(const u16* __restrict__ A, long lda, const u16* __restrict__ Bt, long ldb, int K, char* smem,
;                       f32x16 (&acc)[TM][TN]) {
;     ...
;   for (int kt = 0; kt < nk; kt++) {
;     const int buf = kt & 1;
;     const u16* cA = sA + buf * BM * LD + (wm * 32 * TM + r) * LD + h * 8;
;     const u16* cB = sB + buf * BN * LD + (wn * 32 * TN + r) * LD + h * 8;
;     bf16x8 af[TM], bfr[TN];
; #pragma unroll
;     for (int tm = 0; tm < TM; tm++) af[tm] = *(const bf16x8*)(cA + tm * 32 * LD);
; #pragma unroll
;     for (int tn = 0; tn < TN; tn++) bfr[tn] = *(const bf16x8*)(cB + tn * 32 * LD);
;     if (kt + 1 < nk) GEMM_SSTORE(buf ^ 1)
;     __builtin_amdgcn_sched_barrier(0);
;     __builtin_amdgcn_s_setprio(1);
; #pragma unroll
;     for (int tm = 0; tm < TM; tm++)
; #pragma unroll
;       for (int tn = 0; tn < TN; tn++) acc[tm][tn] = MFMA(af[tm], bfr[tn], acc[tm][tn]);
; #pragma unroll
;     for (int tm = 0; tm < TM; tm++) af[tm] = *(const bf16x8*)(cA + tm * 32 * LD + 16);
; #pragma unroll
;     for (int tn = 0; tn < TN; tn++) bfr[tn] = *(const bf16x8*)(cB + tn * 32 * LD + 16);
; #pragma unroll
;     for (int tm = 0; tm < TM; tm++)
; #pragma unroll
;       for (int tn = 0; tn < TN; tn++) acc[tm][tn] = MFMA(af[tm], bfr[tn], acc[tm][tn]);
;     __builtin_amdgcn_sched_group_barrier(0x8, 4, 0);
;     if (kt + 2 < nk) GEMM_GLOAD((kt + 2) * 64)
; #pragma unroll
;     for (int ks = 2; ks < 4; ks++) {
; #pragma unroll
;       for (int tm = 0; tm < TM; tm++) af[tm] = *(const bf16x8*)(cA + tm * 32 * LD + ks * 16);
; #pragma unroll
;       for (int tn = 0; tn < TN; tn++) bfr[tn] = *(const bf16x8*)(cB + tn * 32 * LD + ks * 16);
; #pragma unroll
;       for (int tm = 0; tm < TM; tm++)
; #pragma unroll
;         for (int tn = 0; tn < TN; tn++) acc[tm][tn] = MFMA(af[tm], bfr[tn], acc[tm][tn]);
;     }
;     __builtin_amdgcn_s_setprio(0);
;     __syncthreads();
;   }
	ds_read_b128 v[94:97], v68 offset:18432
	ds_read_b128 v[98:101], v68 offset:23040
	ds_read_b128 v[126:129], v1 offset:55296
	ds_read_b128 v[130:133], v1 offset:59904
	s_waitcnt vmcnt(1)
	ds_write_b128 v66, v[86:89]
	ds_write_b128 v66, v[102:105] offset:4608
	ds_write_b128 v66, v[106:109] offset:9216
	ds_write_b128 v66, v[110:113] offset:13824
	s_waitcnt vmcnt(0)
	ds_write_b128 v66, v[90:93] offset:36864
	ds_write_b128 v66, v[122:125] offset:41472
	ds_write_b128 v66, v[118:121] offset:46080
	ds_write_b128 v66, v[114:117] offset:50688
	s_setprio 1
	ds_read_b128 v[86:89], v68 offset:18464
	s_waitcnt lgkmcnt(10)
	v_mfma_f32_32x32x16_bf16 v[34:49], v[94:97], v[126:129], v[34:49]
	ds_read_b128 v[90:93], v1 offset:55328
	global_load_dwordx4 v[102:105], v[70:71], off offset:1664
	global_load_dwordx4 v[106:109], v[74:75], off offset:1664
	global_load_dwordx4 v[110:113], v[78:79], off offset:1664
	global_load_dwordx4 v[114:117], v[84:85], off offset:1664
	global_load_dwordx4 v[118:121], v[82:83], off offset:1664
	global_load_dwordx4 v[122:125], v[80:81], off offset:1664
	s_waitcnt lgkmcnt(10)
	v_mfma_f32_32x32x16_bf16 v[50:65], v[94:97], v[130:133], v[50:65]
	ds_read_b128 v[94:97], v1 offset:59936
	s_waitcnt lgkmcnt(1)
	v_mfma_f32_32x32x16_bf16 v[34:49], v[86:89], v[90:93], v[34:49]
	s_waitcnt lgkmcnt(0)
	v_mfma_f32_32x32x16_bf16 v[50:65], v[86:89], v[94:97], v[50:65]
	ds_read_b128 v[86:89], v68 offset:23072
	v_mfma_f32_32x32x16_bf16 v[2:17], v[98:101], v[126:129], v[2:17]
	v_mfma_f32_32x32x16_bf16 v[18:33], v[98:101], v[130:133], v[18:33]
	ds_read_b128 v[98:101], v68 offset:23136
	s_waitcnt lgkmcnt(1)
	v_mfma_f32_32x32x16_bf16 v[2:17], v[86:89], v[90:93], v[2:17]
	ds_read_b128 v[90:93], v1 offset:55360
	v_mfma_f32_32x32x16_bf16 v[18:33], v[86:89], v[94:97], v[18:33]
	ds_read_b128 v[86:89], v68 offset:18496
	ds_read_b128 v[94:97], v1 offset:59968
	s_waitcnt lgkmcnt(1)
	v_mfma_f32_32x32x16_bf16 v[34:49], v[86:89], v[90:93], v[34:49]
	s_waitcnt lgkmcnt(0)
	v_mfma_f32_32x32x16_bf16 v[50:65], v[86:89], v[94:97], v[50:65]
	ds_read_b128 v[86:89], v68 offset:23104
	s_waitcnt lgkmcnt(0)
	v_mfma_f32_32x32x16_bf16 v[2:17], v[86:89], v[90:93], v[2:17]
	ds_read_b128 v[90:93], v1 offset:55392
	v_mfma_f32_32x32x16_bf16 v[18:33], v[86:89], v[94:97], v[18:33]
	ds_read_b128 v[86:89], v68 offset:18528
	ds_read_b128 v[94:97], v1 offset:60000
	s_waitcnt lgkmcnt(1)
	v_mfma_f32_32x32x16_bf16 v[34:49], v[86:89], v[90:93], v[34:49]
	s_waitcnt lgkmcnt(0)
	v_mfma_f32_32x32x16_bf16 v[50:65], v[86:89], v[94:97], v[50:65]
	global_load_dwordx4 v[86:89], v[72:73], off offset:1664
	v_mfma_f32_32x32x16_bf16 v[2:17], v[98:101], v[90:93], v[2:17]
	global_load_dwordx4 v[90:93], v[76:77], off offset:1664
	v_mfma_f32_32x32x16_bf16 v[18:33], v[98:101], v[94:97], v[18:33]
	s_setprio 0
	s_barrier
	ds_read_b128 v[94:97], v68
	ds_read_b128 v[98:101], v68 offset:4608
	ds_read_b128 v[126:129], v1 offset:36864
	ds_read_b128 v[130:133], v1 offset:41472
	s_waitcnt vmcnt(1)
	ds_write_b128 v66, v[86:89] offset:18432
	ds_write_b128 v66, v[102:105] offset:23040
	ds_write_b128 v66, v[106:109] offset:27648
	ds_write_b128 v66, v[110:113] offset:32256
	s_waitcnt vmcnt(0)
	ds_write_b128 v66, v[90:93] offset:55296
	ds_write_b128 v66, v[122:125] offset:59904
	ds_write_b128 v66, v[118:121] offset:64512
	ds_write_b128 v69, v[114:117] offset:32256
	s_setprio 1
	ds_read_b128 v[86:89], v68 offset:32
	s_waitcnt lgkmcnt(10)
	v_mfma_f32_32x32x16_bf16 v[34:49], v[94:97], v[126:129], v[34:49]
	ds_read_b128 v[90:93], v1 offset:36896
	global_load_dwordx4 v[102:105], v[70:71], off offset:1792
	global_load_dwordx4 v[106:109], v[74:75], off offset:1792
	global_load_dwordx4 v[110:113], v[78:79], off offset:1792
	global_load_dwordx4 v[114:117], v[84:85], off offset:1792
	global_load_dwordx4 v[118:121], v[82:83], off offset:1792
	global_load_dwordx4 v[122:125], v[80:81], off offset:1792
	s_waitcnt lgkmcnt(10)
	v_mfma_f32_32x32x16_bf16 v[50:65], v[94:97], v[130:133], v[50:65]
	ds_read_b128 v[94:97], v1 offset:41504
	s_waitcnt lgkmcnt(1)
	v_mfma_f32_32x32x16_bf16 v[34:49], v[86:89], v[90:93], v[34:49]
	s_waitcnt lgkmcnt(0)
	v_mfma_f32_32x32x16_bf16 v[50:65], v[86:89], v[94:97], v[50:65]
	ds_read_b128 v[86:89], v68 offset:4640
	v_mfma_f32_32x32x16_bf16 v[2:17], v[98:101], v[126:129], v[2:17]
	v_mfma_f32_32x32x16_bf16 v[18:33], v[98:101], v[130:133], v[18:33]
	ds_read_b128 v[98:101], v68 offset:4704
	s_waitcnt lgkmcnt(1)
	v_mfma_f32_32x32x16_bf16 v[2:17], v[86:89], v[90:93], v[2:17]
	ds_read_b128 v[90:93], v1 offset:36928
	v_mfma_f32_32x32x16_bf16 v[18:33], v[86:89], v[94:97], v[18:33]
	ds_read_b128 v[86:89], v68 offset:64
	ds_read_b128 v[94:97], v1 offset:41536
	s_waitcnt lgkmcnt(1)
	v_mfma_f32_32x32x16_bf16 v[34:49], v[86:89], v[90:93], v[34:49]
	s_waitcnt lgkmcnt(0)
	v_mfma_f32_32x32x16_bf16 v[50:65], v[86:89], v[94:97], v[50:65]
	ds_read_b128 v[86:89], v68 offset:4672
	s_waitcnt lgkmcnt(0)
	v_mfma_f32_32x32x16_bf16 v[2:17], v[86:89], v[90:93], v[2:17]
	ds_read_b128 v[90:93], v1 offset:36960
	v_mfma_f32_32x32x16_bf16 v[18:33], v[86:89], v[94:97], v[18:33]
	ds_read_b128 v[86:89], v68 offset:96
	ds_read_b128 v[94:97], v1 offset:41568
	s_waitcnt lgkmcnt(1)
	v_mfma_f32_32x32x16_bf16 v[34:49], v[86:89], v[90:93], v[34:49]
	s_waitcnt lgkmcnt(0)
	v_mfma_f32_32x32x16_bf16 v[50:65], v[86:89], v[94:97], v[50:65]
	global_load_dwordx4 v[86:89], v[72:73], off offset:1792
	v_mfma_f32_32x32x16_bf16 v[2:17], v[98:101], v[90:93], v[2:17]
	global_load_dwordx4 v[90:93], v[76:77], off offset:1792
	v_mfma_f32_32x32x16_bf16 v[18:33], v[98:101], v[94:97], v[18:33]
	s_setprio 0
	s_barrier
; #define MFMA(a, b, c) __builtin_amdgcn_mfma_f32_32x32x16_bf16((a), (b), (c), 0, 0, 0)
; template <int TM, int TN>
; DI void gemm_mainloop(const u16* __restrict__ A, long lda, const u16* __restrict__ Bt, long ldb, int K, char* smem,
;                       f32x16 (&acc)[TM][TN]) {
;     ...
;   for (int kt = 0; kt < nk; kt++) {
;     const int buf = kt & 1;
;     const u16* cA = sA + buf * BM * LD + (wm * 32 * TM + r) * LD + h * 8;
;     const u16* cB = sB + buf * BN * LD + (wn * 32 * TN + r) * LD + h * 8;
;     bf16x8 af[TM], bfr[TN];
; #pragma unroll
;     for (int tm = 0; tm < TM; tm++) af[tm] = *(const bf16x8*)(cA + tm * 32 * LD);
; #pragma unroll
;     for (int tn = 0; tn < TN; tn++) bfr[tn] = *(const bf16x8*)(cB + tn * 32 * LD);
;     if (kt + 1 < nk) GEMM_SSTORE(buf ^ 1)
;     __builtin_amdgcn_sched_barrier(0);
;     __builtin_amdgcn_s_setprio(1);
; #pragma unroll
;     for (int tm = 0; tm < TM; tm++)
; #pragma unroll
;       for (int tn = 0; tn < TN; tn++) acc[tm][tn] = MFMA(af[tm], bfr[tn], acc[tm][tn]);
; #pragma unroll
;     for (int tm = 0; tm < TM; tm++) af[tm] = *(const bf16x8*)(cA + tm * 32 * LD + 16);
; #pragma unroll
;     for (int tn = 0; tn < TN; tn++) bfr[tn] = *(const bf16x8*)(cB + tn * 32 * LD + 16);
; #pragma unroll
;     for (int tm = 0; tm < TM; tm++)
; #pragma unroll
;       for (int tn = 0; tn < TN; tn++) acc[tm][tn] = MFMA(af[tm], bfr[tn], acc[tm][tn]);
;     __builtin_amdgcn_sched_group_barrier(0x8, 4, 0);
;     if (kt + 2 < nk) GEMM_GLOAD((kt + 2) * 64)
; #pragma unroll
;     for (int ks = 2; ks < 4; ks++) {
; #pragma unroll
;       for (int tm = 0; tm < TM; tm++) af[tm] = *(const bf16x8*)(cA + tm * 32 * LD + ks * 16);
; #pragma unroll
;       for (int tn = 0; tn < TN; tn++) bfr[tn] = *(const bf16x8*)(cB + tn * 32 * LD + ks * 16);
; #pragma unroll
;       for (int tm = 0; tm < TM; tm++)
; #pragma unroll
;         for (int tn = 0; tn < TN; tn++) acc[tm][tn] = MFMA(af[tm], bfr[tn], acc[tm][tn]);
;     }
;     __builtin_amdgcn_s_setprio(0);
;     __syncthreads();
;   }
	ds_read_b128 v[94:97], v68 offset:18432
	ds_read_b128 v[98:101], v68 offset:23040
	ds_read_b128 v[126:129], v1 offset:55296
	ds_read_b128 v[130:133], v1 offset:59904
	s_waitcnt vmcnt(1)
	ds_write_b128 v66, v[86:89]
	ds_write_b128 v66, v[102:105] offset:4608
	ds_write_b128 v66, v[106:109] offset:9216
	ds_write_b128 v66, v[110:113] offset:13824
	s_waitcnt vmcnt(0)
	ds_write_b128 v66, v[90:93] offset:36864
	ds_write_b128 v66, v[122:125] offset:41472
	ds_write_b128 v66, v[118:121] offset:46080
	ds_write_b128 v66, v[114:117] offset:50688
	s_setprio 1
	ds_read_b128 v[86:89], v68 offset:18464
	s_waitcnt lgkmcnt(10)
	v_mfma_f32_32x32x16_bf16 v[34:49], v[94:97], v[126:129], v[34:49]
	ds_read_b128 v[90:93], v1 offset:55328
	global_load_dwordx4 v[102:105], v[70:71], off offset:1920
	global_load_dwordx4 v[106:109], v[74:75], off offset:1920
	global_load_dwordx4 v[110:113], v[78:79], off offset:1920
	global_load_dwordx4 v[114:117], v[84:85], off offset:1920
	global_load_dwordx4 v[118:121], v[82:83], off offset:1920
	global_load_dwordx4 v[122:125], v[80:81], off offset:1920
	s_waitcnt lgkmcnt(10)
	v_mfma_f32_32x32x16_bf16 v[50:65], v[94:97], v[130:133], v[50:65]
	ds_read_b128 v[94:97], v1 offset:59936
	s_waitcnt lgkmcnt(1)
	v_mfma_f32_32x32x16_bf16 v[34:49], v[86:89], v[90:93], v[34:49]
	s_waitcnt lgkmcnt(0)
	v_mfma_f32_32x32x16_bf16 v[50:65], v[86:89], v[94:97], v[50:65]
	ds_read_b128 v[86:89], v68 offset:23072
	v_mfma_f32_32x32x16_bf16 v[2:17], v[98:101], v[126:129], v[2:17]
	v_mfma_f32_32x32x16_bf16 v[18:33], v[98:101], v[130:133], v[18:33]
	ds_read_b128 v[98:101], v68 offset:23136
	s_waitcnt lgkmcnt(1)
	v_mfma_f32_32x32x16_bf16 v[2:17], v[86:89], v[90:93], v[2:17]
	ds_read_b128 v[90:93], v1 offset:55360
	v_mfma_f32_32x32x16_bf16 v[18:33], v[86:89], v[94:97], v[18:33]
	ds_read_b128 v[86:89], v68 offset:18496
	ds_read_b128 v[94:97], v1 offset:59968
	s_waitcnt lgkmcnt(1)
	v_mfma_f32_32x32x16_bf16 v[34:49], v[86:89], v[90:93], v[34:49]
	s_waitcnt lgkmcnt(0)
	v_mfma_f32_32x32x16_bf16 v[50:65], v[86:89], v[94:97], v[50:65]
	ds_read_b128 v[86:89], v68 offset:23104
	s_waitcnt lgkmcnt(0)
	v_mfma_f32_32x32x16_bf16 v[2:17], v[86:89], v[90:93], v[2:17]
	ds_read_b128 v[90:93], v1 offset:55392
	v_mfma_f32_32x32x16_bf16 v[18:33], v[86:89], v[94:97], v[18:33]
	ds_read_b128 v[86:89], v68 offset:18528
	ds_read_b128 v[94:97], v1 offset:60000
	s_waitcnt lgkmcnt(1)
	v_mfma_f32_32x32x16_bf16 v[34:49], v[86:89], v[90:93], v[34:49]
	s_waitcnt lgkmcnt(0)
	v_mfma_f32_32x32x16_bf16 v[50:65], v[86:89], v[94:97], v[50:65]
	global_load_dwordx4 v[86:89], v[72:73], off offset:1920
	s_nop 0
	global_load_dwordx4 v[70:73], v[76:77], off offset:1920
	v_mfma_f32_32x32x16_bf16 v[2:17], v[98:101], v[90:93], v[2:17]
	v_mfma_f32_32x32x16_bf16 v[18:33], v[98:101], v[94:97], v[18:33]
	s_setprio 0
	s_barrier
	ds_read_b128 v[74:77], v68
	ds_read_b128 v[78:81], v68 offset:4608
	ds_read_b128 v[82:85], v1 offset:36864
	ds_read_b128 v[90:93], v1 offset:41472
	s_waitcnt vmcnt(1)
	ds_write_b128 v66, v[86:89] offset:18432
	ds_write_b128 v66, v[102:105] offset:23040
	ds_write_b128 v66, v[106:109] offset:27648
	ds_write_b128 v66, v[110:113] offset:32256
	s_waitcnt vmcnt(0)
	ds_write_b128 v66, v[70:73] offset:55296
	ds_write_b128 v66, v[122:125] offset:59904
	ds_write_b128 v66, v[118:121] offset:64512
	ds_write_b128 v69, v[114:117] offset:32256
	s_setprio 1
	ds_read_b128 v[70:73], v68 offset:32
	s_waitcnt lgkmcnt(10)
	v_mfma_f32_32x32x16_bf16 v[34:49], v[74:77], v[82:85], v[34:49]
	s_waitcnt lgkmcnt(9)
	v_mfma_f32_32x32x16_bf16 v[50:65], v[74:77], v[90:93], v[50:65]
	ds_read_b128 v[74:77], v1 offset:36896
	v_mfma_f32_32x32x16_bf16 v[2:17], v[78:81], v[82:85], v[2:17]
	v_mfma_f32_32x32x16_bf16 v[18:33], v[78:81], v[90:93], v[18:33]
	ds_read_b128 v[78:81], v1 offset:41504
	s_waitcnt lgkmcnt(1)
	v_mfma_f32_32x32x16_bf16 v[34:49], v[70:73], v[74:77], v[34:49]
	s_waitcnt lgkmcnt(0)
	v_mfma_f32_32x32x16_bf16 v[50:65], v[70:73], v[78:81], v[50:65]
	ds_read_b128 v[70:73], v68 offset:4640
	s_waitcnt lgkmcnt(0)
	v_mfma_f32_32x32x16_bf16 v[2:17], v[70:73], v[74:77], v[2:17]
	ds_read_b128 v[74:77], v1 offset:36928
	v_mfma_f32_32x32x16_bf16 v[18:33], v[70:73], v[78:81], v[18:33]
	ds_read_b128 v[70:73], v68 offset:64
	ds_read_b128 v[78:81], v1 offset:41536
	s_waitcnt lgkmcnt(1)
	v_mfma_f32_32x32x16_bf16 v[34:49], v[70:73], v[74:77], v[34:49]
	s_waitcnt lgkmcnt(0)
	v_mfma_f32_32x32x16_bf16 v[50:65], v[70:73], v[78:81], v[50:65]
	ds_read_b128 v[70:73], v68 offset:4672
	s_waitcnt lgkmcnt(0)
	v_mfma_f32_32x32x16_bf16 v[2:17], v[70:73], v[74:77], v[2:17]
	ds_read_b128 v[74:77], v1 offset:36960
	v_mfma_f32_32x32x16_bf16 v[18:33], v[70:73], v[78:81], v[18:33]
	ds_read_b128 v[70:73], v68 offset:96
	ds_read_b128 v[78:81], v1 offset:41568
	s_waitcnt lgkmcnt(1)
	v_mfma_f32_32x32x16_bf16 v[34:49], v[70:73], v[74:77], v[34:49]
	s_waitcnt lgkmcnt(0)
	v_mfma_f32_32x32x16_bf16 v[50:65], v[70:73], v[78:81], v[50:65]
	ds_read_b128 v[70:73], v68 offset:4704
	s_waitcnt lgkmcnt(0)
	v_mfma_f32_32x32x16_bf16 v[2:17], v[70:73], v[74:77], v[2:17]
	v_mfma_f32_32x32x16_bf16 v[18:33], v[70:73], v[78:81], v[18:33]
	s_setprio 0
	s_barrier
; #define MFMA(a, b, c) __builtin_amdgcn_mfma_f32_32x32x16_bf16((a), (b), (c), 0, 0, 0)
; DI int crow(int i, int h) { return (i & 3) + 8 * (i >> 2) + 4 * h; }
; template <int TM, int TN>
; DI void gemm_mainloop(const u16* __restrict__ A, long lda, const u16* __restrict__ Bt, long ldb, int K, char* smem,
;                       f32x16 (&acc)[TM][TN]) {
;     ...
;     for (int ks = 2; ks < 4; ks++) {
; #pragma unroll
;       for (int tm = 0; tm < TM; tm++) af[tm] = *(const bf16x8*)(cA + tm * 32 * LD + ks * 16);
; #pragma unroll
;       for (int tn = 0; tn < TN; tn++) bfr[tn] = *(const bf16x8*)(cB + tn * 32 * LD + ks * 16);
; #pragma unroll
;       for (int tm = 0; tm < TM; tm++)
; #pragma unroll
;         for (int tn = 0; tn < TN; tn++) acc[tm][tn] = MFMA(af[tm], bfr[tn], acc[tm][tn]);
;     }
;     __builtin_amdgcn_s_setprio(0);
;     __syncthreads();
;   }
; template <int TM, int TN, class Epi>
; DI void gemm_tile(const u16* A, long lda, const u16* Bt, long ldb, int K, int m0, int n0, char* smem, const Epi& epi) {
;     ...
; #pragma unroll
;   for (int tm = 0; tm < TM; tm++)
; #pragma unroll
;     for (int tn = 0; tn < TN; tn++)
; #pragma unroll
;       for (int i = 0; i < 16; i++)
;         Ct[(wm * 32 * TM + tm * 32 + crow(i, h)) * LDC + wn * 32 * TN + tn * 32 + r] = acc[tm][tn][i];
;   __syncthreads();
	ds_read_b128 v[70:73], v68 offset:18432
	ds_read_b128 v[74:77], v68 offset:23040
	ds_read_b128 v[78:81], v1 offset:55296
	ds_read_b128 v[82:85], v1 offset:59904
	s_setprio 1
	s_waitcnt lgkmcnt(1)
	v_mfma_f32_32x32x16_bf16 v[34:49], v[70:73], v[78:81], v[34:49]
	s_waitcnt lgkmcnt(0)
	v_mfma_f32_32x32x16_bf16 v[50:65], v[70:73], v[82:85], v[50:65]
	ds_read_b128 v[70:73], v68 offset:18464
	v_mfma_f32_32x32x16_bf16 v[2:17], v[74:77], v[78:81], v[2:17]
	ds_read_b128 v[78:81], v1 offset:59936
	v_mfma_f32_32x32x16_bf16 v[18:33], v[74:77], v[82:85], v[18:33]
	ds_read_b128 v[74:77], v1 offset:55328
	s_waitcnt lgkmcnt(0)
	v_mfma_f32_32x32x16_bf16 v[34:49], v[70:73], v[74:77], v[34:49]
	v_mfma_f32_32x32x16_bf16 v[50:65], v[70:73], v[78:81], v[50:65]
	ds_read_b128 v[70:73], v68 offset:23072
	s_waitcnt lgkmcnt(0)
	v_mfma_f32_32x32x16_bf16 v[2:17], v[70:73], v[74:77], v[2:17]
	ds_read_b128 v[74:77], v1 offset:55360
	v_mfma_f32_32x32x16_bf16 v[18:33], v[70:73], v[78:81], v[18:33]
	ds_read_b128 v[70:73], v68 offset:18496
	ds_read_b128 v[78:81], v1 offset:59968
	s_waitcnt lgkmcnt(1)
	v_mfma_f32_32x32x16_bf16 v[34:49], v[70:73], v[74:77], v[34:49]
	s_waitcnt lgkmcnt(0)
	v_mfma_f32_32x32x16_bf16 v[50:65], v[70:73], v[78:81], v[50:65]
	ds_read_b128 v[70:73], v68 offset:23104
	s_waitcnt lgkmcnt(0)
	v_mfma_f32_32x32x16_bf16 v[2:17], v[70:73], v[74:77], v[2:17]
	ds_read_b128 v[74:77], v1 offset:55392
	v_mfma_f32_32x32x16_bf16 v[18:33], v[70:73], v[78:81], v[18:33]
	ds_read_b128 v[70:73], v68 offset:18528
	ds_read_b128 v[78:81], v1 offset:60000
	s_waitcnt lgkmcnt(1)
	v_mfma_f32_32x32x16_bf16 v[34:49], v[70:73], v[74:77], v[34:49]
	s_waitcnt lgkmcnt(0)
	v_mfma_f32_32x32x16_bf16 v[50:65], v[70:73], v[78:81], v[50:65]
	ds_read_b128 v[68:71], v68 offset:23136
	s_waitcnt lgkmcnt(0)
	v_mfma_f32_32x32x16_bf16 v[2:17], v[68:71], v[74:77], v[2:17]
	v_mfma_f32_32x32x16_bf16 v[18:33], v[68:71], v[78:81], v[18:33]
	s_setprio 0
	v_mov_b32_e32 v1, v0
	s_barrier
	s_mov_b32 s4, 0
	v_lshrrev_b32_e32 v66, 1, v1
	v_and_b32_e32 v66, 0xfffffc0, v66
	v_lshrrev_b32_e32 v68, 3, v1
	v_and_or_b32 v66, v68, 4, v66
	v_and_b32_e32 v68, 0x5f, v1
	v_mul_lo_u32 v66, v66, s22
	v_lshl_add_u32 v66, v68, 2, v66
	ds_write2_b32 v66, v34, v50 offset1:32
	v_add_u32_e32 v34, 0x400, v66
	ds_write2_b32 v34, v36, v52 offset0:8 offset1:40
	ds_write2_b32 v34, v37, v53 offset0:140 offset1:172
	v_add_u32_e32 v34, 0x1000, v66
	ds_write2_b32 v34, v38, v54 offset0:32 offset1:64
	ds_write2_b32 v34, v39, v55 offset0:164 offset1:196
	v_add_u32_e32 v34, 0x1400, v66
	ds_write2_b32 v34, v40, v56 offset0:40 offset1:72
	ds_write2_b32 v34, v41, v57 offset0:172 offset1:204
	v_add_u32_e32 v34, 0x2000, v66
	ds_write2_b32 v34, v42, v58 offset0:64 offset1:96
	ds_write2_b32 v34, v43, v59 offset0:196 offset1:228
	v_add_u32_e32 v34, 0x2400, v66
	ds_write2_b32 v34, v44, v60 offset0:72 offset1:104
	ds_write2_b32 v34, v45, v61 offset0:204 offset1:236
	v_add_u32_e32 v34, 0x3000, v66
	ds_write2_b32 v34, v46, v62 offset0:96 offset1:128
	v_add_u32_e32 v34, 0x3200, v66
	ds_write2_b32 v34, v47, v63 offset0:100 offset1:132
	v_add_u32_e32 v34, 0x3400, v66
	ds_write2_b32 v34, v48, v64 offset0:104 offset1:136
	v_add_u32_e32 v34, 0x3600, v66
	ds_write2_b32 v34, v49, v65 offset0:108 offset1:140
	v_add_u32_e32 v34, 0x4000, v66
	ds_write2_b32 v34, v2, v18 offset0:128 offset1:160
	v_add_u32_e32 v2, 0x4400, v66
	ds_write2_b32 v2, v3, v19 offset0:4 offset1:36
	ds_write2_b32 v2, v4, v20 offset0:136 offset1:168
	v_add_u32_e32 v2, 0x4800, v66
	ds_write2_b32 v2, v5, v21 offset0:12 offset1:44
	v_add_u32_e32 v2, 0x5000, v66
	ds_write2_b32 v2, v6, v22 offset0:160 offset1:192
	v_add_u32_e32 v2, 0x5400, v66
	ds_write2_b32 v2, v7, v23 offset0:36 offset1:68
	ds_write2_b32 v2, v8, v24 offset0:168 offset1:200
	v_add_u32_e32 v2, 0x5800, v66
	ds_write2_b32 v2, v9, v25 offset0:44 offset1:76
	v_add_u32_e32 v2, 0x6000, v66
	ds_write2_b32 v2, v10, v26 offset0:192 offset1:224
	v_add_u32_e32 v2, 0x6400, v66
	ds_write2_b32 v2, v11, v27 offset0:68 offset1:100
	ds_write2_b32 v2, v12, v28 offset0:200 offset1:232
	v_add_u32_e32 v2, 0x6800, v66
	ds_write2_b32 v2, v13, v29 offset0:76 offset1:108
	v_add_u32_e32 v2, 0x7200, v66
	ds_write2_b32 v2, v14, v30 offset0:96 offset1:128
	v_add_u32_e32 v2, 0x7400, v66
	ds_write2_b32 v2, v15, v31 offset0:100 offset1:132
	v_add_u32_e32 v2, 0x7600, v66
	ds_write2_b32 v2, v16, v32 offset0:104 offset1:136
	v_add_u32_e32 v2, 0x7800, v66
	ds_write2_b32 v2, v17, v33 offset0:108 offset1:140
	v_lshlrev_b32_e32 v2, 3, v1
	v_and_b32_e32 v2, 0x78, v2
	v_lshl_or_b32 v4, s10, 7, v2
	v_ashrrev_i32_e32 v5, 31, v4
	v_lshlrev_b32_e32 v2, 2, v2
	v_cmp_gt_i32_e32 vcc, s23, v4
	v_lshl_add_u64 v[4:5], v[4:5], 1, s[6:7]
	ds_write2_b32 v66, v35, v51 offset0:132 offset1:164
	s_waitcnt lgkmcnt(0)
	s_barrier
	s_branch .LBB0_1066

; #define MFMA(a, b, c) __builtin_amdgcn_mfma_f32_32x32x16_bf16((a), (b), (c), 0, 0, 0)
; template <int TM, int TN>
; DI void gemm_mainloop(const u16* __restrict__ A, long lda, const u16* __restrict__ Bt, long ldb, int K, char* smem,
;                       f32x16 (&acc)[TM][TN]) {
;     ...
;   const int nk = K / 64;
;   const int lrow = tid >> 3, lch = (tid & 7) * 8;
;   const u16* gA = A + (long)lrow * lda + lch;
;   const u16* gB = Bt + (long)lrow * ldb + lch;
;   const int soff = lrow * LD + lch;
;     ...
;   GEMM_GLOAD(0)
;   __syncthreads();
;   GEMM_SSTORE(0)
;   if (nk > 1) GEMM_GLOAD(64)
;   __syncthreads();
;   for (int kt = 0; kt < nk; kt++) {
;     const int buf = kt & 1;
;     const u16* cA = sA + buf * BM * LD + (wm * 32 * TM + r) * LD + h * 8;
;     const u16* cB = sB + buf * BN * LD + (wn * 32 * TN + r) * LD + h * 8;
;     bf16x8 af[TM], bfr[TN];
; #pragma unroll
;     for (int tm = 0; tm < TM; tm++) af[tm] = *(const bf16x8*)(cA + tm * 32 * LD);
; #pragma unroll
;     for (int tn = 0; tn < TN; tn++) bfr[tn] = *(const bf16x8*)(cB + tn * 32 * LD);
;     if (kt + 1 < nk) GEMM_SSTORE(buf ^ 1)
;     __builtin_amdgcn_sched_barrier(0);
;     __builtin_amdgcn_s_setprio(1);
; #pragma unroll
;     for (int tm = 0; tm < TM; tm++)
; #pragma unroll
;       for (int tn = 0; tn < TN; tn++) acc[tm][tn] = MFMA(af[tm], bfr[tn], acc[tm][tn]);
; #pragma unroll
;     for (int tm = 0; tm < TM; tm++) af[tm] = *(const bf16x8*)(cA + tm * 32 * LD + 16);
; #pragma unroll
;     for (int tn = 0; tn < TN; tn++) bfr[tn] = *(const bf16x8*)(cB + tn * 32 * LD + 16);
; #pragma unroll
;     for (int tm = 0; tm < TM; tm++)
; #pragma unroll
;       for (int tn = 0; tn < TN; tn++) acc[tm][tn] = MFMA(af[tm], bfr[tn], acc[tm][tn]);
;     __builtin_amdgcn_sched_group_barrier(0x8, 4, 0);
;     if (kt + 2 < nk) GEMM_GLOAD((kt + 2) * 64)
; #pragma unroll
;     for (int ks = 2; ks < 4; ks++) {
; #pragma unroll
;       for (int tm = 0; tm < TM; tm++) af[tm] = *(const bf16x8*)(cA + tm * 32 * LD + ks * 16);
; #pragma unroll
;       for (int tn = 0; tn < TN; tn++) bfr[tn] = *(const bf16x8*)(cB + tn * 32 * LD + ks * 16);
; #pragma unroll
;       for (int tm = 0; tm < TM; tm++)
; #pragma unroll
;         for (int tn = 0; tn < TN; tn++) acc[tm][tn] = MFMA(af[tm], bfr[tn], acc[tm][tn]);
;     }
;     __builtin_amdgcn_s_setprio(0);
;     __syncthreads();
;   }
.LBB0_1337:
	s_ashr_i32 s4, s24, 31
	s_lshr_b32 s4, s4, 27
	s_add_i32 s4, s24, s4
	s_and_b32 s5, s4, 0xffffffe0
	s_lshl_b32 s4, s4, 2
	s_sub_i32 s26, s24, s5
	s_and_b32 s25, s4, 0xffffff80
	s_lshl_b32 s6, s26, 7
	s_mul_i32 s4, s25, 0x880
	s_mul_hi_i32 s5, s25, 0x880
	s_add_u32 s4, s8, s4
	v_mov_b32_e32 v1, v0
	s_addc_u32 s5, s9, s5
	s_ashr_i32 s7, s6, 31
	v_lshlrev_b32_e32 v2, 3, v1
	v_ashrrev_i32_e32 v68, 3, v1
	v_and_b32_e32 v69, 56, v2
	v_mov_b64_e32 v[2:3], s[4:5]
	v_mad_i64_i32 v[2:3], s[4:5], v68, s15, v[2:3]
	v_lshlrev_b32_e32 v66, 1, v69
	v_lshl_add_u64 v[72:73], v[2:3], 0, v[66:67]
	s_mul_i32 s26, s26, 0x44000
	v_add_co_u32_e32 v70, vcc, s17, v72
	s_mul_hi_i32 s27, s6, 0x880
	s_add_u32 s26, s10, s26
	v_addc_co_u32_e32 v71, vcc, 0, v73, vcc
	s_addc_u32 s27, s11, s27
	v_add_co_u32_e32 v74, vcc, s18, v72
	v_mov_b64_e32 v[2:3], s[26:27]
	s_nop 0
	v_addc_co_u32_e32 v75, vcc, 0, v73, vcc
	v_mad_i64_i32 v[18:19], s[4:5], v68, s15, v[2:3]
	v_add_co_u32_e32 v76, vcc, s19, v72
	v_lshl_add_u64 v[78:79], v[18:19], 0, v[66:67]
	s_nop 0
	v_addc_co_u32_e32 v77, vcc, 0, v73, vcc
	v_add_co_u32_e32 v80, vcc, s17, v78
	global_load_dwordx4 v[2:5], v[72:73], off
	s_nop 0
	v_addc_co_u32_e32 v81, vcc, 0, v79, vcc
	v_add_co_u32_e32 v82, vcc, s18, v78
	global_load_dwordx4 v[6:9], v[70:71], off
	s_nop 0
	v_addc_co_u32_e32 v83, vcc, 0, v79, vcc
	v_add_co_u32_e32 v84, vcc, s19, v78
	global_load_dwordx4 v[10:13], v[74:75], off
	s_nop 0
	v_addc_co_u32_e32 v85, vcc, 0, v79, vcc
	global_load_dwordx4 v[14:17], v[76:77], off
	global_load_dwordx4 v[18:21], v[78:79], off
	global_load_dwordx4 v[22:25], v[80:81], off
	global_load_dwordx4 v[26:29], v[82:83], off
	global_load_dwordx4 v[30:33], v[84:85], off
	s_barrier
	global_load_dwordx4 v[34:37], v[72:73], off offset:128
	global_load_dwordx4 v[38:41], v[70:71], off offset:128
	global_load_dwordx4 v[42:45], v[74:75], off offset:128
	global_load_dwordx4 v[46:49], v[76:77], off offset:128
	global_load_dwordx4 v[50:53], v[78:79], off offset:128
	global_load_dwordx4 v[54:57], v[80:81], off offset:128
	global_load_dwordx4 v[58:61], v[82:83], off offset:128
	global_load_dwordx4 v[62:65], v[84:85], off offset:128
	v_and_b32_e32 v66, 31, v1
	v_lshrrev_b32_e32 v86, 1, v1
	v_mul_lo_u32 v68, v68, s16
	v_and_or_b32 v87, v86, s20, v66
	v_and_b32_e32 v86, 16, v86
	v_and_b32_e32 v1, 0x5f, v1
	v_add_lshl_u32 v66, v68, v69, 1
	v_mad_u64_u32 v[68:69], s[4:5], v87, s21, v[86:87]
	v_mad_u32_u24 v1, v1, s21, v86
	v_add_u32_e32 v69, 0x9000, v66
	s_waitcnt vmcnt(15)
	ds_write_b128 v66, v[2:5]
	s_waitcnt vmcnt(14)
	ds_write_b128 v66, v[6:9] offset:4608
	s_waitcnt vmcnt(13)
	ds_write_b128 v66, v[10:13] offset:9216
	s_waitcnt vmcnt(12)
	ds_write_b128 v66, v[14:17] offset:13824
	s_waitcnt vmcnt(11)
	ds_write_b128 v66, v[18:21] offset:36864
	s_waitcnt vmcnt(10)
	ds_write_b128 v66, v[22:25] offset:41472
	s_waitcnt vmcnt(9)
	ds_write_b128 v66, v[26:29] offset:46080
	s_waitcnt vmcnt(8)
	ds_write_b128 v66, v[30:33] offset:50688
	s_waitcnt lgkmcnt(0)
	s_barrier
	ds_read_b128 v[2:5], v68
	ds_read_b128 v[18:21], v68 offset:4608
	ds_read_b128 v[6:9], v1 offset:36864
	ds_read_b128 v[22:25], v1 offset:41472
	s_waitcnt vmcnt(7)
	ds_write_b128 v66, v[34:37] offset:18432
	s_waitcnt vmcnt(6)
	ds_write_b128 v66, v[38:41] offset:23040
	s_waitcnt vmcnt(5)
	ds_write_b128 v66, v[42:45] offset:27648
	s_waitcnt vmcnt(4)
	ds_write_b128 v66, v[46:49] offset:32256
	s_waitcnt vmcnt(3)
	ds_write_b128 v66, v[50:53] offset:55296
	s_waitcnt vmcnt(2)
	ds_write_b128 v66, v[54:57] offset:59904
	s_waitcnt vmcnt(1)
	ds_write_b128 v66, v[58:61] offset:64512
	s_waitcnt vmcnt(0)
	ds_write_b128 v69, v[62:65] offset:32256
	s_setprio 1
	ds_read_b128 v[86:89], v68 offset:32
	s_waitcnt lgkmcnt(10)
	v_mfma_f32_32x32x16_bf16 v[34:49], v[2:5], v[6:9], 0
	ds_read_b128 v[90:93], v1 offset:36896
	ds_read_b128 v[94:97], v1 offset:41504
	ds_read_b128 v[98:101], v68 offset:4704
	global_load_dwordx4 v[102:105], v[70:71], off offset:256
	global_load_dwordx4 v[106:109], v[74:75], off offset:256
	global_load_dwordx4 v[110:113], v[76:77], off offset:256
	global_load_dwordx4 v[114:117], v[84:85], off offset:256
	s_waitcnt lgkmcnt(12)
	v_mfma_f32_32x32x16_bf16 v[50:65], v[2:5], v[22:25], 0
	global_load_dwordx4 v[118:121], v[82:83], off offset:256
	global_load_dwordx4 v[122:125], v[80:81], off offset:256
	s_waitcnt lgkmcnt(2)
	v_mfma_f32_32x32x16_bf16 v[34:49], v[86:89], v[90:93], v[34:49]
	s_waitcnt lgkmcnt(1)
	v_mfma_f32_32x32x16_bf16 v[50:65], v[86:89], v[94:97], v[50:65]
	ds_read_b128 v[86:89], v68 offset:4640
	v_mfma_f32_32x32x16_bf16 v[2:17], v[18:21], v[6:9], 0
	v_mfma_f32_32x32x16_bf16 v[18:33], v[18:21], v[22:25], 0
	s_waitcnt lgkmcnt(0)
	v_mfma_f32_32x32x16_bf16 v[2:17], v[86:89], v[90:93], v[2:17]
	ds_read_b128 v[90:93], v1 offset:36928
	v_mfma_f32_32x32x16_bf16 v[18:33], v[86:89], v[94:97], v[18:33]
	ds_read_b128 v[86:89], v68 offset:64
	ds_read_b128 v[94:97], v1 offset:41536
	s_waitcnt lgkmcnt(1)
	v_mfma_f32_32x32x16_bf16 v[34:49], v[86:89], v[90:93], v[34:49]
	s_waitcnt lgkmcnt(0)
	v_mfma_f32_32x32x16_bf16 v[50:65], v[86:89], v[94:97], v[50:65]
	ds_read_b128 v[86:89], v68 offset:4672
	s_waitcnt lgkmcnt(0)
	v_mfma_f32_32x32x16_bf16 v[2:17], v[86:89], v[90:93], v[2:17]
	ds_read_b128 v[90:93], v1 offset:36960
	v_mfma_f32_32x32x16_bf16 v[18:33], v[86:89], v[94:97], v[18:33]
	ds_read_b128 v[86:89], v68 offset:96
	ds_read_b128 v[94:97], v1 offset:41568
	s_waitcnt lgkmcnt(1)
	v_mfma_f32_32x32x16_bf16 v[34:49], v[86:89], v[90:93], v[34:49]
	s_waitcnt lgkmcnt(0)
	v_mfma_f32_32x32x16_bf16 v[50:65], v[86:89], v[94:97], v[50:65]
	global_load_dwordx4 v[86:89], v[72:73], off offset:256
	v_mfma_f32_32x32x16_bf16 v[2:17], v[98:101], v[90:93], v[2:17]
	global_load_dwordx4 v[90:93], v[78:79], off offset:256
	v_mfma_f32_32x32x16_bf16 v[18:33], v[98:101], v[94:97], v[18:33]
	s_setprio 0
	s_barrier
; #define MFMA(a, b, c) __builtin_amdgcn_mfma_f32_32x32x16_bf16((a), (b), (c), 0, 0, 0)
; template <int TM, int TN>
; DI void gemm_mainloop(const u16* __restrict__ A, long lda, const u16* __restrict__ Bt, long ldb, int K, char* smem,
;                       f32x16 (&acc)[TM][TN]) {
;     ...
;   for (int kt = 0; kt < nk; kt++) {
;     const int buf = kt & 1;
;     const u16* cA = sA + buf * BM * LD + (wm * 32 * TM + r) * LD + h * 8;
;     const u16* cB = sB + buf * BN * LD + (wn * 32 * TN + r) * LD + h * 8;
;     bf16x8 af[TM], bfr[TN];
; #pragma unroll
;     for (int tm = 0; tm < TM; tm++) af[tm] = *(const bf16x8*)(cA + tm * 32 * LD);
; #pragma unroll
;     for (int tn = 0; tn < TN; tn++) bfr[tn] = *(const bf16x8*)(cB + tn * 32 * LD);
;     if (kt + 1 < nk) GEMM_SSTORE(buf ^ 1)
;     __builtin_amdgcn_sched_barrier(0);
;     __builtin_amdgcn_s_setprio(1);
; #pragma unroll
;     for (int tm = 0; tm < TM; tm++)
; #pragma unroll
;       for (int tn = 0; tn < TN; tn++) acc[tm][tn] = MFMA(af[tm], bfr[tn], acc[tm][tn]);
; #pragma unroll
;     for (int tm = 0; tm < TM; tm++) af[tm] = *(const bf16x8*)(cA + tm * 32 * LD + 16);
; #pragma unroll
;     for (int tn = 0; tn < TN; tn++) bfr[tn] = *(const bf16x8*)(cB + tn * 32 * LD + 16);
; #pragma unroll
;     for (int tm = 0; tm < TM; tm++)
; #pragma unroll
;       for (int tn = 0; tn < TN; tn++) acc[tm][tn] = MFMA(af[tm], bfr[tn], acc[tm][tn]);
;     __builtin_amdgcn_sched_group_barrier(0x8, 4, 0);
;     if (kt + 2 < nk) GEMM_GLOAD((kt + 2) * 64)
; #pragma unroll
;     for (int ks = 2; ks < 4; ks++) {
; #pragma unroll
;       for (int tm = 0; tm < TM; tm++) af[tm] = *(const bf16x8*)(cA + tm * 32 * LD + ks * 16);
; #pragma unroll
;       for (int tn = 0; tn < TN; tn++) bfr[tn] = *(const bf16x8*)(cB + tn * 32 * LD + ks * 16);
; #pragma unroll
;       for (int tm = 0; tm < TM; tm++)
; #pragma unroll
;         for (int tn = 0; tn < TN; tn++) acc[tm][tn] = MFMA(af[tm], bfr[tn], acc[tm][tn]);
;     }
;     __builtin_amdgcn_s_setprio(0);
;     __syncthreads();
;   }
	ds_read_b128 v[94:97], v68 offset:18432
	ds_read_b128 v[98:101], v68 offset:23040
	ds_read_b128 v[126:129], v1 offset:55296
	ds_read_b128 v[130:133], v1 offset:59904
	s_waitcnt vmcnt(1)
	ds_write_b128 v66, v[86:89]
	ds_write_b128 v66, v[102:105] offset:4608
	ds_write_b128 v66, v[106:109] offset:9216
	ds_write_b128 v66, v[110:113] offset:13824
	s_waitcnt vmcnt(0)
	ds_write_b128 v66, v[90:93] offset:36864
	ds_write_b128 v66, v[122:125] offset:41472
	ds_write_b128 v66, v[118:121] offset:46080
	ds_write_b128 v66, v[114:117] offset:50688
	s_setprio 1
	ds_read_b128 v[86:89], v68 offset:18464
	s_waitcnt lgkmcnt(10)
	v_mfma_f32_32x32x16_bf16 v[34:49], v[94:97], v[126:129], v[34:49]
	ds_read_b128 v[90:93], v1 offset:55328
	global_load_dwordx4 v[102:105], v[70:71], off offset:384
	global_load_dwordx4 v[106:109], v[74:75], off offset:384
	global_load_dwordx4 v[110:113], v[76:77], off offset:384
	global_load_dwordx4 v[114:117], v[84:85], off offset:384
	global_load_dwordx4 v[118:121], v[82:83], off offset:384
	global_load_dwordx4 v[122:125], v[80:81], off offset:384
	s_waitcnt lgkmcnt(10)
	v_mfma_f32_32x32x16_bf16 v[50:65], v[94:97], v[130:133], v[50:65]
	ds_read_b128 v[94:97], v1 offset:59936
	s_waitcnt lgkmcnt(1)
	v_mfma_f32_32x32x16_bf16 v[34:49], v[86:89], v[90:93], v[34:49]
	s_waitcnt lgkmcnt(0)
	v_mfma_f32_32x32x16_bf16 v[50:65], v[86:89], v[94:97], v[50:65]
	ds_read_b128 v[86:89], v68 offset:23072
	v_mfma_f32_32x32x16_bf16 v[2:17], v[98:101], v[126:129], v[2:17]
	v_mfma_f32_32x32x16_bf16 v[18:33], v[98:101], v[130:133], v[18:33]
	ds_read_b128 v[98:101], v68 offset:23136
	s_waitcnt lgkmcnt(1)
	v_mfma_f32_32x32x16_bf16 v[2:17], v[86:89], v[90:93], v[2:17]
	ds_read_b128 v[90:93], v1 offset:55360
	v_mfma_f32_32x32x16_bf16 v[18:33], v[86:89], v[94:97], v[18:33]
	ds_read_b128 v[86:89], v68 offset:18496
	ds_read_b128 v[94:97], v1 offset:59968
	s_waitcnt lgkmcnt(1)
	v_mfma_f32_32x32x16_bf16 v[34:49], v[86:89], v[90:93], v[34:49]
	s_waitcnt lgkmcnt(0)
	v_mfma_f32_32x32x16_bf16 v[50:65], v[86:89], v[94:97], v[50:65]
	ds_read_b128 v[86:89], v68 offset:23104
	s_waitcnt lgkmcnt(0)
	v_mfma_f32_32x32x16_bf16 v[2:17], v[86:89], v[90:93], v[2:17]
	ds_read_b128 v[90:93], v1 offset:55392
	v_mfma_f32_32x32x16_bf16 v[18:33], v[86:89], v[94:97], v[18:33]
	ds_read_b128 v[86:89], v68 offset:18528
	ds_read_b128 v[94:97], v1 offset:60000
	s_waitcnt lgkmcnt(1)
	v_mfma_f32_32x32x16_bf16 v[34:49], v[86:89], v[90:93], v[34:49]
	s_waitcnt lgkmcnt(0)
	v_mfma_f32_32x32x16_bf16 v[50:65], v[86:89], v[94:97], v[50:65]
	global_load_dwordx4 v[86:89], v[72:73], off offset:384
	v_mfma_f32_32x32x16_bf16 v[2:17], v[98:101], v[90:93], v[2:17]
	global_load_dwordx4 v[90:93], v[78:79], off offset:384
	v_mfma_f32_32x32x16_bf16 v[18:33], v[98:101], v[94:97], v[18:33]
	s_setprio 0
	s_barrier
	ds_read_b128 v[94:97], v68
	ds_read_b128 v[98:101], v68 offset:4608
	ds_read_b128 v[126:129], v1 offset:36864
	ds_read_b128 v[130:133], v1 offset:41472
	s_waitcnt vmcnt(1)
	ds_write_b128 v66, v[86:89] offset:18432
	ds_write_b128 v66, v[102:105] offset:23040
	ds_write_b128 v66, v[106:109] offset:27648
	ds_write_b128 v66, v[110:113] offset:32256
	s_waitcnt vmcnt(0)
	ds_write_b128 v66, v[90:93] offset:55296
	ds_write_b128 v66, v[122:125] offset:59904
	ds_write_b128 v66, v[118:121] offset:64512
	ds_write_b128 v69, v[114:117] offset:32256
	s_setprio 1
	ds_read_b128 v[86:89], v68 offset:32
	s_waitcnt lgkmcnt(10)
	v_mfma_f32_32x32x16_bf16 v[34:49], v[94:97], v[126:129], v[34:49]
	ds_read_b128 v[90:93], v1 offset:36896
	global_load_dwordx4 v[102:105], v[70:71], off offset:512
	global_load_dwordx4 v[106:109], v[74:75], off offset:512
	global_load_dwordx4 v[110:113], v[76:77], off offset:512
	global_load_dwordx4 v[114:117], v[84:85], off offset:512
	global_load_dwordx4 v[118:121], v[82:83], off offset:512
	global_load_dwordx4 v[122:125], v[80:81], off offset:512
	s_waitcnt lgkmcnt(10)
	v_mfma_f32_32x32x16_bf16 v[50:65], v[94:97], v[130:133], v[50:65]
	ds_read_b128 v[94:97], v1 offset:41504
	s_waitcnt lgkmcnt(1)
	v_mfma_f32_32x32x16_bf16 v[34:49], v[86:89], v[90:93], v[34:49]
	s_waitcnt lgkmcnt(0)
	v_mfma_f32_32x32x16_bf16 v[50:65], v[86:89], v[94:97], v[50:65]
	ds_read_b128 v[86:89], v68 offset:4640
	v_mfma_f32_32x32x16_bf16 v[2:17], v[98:101], v[126:129], v[2:17]
	v_mfma_f32_32x32x16_bf16 v[18:33], v[98:101], v[130:133], v[18:33]
	ds_read_b128 v[98:101], v68 offset:4704
	s_waitcnt lgkmcnt(1)
	v_mfma_f32_32x32x16_bf16 v[2:17], v[86:89], v[90:93], v[2:17]
	ds_read_b128 v[90:93], v1 offset:36928
	v_mfma_f32_32x32x16_bf16 v[18:33], v[86:89], v[94:97], v[18:33]
	ds_read_b128 v[86:89], v68 offset:64
	ds_read_b128 v[94:97], v1 offset:41536
	s_waitcnt lgkmcnt(1)
	v_mfma_f32_32x32x16_bf16 v[34:49], v[86:89], v[90:93], v[34:49]
	s_waitcnt lgkmcnt(0)
	v_mfma_f32_32x32x16_bf16 v[50:65], v[86:89], v[94:97], v[50:65]
	ds_read_b128 v[86:89], v68 offset:4672
	s_waitcnt lgkmcnt(0)
	v_mfma_f32_32x32x16_bf16 v[2:17], v[86:89], v[90:93], v[2:17]
	ds_read_b128 v[90:93], v1 offset:36960
	v_mfma_f32_32x32x16_bf16 v[18:33], v[86:89], v[94:97], v[18:33]
	ds_read_b128 v[86:89], v68 offset:96
	ds_read_b128 v[94:97], v1 offset:41568
	s_waitcnt lgkmcnt(1)
	v_mfma_f32_32x32x16_bf16 v[34:49], v[86:89], v[90:93], v[34:49]
	s_waitcnt lgkmcnt(0)
	v_mfma_f32_32x32x16_bf16 v[50:65], v[86:89], v[94:97], v[50:65]
	global_load_dwordx4 v[86:89], v[72:73], off offset:512
	v_mfma_f32_32x32x16_bf16 v[2:17], v[98:101], v[90:93], v[2:17]
	global_load_dwordx4 v[90:93], v[78:79], off offset:512
	v_mfma_f32_32x32x16_bf16 v[18:33], v[98:101], v[94:97], v[18:33]
	s_setprio 0
	s_barrier
; #define MFMA(a, b, c) __builtin_amdgcn_mfma_f32_32x32x16_bf16((a), (b), (c), 0, 0, 0)
; template <int TM, int TN>
; DI void gemm_mainloop(const u16* __restrict__ A, long lda, const u16* __restrict__ Bt, long ldb, int K, char* smem,
;                       f32x16 (&acc)[TM][TN]) {
;     ...
;   for (int kt = 0; kt < nk; kt++) {
;     const int buf = kt & 1;
;     const u16* cA = sA + buf * BM * LD + (wm * 32 * TM + r) * LD + h * 8;
;     const u16* cB = sB + buf * BN * LD + (wn * 32 * TN + r) * LD + h * 8;
;     bf16x8 af[TM], bfr[TN];
; #pragma unroll
;     for (int tm = 0; tm < TM; tm++) af[tm] = *(const bf16x8*)(cA + tm * 32 * LD);
; #pragma unroll
;     for (int tn = 0; tn < TN; tn++) bfr[tn] = *(const bf16x8*)(cB + tn * 32 * LD);
;     if (kt + 1 < nk) GEMM_SSTORE(buf ^ 1)
;     __builtin_amdgcn_sched_barrier(0);
;     __builtin_amdgcn_s_setprio(1);
; #pragma unroll
;     for (int tm = 0; tm < TM; tm++)
; #pragma unroll
;       for (int tn = 0; tn < TN; tn++) acc[tm][tn] = MFMA(af[tm], bfr[tn], acc[tm][tn]);
; #pragma unroll
;     for (int tm = 0; tm < TM; tm++) af[tm] = *(const bf16x8*)(cA + tm * 32 * LD + 16);
; #pragma unroll
;     for (int tn = 0; tn < TN; tn++) bfr[tn] = *(const bf16x8*)(cB + tn * 32 * LD + 16);
; #pragma unroll
;     for (int tm = 0; tm < TM; tm++)
; #pragma unroll
;       for (int tn = 0; tn < TN; tn++) acc[tm][tn] = MFMA(af[tm], bfr[tn], acc[tm][tn]);
;     __builtin_amdgcn_sched_group_barrier(0x8, 4, 0);
;     if (kt + 2 < nk) GEMM_GLOAD((kt + 2) * 64)
; #pragma unroll
;     for (int ks = 2; ks < 4; ks++) {
; #pragma unroll
;       for (int tm = 0; tm < TM; tm++) af[tm] = *(const bf16x8*)(cA + tm * 32 * LD + ks * 16);
; #pragma unroll
;       for (int tn = 0; tn < TN; tn++) bfr[tn] = *(const bf16x8*)(cB + tn * 32 * LD + ks * 16);
; #pragma unroll
;       for (int tm = 0; tm < TM; tm++)
; #pragma unroll
;         for (int tn = 0; tn < TN; tn++) acc[tm][tn] = MFMA(af[tm], bfr[tn], acc[tm][tn]);
;     }
;     __builtin_amdgcn_s_setprio(0);
;     __syncthreads();
;   }
	ds_read_b128 v[94:97], v68 offset:18432
	ds_read_b128 v[98:101], v68 offset:23040
	ds_read_b128 v[126:129], v1 offset:55296
	ds_read_b128 v[130:133], v1 offset:59904
	s_waitcnt vmcnt(1)
	ds_write_b128 v66, v[86:89]
	ds_write_b128 v66, v[102:105] offset:4608
	ds_write_b128 v66, v[106:109] offset:9216
	ds_write_b128 v66, v[110:113] offset:13824
	s_waitcnt vmcnt(0)
	ds_write_b128 v66, v[90:93] offset:36864
	ds_write_b128 v66, v[122:125] offset:41472
	ds_write_b128 v66, v[118:121] offset:46080
	ds_write_b128 v66, v[114:117] offset:50688
	s_setprio 1
	ds_read_b128 v[86:89], v68 offset:18464
	s_waitcnt lgkmcnt(10)
	v_mfma_f32_32x32x16_bf16 v[34:49], v[94:97], v[126:129], v[34:49]
	ds_read_b128 v[90:93], v1 offset:55328
	global_load_dwordx4 v[102:105], v[70:71], off offset:640
	global_load_dwordx4 v[106:109], v[74:75], off offset:640
	global_load_dwordx4 v[110:113], v[76:77], off offset:640
	global_load_dwordx4 v[114:117], v[84:85], off offset:640
	global_load_dwordx4 v[118:121], v[82:83], off offset:640
	global_load_dwordx4 v[122:125], v[80:81], off offset:640
	s_waitcnt lgkmcnt(10)
	v_mfma_f32_32x32x16_bf16 v[50:65], v[94:97], v[130:133], v[50:65]
	ds_read_b128 v[94:97], v1 offset:59936
	s_waitcnt lgkmcnt(1)
	v_mfma_f32_32x32x16_bf16 v[34:49], v[86:89], v[90:93], v[34:49]
	s_waitcnt lgkmcnt(0)
	v_mfma_f32_32x32x16_bf16 v[50:65], v[86:89], v[94:97], v[50:65]
	ds_read_b128 v[86:89], v68 offset:23072
	v_mfma_f32_32x32x16_bf16 v[2:17], v[98:101], v[126:129], v[2:17]
	v_mfma_f32_32x32x16_bf16 v[18:33], v[98:101], v[130:133], v[18:33]
	ds_read_b128 v[98:101], v68 offset:23136
	s_waitcnt lgkmcnt(1)
	v_mfma_f32_32x32x16_bf16 v[2:17], v[86:89], v[90:93], v[2:17]
	ds_read_b128 v[90:93], v1 offset:55360
	v_mfma_f32_32x32x16_bf16 v[18:33], v[86:89], v[94:97], v[18:33]
	ds_read_b128 v[86:89], v68 offset:18496
	ds_read_b128 v[94:97], v1 offset:59968
	s_waitcnt lgkmcnt(1)
	v_mfma_f32_32x32x16_bf16 v[34:49], v[86:89], v[90:93], v[34:49]
	s_waitcnt lgkmcnt(0)
	v_mfma_f32_32x32x16_bf16 v[50:65], v[86:89], v[94:97], v[50:65]
	ds_read_b128 v[86:89], v68 offset:23104
	s_waitcnt lgkmcnt(0)
	v_mfma_f32_32x32x16_bf16 v[2:17], v[86:89], v[90:93], v[2:17]
	ds_read_b128 v[90:93], v1 offset:55392
	v_mfma_f32_32x32x16_bf16 v[18:33], v[86:89], v[94:97], v[18:33]
	ds_read_b128 v[86:89], v68 offset:18528
	ds_read_b128 v[94:97], v1 offset:60000
	s_waitcnt lgkmcnt(1)
	v_mfma_f32_32x32x16_bf16 v[34:49], v[86:89], v[90:93], v[34:49]
	s_waitcnt lgkmcnt(0)
	v_mfma_f32_32x32x16_bf16 v[50:65], v[86:89], v[94:97], v[50:65]
	global_load_dwordx4 v[86:89], v[72:73], off offset:640
	v_mfma_f32_32x32x16_bf16 v[2:17], v[98:101], v[90:93], v[2:17]
	global_load_dwordx4 v[90:93], v[78:79], off offset:640
	v_mfma_f32_32x32x16_bf16 v[18:33], v[98:101], v[94:97], v[18:33]
	s_setprio 0
	s_barrier
	ds_read_b128 v[94:97], v68
	ds_read_b128 v[98:101], v68 offset:4608
	ds_read_b128 v[126:129], v1 offset:36864
	ds_read_b128 v[130:133], v1 offset:41472
	s_waitcnt vmcnt(1)
	ds_write_b128 v66, v[86:89] offset:18432
	ds_write_b128 v66, v[102:105] offset:23040
	ds_write_b128 v66, v[106:109] offset:27648
	ds_write_b128 v66, v[110:113] offset:32256
	s_waitcnt vmcnt(0)
	ds_write_b128 v66, v[90:93] offset:55296
	ds_write_b128 v66, v[122:125] offset:59904
	ds_write_b128 v66, v[118:121] offset:64512
	ds_write_b128 v69, v[114:117] offset:32256
	s_setprio 1
	ds_read_b128 v[86:89], v68 offset:32
	s_waitcnt lgkmcnt(10)
	v_mfma_f32_32x32x16_bf16 v[34:49], v[94:97], v[126:129], v[34:49]
	ds_read_b128 v[90:93], v1 offset:36896
	global_load_dwordx4 v[102:105], v[70:71], off offset:768
	global_load_dwordx4 v[106:109], v[74:75], off offset:768
	global_load_dwordx4 v[110:113], v[76:77], off offset:768
	global_load_dwordx4 v[114:117], v[84:85], off offset:768
	global_load_dwordx4 v[118:121], v[82:83], off offset:768
	global_load_dwordx4 v[122:125], v[80:81], off offset:768
	s_waitcnt lgkmcnt(10)
	v_mfma_f32_32x32x16_bf16 v[50:65], v[94:97], v[130:133], v[50:65]
	ds_read_b128 v[94:97], v1 offset:41504
	s_waitcnt lgkmcnt(1)
	v_mfma_f32_32x32x16_bf16 v[34:49], v[86:89], v[90:93], v[34:49]
	s_waitcnt lgkmcnt(0)
	v_mfma_f32_32x32x16_bf16 v[50:65], v[86:89], v[94:97], v[50:65]
	ds_read_b128 v[86:89], v68 offset:4640
	v_mfma_f32_32x32x16_bf16 v[2:17], v[98:101], v[126:129], v[2:17]
	v_mfma_f32_32x32x16_bf16 v[18:33], v[98:101], v[130:133], v[18:33]
	ds_read_b128 v[98:101], v68 offset:4704
	s_waitcnt lgkmcnt(1)
	v_mfma_f32_32x32x16_bf16 v[2:17], v[86:89], v[90:93], v[2:17]
	ds_read_b128 v[90:93], v1 offset:36928
	v_mfma_f32_32x32x16_bf16 v[18:33], v[86:89], v[94:97], v[18:33]
	ds_read_b128 v[86:89], v68 offset:64
	ds_read_b128 v[94:97], v1 offset:41536
	s_waitcnt lgkmcnt(1)
	v_mfma_f32_32x32x16_bf16 v[34:49], v[86:89], v[90:93], v[34:49]
	s_waitcnt lgkmcnt(0)
	v_mfma_f32_32x32x16_bf16 v[50:65], v[86:89], v[94:97], v[50:65]
	ds_read_b128 v[86:89], v68 offset:4672
	s_waitcnt lgkmcnt(0)
	v_mfma_f32_32x32x16_bf16 v[2:17], v[86:89], v[90:93], v[2:17]
	ds_read_b128 v[90:93], v1 offset:36960
	v_mfma_f32_32x32x16_bf16 v[18:33], v[86:89], v[94:97], v[18:33]
	ds_read_b128 v[86:89], v68 offset:96
	ds_read_b128 v[94:97], v1 offset:41568
	s_waitcnt lgkmcnt(1)
	v_mfma_f32_32x32x16_bf16 v[34:49], v[86:89], v[90:93], v[34:49]
	s_waitcnt lgkmcnt(0)
	v_mfma_f32_32x32x16_bf16 v[50:65], v[86:89], v[94:97], v[50:65]
	global_load_dwordx4 v[86:89], v[72:73], off offset:768
	v_mfma_f32_32x32x16_bf16 v[2:17], v[98:101], v[90:93], v[2:17]
	global_load_dwordx4 v[90:93], v[78:79], off offset:768
	v_mfma_f32_32x32x16_bf16 v[18:33], v[98:101], v[94:97], v[18:33]
	s_setprio 0
	s_barrier
; #define MFMA(a, b, c) __builtin_amdgcn_mfma_f32_32x32x16_bf16((a), (b), (c), 0, 0, 0)
; template <int TM, int TN>
; DI void gemm_mainloop(const u16* __restrict__ A, long lda, const u16* __restrict__ Bt, long ldb, int K, char* smem,
;                       f32x16 (&acc)[TM][TN]) {
;     ...
;   for (int kt = 0; kt < nk; kt++) {
;     const int buf = kt & 1;
;     const u16* cA = sA + buf * BM * LD + (wm * 32 * TM + r) * LD + h * 8;
;     const u16* cB = sB + buf * BN * LD + (wn * 32 * TN + r) * LD + h * 8;
;     bf16x8 af[TM], bfr[TN];
; #pragma unroll
;     for (int tm = 0; tm < TM; tm++) af[tm] = *(const bf16x8*)(cA + tm * 32 * LD);
; #pragma unroll
;     for (int tn = 0; tn < TN; tn++) bfr[tn] = *(const bf16x8*)(cB + tn * 32 * LD);
;     if (kt + 1 < nk) GEMM_SSTORE(buf ^ 1)
;     __builtin_amdgcn_sched_barrier(0);
;     __builtin_amdgcn_s_setprio(1);
; #pragma unroll
;     for (int tm = 0; tm < TM; tm++)
; #pragma unroll
;       for (int tn = 0; tn < TN; tn++) acc[tm][tn] = MFMA(af[tm], bfr[tn], acc[tm][tn]);
; #pragma unroll
;     for (int tm = 0; tm < TM; tm++) af[tm] = *(const bf16x8*)(cA + tm * 32 * LD + 16);
; #pragma unroll
;     for (int tn = 0; tn < TN; tn++) bfr[tn] = *(const bf16x8*)(cB + tn * 32 * LD + 16);
; #pragma unroll
;     for (int tm = 0; tm < TM; tm++)
; #pragma unroll
;       for (int tn = 0; tn < TN; tn++) acc[tm][tn] = MFMA(af[tm], bfr[tn], acc[tm][tn]);
;     __builtin_amdgcn_sched_group_barrier(0x8, 4, 0);
;     if (kt + 2 < nk) GEMM_GLOAD((kt + 2) * 64)
; #pragma unroll
;     for (int ks = 2; ks < 4; ks++) {
; #pragma unroll
;       for (int tm = 0; tm < TM; tm++) af[tm] = *(const bf16x8*)(cA + tm * 32 * LD + ks * 16);
; #pragma unroll
;       for (int tn = 0; tn < TN; tn++) bfr[tn] = *(const bf16x8*)(cB + tn * 32 * LD + ks * 16);
; #pragma unroll
;       for (int tm = 0; tm < TM; tm++)
; #pragma unroll
;         for (int tn = 0; tn < TN; tn++) acc[tm][tn] = MFMA(af[tm], bfr[tn], acc[tm][tn]);
;     }
;     __builtin_amdgcn_s_setprio(0);
;     __syncthreads();
;   }
	ds_read_b128 v[94:97], v68 offset:18432
	ds_read_b128 v[98:101], v68 offset:23040
	ds_read_b128 v[126:129], v1 offset:55296
	ds_read_b128 v[130:133], v1 offset:59904
	s_waitcnt vmcnt(1)
	ds_write_b128 v66, v[86:89]
	ds_write_b128 v66, v[102:105] offset:4608
	ds_write_b128 v66, v[106:109] offset:9216
	ds_write_b128 v66, v[110:113] offset:13824
	s_waitcnt vmcnt(0)
	ds_write_b128 v66, v[90:93] offset:36864
	ds_write_b128 v66, v[122:125] offset:41472
	ds_write_b128 v66, v[118:121] offset:46080
	ds_write_b128 v66, v[114:117] offset:50688
	s_setprio 1
	ds_read_b128 v[86:89], v68 offset:18464
	s_waitcnt lgkmcnt(10)
	v_mfma_f32_32x32x16_bf16 v[34:49], v[94:97], v[126:129], v[34:49]
	ds_read_b128 v[90:93], v1 offset:55328
	global_load_dwordx4 v[102:105], v[70:71], off offset:896
	global_load_dwordx4 v[106:109], v[74:75], off offset:896
	global_load_dwordx4 v[110:113], v[76:77], off offset:896
	global_load_dwordx4 v[114:117], v[84:85], off offset:896
	global_load_dwordx4 v[118:121], v[82:83], off offset:896
	global_load_dwordx4 v[122:125], v[80:81], off offset:896
	s_waitcnt lgkmcnt(10)
	v_mfma_f32_32x32x16_bf16 v[50:65], v[94:97], v[130:133], v[50:65]
	ds_read_b128 v[94:97], v1 offset:59936
	s_waitcnt lgkmcnt(1)
	v_mfma_f32_32x32x16_bf16 v[34:49], v[86:89], v[90:93], v[34:49]
	s_waitcnt lgkmcnt(0)
	v_mfma_f32_32x32x16_bf16 v[50:65], v[86:89], v[94:97], v[50:65]
	ds_read_b128 v[86:89], v68 offset:23072
	v_mfma_f32_32x32x16_bf16 v[2:17], v[98:101], v[126:129], v[2:17]
	v_mfma_f32_32x32x16_bf16 v[18:33], v[98:101], v[130:133], v[18:33]
	ds_read_b128 v[98:101], v68 offset:23136
	s_waitcnt lgkmcnt(1)
	v_mfma_f32_32x32x16_bf16 v[2:17], v[86:89], v[90:93], v[2:17]
	ds_read_b128 v[90:93], v1 offset:55360
	v_mfma_f32_32x32x16_bf16 v[18:33], v[86:89], v[94:97], v[18:33]
	ds_read_b128 v[86:89], v68 offset:18496
	ds_read_b128 v[94:97], v1 offset:59968
	s_waitcnt lgkmcnt(1)
	v_mfma_f32_32x32x16_bf16 v[34:49], v[86:89], v[90:93], v[34:49]
	s_waitcnt lgkmcnt(0)
	v_mfma_f32_32x32x16_bf16 v[50:65], v[86:89], v[94:97], v[50:65]
	ds_read_b128 v[86:89], v68 offset:23104
	s_waitcnt lgkmcnt(0)
	v_mfma_f32_32x32x16_bf16 v[2:17], v[86:89], v[90:93], v[2:17]
	ds_read_b128 v[90:93], v1 offset:55392
	v_mfma_f32_32x32x16_bf16 v[18:33], v[86:89], v[94:97], v[18:33]
	ds_read_b128 v[86:89], v68 offset:18528
	ds_read_b128 v[94:97], v1 offset:60000
	s_waitcnt lgkmcnt(1)
	v_mfma_f32_32x32x16_bf16 v[34:49], v[86:89], v[90:93], v[34:49]
	s_waitcnt lgkmcnt(0)
	v_mfma_f32_32x32x16_bf16 v[50:65], v[86:89], v[94:97], v[50:65]
	global_load_dwordx4 v[86:89], v[72:73], off offset:896
	v_mfma_f32_32x32x16_bf16 v[2:17], v[98:101], v[90:93], v[2:17]
	global_load_dwordx4 v[90:93], v[78:79], off offset:896
	v_mfma_f32_32x32x16_bf16 v[18:33], v[98:101], v[94:97], v[18:33]
	s_setprio 0
	s_barrier
	ds_read_b128 v[94:97], v68
	ds_read_b128 v[98:101], v68 offset:4608
	ds_read_b128 v[126:129], v1 offset:36864
	ds_read_b128 v[130:133], v1 offset:41472
	s_waitcnt vmcnt(1)
	ds_write_b128 v66, v[86:89] offset:18432
	ds_write_b128 v66, v[102:105] offset:23040
	ds_write_b128 v66, v[106:109] offset:27648
	ds_write_b128 v66, v[110:113] offset:32256
	s_waitcnt vmcnt(0)
	ds_write_b128 v66, v[90:93] offset:55296
	ds_write_b128 v66, v[122:125] offset:59904
	ds_write_b128 v66, v[118:121] offset:64512
	ds_write_b128 v69, v[114:117] offset:32256
	s_setprio 1
	ds_read_b128 v[86:89], v68 offset:32
	s_waitcnt lgkmcnt(10)
	v_mfma_f32_32x32x16_bf16 v[34:49], v[94:97], v[126:129], v[34:49]
	ds_read_b128 v[90:93], v1 offset:36896
	global_load_dwordx4 v[102:105], v[70:71], off offset:1024
	global_load_dwordx4 v[106:109], v[74:75], off offset:1024
	global_load_dwordx4 v[110:113], v[76:77], off offset:1024
	global_load_dwordx4 v[114:117], v[84:85], off offset:1024
	global_load_dwordx4 v[118:121], v[82:83], off offset:1024
	global_load_dwordx4 v[122:125], v[80:81], off offset:1024
	s_waitcnt lgkmcnt(10)
	v_mfma_f32_32x32x16_bf16 v[50:65], v[94:97], v[130:133], v[50:65]
	ds_read_b128 v[94:97], v1 offset:41504
	s_waitcnt lgkmcnt(1)
	v_mfma_f32_32x32x16_bf16 v[34:49], v[86:89], v[90:93], v[34:49]
	s_waitcnt lgkmcnt(0)
	v_mfma_f32_32x32x16_bf16 v[50:65], v[86:89], v[94:97], v[50:65]
	ds_read_b128 v[86:89], v68 offset:4640
	v_mfma_f32_32x32x16_bf16 v[2:17], v[98:101], v[126:129], v[2:17]
	v_mfma_f32_32x32x16_bf16 v[18:33], v[98:101], v[130:133], v[18:33]
	ds_read_b128 v[98:101], v68 offset:4704
	s_waitcnt lgkmcnt(1)
	v_mfma_f32_32x32x16_bf16 v[2:17], v[86:89], v[90:93], v[2:17]
	ds_read_b128 v[90:93], v1 offset:36928
	v_mfma_f32_32x32x16_bf16 v[18:33], v[86:89], v[94:97], v[18:33]
	ds_read_b128 v[86:89], v68 offset:64
	ds_read_b128 v[94:97], v1 offset:41536
	s_waitcnt lgkmcnt(1)
	v_mfma_f32_32x32x16_bf16 v[34:49], v[86:89], v[90:93], v[34:49]
	s_waitcnt lgkmcnt(0)
	v_mfma_f32_32x32x16_bf16 v[50:65], v[86:89], v[94:97], v[50:65]
	ds_read_b128 v[86:89], v68 offset:4672
	s_waitcnt lgkmcnt(0)
	v_mfma_f32_32x32x16_bf16 v[2:17], v[86:89], v[90:93], v[2:17]
	ds_read_b128 v[90:93], v1 offset:36960
	v_mfma_f32_32x32x16_bf16 v[18:33], v[86:89], v[94:97], v[18:33]
	ds_read_b128 v[86:89], v68 offset:96
	ds_read_b128 v[94:97], v1 offset:41568
	s_waitcnt lgkmcnt(1)
	v_mfma_f32_32x32x16_bf16 v[34:49], v[86:89], v[90:93], v[34:49]
	s_waitcnt lgkmcnt(0)
	v_mfma_f32_32x32x16_bf16 v[50:65], v[86:89], v[94:97], v[50:65]
	global_load_dwordx4 v[86:89], v[72:73], off offset:1024
	v_mfma_f32_32x32x16_bf16 v[2:17], v[98:101], v[90:93], v[2:17]
	global_load_dwordx4 v[90:93], v[78:79], off offset:1024
	v_mfma_f32_32x32x16_bf16 v[18:33], v[98:101], v[94:97], v[18:33]
	s_setprio 0
	s_barrier
; #define MFMA(a, b, c) __builtin_amdgcn_mfma_f32_32x32x16_bf16((a), (b), (c), 0, 0, 0)
; template <int TM, int TN>
; DI void gemm_mainloop(const u16* __restrict__ A, long lda, const u16* __restrict__ Bt, long ldb, int K, char* smem,
;                       f32x16 (&acc)[TM][TN]) {
;     ...
;   for (int kt = 0; kt < nk; kt++) {
;     const int buf = kt & 1;
;     const u16* cA = sA + buf * BM * LD + (wm * 32 * TM + r) * LD + h * 8;
;     const u16* cB = sB + buf * BN * LD + (wn * 32 * TN + r) * LD + h * 8;
;     bf16x8 af[TM], bfr[TN];
; #pragma unroll
;     for (int tm = 0; tm < TM; tm++) af[tm] = *(const bf16x8*)(cA + tm * 32 * LD);
; #pragma unroll
;     for (int tn = 0; tn < TN; tn++) bfr[tn] = *(const bf16x8*)(cB + tn * 32 * LD);
;     if (kt + 1 < nk) GEMM_SSTORE(buf ^ 1)
;     __builtin_amdgcn_sched_barrier(0);
;     __builtin_amdgcn_s_setprio(1);
; #pragma unroll
;     for (int tm = 0; tm < TM; tm++)
; #pragma unroll
;       for (int tn = 0; tn < TN; tn++) acc[tm][tn] = MFMA(af[tm], bfr[tn], acc[tm][tn]);
; #pragma unroll
;     for (int tm = 0; tm < TM; tm++) af[tm] = *(const bf16x8*)(cA + tm * 32 * LD + 16);
; #pragma unroll
;     for (int tn = 0; tn < TN; tn++) bfr[tn] = *(const bf16x8*)(cB + tn * 32 * LD + 16);
; #pragma unroll
;     for (int tm = 0; tm < TM; tm++)
; #pragma unroll
;       for (int tn = 0; tn < TN; tn++) acc[tm][tn] = MFMA(af[tm], bfr[tn], acc[tm][tn]);
;     __builtin_amdgcn_sched_group_barrier(0x8, 4, 0);
;     if (kt + 2 < nk) GEMM_GLOAD((kt + 2) * 64)
; #pragma unroll
;     for (int ks = 2; ks < 4; ks++) {
; #pragma unroll
;       for (int tm = 0; tm < TM; tm++) af[tm] = *(const bf16x8*)(cA + tm * 32 * LD + ks * 16);
; #pragma unroll
;       for (int tn = 0; tn < TN; tn++) bfr[tn] = *(const bf16x8*)(cB + tn * 32 * LD + ks * 16);
; #pragma unroll
;       for (int tm = 0; tm < TM; tm++)
; #pragma unroll
;         for (int tn = 0; tn < TN; tn++) acc[tm][tn] = MFMA(af[tm], bfr[tn], acc[tm][tn]);
;     }
;     __builtin_amdgcn_s_setprio(0);
;     __syncthreads();
;   }
	ds_read_b128 v[94:97], v68 offset:18432
	ds_read_b128 v[98:101], v68 offset:23040
	ds_read_b128 v[126:129], v1 offset:55296
	ds_read_b128 v[130:133], v1 offset:59904
	s_waitcnt vmcnt(1)
	ds_write_b128 v66, v[86:89]
	ds_write_b128 v66, v[102:105] offset:4608
	ds_write_b128 v66, v[106:109] offset:9216
	ds_write_b128 v66, v[110:113] offset:13824
	s_waitcnt vmcnt(0)
	ds_write_b128 v66, v[90:93] offset:36864
	ds_write_b128 v66, v[122:125] offset:41472
	ds_write_b128 v66, v[118:121] offset:46080
	ds_write_b128 v66, v[114:117] offset:50688
	s_setprio 1
	ds_read_b128 v[86:89], v68 offset:18464
	s_waitcnt lgkmcnt(10)
	v_mfma_f32_32x32x16_bf16 v[34:49], v[94:97], v[126:129], v[34:49]
	ds_read_b128 v[90:93], v1 offset:55328
	global_load_dwordx4 v[102:105], v[70:71], off offset:1152
	global_load_dwordx4 v[106:109], v[74:75], off offset:1152
	global_load_dwordx4 v[110:113], v[76:77], off offset:1152
	global_load_dwordx4 v[114:117], v[84:85], off offset:1152
	global_load_dwordx4 v[118:121], v[82:83], off offset:1152
	global_load_dwordx4 v[122:125], v[80:81], off offset:1152
	s_waitcnt lgkmcnt(10)
	v_mfma_f32_32x32x16_bf16 v[50:65], v[94:97], v[130:133], v[50:65]
	ds_read_b128 v[94:97], v1 offset:59936
	s_waitcnt lgkmcnt(1)
	v_mfma_f32_32x32x16_bf16 v[34:49], v[86:89], v[90:93], v[34:49]
	s_waitcnt lgkmcnt(0)
	v_mfma_f32_32x32x16_bf16 v[50:65], v[86:89], v[94:97], v[50:65]
	ds_read_b128 v[86:89], v68 offset:23072
	v_mfma_f32_32x32x16_bf16 v[2:17], v[98:101], v[126:129], v[2:17]
	v_mfma_f32_32x32x16_bf16 v[18:33], v[98:101], v[130:133], v[18:33]
	ds_read_b128 v[98:101], v68 offset:23136
	s_waitcnt lgkmcnt(1)
	v_mfma_f32_32x32x16_bf16 v[2:17], v[86:89], v[90:93], v[2:17]
	ds_read_b128 v[90:93], v1 offset:55360
	v_mfma_f32_32x32x16_bf16 v[18:33], v[86:89], v[94:97], v[18:33]
	ds_read_b128 v[86:89], v68 offset:18496
	ds_read_b128 v[94:97], v1 offset:59968
	s_waitcnt lgkmcnt(1)
	v_mfma_f32_32x32x16_bf16 v[34:49], v[86:89], v[90:93], v[34:49]
	s_waitcnt lgkmcnt(0)
	v_mfma_f32_32x32x16_bf16 v[50:65], v[86:89], v[94:97], v[50:65]
	ds_read_b128 v[86:89], v68 offset:23104
	s_waitcnt lgkmcnt(0)
	v_mfma_f32_32x32x16_bf16 v[2:17], v[86:89], v[90:93], v[2:17]
	ds_read_b128 v[90:93], v1 offset:55392
	v_mfma_f32_32x32x16_bf16 v[18:33], v[86:89], v[94:97], v[18:33]
	ds_read_b128 v[86:89], v68 offset:18528
	ds_read_b128 v[94:97], v1 offset:60000
	s_waitcnt lgkmcnt(1)
	v_mfma_f32_32x32x16_bf16 v[34:49], v[86:89], v[90:93], v[34:49]
	s_waitcnt lgkmcnt(0)
	v_mfma_f32_32x32x16_bf16 v[50:65], v[86:89], v[94:97], v[50:65]
	global_load_dwordx4 v[86:89], v[72:73], off offset:1152
	v_mfma_f32_32x32x16_bf16 v[2:17], v[98:101], v[90:93], v[2:17]
	global_load_dwordx4 v[90:93], v[78:79], off offset:1152
	v_mfma_f32_32x32x16_bf16 v[18:33], v[98:101], v[94:97], v[18:33]
	s_setprio 0
	s_barrier
	ds_read_b128 v[94:97], v68
	ds_read_b128 v[98:101], v68 offset:4608
	ds_read_b128 v[126:129], v1 offset:36864
	ds_read_b128 v[130:133], v1 offset:41472
	s_waitcnt vmcnt(1)
	ds_write_b128 v66, v[86:89] offset:18432
	ds_write_b128 v66, v[102:105] offset:23040
	ds_write_b128 v66, v[106:109] offset:27648
	ds_write_b128 v66, v[110:113] offset:32256
	s_waitcnt vmcnt(0)
	ds_write_b128 v66, v[90:93] offset:55296
	ds_write_b128 v66, v[122:125] offset:59904
	ds_write_b128 v66, v[118:121] offset:64512
	ds_write_b128 v69, v[114:117] offset:32256
	s_setprio 1
	ds_read_b128 v[86:89], v68 offset:32
	s_waitcnt lgkmcnt(10)
	v_mfma_f32_32x32x16_bf16 v[34:49], v[94:97], v[126:129], v[34:49]
	ds_read_b128 v[90:93], v1 offset:36896
	global_load_dwordx4 v[102:105], v[70:71], off offset:1280
	global_load_dwordx4 v[106:109], v[74:75], off offset:1280
	global_load_dwordx4 v[110:113], v[76:77], off offset:1280
	global_load_dwordx4 v[114:117], v[84:85], off offset:1280
	global_load_dwordx4 v[118:121], v[82:83], off offset:1280
	global_load_dwordx4 v[122:125], v[80:81], off offset:1280
	s_waitcnt lgkmcnt(10)
	v_mfma_f32_32x32x16_bf16 v[50:65], v[94:97], v[130:133], v[50:65]
	ds_read_b128 v[94:97], v1 offset:41504
	s_waitcnt lgkmcnt(1)
	v_mfma_f32_32x32x16_bf16 v[34:49], v[86:89], v[90:93], v[34:49]
	s_waitcnt lgkmcnt(0)
	v_mfma_f32_32x32x16_bf16 v[50:65], v[86:89], v[94:97], v[50:65]
	ds_read_b128 v[86:89], v68 offset:4640
	v_mfma_f32_32x32x16_bf16 v[2:17], v[98:101], v[126:129], v[2:17]
	v_mfma_f32_32x32x16_bf16 v[18:33], v[98:101], v[130:133], v[18:33]
	ds_read_b128 v[98:101], v68 offset:4704
	s_waitcnt lgkmcnt(1)
	v_mfma_f32_32x32x16_bf16 v[2:17], v[86:89], v[90:93], v[2:17]
	ds_read_b128 v[90:93], v1 offset:36928
	v_mfma_f32_32x32x16_bf16 v[18:33], v[86:89], v[94:97], v[18:33]
	ds_read_b128 v[86:89], v68 offset:64
	ds_read_b128 v[94:97], v1 offset:41536
	s_waitcnt lgkmcnt(1)
	v_mfma_f32_32x32x16_bf16 v[34:49], v[86:89], v[90:93], v[34:49]
	s_waitcnt lgkmcnt(0)
	v_mfma_f32_32x32x16_bf16 v[50:65], v[86:89], v[94:97], v[50:65]
	ds_read_b128 v[86:89], v68 offset:4672
	s_waitcnt lgkmcnt(0)
	v_mfma_f32_32x32x16_bf16 v[2:17], v[86:89], v[90:93], v[2:17]
	ds_read_b128 v[90:93], v1 offset:36960
	v_mfma_f32_32x32x16_bf16 v[18:33], v[86:89], v[94:97], v[18:33]
	ds_read_b128 v[86:89], v68 offset:96
	ds_read_b128 v[94:97], v1 offset:41568
	s_waitcnt lgkmcnt(1)
	v_mfma_f32_32x32x16_bf16 v[34:49], v[86:89], v[90:93], v[34:49]
	s_waitcnt lgkmcnt(0)
	v_mfma_f32_32x32x16_bf16 v[50:65], v[86:89], v[94:97], v[50:65]
	global_load_dwordx4 v[86:89], v[72:73], off offset:1280
	v_mfma_f32_32x32x16_bf16 v[2:17], v[98:101], v[90:93], v[2:17]
	global_load_dwordx4 v[90:93], v[78:79], off offset:1280
	v_mfma_f32_32x32x16_bf16 v[18:33], v[98:101], v[94:97], v[18:33]
	s_setprio 0
	s_barrier
; #define MFMA(a, b, c) __builtin_amdgcn_mfma_f32_32x32x16_bf16((a), (b), (c), 0, 0, 0)
; template <int TM, int TN>
; DI void gemm_mainloop(const u16* __restrict__ A, long lda, const u16* __restrict__ Bt, long ldb, int K, char* smem,
;                       f32x16 (&acc)[TM][TN]) {
;     ...
;   for (int kt = 0; kt < nk; kt++) {
;     const int buf = kt & 1;
;     const u16* cA = sA + buf * BM * LD + (wm * 32 * TM + r) * LD + h * 8;
;     const u16* cB = sB + buf * BN * LD + (wn * 32 * TN + r) * LD + h * 8;
;     bf16x8 af[TM], bfr[TN];
; #pragma unroll
;     for (int tm = 0; tm < TM; tm++) af[tm] = *(const bf16x8*)(cA + tm * 32 * LD);
; #pragma unroll
;     for (int tn = 0; tn < TN; tn++) bfr[tn] = *(const bf16x8*)(cB + tn * 32 * LD);
;     if (kt + 1 < nk) GEMM_SSTORE(buf ^ 1)
;     __builtin_amdgcn_sched_barrier(0);
;     __builtin_amdgcn_s_setprio(1);
; #pragma unroll
;     for (int tm = 0; tm < TM; tm++)
; #pragma unroll
;       for (int tn = 0; tn < TN; tn++) acc[tm][tn] = MFMA(af[tm], bfr[tn], acc[tm][tn]);
; #pragma unroll
;     for (int tm = 0; tm < TM; tm++) af[tm] = *(const bf16x8*)(cA + tm * 32 * LD + 16);
; #pragma unroll
;     for (int tn = 0; tn < TN; tn++) bfr[tn] = *(const bf16x8*)(cB + tn * 32 * LD + 16);
; #pragma unroll
;     for (int tm = 0; tm < TM; tm++)
; #pragma unroll
;       for (int tn = 0; tn < TN; tn++) acc[tm][tn] = MFMA(af[tm], bfr[tn], acc[tm][tn]);
;     __builtin_amdgcn_sched_group_barrier(0x8, 4, 0);
;     if (kt + 2 < nk) GEMM_GLOAD((kt + 2) * 64)
; #pragma unroll
;     for (int ks = 2; ks < 4; ks++) {
; #pragma unroll
;       for (int tm = 0; tm < TM; tm++) af[tm] = *(const bf16x8*)(cA + tm * 32 * LD + ks * 16);
; #pragma unroll
;       for (int tn = 0; tn < TN; tn++) bfr[tn] = *(const bf16x8*)(cB + tn * 32 * LD + ks * 16);
; #pragma unroll
;       for (int tm = 0; tm < TM; tm++)
; #pragma unroll
;         for (int tn = 0; tn < TN; tn++) acc[tm][tn] = MFMA(af[tm], bfr[tn], acc[tm][tn]);
;     }
;     __builtin_amdgcn_s_setprio(0);
;     __syncthreads();
;   }
	ds_read_b128 v[94:97], v68 offset:18432
	ds_read_b128 v[98:101], v68 offset:23040
	ds_read_b128 v[126:129], v1 offset:55296
	ds_read_b128 v[130:133], v1 offset:59904
	s_waitcnt vmcnt(1)
	ds_write_b128 v66, v[86:89]
	ds_write_b128 v66, v[102:105] offset:4608
	ds_write_b128 v66, v[106:109] offset:9216
	ds_write_b128 v66, v[110:113] offset:13824
	s_waitcnt vmcnt(0)
	ds_write_b128 v66, v[90:93] offset:36864
	ds_write_b128 v66, v[122:125] offset:41472
	ds_write_b128 v66, v[118:121] offset:46080
	ds_write_b128 v66, v[114:117] offset:50688
	s_setprio 1
	ds_read_b128 v[86:89], v68 offset:18464
	s_waitcnt lgkmcnt(10)
	v_mfma_f32_32x32x16_bf16 v[34:49], v[94:97], v[126:129], v[34:49]
	ds_read_b128 v[90:93], v1 offset:55328
	global_load_dwordx4 v[102:105], v[70:71], off offset:1408
	global_load_dwordx4 v[106:109], v[74:75], off offset:1408
	global_load_dwordx4 v[110:113], v[76:77], off offset:1408
	global_load_dwordx4 v[114:117], v[84:85], off offset:1408
	global_load_dwordx4 v[118:121], v[82:83], off offset:1408
	global_load_dwordx4 v[122:125], v[80:81], off offset:1408
	s_waitcnt lgkmcnt(10)
	v_mfma_f32_32x32x16_bf16 v[50:65], v[94:97], v[130:133], v[50:65]
	ds_read_b128 v[94:97], v1 offset:59936
	s_waitcnt lgkmcnt(1)
	v_mfma_f32_32x32x16_bf16 v[34:49], v[86:89], v[90:93], v[34:49]
	s_waitcnt lgkmcnt(0)
	v_mfma_f32_32x32x16_bf16 v[50:65], v[86:89], v[94:97], v[50:65]
	ds_read_b128 v[86:89], v68 offset:23072
	v_mfma_f32_32x32x16_bf16 v[2:17], v[98:101], v[126:129], v[2:17]
	v_mfma_f32_32x32x16_bf16 v[18:33], v[98:101], v[130:133], v[18:33]
	ds_read_b128 v[98:101], v68 offset:23136
	s_waitcnt lgkmcnt(1)
	v_mfma_f32_32x32x16_bf16 v[2:17], v[86:89], v[90:93], v[2:17]
	ds_read_b128 v[90:93], v1 offset:55360
	v_mfma_f32_32x32x16_bf16 v[18:33], v[86:89], v[94:97], v[18:33]
	ds_read_b128 v[86:89], v68 offset:18496
	ds_read_b128 v[94:97], v1 offset:59968
	s_waitcnt lgkmcnt(1)
	v_mfma_f32_32x32x16_bf16 v[34:49], v[86:89], v[90:93], v[34:49]
	s_waitcnt lgkmcnt(0)
	v_mfma_f32_32x32x16_bf16 v[50:65], v[86:89], v[94:97], v[50:65]
	ds_read_b128 v[86:89], v68 offset:23104
	s_waitcnt lgkmcnt(0)
	v_mfma_f32_32x32x16_bf16 v[2:17], v[86:89], v[90:93], v[2:17]
	ds_read_b128 v[90:93], v1 offset:55392
	v_mfma_f32_32x32x16_bf16 v[18:33], v[86:89], v[94:97], v[18:33]
	ds_read_b128 v[86:89], v68 offset:18528
	ds_read_b128 v[94:97], v1 offset:60000
	s_waitcnt lgkmcnt(1)
	v_mfma_f32_32x32x16_bf16 v[34:49], v[86:89], v[90:93], v[34:49]
	s_waitcnt lgkmcnt(0)
	v_mfma_f32_32x32x16_bf16 v[50:65], v[86:89], v[94:97], v[50:65]
	global_load_dwordx4 v[86:89], v[72:73], off offset:1408
	v_mfma_f32_32x32x16_bf16 v[2:17], v[98:101], v[90:93], v[2:17]
	global_load_dwordx4 v[90:93], v[78:79], off offset:1408
	v_mfma_f32_32x32x16_bf16 v[18:33], v[98:101], v[94:97], v[18:33]
	s_setprio 0
	s_barrier
	ds_read_b128 v[94:97], v68
	ds_read_b128 v[98:101], v68 offset:4608
	ds_read_b128 v[126:129], v1 offset:36864
	ds_read_b128 v[130:133], v1 offset:41472
	s_waitcnt vmcnt(1)
	ds_write_b128 v66, v[86:89] offset:18432
	ds_write_b128 v66, v[102:105] offset:23040
	ds_write_b128 v66, v[106:109] offset:27648
	ds_write_b128 v66, v[110:113] offset:32256
	s_waitcnt vmcnt(0)
	ds_write_b128 v66, v[90:93] offset:55296
	ds_write_b128 v66, v[122:125] offset:59904
	ds_write_b128 v66, v[118:121] offset:64512
	ds_write_b128 v69, v[114:117] offset:32256
	s_setprio 1
	ds_read_b128 v[86:89], v68 offset:32
	s_waitcnt lgkmcnt(10)
	v_mfma_f32_32x32x16_bf16 v[34:49], v[94:97], v[126:129], v[34:49]
	ds_read_b128 v[90:93], v1 offset:36896
	global_load_dwordx4 v[102:105], v[70:71], off offset:1536
	global_load_dwordx4 v[106:109], v[74:75], off offset:1536
	global_load_dwordx4 v[110:113], v[76:77], off offset:1536
	global_load_dwordx4 v[114:117], v[84:85], off offset:1536
	global_load_dwordx4 v[118:121], v[82:83], off offset:1536
	global_load_dwordx4 v[122:125], v[80:81], off offset:1536
	s_waitcnt lgkmcnt(10)
	v_mfma_f32_32x32x16_bf16 v[50:65], v[94:97], v[130:133], v[50:65]
	ds_read_b128 v[94:97], v1 offset:41504
	s_waitcnt lgkmcnt(1)
	v_mfma_f32_32x32x16_bf16 v[34:49], v[86:89], v[90:93], v[34:49]
	s_waitcnt lgkmcnt(0)
	v_mfma_f32_32x32x16_bf16 v[50:65], v[86:89], v[94:97], v[50:65]
	ds_read_b128 v[86:89], v68 offset:4640
	v_mfma_f32_32x32x16_bf16 v[2:17], v[98:101], v[126:129], v[2:17]
	v_mfma_f32_32x32x16_bf16 v[18:33], v[98:101], v[130:133], v[18:33]
	ds_read_b128 v[98:101], v68 offset:4704
	s_waitcnt lgkmcnt(1)
	v_mfma_f32_32x32x16_bf16 v[2:17], v[86:89], v[90:93], v[2:17]
	ds_read_b128 v[90:93], v1 offset:36928
	v_mfma_f32_32x32x16_bf16 v[18:33], v[86:89], v[94:97], v[18:33]
	ds_read_b128 v[86:89], v68 offset:64
	ds_read_b128 v[94:97], v1 offset:41536
	s_waitcnt lgkmcnt(1)
	v_mfma_f32_32x32x16_bf16 v[34:49], v[86:89], v[90:93], v[34:49]
	s_waitcnt lgkmcnt(0)
	v_mfma_f32_32x32x16_bf16 v[50:65], v[86:89], v[94:97], v[50:65]
	ds_read_b128 v[86:89], v68 offset:4672
	s_waitcnt lgkmcnt(0)
	v_mfma_f32_32x32x16_bf16 v[2:17], v[86:89], v[90:93], v[2:17]
	ds_read_b128 v[90:93], v1 offset:36960
	v_mfma_f32_32x32x16_bf16 v[18:33], v[86:89], v[94:97], v[18:33]
	ds_read_b128 v[86:89], v68 offset:96
	ds_read_b128 v[94:97], v1 offset:41568
	s_waitcnt lgkmcnt(1)
	v_mfma_f32_32x32x16_bf16 v[34:49], v[86:89], v[90:93], v[34:49]
	s_waitcnt lgkmcnt(0)
	v_mfma_f32_32x32x16_bf16 v[50:65], v[86:89], v[94:97], v[50:65]
	global_load_dwordx4 v[86:89], v[72:73], off offset:1536
	v_mfma_f32_32x32x16_bf16 v[2:17], v[98:101], v[90:93], v[2:17]
	global_load_dwordx4 v[90:93], v[78:79], off offset:1536
	v_mfma_f32_32x32x16_bf16 v[18:33], v[98:101], v[94:97], v[18:33]
	s_setprio 0
	s_barrier
; #define MFMA(a, b, c) __builtin_amdgcn_mfma_f32_32x32x16_bf16((a), (b), (c), 0, 0, 0)
; template <int TM, int TN>
; DI void gemm_mainloop(const u16* __restrict__ A, long lda, const u16* __restrict__ Bt, long ldb, int K, char* smem,
;                       f32x16 (&acc)[TM][TN]) {
;     ...
;   for (int kt = 0; kt < nk; kt++) {
;     const int buf = kt & 1;
;     const u16* cA = sA + buf * BM * LD + (wm * 32 * TM + r) * LD + h * 8;
;     const u16* cB = sB + buf * BN * LD + (wn * 32 * TN + r) * LD + h * 8;
;     bf16x8 af[TM], bfr[TN];
; #pragma unroll
;     for (int tm = 0; tm < TM; tm++) af[tm] = *(const bf16x8*)(cA + tm * 32 * LD);
; #pragma unroll
;     for (int tn = 0; tn < TN; tn++) bfr[tn] = *(const bf16x8*)(cB + tn * 32 * LD);
;     if (kt + 1 < nk) GEMM_SSTORE(buf ^ 1)
;     __builtin_amdgcn_sched_barrier(0);
;     __builtin_amdgcn_s_setprio(1);
; #pragma unroll
;     for (int tm = 0; tm < TM; tm++)
; #pragma unroll
;       for (int tn = 0; tn < TN; tn++) acc[tm][tn] = MFMA(af[tm], bfr[tn], acc[tm][tn]);
; #pragma unroll
;     for (int tm = 0; tm < TM; tm++) af[tm] = *(const bf16x8*)(cA + tm * 32 * LD + 16);
; #pragma unroll
;     for (int tn = 0; tn < TN; tn++) bfr[tn] = *(const bf16x8*)(cB + tn * 32 * LD + 16);
; #pragma unroll
;     for (int tm = 0; tm < TM; tm++)
; #pragma unroll
;       for (int tn = 0; tn < TN; tn++) acc[tm][tn] = MFMA(af[tm], bfr[tn], acc[tm][tn]);
;     __builtin_amdgcn_sched_group_barrier(0x8, 4, 0);
;     if (kt + 2 < nk) GEMM_GLOAD((kt + 2) * 64)
; #pragma unroll
;     for (int ks = 2; ks < 4; ks++) {
; #pragma unroll
;       for (int tm = 0; tm < TM; tm++) af[tm] = *(const bf16x8*)(cA + tm * 32 * LD + ks * 16);
; #pragma unroll
;       for (int tn = 0; tn < TN; tn++) bfr[tn] = *(const bf16x8*)(cB + tn * 32 * LD + ks * 16);
; #pragma unroll
;       for (int tm = 0; tm < TM; tm++)
; #pragma unroll
;         for (int tn = 0; tn < TN; tn++) acc[tm][tn] = MFMA(af[tm], bfr[tn], acc[tm][tn]);
;     }
;     __builtin_amdgcn_s_setprio(0);
;     __syncthreads();
;   }
	ds_read_b128 v[94:97], v68 offset:18432
	ds_read_b128 v[98:101], v68 offset:23040
	ds_read_b128 v[126:129], v1 offset:55296
	ds_read_b128 v[130:133], v1 offset:59904
	s_waitcnt vmcnt(1)
	ds_write_b128 v66, v[86:89]
	ds_write_b128 v66, v[102:105] offset:4608
	ds_write_b128 v66, v[106:109] offset:9216
	ds_write_b128 v66, v[110:113] offset:13824
	s_waitcnt vmcnt(0)
	ds_write_b128 v66, v[90:93] offset:36864
	ds_write_b128 v66, v[122:125] offset:41472
	ds_write_b128 v66, v[118:121] offset:46080
	ds_write_b128 v66, v[114:117] offset:50688
	s_setprio 1
	ds_read_b128 v[86:89], v68 offset:18464
	s_waitcnt lgkmcnt(10)
	v_mfma_f32_32x32x16_bf16 v[34:49], v[94:97], v[126:129], v[34:49]
	ds_read_b128 v[90:93], v1 offset:55328
	global_load_dwordx4 v[102:105], v[70:71], off offset:1664
	global_load_dwordx4 v[106:109], v[74:75], off offset:1664
	global_load_dwordx4 v[110:113], v[76:77], off offset:1664
	global_load_dwordx4 v[114:117], v[84:85], off offset:1664
	global_load_dwordx4 v[118:121], v[82:83], off offset:1664
	global_load_dwordx4 v[122:125], v[80:81], off offset:1664
	s_waitcnt lgkmcnt(10)
	v_mfma_f32_32x32x16_bf16 v[50:65], v[94:97], v[130:133], v[50:65]
	ds_read_b128 v[94:97], v1 offset:59936
	s_waitcnt lgkmcnt(1)
	v_mfma_f32_32x32x16_bf16 v[34:49], v[86:89], v[90:93], v[34:49]
	s_waitcnt lgkmcnt(0)
	v_mfma_f32_32x32x16_bf16 v[50:65], v[86:89], v[94:97], v[50:65]
	ds_read_b128 v[86:89], v68 offset:23072
	v_mfma_f32_32x32x16_bf16 v[2:17], v[98:101], v[126:129], v[2:17]
	v_mfma_f32_32x32x16_bf16 v[18:33], v[98:101], v[130:133], v[18:33]
	ds_read_b128 v[98:101], v68 offset:23136
	s_waitcnt lgkmcnt(1)
	v_mfma_f32_32x32x16_bf16 v[2:17], v[86:89], v[90:93], v[2:17]
	ds_read_b128 v[90:93], v1 offset:55360
	v_mfma_f32_32x32x16_bf16 v[18:33], v[86:89], v[94:97], v[18:33]
	ds_read_b128 v[86:89], v68 offset:18496
	ds_read_b128 v[94:97], v1 offset:59968
	s_waitcnt lgkmcnt(1)
	v_mfma_f32_32x32x16_bf16 v[34:49], v[86:89], v[90:93], v[34:49]
	s_waitcnt lgkmcnt(0)
	v_mfma_f32_32x32x16_bf16 v[50:65], v[86:89], v[94:97], v[50:65]
	ds_read_b128 v[86:89], v68 offset:23104
	s_waitcnt lgkmcnt(0)
	v_mfma_f32_32x32x16_bf16 v[2:17], v[86:89], v[90:93], v[2:17]
	ds_read_b128 v[90:93], v1 offset:55392
	v_mfma_f32_32x32x16_bf16 v[18:33], v[86:89], v[94:97], v[18:33]
	ds_read_b128 v[86:89], v68 offset:18528
	ds_read_b128 v[94:97], v1 offset:60000
	s_waitcnt lgkmcnt(1)
	v_mfma_f32_32x32x16_bf16 v[34:49], v[86:89], v[90:93], v[34:49]
	s_waitcnt lgkmcnt(0)
	v_mfma_f32_32x32x16_bf16 v[50:65], v[86:89], v[94:97], v[50:65]
	global_load_dwordx4 v[86:89], v[72:73], off offset:1664
	v_mfma_f32_32x32x16_bf16 v[2:17], v[98:101], v[90:93], v[2:17]
	global_load_dwordx4 v[90:93], v[78:79], off offset:1664
	v_mfma_f32_32x32x16_bf16 v[18:33], v[98:101], v[94:97], v[18:33]
	s_setprio 0
	s_barrier
	ds_read_b128 v[94:97], v68
	ds_read_b128 v[98:101], v68 offset:4608
	ds_read_b128 v[126:129], v1 offset:36864
	ds_read_b128 v[130:133], v1 offset:41472
	s_waitcnt vmcnt(1)
	ds_write_b128 v66, v[86:89] offset:18432
	ds_write_b128 v66, v[102:105] offset:23040
	ds_write_b128 v66, v[106:109] offset:27648
	ds_write_b128 v66, v[110:113] offset:32256
	s_waitcnt vmcnt(0)
	ds_write_b128 v66, v[90:93] offset:55296
	ds_write_b128 v66, v[122:125] offset:59904
	ds_write_b128 v66, v[118:121] offset:64512
	ds_write_b128 v69, v[114:117] offset:32256
	s_setprio 1
	ds_read_b128 v[86:89], v68 offset:32
	s_waitcnt lgkmcnt(10)
	v_mfma_f32_32x32x16_bf16 v[34:49], v[94:97], v[126:129], v[34:49]
	ds_read_b128 v[90:93], v1 offset:36896
	global_load_dwordx4 v[102:105], v[70:71], off offset:1792
	global_load_dwordx4 v[106:109], v[74:75], off offset:1792
	global_load_dwordx4 v[110:113], v[76:77], off offset:1792
	global_load_dwordx4 v[114:117], v[84:85], off offset:1792
	global_load_dwordx4 v[118:121], v[82:83], off offset:1792
	global_load_dwordx4 v[122:125], v[80:81], off offset:1792
	s_waitcnt lgkmcnt(10)
	v_mfma_f32_32x32x16_bf16 v[50:65], v[94:97], v[130:133], v[50:65]
	ds_read_b128 v[94:97], v1 offset:41504
	s_waitcnt lgkmcnt(1)
	v_mfma_f32_32x32x16_bf16 v[34:49], v[86:89], v[90:93], v[34:49]
	s_waitcnt lgkmcnt(0)
	v_mfma_f32_32x32x16_bf16 v[50:65], v[86:89], v[94:97], v[50:65]
	ds_read_b128 v[86:89], v68 offset:4640
	v_mfma_f32_32x32x16_bf16 v[2:17], v[98:101], v[126:129], v[2:17]
	v_mfma_f32_32x32x16_bf16 v[18:33], v[98:101], v[130:133], v[18:33]
	ds_read_b128 v[98:101], v68 offset:4704
	s_waitcnt lgkmcnt(1)
	v_mfma_f32_32x32x16_bf16 v[2:17], v[86:89], v[90:93], v[2:17]
	ds_read_b128 v[90:93], v1 offset:36928
	v_mfma_f32_32x32x16_bf16 v[18:33], v[86:89], v[94:97], v[18:33]
	ds_read_b128 v[86:89], v68 offset:64
	ds_read_b128 v[94:97], v1 offset:41536
	s_waitcnt lgkmcnt(1)
	v_mfma_f32_32x32x16_bf16 v[34:49], v[86:89], v[90:93], v[34:49]
	s_waitcnt lgkmcnt(0)
	v_mfma_f32_32x32x16_bf16 v[50:65], v[86:89], v[94:97], v[50:65]
	ds_read_b128 v[86:89], v68 offset:4672
	s_waitcnt lgkmcnt(0)
	v_mfma_f32_32x32x16_bf16 v[2:17], v[86:89], v[90:93], v[2:17]
	ds_read_b128 v[90:93], v1 offset:36960
	v_mfma_f32_32x32x16_bf16 v[18:33], v[86:89], v[94:97], v[18:33]
	ds_read_b128 v[86:89], v68 offset:96
	ds_read_b128 v[94:97], v1 offset:41568
	s_waitcnt lgkmcnt(1)
	v_mfma_f32_32x32x16_bf16 v[34:49], v[86:89], v[90:93], v[34:49]
	s_waitcnt lgkmcnt(0)
	v_mfma_f32_32x32x16_bf16 v[50:65], v[86:89], v[94:97], v[50:65]
	global_load_dwordx4 v[86:89], v[72:73], off offset:1792
	v_mfma_f32_32x32x16_bf16 v[2:17], v[98:101], v[90:93], v[2:17]
	global_load_dwordx4 v[90:93], v[78:79], off offset:1792
	v_mfma_f32_32x32x16_bf16 v[18:33], v[98:101], v[94:97], v[18:33]
	s_setprio 0
	s_barrier
; #define MFMA(a, b, c) __builtin_amdgcn_mfma_f32_32x32x16_bf16((a), (b), (c), 0, 0, 0)
; template <int TM, int TN>
; DI void gemm_mainloop(const u16* __restrict__ A, long lda, const u16* __restrict__ Bt, long ldb, int K, char* smem,
;                       f32x16 (&acc)[TM][TN]) {
;     ...
;   for (int kt = 0; kt < nk; kt++) {
;     const int buf = kt & 1;
;     const u16* cA = sA + buf * BM * LD + (wm * 32 * TM + r) * LD + h * 8;
;     const u16* cB = sB + buf * BN * LD + (wn * 32 * TN + r) * LD + h * 8;
;     bf16x8 af[TM], bfr[TN];
; #pragma unroll
;     for (int tm = 0; tm < TM; tm++) af[tm] = *(const bf16x8*)(cA + tm * 32 * LD);
; #pragma unroll
;     for (int tn = 0; tn < TN; tn++) bfr[tn] = *(const bf16x8*)(cB + tn * 32 * LD);
;     if (kt + 1 < nk) GEMM_SSTORE(buf ^ 1)
;     __builtin_amdgcn_sched_barrier(0);
;     __builtin_amdgcn_s_setprio(1);
; #pragma unroll
;     for (int tm = 0; tm < TM; tm++)
; #pragma unroll
;       for (int tn = 0; tn < TN; tn++) acc[tm][tn] = MFMA(af[tm], bfr[tn], acc[tm][tn]);
; #pragma unroll
;     for (int tm = 0; tm < TM; tm++) af[tm] = *(const bf16x8*)(cA + tm * 32 * LD + 16);
; #pragma unroll
;     for (int tn = 0; tn < TN; tn++) bfr[tn] = *(const bf16x8*)(cB + tn * 32 * LD + 16);
; #pragma unroll
;     for (int tm = 0; tm < TM; tm++)
; #pragma unroll
;       for (int tn = 0; tn < TN; tn++) acc[tm][tn] = MFMA(af[tm], bfr[tn], acc[tm][tn]);
;     __builtin_amdgcn_sched_group_barrier(0x8, 4, 0);
;     if (kt + 2 < nk) GEMM_GLOAD((kt + 2) * 64)
; #pragma unroll
;     for (int ks = 2; ks < 4; ks++) {
; #pragma unroll
;       for (int tm = 0; tm < TM; tm++) af[tm] = *(const bf16x8*)(cA + tm * 32 * LD + ks * 16);
; #pragma unroll
;       for (int tn = 0; tn < TN; tn++) bfr[tn] = *(const bf16x8*)(cB + tn * 32 * LD + ks * 16);
; #pragma unroll
;       for (int tm = 0; tm < TM; tm++)
; #pragma unroll
;         for (int tn = 0; tn < TN; tn++) acc[tm][tn] = MFMA(af[tm], bfr[tn], acc[tm][tn]);
;     }
;     __builtin_amdgcn_s_setprio(0);
;     __syncthreads();
;   }
	ds_read_b128 v[94:97], v68 offset:18432
	ds_read_b128 v[98:101], v68 offset:23040
	ds_read_b128 v[126:129], v1 offset:55296
	ds_read_b128 v[130:133], v1 offset:59904
	s_waitcnt vmcnt(1)
	ds_write_b128 v66, v[86:89]
	ds_write_b128 v66, v[102:105] offset:4608
	ds_write_b128 v66, v[106:109] offset:9216
	ds_write_b128 v66, v[110:113] offset:13824
	s_waitcnt vmcnt(0)
	ds_write_b128 v66, v[90:93] offset:36864
	ds_write_b128 v66, v[122:125] offset:41472
	ds_write_b128 v66, v[118:121] offset:46080
	ds_write_b128 v66, v[114:117] offset:50688
	s_setprio 1
	ds_read_b128 v[86:89], v68 offset:18464
	s_waitcnt lgkmcnt(10)
	v_mfma_f32_32x32x16_bf16 v[34:49], v[94:97], v[126:129], v[34:49]
	ds_read_b128 v[90:93], v1 offset:55328
	global_load_dwordx4 v[102:105], v[70:71], off offset:1920
	global_load_dwordx4 v[106:109], v[74:75], off offset:1920
	global_load_dwordx4 v[110:113], v[76:77], off offset:1920
	global_load_dwordx4 v[114:117], v[84:85], off offset:1920
	global_load_dwordx4 v[118:121], v[82:83], off offset:1920
	global_load_dwordx4 v[122:125], v[80:81], off offset:1920
	s_waitcnt lgkmcnt(10)
	v_mfma_f32_32x32x16_bf16 v[50:65], v[94:97], v[130:133], v[50:65]
	ds_read_b128 v[94:97], v1 offset:59936
	s_waitcnt lgkmcnt(1)
	v_mfma_f32_32x32x16_bf16 v[34:49], v[86:89], v[90:93], v[34:49]
	s_waitcnt lgkmcnt(0)
	v_mfma_f32_32x32x16_bf16 v[50:65], v[86:89], v[94:97], v[50:65]
	ds_read_b128 v[86:89], v68 offset:23072
	v_mfma_f32_32x32x16_bf16 v[2:17], v[98:101], v[126:129], v[2:17]
	v_mfma_f32_32x32x16_bf16 v[18:33], v[98:101], v[130:133], v[18:33]
	ds_read_b128 v[98:101], v68 offset:23136
	s_waitcnt lgkmcnt(1)
	v_mfma_f32_32x32x16_bf16 v[2:17], v[86:89], v[90:93], v[2:17]
	ds_read_b128 v[90:93], v1 offset:55360
	v_mfma_f32_32x32x16_bf16 v[18:33], v[86:89], v[94:97], v[18:33]
	ds_read_b128 v[86:89], v68 offset:18496
	ds_read_b128 v[94:97], v1 offset:59968
	s_waitcnt lgkmcnt(1)
	v_mfma_f32_32x32x16_bf16 v[34:49], v[86:89], v[90:93], v[34:49]
	s_waitcnt lgkmcnt(0)
	v_mfma_f32_32x32x16_bf16 v[50:65], v[86:89], v[94:97], v[50:65]
	ds_read_b128 v[86:89], v68 offset:23104
	s_waitcnt lgkmcnt(0)
	v_mfma_f32_32x32x16_bf16 v[2:17], v[86:89], v[90:93], v[2:17]
	ds_read_b128 v[90:93], v1 offset:55392
	v_mfma_f32_32x32x16_bf16 v[18:33], v[86:89], v[94:97], v[18:33]
	ds_read_b128 v[86:89], v68 offset:18528
	ds_read_b128 v[94:97], v1 offset:60000
	s_waitcnt lgkmcnt(1)
	v_mfma_f32_32x32x16_bf16 v[34:49], v[86:89], v[90:93], v[34:49]
	s_waitcnt lgkmcnt(0)
	v_mfma_f32_32x32x16_bf16 v[50:65], v[86:89], v[94:97], v[50:65]
	global_load_dwordx4 v[86:89], v[72:73], off offset:1920
	s_nop 0
	global_load_dwordx4 v[70:73], v[78:79], off offset:1920
	v_mfma_f32_32x32x16_bf16 v[2:17], v[98:101], v[90:93], v[2:17]
	v_mfma_f32_32x32x16_bf16 v[18:33], v[98:101], v[94:97], v[18:33]
	s_setprio 0
	s_barrier
	ds_read_b128 v[74:77], v68
	ds_read_b128 v[78:81], v68 offset:4608
	ds_read_b128 v[82:85], v1 offset:36864
	ds_read_b128 v[90:93], v1 offset:41472
	s_waitcnt vmcnt(1)
	ds_write_b128 v66, v[86:89] offset:18432
	ds_write_b128 v66, v[102:105] offset:23040
	ds_write_b128 v66, v[106:109] offset:27648
	ds_write_b128 v66, v[110:113] offset:32256
	s_waitcnt vmcnt(0)
	ds_write_b128 v66, v[70:73] offset:55296
	ds_write_b128 v66, v[122:125] offset:59904
	ds_write_b128 v66, v[118:121] offset:64512
	ds_write_b128 v69, v[114:117] offset:32256
	s_setprio 1
	ds_read_b128 v[70:73], v68 offset:32
	s_waitcnt lgkmcnt(10)
	v_mfma_f32_32x32x16_bf16 v[34:49], v[74:77], v[82:85], v[34:49]
	s_waitcnt lgkmcnt(9)
	v_mfma_f32_32x32x16_bf16 v[50:65], v[74:77], v[90:93], v[50:65]
	ds_read_b128 v[74:77], v1 offset:36896
	v_mfma_f32_32x32x16_bf16 v[2:17], v[78:81], v[82:85], v[2:17]
	v_mfma_f32_32x32x16_bf16 v[18:33], v[78:81], v[90:93], v[18:33]
	ds_read_b128 v[78:81], v1 offset:41504
	s_waitcnt lgkmcnt(1)
	v_mfma_f32_32x32x16_bf16 v[34:49], v[70:73], v[74:77], v[34:49]
	s_waitcnt lgkmcnt(0)
	v_mfma_f32_32x32x16_bf16 v[50:65], v[70:73], v[78:81], v[50:65]
	ds_read_b128 v[70:73], v68 offset:4640
	s_waitcnt lgkmcnt(0)
	v_mfma_f32_32x32x16_bf16 v[2:17], v[70:73], v[74:77], v[2:17]
	ds_read_b128 v[74:77], v1 offset:36928
	v_mfma_f32_32x32x16_bf16 v[18:33], v[70:73], v[78:81], v[18:33]
	ds_read_b128 v[70:73], v68 offset:64
	ds_read_b128 v[78:81], v1 offset:41536
	s_waitcnt lgkmcnt(1)
	v_mfma_f32_32x32x16_bf16 v[34:49], v[70:73], v[74:77], v[34:49]
	s_waitcnt lgkmcnt(0)
	v_mfma_f32_32x32x16_bf16 v[50:65], v[70:73], v[78:81], v[50:65]
	ds_read_b128 v[70:73], v68 offset:4672
	s_waitcnt lgkmcnt(0)
	v_mfma_f32_32x32x16_bf16 v[2:17], v[70:73], v[74:77], v[2:17]
	ds_read_b128 v[74:77], v1 offset:36960
	v_mfma_f32_32x32x16_bf16 v[18:33], v[70:73], v[78:81], v[18:33]
	ds_read_b128 v[70:73], v68 offset:96
	ds_read_b128 v[78:81], v1 offset:41568
	s_waitcnt lgkmcnt(1)
	v_mfma_f32_32x32x16_bf16 v[34:49], v[70:73], v[74:77], v[34:49]
	s_waitcnt lgkmcnt(0)
	v_mfma_f32_32x32x16_bf16 v[50:65], v[70:73], v[78:81], v[50:65]
	ds_read_b128 v[70:73], v68 offset:4704
	s_waitcnt lgkmcnt(0)
	v_mfma_f32_32x32x16_bf16 v[2:17], v[70:73], v[74:77], v[2:17]
	v_mfma_f32_32x32x16_bf16 v[18:33], v[70:73], v[78:81], v[18:33]
	s_setprio 0
	s_barrier
; #define MFMA(a, b, c) __builtin_amdgcn_mfma_f32_32x32x16_bf16((a), (b), (c), 0, 0, 0)
; DI int crow(int i, int h) { return (i & 3) + 8 * (i >> 2) + 4 * h; }
; template <int TM, int TN>
; DI void gemm_mainloop(const u16* __restrict__ A, long lda, const u16* __restrict__ Bt, long ldb, int K, char* smem,
;                       f32x16 (&acc)[TM][TN]) {
;     ...
;     for (int ks = 2; ks < 4; ks++) {
; #pragma unroll
;       for (int tm = 0; tm < TM; tm++) af[tm] = *(const bf16x8*)(cA + tm * 32 * LD + ks * 16);
; #pragma unroll
;       for (int tn = 0; tn < TN; tn++) bfr[tn] = *(const bf16x8*)(cB + tn * 32 * LD + ks * 16);
; #pragma unroll
;       for (int tm = 0; tm < TM; tm++)
; #pragma unroll
;         for (int tn = 0; tn < TN; tn++) acc[tm][tn] = MFMA(af[tm], bfr[tn], acc[tm][tn]);
;     }
;     __builtin_amdgcn_s_setprio(0);
;     __syncthreads();
;   }
; template <int TM, int TN, class Epi>
; DI void gemm_tile(const u16* A, long lda, const u16* Bt, long ldb, int K, int m0, int n0, char* smem, const Epi& epi) {
;     ...
; #pragma unroll
;   for (int tm = 0; tm < TM; tm++)
; #pragma unroll
;     for (int tn = 0; tn < TN; tn++)
; #pragma unroll
;       for (int i = 0; i < 16; i++)
;         Ct[(wm * 32 * TM + tm * 32 + crow(i, h)) * LDC + wn * 32 * TN + tn * 32 + r] = acc[tm][tn][i];
;   __syncthreads();
	ds_read_b128 v[70:73], v68 offset:18432
	ds_read_b128 v[74:77], v68 offset:23040
	ds_read_b128 v[78:81], v1 offset:55296
	ds_read_b128 v[82:85], v1 offset:59904
	s_setprio 1
	s_waitcnt lgkmcnt(1)
	v_mfma_f32_32x32x16_bf16 v[34:49], v[70:73], v[78:81], v[34:49]
	s_waitcnt lgkmcnt(0)
	v_mfma_f32_32x32x16_bf16 v[50:65], v[70:73], v[82:85], v[50:65]
	ds_read_b128 v[70:73], v68 offset:18464
	v_mfma_f32_32x32x16_bf16 v[2:17], v[74:77], v[78:81], v[2:17]
	ds_read_b128 v[78:81], v1 offset:59936
	v_mfma_f32_32x32x16_bf16 v[18:33], v[74:77], v[82:85], v[18:33]
	ds_read_b128 v[74:77], v1 offset:55328
	s_waitcnt lgkmcnt(0)
	v_mfma_f32_32x32x16_bf16 v[34:49], v[70:73], v[74:77], v[34:49]
	v_mfma_f32_32x32x16_bf16 v[50:65], v[70:73], v[78:81], v[50:65]
	ds_read_b128 v[70:73], v68 offset:23072
	s_waitcnt lgkmcnt(0)
	v_mfma_f32_32x32x16_bf16 v[2:17], v[70:73], v[74:77], v[2:17]
	ds_read_b128 v[74:77], v1 offset:55360
	v_mfma_f32_32x32x16_bf16 v[18:33], v[70:73], v[78:81], v[18:33]
	ds_read_b128 v[70:73], v68 offset:18496
	ds_read_b128 v[78:81], v1 offset:59968
	s_waitcnt lgkmcnt(1)
	v_mfma_f32_32x32x16_bf16 v[34:49], v[70:73], v[74:77], v[34:49]
	s_waitcnt lgkmcnt(0)
	v_mfma_f32_32x32x16_bf16 v[50:65], v[70:73], v[78:81], v[50:65]
	ds_read_b128 v[70:73], v68 offset:23104
	s_waitcnt lgkmcnt(0)
	v_mfma_f32_32x32x16_bf16 v[2:17], v[70:73], v[74:77], v[2:17]
	ds_read_b128 v[74:77], v1 offset:55392
	v_mfma_f32_32x32x16_bf16 v[18:33], v[70:73], v[78:81], v[18:33]
	ds_read_b128 v[70:73], v68 offset:18528
	ds_read_b128 v[78:81], v1 offset:60000
	s_waitcnt lgkmcnt(1)
	v_mfma_f32_32x32x16_bf16 v[34:49], v[70:73], v[74:77], v[34:49]
	s_waitcnt lgkmcnt(0)
	v_mfma_f32_32x32x16_bf16 v[50:65], v[70:73], v[78:81], v[50:65]
	ds_read_b128 v[68:71], v68 offset:23136
	s_waitcnt lgkmcnt(0)
	v_mfma_f32_32x32x16_bf16 v[2:17], v[68:71], v[74:77], v[2:17]
	v_mfma_f32_32x32x16_bf16 v[18:33], v[68:71], v[78:81], v[18:33]
	s_setprio 0
	v_mov_b32_e32 v1, v0
	s_barrier
	s_lshl_b64 s[4:5], s[6:7], 1
	v_lshrrev_b32_e32 v66, 1, v1
	v_and_b32_e32 v66, 0xfffffc0, v66
	v_lshrrev_b32_e32 v68, 3, v1
	v_and_or_b32 v66, v68, 4, v66
	v_and_b32_e32 v68, 0x5f, v1
	v_mul_lo_u32 v66, v66, s22
	v_lshl_add_u32 v66, v68, 2, v66
	ds_write2_b32 v66, v34, v50 offset1:32
	v_add_u32_e32 v34, 0x400, v66
	ds_write2_b32 v34, v36, v52 offset0:8 offset1:40
	ds_write2_b32 v34, v37, v53 offset0:140 offset1:172
	v_add_u32_e32 v34, 0x1000, v66
	ds_write2_b32 v34, v38, v54 offset0:32 offset1:64
	ds_write2_b32 v34, v39, v55 offset0:164 offset1:196
	v_add_u32_e32 v34, 0x1400, v66
	ds_write2_b32 v34, v40, v56 offset0:40 offset1:72
	ds_write2_b32 v34, v41, v57 offset0:172 offset1:204
	v_add_u32_e32 v34, 0x2000, v66
	ds_write2_b32 v34, v42, v58 offset0:64 offset1:96
	ds_write2_b32 v34, v43, v59 offset0:196 offset1:228
	v_add_u32_e32 v34, 0x2400, v66
	ds_write2_b32 v34, v44, v60 offset0:72 offset1:104
	ds_write2_b32 v34, v45, v61 offset0:204 offset1:236
	v_add_u32_e32 v34, 0x3000, v66
	ds_write2_b32 v34, v46, v62 offset0:96 offset1:128
	v_add_u32_e32 v34, 0x3200, v66
	ds_write2_b32 v34, v47, v63 offset0:100 offset1:132
	v_add_u32_e32 v34, 0x3400, v66
	ds_write2_b32 v34, v48, v64 offset0:104 offset1:136
	v_add_u32_e32 v34, 0x3600, v66
	ds_write2_b32 v34, v49, v65 offset0:108 offset1:140
	v_add_u32_e32 v34, 0x4000, v66
	ds_write2_b32 v34, v2, v18 offset0:128 offset1:160
	v_add_u32_e32 v2, 0x4400, v66
	ds_write2_b32 v2, v3, v19 offset0:4 offset1:36
	ds_write2_b32 v2, v4, v20 offset0:136 offset1:168
	v_add_u32_e32 v2, 0x4800, v66
	ds_write2_b32 v2, v5, v21 offset0:12 offset1:44
	v_add_u32_e32 v2, 0x5000, v66
	ds_write2_b32 v2, v6, v22 offset0:160 offset1:192
	v_add_u32_e32 v2, 0x5400, v66
	ds_write2_b32 v2, v7, v23 offset0:36 offset1:68
	ds_write2_b32 v2, v8, v24 offset0:168 offset1:200
	v_add_u32_e32 v2, 0x5800, v66
	ds_write2_b32 v2, v9, v25 offset0:44 offset1:76
	v_add_u32_e32 v2, 0x6000, v66
	ds_write2_b32 v2, v10, v26 offset0:192 offset1:224
	v_add_u32_e32 v2, 0x6400, v66
	ds_write2_b32 v2, v11, v27 offset0:68 offset1:100
	ds_write2_b32 v2, v12, v28 offset0:200 offset1:232
	v_add_u32_e32 v2, 0x6800, v66
	ds_write2_b32 v2, v13, v29 offset0:76 offset1:108
	v_add_u32_e32 v2, 0x7200, v66
	ds_write2_b32 v2, v14, v30 offset0:96 offset1:128
	v_add_u32_e32 v2, 0x7400, v66
	ds_write2_b32 v2, v15, v31 offset0:100 offset1:132
	v_add_u32_e32 v2, 0x7600, v66
	ds_write2_b32 v2, v16, v32 offset0:104 offset1:136
	v_add_u32_e32 v2, 0x7800, v66
	ds_write2_b32 v2, v17, v33 offset0:108 offset1:140
	v_lshlrev_b32_e32 v2, 3, v1
	v_and_b32_e32 v3, 0x78, v2
	s_add_u32 s4, s3, s4
	ds_write2_b32 v66, v35, v51 offset0:132 offset1:164
	s_addc_u32 s5, s14, s5
	v_lshlrev_b32_e32 v66, 1, v3
	v_lshlrev_b32_e32 v2, 2, v3
	v_lshl_add_u64 v[4:5], s[4:5], 0, v[66:67]
	s_mov_b32 s4, 0
	s_waitcnt lgkmcnt(0)
	s_barrier

; #define MFMA(a, b, c) __builtin_amdgcn_mfma_f32_32x32x16_bf16((a), (b), (c), 0, 0, 0)
; template <int TM, int TN>
; DI void gemm_mainloop(const u16* __restrict__ A, long lda, const u16* __restrict__ Bt, long ldb, int K, char* smem,
;                       f32x16 (&acc)[TM][TN]) {
;     ...
;   const int nk = K / 64;
;   const int lrow = tid >> 3, lch = (tid & 7) * 8;
;   const u16* gA = A + (long)lrow * lda + lch;
;   const u16* gB = Bt + (long)lrow * ldb + lch;
;   const int soff = lrow * LD + lch;
;     ...
;   GEMM_GLOAD(0)
;   __syncthreads();
;   GEMM_SSTORE(0)
;   if (nk > 1) GEMM_GLOAD(64)
;   __syncthreads();
;   for (int kt = 0; kt < nk; kt++) {
;     const int buf = kt & 1;
;     const u16* cA = sA + buf * BM * LD + (wm * 32 * TM + r) * LD + h * 8;
;     const u16* cB = sB + buf * BN * LD + (wn * 32 * TN + r) * LD + h * 8;
;     bf16x8 af[TM], bfr[TN];
; #pragma unroll
;     for (int tm = 0; tm < TM; tm++) af[tm] = *(const bf16x8*)(cA + tm * 32 * LD);
; #pragma unroll
;     for (int tn = 0; tn < TN; tn++) bfr[tn] = *(const bf16x8*)(cB + tn * 32 * LD);
;     if (kt + 1 < nk) GEMM_SSTORE(buf ^ 1)
;     __builtin_amdgcn_sched_barrier(0);
;     __builtin_amdgcn_s_setprio(1);
; #pragma unroll
;     for (int tm = 0; tm < TM; tm++)
; #pragma unroll
;       for (int tn = 0; tn < TN; tn++) acc[tm][tn] = MFMA(af[tm], bfr[tn], acc[tm][tn]);
; #pragma unroll
;     for (int tm = 0; tm < TM; tm++) af[tm] = *(const bf16x8*)(cA + tm * 32 * LD + 16);
; #pragma unroll
;     for (int tn = 0; tn < TN; tn++) bfr[tn] = *(const bf16x8*)(cB + tn * 32 * LD + 16);
; #pragma unroll
;     for (int tm = 0; tm < TM; tm++)
; #pragma unroll
;       for (int tn = 0; tn < TN; tn++) acc[tm][tn] = MFMA(af[tm], bfr[tn], acc[tm][tn]);
;     __builtin_amdgcn_sched_group_barrier(0x8, 4, 0);
;     if (kt + 2 < nk) GEMM_GLOAD((kt + 2) * 64)
; #pragma unroll
;     for (int ks = 2; ks < 4; ks++) {
; #pragma unroll
;       for (int tm = 0; tm < TM; tm++) af[tm] = *(const bf16x8*)(cA + tm * 32 * LD + ks * 16);
; #pragma unroll
;       for (int tn = 0; tn < TN; tn++) bfr[tn] = *(const bf16x8*)(cB + tn * 32 * LD + ks * 16);
; #pragma unroll
;       for (int tm = 0; tm < TM; tm++)
; #pragma unroll
;         for (int tn = 0; tn < TN; tn++) acc[tm][tn] = MFMA(af[tm], bfr[tn], acc[tm][tn]);
;     }
;     __builtin_amdgcn_s_setprio(0);
;     __syncthreads();
;   }
.LBB0_1538:
	s_mul_hi_i32 s4, s36, 0x66666667
	s_lshr_b32 s5, s4, 31
	s_ashr_i32 s4, s4, 3
	s_add_i32 s4, s4, s5
	s_mul_i32 s5, s4, 20
	s_sub_i32 s6, s36, s5
	s_lshl_b32 s37, s4, 7
	s_mul_i32 s4, s4, 0x44000
	s_mul_hi_i32 s5, s37, 0x880
	s_add_u32 s4, s8, s4
	v_mov_b32_e32 v1, v0
	s_addc_u32 s5, s9, s5
	s_mul_i32 s7, s6, 0x44000
	v_lshlrev_b32_e32 v2, 3, v1
	v_ashrrev_i32_e32 v68, 3, v1
	v_and_b32_e32 v69, 56, v2
	v_mov_b64_e32 v[2:3], s[4:5]
	v_mad_i64_i32 v[2:3], s[4:5], v68, s21, v[2:3]
	v_lshlrev_b32_e32 v66, 1, v69
	v_lshl_add_u64 v[72:73], v[2:3], 0, v[66:67]
	s_ashr_i32 s17, s7, 31
	v_add_co_u32_e32 v70, vcc, s23, v72
	s_add_u32 s16, s3, s7
	s_nop 0
	v_addc_co_u32_e32 v71, vcc, 0, v73, vcc
	s_addc_u32 s17, s20, s17
	v_add_co_u32_e32 v74, vcc, s24, v72
	v_mov_b64_e32 v[2:3], s[16:17]
	s_nop 0
	v_addc_co_u32_e32 v75, vcc, 0, v73, vcc
	v_mad_i64_i32 v[18:19], s[4:5], v68, s21, v[2:3]
	v_add_co_u32_e32 v76, vcc, s25, v72
	v_lshl_add_u64 v[78:79], v[18:19], 0, v[66:67]
	s_nop 0
	v_addc_co_u32_e32 v77, vcc, 0, v73, vcc
	v_add_co_u32_e32 v80, vcc, s23, v78
	global_load_dwordx4 v[2:5], v[72:73], off
	s_nop 0
	v_addc_co_u32_e32 v81, vcc, 0, v79, vcc
	v_add_co_u32_e32 v82, vcc, s24, v78
	global_load_dwordx4 v[6:9], v[70:71], off
	s_nop 0
	v_addc_co_u32_e32 v83, vcc, 0, v79, vcc
	v_add_co_u32_e32 v84, vcc, s25, v78
	global_load_dwordx4 v[10:13], v[74:75], off
	s_nop 0
	v_addc_co_u32_e32 v85, vcc, 0, v79, vcc
	global_load_dwordx4 v[14:17], v[76:77], off
	global_load_dwordx4 v[18:21], v[78:79], off
	global_load_dwordx4 v[22:25], v[80:81], off
	global_load_dwordx4 v[26:29], v[82:83], off
	global_load_dwordx4 v[30:33], v[84:85], off
	s_barrier
	global_load_dwordx4 v[34:37], v[72:73], off offset:128
	global_load_dwordx4 v[38:41], v[70:71], off offset:128
	global_load_dwordx4 v[42:45], v[74:75], off offset:128
	global_load_dwordx4 v[46:49], v[76:77], off offset:128
	global_load_dwordx4 v[50:53], v[78:79], off offset:128
	global_load_dwordx4 v[54:57], v[80:81], off offset:128
	global_load_dwordx4 v[58:61], v[82:83], off offset:128
	global_load_dwordx4 v[62:65], v[84:85], off offset:128
	v_and_b32_e32 v66, 31, v1
	v_lshrrev_b32_e32 v86, 1, v1
	v_and_b32_e32 v1, 0x5f, v1
	v_mul_lo_u32 v68, v68, s22
	v_and_or_b32 v87, v86, s26, v66
	v_and_b32_e32 v86, 16, v86
	v_add_lshl_u32 v66, v68, v69, 1
	v_mad_u64_u32 v[68:69], s[4:5], v87, s27, v[86:87]
	v_mad_u32_u24 v1, v1, s27, v86
	v_add_u32_e32 v69, 0x9000, v66
	s_waitcnt vmcnt(15)
	ds_write_b128 v66, v[2:5]
	s_waitcnt vmcnt(14)
	ds_write_b128 v66, v[6:9] offset:4608
	s_waitcnt vmcnt(13)
	ds_write_b128 v66, v[10:13] offset:9216
	s_waitcnt vmcnt(12)
	ds_write_b128 v66, v[14:17] offset:13824
	s_waitcnt vmcnt(11)
	ds_write_b128 v66, v[18:21] offset:36864
	s_waitcnt vmcnt(10)
	ds_write_b128 v66, v[22:25] offset:41472
	s_waitcnt vmcnt(9)
	ds_write_b128 v66, v[26:29] offset:46080
	s_waitcnt vmcnt(8)
	ds_write_b128 v66, v[30:33] offset:50688
	s_waitcnt lgkmcnt(0)
	s_barrier
	ds_read_b128 v[2:5], v68
	ds_read_b128 v[18:21], v68 offset:4608
	ds_read_b128 v[6:9], v1 offset:36864
	ds_read_b128 v[22:25], v1 offset:41472
	s_waitcnt vmcnt(7)
	ds_write_b128 v66, v[34:37] offset:18432
	s_waitcnt vmcnt(6)
	ds_write_b128 v66, v[38:41] offset:23040
	s_waitcnt vmcnt(5)
	ds_write_b128 v66, v[42:45] offset:27648
	s_waitcnt vmcnt(4)
	ds_write_b128 v66, v[46:49] offset:32256
	s_waitcnt vmcnt(3)
	ds_write_b128 v66, v[50:53] offset:55296
	s_waitcnt vmcnt(2)
	ds_write_b128 v66, v[54:57] offset:59904
	s_waitcnt vmcnt(1)
	ds_write_b128 v66, v[58:61] offset:64512
	s_waitcnt vmcnt(0)
	ds_write_b128 v69, v[62:65] offset:32256
	s_setprio 1
	ds_read_b128 v[86:89], v68 offset:32
	s_waitcnt lgkmcnt(10)
	v_mfma_f32_32x32x16_bf16 v[34:49], v[2:5], v[6:9], 0
	ds_read_b128 v[90:93], v1 offset:36896
	ds_read_b128 v[94:97], v1 offset:41504
	ds_read_b128 v[98:101], v68 offset:4704
	global_load_dwordx4 v[102:105], v[70:71], off offset:256
	global_load_dwordx4 v[106:109], v[74:75], off offset:256
	global_load_dwordx4 v[110:113], v[76:77], off offset:256
	global_load_dwordx4 v[114:117], v[84:85], off offset:256
	s_waitcnt lgkmcnt(12)
	v_mfma_f32_32x32x16_bf16 v[50:65], v[2:5], v[22:25], 0
	global_load_dwordx4 v[118:121], v[82:83], off offset:256
	global_load_dwordx4 v[122:125], v[80:81], off offset:256
	s_waitcnt lgkmcnt(2)
	v_mfma_f32_32x32x16_bf16 v[34:49], v[86:89], v[90:93], v[34:49]
	s_waitcnt lgkmcnt(1)
	v_mfma_f32_32x32x16_bf16 v[50:65], v[86:89], v[94:97], v[50:65]
	ds_read_b128 v[86:89], v68 offset:4640
	v_mfma_f32_32x32x16_bf16 v[2:17], v[18:21], v[6:9], 0
	v_mfma_f32_32x32x16_bf16 v[18:33], v[18:21], v[22:25], 0
	s_waitcnt lgkmcnt(0)
	v_mfma_f32_32x32x16_bf16 v[2:17], v[86:89], v[90:93], v[2:17]
	ds_read_b128 v[90:93], v1 offset:36928
	v_mfma_f32_32x32x16_bf16 v[18:33], v[86:89], v[94:97], v[18:33]
	ds_read_b128 v[86:89], v68 offset:64
	ds_read_b128 v[94:97], v1 offset:41536
	s_waitcnt lgkmcnt(1)
	v_mfma_f32_32x32x16_bf16 v[34:49], v[86:89], v[90:93], v[34:49]
	s_waitcnt lgkmcnt(0)
	v_mfma_f32_32x32x16_bf16 v[50:65], v[86:89], v[94:97], v[50:65]
	ds_read_b128 v[86:89], v68 offset:4672
	s_waitcnt lgkmcnt(0)
	v_mfma_f32_32x32x16_bf16 v[2:17], v[86:89], v[90:93], v[2:17]
	ds_read_b128 v[90:93], v1 offset:36960
	v_mfma_f32_32x32x16_bf16 v[18:33], v[86:89], v[94:97], v[18:33]
	ds_read_b128 v[86:89], v68 offset:96
	ds_read_b128 v[94:97], v1 offset:41568
	s_waitcnt lgkmcnt(1)
	v_mfma_f32_32x32x16_bf16 v[34:49], v[86:89], v[90:93], v[34:49]
	s_waitcnt lgkmcnt(0)
	v_mfma_f32_32x32x16_bf16 v[50:65], v[86:89], v[94:97], v[50:65]
	global_load_dwordx4 v[86:89], v[72:73], off offset:256
	v_mfma_f32_32x32x16_bf16 v[2:17], v[98:101], v[90:93], v[2:17]
	global_load_dwordx4 v[90:93], v[78:79], off offset:256
	v_mfma_f32_32x32x16_bf16 v[18:33], v[98:101], v[94:97], v[18:33]
	s_setprio 0
	s_barrier
; #define MFMA(a, b, c) __builtin_amdgcn_mfma_f32_32x32x16_bf16((a), (b), (c), 0, 0, 0)
; template <int TM, int TN>
; DI void gemm_mainloop(const u16* __restrict__ A, long lda, const u16* __restrict__ Bt, long ldb, int K, char* smem,
;                       f32x16 (&acc)[TM][TN]) {
;     ...
;   for (int kt = 0; kt < nk; kt++) {
;     const int buf = kt & 1;
;     const u16* cA = sA + buf * BM * LD + (wm * 32 * TM + r) * LD + h * 8;
;     const u16* cB = sB + buf * BN * LD + (wn * 32 * TN + r) * LD + h * 8;
;     bf16x8 af[TM], bfr[TN];
; #pragma unroll
;     for (int tm = 0; tm < TM; tm++) af[tm] = *(const bf16x8*)(cA + tm * 32 * LD);
; #pragma unroll
;     for (int tn = 0; tn < TN; tn++) bfr[tn] = *(const bf16x8*)(cB + tn * 32 * LD);
;     if (kt + 1 < nk) GEMM_SSTORE(buf ^ 1)
;     __builtin_amdgcn_sched_barrier(0);
;     __builtin_amdgcn_s_setprio(1);
; #pragma unroll
;     for (int tm = 0; tm < TM; tm++)
; #pragma unroll
;       for (int tn = 0; tn < TN; tn++) acc[tm][tn] = MFMA(af[tm], bfr[tn], acc[tm][tn]);
; #pragma unroll
;     for (int tm = 0; tm < TM; tm++) af[tm] = *(const bf16x8*)(cA + tm * 32 * LD + 16);
; #pragma unroll
;     for (int tn = 0; tn < TN; tn++) bfr[tn] = *(const bf16x8*)(cB + tn * 32 * LD + 16);
; #pragma unroll
;     for (int tm = 0; tm < TM; tm++)
; #pragma unroll
;       for (int tn = 0; tn < TN; tn++) acc[tm][tn] = MFMA(af[tm], bfr[tn], acc[tm][tn]);
;     __builtin_amdgcn_sched_group_barrier(0x8, 4, 0);
;     if (kt + 2 < nk) GEMM_GLOAD((kt + 2) * 64)
; #pragma unroll
;     for (int ks = 2; ks < 4; ks++) {
; #pragma unroll
;       for (int tm = 0; tm < TM; tm++) af[tm] = *(const bf16x8*)(cA + tm * 32 * LD + ks * 16);
; #pragma unroll
;       for (int tn = 0; tn < TN; tn++) bfr[tn] = *(const bf16x8*)(cB + tn * 32 * LD + ks * 16);
; #pragma unroll
;       for (int tm = 0; tm < TM; tm++)
; #pragma unroll
;         for (int tn = 0; tn < TN; tn++) acc[tm][tn] = MFMA(af[tm], bfr[tn], acc[tm][tn]);
;     }
;     __builtin_amdgcn_s_setprio(0);
;     __syncthreads();
;   }
	ds_read_b128 v[94:97], v68 offset:18432
	ds_read_b128 v[98:101], v68 offset:23040
	ds_read_b128 v[126:129], v1 offset:55296
	ds_read_b128 v[130:133], v1 offset:59904
	s_waitcnt vmcnt(1)
	ds_write_b128 v66, v[86:89]
	ds_write_b128 v66, v[102:105] offset:4608
	ds_write_b128 v66, v[106:109] offset:9216
	ds_write_b128 v66, v[110:113] offset:13824
	s_waitcnt vmcnt(0)
	ds_write_b128 v66, v[90:93] offset:36864
	ds_write_b128 v66, v[122:125] offset:41472
	ds_write_b128 v66, v[118:121] offset:46080
	ds_write_b128 v66, v[114:117] offset:50688
	s_setprio 1
	ds_read_b128 v[86:89], v68 offset:18464
	s_waitcnt lgkmcnt(10)
	v_mfma_f32_32x32x16_bf16 v[34:49], v[94:97], v[126:129], v[34:49]
	ds_read_b128 v[90:93], v1 offset:55328
	global_load_dwordx4 v[102:105], v[70:71], off offset:384
	global_load_dwordx4 v[106:109], v[74:75], off offset:384
	global_load_dwordx4 v[110:113], v[76:77], off offset:384
	global_load_dwordx4 v[114:117], v[84:85], off offset:384
	global_load_dwordx4 v[118:121], v[82:83], off offset:384
	global_load_dwordx4 v[122:125], v[80:81], off offset:384
	s_waitcnt lgkmcnt(10)
	v_mfma_f32_32x32x16_bf16 v[50:65], v[94:97], v[130:133], v[50:65]
	ds_read_b128 v[94:97], v1 offset:59936
	s_waitcnt lgkmcnt(1)
	v_mfma_f32_32x32x16_bf16 v[34:49], v[86:89], v[90:93], v[34:49]
	s_waitcnt lgkmcnt(0)
	v_mfma_f32_32x32x16_bf16 v[50:65], v[86:89], v[94:97], v[50:65]
	ds_read_b128 v[86:89], v68 offset:23072
	v_mfma_f32_32x32x16_bf16 v[2:17], v[98:101], v[126:129], v[2:17]
	v_mfma_f32_32x32x16_bf16 v[18:33], v[98:101], v[130:133], v[18:33]
	ds_read_b128 v[98:101], v68 offset:23136
	s_waitcnt lgkmcnt(1)
	v_mfma_f32_32x32x16_bf16 v[2:17], v[86:89], v[90:93], v[2:17]
	ds_read_b128 v[90:93], v1 offset:55360
	v_mfma_f32_32x32x16_bf16 v[18:33], v[86:89], v[94:97], v[18:33]
	ds_read_b128 v[86:89], v68 offset:18496
	ds_read_b128 v[94:97], v1 offset:59968
	s_waitcnt lgkmcnt(1)
	v_mfma_f32_32x32x16_bf16 v[34:49], v[86:89], v[90:93], v[34:49]
	s_waitcnt lgkmcnt(0)
	v_mfma_f32_32x32x16_bf16 v[50:65], v[86:89], v[94:97], v[50:65]
	ds_read_b128 v[86:89], v68 offset:23104
	s_waitcnt lgkmcnt(0)
	v_mfma_f32_32x32x16_bf16 v[2:17], v[86:89], v[90:93], v[2:17]
	ds_read_b128 v[90:93], v1 offset:55392
	v_mfma_f32_32x32x16_bf16 v[18:33], v[86:89], v[94:97], v[18:33]
	ds_read_b128 v[86:89], v68 offset:18528
	ds_read_b128 v[94:97], v1 offset:60000
	s_waitcnt lgkmcnt(1)
	v_mfma_f32_32x32x16_bf16 v[34:49], v[86:89], v[90:93], v[34:49]
	s_waitcnt lgkmcnt(0)
	v_mfma_f32_32x32x16_bf16 v[50:65], v[86:89], v[94:97], v[50:65]
	global_load_dwordx4 v[86:89], v[72:73], off offset:384
	v_mfma_f32_32x32x16_bf16 v[2:17], v[98:101], v[90:93], v[2:17]
	global_load_dwordx4 v[90:93], v[78:79], off offset:384
	v_mfma_f32_32x32x16_bf16 v[18:33], v[98:101], v[94:97], v[18:33]
	s_setprio 0
	s_barrier
	ds_read_b128 v[94:97], v68
	ds_read_b128 v[98:101], v68 offset:4608
	ds_read_b128 v[126:129], v1 offset:36864
	ds_read_b128 v[130:133], v1 offset:41472
	s_waitcnt vmcnt(1)
	ds_write_b128 v66, v[86:89] offset:18432
	ds_write_b128 v66, v[102:105] offset:23040
	ds_write_b128 v66, v[106:109] offset:27648
	ds_write_b128 v66, v[110:113] offset:32256
	s_waitcnt vmcnt(0)
	ds_write_b128 v66, v[90:93] offset:55296
	ds_write_b128 v66, v[122:125] offset:59904
	ds_write_b128 v66, v[118:121] offset:64512
	ds_write_b128 v69, v[114:117] offset:32256
	s_setprio 1
	ds_read_b128 v[86:89], v68 offset:32
	s_waitcnt lgkmcnt(10)
	v_mfma_f32_32x32x16_bf16 v[34:49], v[94:97], v[126:129], v[34:49]
	ds_read_b128 v[90:93], v1 offset:36896
	global_load_dwordx4 v[102:105], v[70:71], off offset:512
	global_load_dwordx4 v[106:109], v[74:75], off offset:512
	global_load_dwordx4 v[110:113], v[76:77], off offset:512
	global_load_dwordx4 v[114:117], v[84:85], off offset:512
	global_load_dwordx4 v[118:121], v[82:83], off offset:512
	global_load_dwordx4 v[122:125], v[80:81], off offset:512
	s_waitcnt lgkmcnt(10)
	v_mfma_f32_32x32x16_bf16 v[50:65], v[94:97], v[130:133], v[50:65]
	ds_read_b128 v[94:97], v1 offset:41504
	s_waitcnt lgkmcnt(1)
	v_mfma_f32_32x32x16_bf16 v[34:49], v[86:89], v[90:93], v[34:49]
	s_waitcnt lgkmcnt(0)
	v_mfma_f32_32x32x16_bf16 v[50:65], v[86:89], v[94:97], v[50:65]
	ds_read_b128 v[86:89], v68 offset:4640
	v_mfma_f32_32x32x16_bf16 v[2:17], v[98:101], v[126:129], v[2:17]
	v_mfma_f32_32x32x16_bf16 v[18:33], v[98:101], v[130:133], v[18:33]
	ds_read_b128 v[98:101], v68 offset:4704
	s_waitcnt lgkmcnt(1)
	v_mfma_f32_32x32x16_bf16 v[2:17], v[86:89], v[90:93], v[2:17]
	ds_read_b128 v[90:93], v1 offset:36928
	v_mfma_f32_32x32x16_bf16 v[18:33], v[86:89], v[94:97], v[18:33]
	ds_read_b128 v[86:89], v68 offset:64
	ds_read_b128 v[94:97], v1 offset:41536
	s_waitcnt lgkmcnt(1)
	v_mfma_f32_32x32x16_bf16 v[34:49], v[86:89], v[90:93], v[34:49]
	s_waitcnt lgkmcnt(0)
	v_mfma_f32_32x32x16_bf16 v[50:65], v[86:89], v[94:97], v[50:65]
	ds_read_b128 v[86:89], v68 offset:4672
	s_waitcnt lgkmcnt(0)
	v_mfma_f32_32x32x16_bf16 v[2:17], v[86:89], v[90:93], v[2:17]
	ds_read_b128 v[90:93], v1 offset:36960
	v_mfma_f32_32x32x16_bf16 v[18:33], v[86:89], v[94:97], v[18:33]
	ds_read_b128 v[86:89], v68 offset:96
	ds_read_b128 v[94:97], v1 offset:41568
	s_waitcnt lgkmcnt(1)
	v_mfma_f32_32x32x16_bf16 v[34:49], v[86:89], v[90:93], v[34:49]
	s_waitcnt lgkmcnt(0)
	v_mfma_f32_32x32x16_bf16 v[50:65], v[86:89], v[94:97], v[50:65]
	global_load_dwordx4 v[86:89], v[72:73], off offset:512
	v_mfma_f32_32x32x16_bf16 v[2:17], v[98:101], v[90:93], v[2:17]
	global_load_dwordx4 v[90:93], v[78:79], off offset:512
	v_mfma_f32_32x32x16_bf16 v[18:33], v[98:101], v[94:97], v[18:33]
	s_setprio 0
	s_barrier
; #define MFMA(a, b, c) __builtin_amdgcn_mfma_f32_32x32x16_bf16((a), (b), (c), 0, 0, 0)
; template <int TM, int TN>
; DI void gemm_mainloop(const u16* __restrict__ A, long lda, const u16* __restrict__ Bt, long ldb, int K, char* smem,
;                       f32x16 (&acc)[TM][TN]) {
;     ...
;   for (int kt = 0; kt < nk; kt++) {
;     const int buf = kt & 1;
;     const u16* cA = sA + buf * BM * LD + (wm * 32 * TM + r) * LD + h * 8;
;     const u16* cB = sB + buf * BN * LD + (wn * 32 * TN + r) * LD + h * 8;
;     bf16x8 af[TM], bfr[TN];
; #pragma unroll
;     for (int tm = 0; tm < TM; tm++) af[tm] = *(const bf16x8*)(cA + tm * 32 * LD);
; #pragma unroll
;     for (int tn = 0; tn < TN; tn++) bfr[tn] = *(const bf16x8*)(cB + tn * 32 * LD);
;     if (kt + 1 < nk) GEMM_SSTORE(buf ^ 1)
;     __builtin_amdgcn_sched_barrier(0);
;     __builtin_amdgcn_s_setprio(1);
; #pragma unroll
;     for (int tm = 0; tm < TM; tm++)
; #pragma unroll
;       for (int tn = 0; tn < TN; tn++) acc[tm][tn] = MFMA(af[tm], bfr[tn], acc[tm][tn]);
; #pragma unroll
;     for (int tm = 0; tm < TM; tm++) af[tm] = *(const bf16x8*)(cA + tm * 32 * LD + 16);
; #pragma unroll
;     for (int tn = 0; tn < TN; tn++) bfr[tn] = *(const bf16x8*)(cB + tn * 32 * LD + 16);
; #pragma unroll
;     for (int tm = 0; tm < TM; tm++)
; #pragma unroll
;       for (int tn = 0; tn < TN; tn++) acc[tm][tn] = MFMA(af[tm], bfr[tn], acc[tm][tn]);
;     __builtin_amdgcn_sched_group_barrier(0x8, 4, 0);
;     if (kt + 2 < nk) GEMM_GLOAD((kt + 2) * 64)
; #pragma unroll
;     for (int ks = 2; ks < 4; ks++) {
; #pragma unroll
;       for (int tm = 0; tm < TM; tm++) af[tm] = *(const bf16x8*)(cA + tm * 32 * LD + ks * 16);
; #pragma unroll
;       for (int tn = 0; tn < TN; tn++) bfr[tn] = *(const bf16x8*)(cB + tn * 32 * LD + ks * 16);
; #pragma unroll
;       for (int tm = 0; tm < TM; tm++)
; #pragma unroll
;         for (int tn = 0; tn < TN; tn++) acc[tm][tn] = MFMA(af[tm], bfr[tn], acc[tm][tn]);
;     }
;     __builtin_amdgcn_s_setprio(0);
;     __syncthreads();
;   }
	ds_read_b128 v[94:97], v68 offset:18432
	ds_read_b128 v[98:101], v68 offset:23040
	ds_read_b128 v[126:129], v1 offset:55296
	ds_read_b128 v[130:133], v1 offset:59904
	s_waitcnt vmcnt(1)
	ds_write_b128 v66, v[86:89]
	ds_write_b128 v66, v[102:105] offset:4608
	ds_write_b128 v66, v[106:109] offset:9216
	ds_write_b128 v66, v[110:113] offset:13824
	s_waitcnt vmcnt(0)
	ds_write_b128 v66, v[90:93] offset:36864
	ds_write_b128 v66, v[122:125] offset:41472
	ds_write_b128 v66, v[118:121] offset:46080
	ds_write_b128 v66, v[114:117] offset:50688
	s_setprio 1
	ds_read_b128 v[86:89], v68 offset:18464
	s_waitcnt lgkmcnt(10)
	v_mfma_f32_32x32x16_bf16 v[34:49], v[94:97], v[126:129], v[34:49]
	ds_read_b128 v[90:93], v1 offset:55328
	global_load_dwordx4 v[102:105], v[70:71], off offset:640
	global_load_dwordx4 v[106:109], v[74:75], off offset:640
	global_load_dwordx4 v[110:113], v[76:77], off offset:640
	global_load_dwordx4 v[114:117], v[84:85], off offset:640
	global_load_dwordx4 v[118:121], v[82:83], off offset:640
	global_load_dwordx4 v[122:125], v[80:81], off offset:640
	s_waitcnt lgkmcnt(10)
	v_mfma_f32_32x32x16_bf16 v[50:65], v[94:97], v[130:133], v[50:65]
	ds_read_b128 v[94:97], v1 offset:59936
	s_waitcnt lgkmcnt(1)
	v_mfma_f32_32x32x16_bf16 v[34:49], v[86:89], v[90:93], v[34:49]
	s_waitcnt lgkmcnt(0)
	v_mfma_f32_32x32x16_bf16 v[50:65], v[86:89], v[94:97], v[50:65]
	ds_read_b128 v[86:89], v68 offset:23072
	v_mfma_f32_32x32x16_bf16 v[2:17], v[98:101], v[126:129], v[2:17]
	v_mfma_f32_32x32x16_bf16 v[18:33], v[98:101], v[130:133], v[18:33]
	ds_read_b128 v[98:101], v68 offset:23136
	s_waitcnt lgkmcnt(1)
	v_mfma_f32_32x32x16_bf16 v[2:17], v[86:89], v[90:93], v[2:17]
	ds_read_b128 v[90:93], v1 offset:55360
	v_mfma_f32_32x32x16_bf16 v[18:33], v[86:89], v[94:97], v[18:33]
	ds_read_b128 v[86:89], v68 offset:18496
	ds_read_b128 v[94:97], v1 offset:59968
	s_waitcnt lgkmcnt(1)
	v_mfma_f32_32x32x16_bf16 v[34:49], v[86:89], v[90:93], v[34:49]
	s_waitcnt lgkmcnt(0)
	v_mfma_f32_32x32x16_bf16 v[50:65], v[86:89], v[94:97], v[50:65]
	ds_read_b128 v[86:89], v68 offset:23104
	s_waitcnt lgkmcnt(0)
	v_mfma_f32_32x32x16_bf16 v[2:17], v[86:89], v[90:93], v[2:17]
	ds_read_b128 v[90:93], v1 offset:55392
	v_mfma_f32_32x32x16_bf16 v[18:33], v[86:89], v[94:97], v[18:33]
	ds_read_b128 v[86:89], v68 offset:18528
	ds_read_b128 v[94:97], v1 offset:60000
	s_waitcnt lgkmcnt(1)
	v_mfma_f32_32x32x16_bf16 v[34:49], v[86:89], v[90:93], v[34:49]
	s_waitcnt lgkmcnt(0)
	v_mfma_f32_32x32x16_bf16 v[50:65], v[86:89], v[94:97], v[50:65]
	global_load_dwordx4 v[86:89], v[72:73], off offset:640
	v_mfma_f32_32x32x16_bf16 v[2:17], v[98:101], v[90:93], v[2:17]
	global_load_dwordx4 v[90:93], v[78:79], off offset:640
	v_mfma_f32_32x32x16_bf16 v[18:33], v[98:101], v[94:97], v[18:33]
	s_setprio 0
	s_barrier
	ds_read_b128 v[94:97], v68
	ds_read_b128 v[98:101], v68 offset:4608
	ds_read_b128 v[126:129], v1 offset:36864
	ds_read_b128 v[130:133], v1 offset:41472
	s_waitcnt vmcnt(1)
	ds_write_b128 v66, v[86:89] offset:18432
	ds_write_b128 v66, v[102:105] offset:23040
	ds_write_b128 v66, v[106:109] offset:27648
	ds_write_b128 v66, v[110:113] offset:32256
	s_waitcnt vmcnt(0)
	ds_write_b128 v66, v[90:93] offset:55296
	ds_write_b128 v66, v[122:125] offset:59904
	ds_write_b128 v66, v[118:121] offset:64512
	ds_write_b128 v69, v[114:117] offset:32256
	s_setprio 1
	ds_read_b128 v[86:89], v68 offset:32
	s_waitcnt lgkmcnt(10)
	v_mfma_f32_32x32x16_bf16 v[34:49], v[94:97], v[126:129], v[34:49]
	ds_read_b128 v[90:93], v1 offset:36896
	global_load_dwordx4 v[102:105], v[70:71], off offset:768
	global_load_dwordx4 v[106:109], v[74:75], off offset:768
	global_load_dwordx4 v[110:113], v[76:77], off offset:768
	global_load_dwordx4 v[114:117], v[84:85], off offset:768
	global_load_dwordx4 v[118:121], v[82:83], off offset:768
	global_load_dwordx4 v[122:125], v[80:81], off offset:768
	s_waitcnt lgkmcnt(10)
	v_mfma_f32_32x32x16_bf16 v[50:65], v[94:97], v[130:133], v[50:65]
	ds_read_b128 v[94:97], v1 offset:41504
	s_waitcnt lgkmcnt(1)
	v_mfma_f32_32x32x16_bf16 v[34:49], v[86:89], v[90:93], v[34:49]
	s_waitcnt lgkmcnt(0)
	v_mfma_f32_32x32x16_bf16 v[50:65], v[86:89], v[94:97], v[50:65]
	ds_read_b128 v[86:89], v68 offset:4640
	v_mfma_f32_32x32x16_bf16 v[2:17], v[98:101], v[126:129], v[2:17]
	v_mfma_f32_32x32x16_bf16 v[18:33], v[98:101], v[130:133], v[18:33]
	ds_read_b128 v[98:101], v68 offset:4704
	s_waitcnt lgkmcnt(1)
	v_mfma_f32_32x32x16_bf16 v[2:17], v[86:89], v[90:93], v[2:17]
	ds_read_b128 v[90:93], v1 offset:36928
	v_mfma_f32_32x32x16_bf16 v[18:33], v[86:89], v[94:97], v[18:33]
	ds_read_b128 v[86:89], v68 offset:64
	ds_read_b128 v[94:97], v1 offset:41536
	s_waitcnt lgkmcnt(1)
	v_mfma_f32_32x32x16_bf16 v[34:49], v[86:89], v[90:93], v[34:49]
	s_waitcnt lgkmcnt(0)
	v_mfma_f32_32x32x16_bf16 v[50:65], v[86:89], v[94:97], v[50:65]
	ds_read_b128 v[86:89], v68 offset:4672
	s_waitcnt lgkmcnt(0)
	v_mfma_f32_32x32x16_bf16 v[2:17], v[86:89], v[90:93], v[2:17]
	ds_read_b128 v[90:93], v1 offset:36960
	v_mfma_f32_32x32x16_bf16 v[18:33], v[86:89], v[94:97], v[18:33]
	ds_read_b128 v[86:89], v68 offset:96
	ds_read_b128 v[94:97], v1 offset:41568
	s_waitcnt lgkmcnt(1)
	v_mfma_f32_32x32x16_bf16 v[34:49], v[86:89], v[90:93], v[34:49]
	s_waitcnt lgkmcnt(0)
	v_mfma_f32_32x32x16_bf16 v[50:65], v[86:89], v[94:97], v[50:65]
	global_load_dwordx4 v[86:89], v[72:73], off offset:768
	v_mfma_f32_32x32x16_bf16 v[2:17], v[98:101], v[90:93], v[2:17]
	global_load_dwordx4 v[90:93], v[78:79], off offset:768
	v_mfma_f32_32x32x16_bf16 v[18:33], v[98:101], v[94:97], v[18:33]
	s_setprio 0
	s_barrier
; #define MFMA(a, b, c) __builtin_amdgcn_mfma_f32_32x32x16_bf16((a), (b), (c), 0, 0, 0)
; template <int TM, int TN>
; DI void gemm_mainloop(const u16* __restrict__ A, long lda, const u16* __restrict__ Bt, long ldb, int K, char* smem,
;                       f32x16 (&acc)[TM][TN]) {
;     ...
;   for (int kt = 0; kt < nk; kt++) {
;     const int buf = kt & 1;
;     const u16* cA = sA + buf * BM * LD + (wm * 32 * TM + r) * LD + h * 8;
;     const u16* cB = sB + buf * BN * LD + (wn * 32 * TN + r) * LD + h * 8;
;     bf16x8 af[TM], bfr[TN];
; #pragma unroll
;     for (int tm = 0; tm < TM; tm++) af[tm] = *(const bf16x8*)(cA + tm * 32 * LD);
; #pragma unroll
;     for (int tn = 0; tn < TN; tn++) bfr[tn] = *(const bf16x8*)(cB + tn * 32 * LD);
;     if (kt + 1 < nk) GEMM_SSTORE(buf ^ 1)
;     __builtin_amdgcn_sched_barrier(0);
;     __builtin_amdgcn_s_setprio(1);
; #pragma unroll
;     for (int tm = 0; tm < TM; tm++)
; #pragma unroll
;       for (int tn = 0; tn < TN; tn++) acc[tm][tn] = MFMA(af[tm], bfr[tn], acc[tm][tn]);
; #pragma unroll
;     for (int tm = 0; tm < TM; tm++) af[tm] = *(const bf16x8*)(cA + tm * 32 * LD + 16);
; #pragma unroll
;     for (int tn = 0; tn < TN; tn++) bfr[tn] = *(const bf16x8*)(cB + tn * 32 * LD + 16);
; #pragma unroll
;     for (int tm = 0; tm < TM; tm++)
; #pragma unroll
;       for (int tn = 0; tn < TN; tn++) acc[tm][tn] = MFMA(af[tm], bfr[tn], acc[tm][tn]);
;     __builtin_amdgcn_sched_group_barrier(0x8, 4, 0);
;     if (kt + 2 < nk) GEMM_GLOAD((kt + 2) * 64)
; #pragma unroll
;     for (int ks = 2; ks < 4; ks++) {
; #pragma unroll
;       for (int tm = 0; tm < TM; tm++) af[tm] = *(const bf16x8*)(cA + tm * 32 * LD + ks * 16);
; #pragma unroll
;       for (int tn = 0; tn < TN; tn++) bfr[tn] = *(const bf16x8*)(cB + tn * 32 * LD + ks * 16);
; #pragma unroll
;       for (int tm = 0; tm < TM; tm++)
; #pragma unroll
;         for (int tn = 0; tn < TN; tn++) acc[tm][tn] = MFMA(af[tm], bfr[tn], acc[tm][tn]);
;     }
;     __builtin_amdgcn_s_setprio(0);
;     __syncthreads();
;   }
	ds_read_b128 v[94:97], v68 offset:18432
	ds_read_b128 v[98:101], v68 offset:23040
	ds_read_b128 v[126:129], v1 offset:55296
	ds_read_b128 v[130:133], v1 offset:59904
	s_waitcnt vmcnt(1)
	ds_write_b128 v66, v[86:89]
	ds_write_b128 v66, v[102:105] offset:4608
	ds_write_b128 v66, v[106:109] offset:9216
	ds_write_b128 v66, v[110:113] offset:13824
	s_waitcnt vmcnt(0)
	ds_write_b128 v66, v[90:93] offset:36864
	ds_write_b128 v66, v[122:125] offset:41472
	ds_write_b128 v66, v[118:121] offset:46080
	ds_write_b128 v66, v[114:117] offset:50688
	s_setprio 1
	ds_read_b128 v[86:89], v68 offset:18464
	s_waitcnt lgkmcnt(10)
	v_mfma_f32_32x32x16_bf16 v[34:49], v[94:97], v[126:129], v[34:49]
	ds_read_b128 v[90:93], v1 offset:55328
	global_load_dwordx4 v[102:105], v[70:71], off offset:896
	global_load_dwordx4 v[106:109], v[74:75], off offset:896
	global_load_dwordx4 v[110:113], v[76:77], off offset:896
	global_load_dwordx4 v[114:117], v[84:85], off offset:896
	global_load_dwordx4 v[118:121], v[82:83], off offset:896
	global_load_dwordx4 v[122:125], v[80:81], off offset:896
	s_waitcnt lgkmcnt(10)
	v_mfma_f32_32x32x16_bf16 v[50:65], v[94:97], v[130:133], v[50:65]
	ds_read_b128 v[94:97], v1 offset:59936
	s_waitcnt lgkmcnt(1)
	v_mfma_f32_32x32x16_bf16 v[34:49], v[86:89], v[90:93], v[34:49]
	s_waitcnt lgkmcnt(0)
	v_mfma_f32_32x32x16_bf16 v[50:65], v[86:89], v[94:97], v[50:65]
	ds_read_b128 v[86:89], v68 offset:23072
	v_mfma_f32_32x32x16_bf16 v[2:17], v[98:101], v[126:129], v[2:17]
	v_mfma_f32_32x32x16_bf16 v[18:33], v[98:101], v[130:133], v[18:33]
	ds_read_b128 v[98:101], v68 offset:23136
	s_waitcnt lgkmcnt(1)
	v_mfma_f32_32x32x16_bf16 v[2:17], v[86:89], v[90:93], v[2:17]
	ds_read_b128 v[90:93], v1 offset:55360
	v_mfma_f32_32x32x16_bf16 v[18:33], v[86:89], v[94:97], v[18:33]
	ds_read_b128 v[86:89], v68 offset:18496
	ds_read_b128 v[94:97], v1 offset:59968
	s_waitcnt lgkmcnt(1)
	v_mfma_f32_32x32x16_bf16 v[34:49], v[86:89], v[90:93], v[34:49]
	s_waitcnt lgkmcnt(0)
	v_mfma_f32_32x32x16_bf16 v[50:65], v[86:89], v[94:97], v[50:65]
	ds_read_b128 v[86:89], v68 offset:23104
	s_waitcnt lgkmcnt(0)
	v_mfma_f32_32x32x16_bf16 v[2:17], v[86:89], v[90:93], v[2:17]
	ds_read_b128 v[90:93], v1 offset:55392
	v_mfma_f32_32x32x16_bf16 v[18:33], v[86:89], v[94:97], v[18:33]
	ds_read_b128 v[86:89], v68 offset:18528
	ds_read_b128 v[94:97], v1 offset:60000
	s_waitcnt lgkmcnt(1)
	v_mfma_f32_32x32x16_bf16 v[34:49], v[86:89], v[90:93], v[34:49]
	s_waitcnt lgkmcnt(0)
	v_mfma_f32_32x32x16_bf16 v[50:65], v[86:89], v[94:97], v[50:65]
	global_load_dwordx4 v[86:89], v[72:73], off offset:896
	v_mfma_f32_32x32x16_bf16 v[2:17], v[98:101], v[90:93], v[2:17]
	global_load_dwordx4 v[90:93], v[78:79], off offset:896
	v_mfma_f32_32x32x16_bf16 v[18:33], v[98:101], v[94:97], v[18:33]
	s_setprio 0
	s_barrier
	ds_read_b128 v[94:97], v68
	ds_read_b128 v[98:101], v68 offset:4608
	ds_read_b128 v[126:129], v1 offset:36864
	ds_read_b128 v[130:133], v1 offset:41472
	s_waitcnt vmcnt(1)
	ds_write_b128 v66, v[86:89] offset:18432
	ds_write_b128 v66, v[102:105] offset:23040
	ds_write_b128 v66, v[106:109] offset:27648
	ds_write_b128 v66, v[110:113] offset:32256
	s_waitcnt vmcnt(0)
	ds_write_b128 v66, v[90:93] offset:55296
	ds_write_b128 v66, v[122:125] offset:59904
	ds_write_b128 v66, v[118:121] offset:64512
	ds_write_b128 v69, v[114:117] offset:32256
	s_setprio 1
	ds_read_b128 v[86:89], v68 offset:32
	s_waitcnt lgkmcnt(10)
	v_mfma_f32_32x32x16_bf16 v[34:49], v[94:97], v[126:129], v[34:49]
	ds_read_b128 v[90:93], v1 offset:36896
	global_load_dwordx4 v[102:105], v[70:71], off offset:1024
	global_load_dwordx4 v[106:109], v[74:75], off offset:1024
	global_load_dwordx4 v[110:113], v[76:77], off offset:1024
	global_load_dwordx4 v[114:117], v[84:85], off offset:1024
	global_load_dwordx4 v[118:121], v[82:83], off offset:1024
	global_load_dwordx4 v[122:125], v[80:81], off offset:1024
	s_waitcnt lgkmcnt(10)
	v_mfma_f32_32x32x16_bf16 v[50:65], v[94:97], v[130:133], v[50:65]
	ds_read_b128 v[94:97], v1 offset:41504
	s_waitcnt lgkmcnt(1)
	v_mfma_f32_32x32x16_bf16 v[34:49], v[86:89], v[90:93], v[34:49]
	s_waitcnt lgkmcnt(0)
	v_mfma_f32_32x32x16_bf16 v[50:65], v[86:89], v[94:97], v[50:65]
	ds_read_b128 v[86:89], v68 offset:4640
	v_mfma_f32_32x32x16_bf16 v[2:17], v[98:101], v[126:129], v[2:17]
	v_mfma_f32_32x32x16_bf16 v[18:33], v[98:101], v[130:133], v[18:33]
	ds_read_b128 v[98:101], v68 offset:4704
	s_waitcnt lgkmcnt(1)
	v_mfma_f32_32x32x16_bf16 v[2:17], v[86:89], v[90:93], v[2:17]
	ds_read_b128 v[90:93], v1 offset:36928
	v_mfma_f32_32x32x16_bf16 v[18:33], v[86:89], v[94:97], v[18:33]
	ds_read_b128 v[86:89], v68 offset:64
	ds_read_b128 v[94:97], v1 offset:41536
	s_waitcnt lgkmcnt(1)
	v_mfma_f32_32x32x16_bf16 v[34:49], v[86:89], v[90:93], v[34:49]
	s_waitcnt lgkmcnt(0)
	v_mfma_f32_32x32x16_bf16 v[50:65], v[86:89], v[94:97], v[50:65]
	ds_read_b128 v[86:89], v68 offset:4672
	s_waitcnt lgkmcnt(0)
	v_mfma_f32_32x32x16_bf16 v[2:17], v[86:89], v[90:93], v[2:17]
	ds_read_b128 v[90:93], v1 offset:36960
	v_mfma_f32_32x32x16_bf16 v[18:33], v[86:89], v[94:97], v[18:33]
	ds_read_b128 v[86:89], v68 offset:96
	ds_read_b128 v[94:97], v1 offset:41568
	s_waitcnt lgkmcnt(1)
	v_mfma_f32_32x32x16_bf16 v[34:49], v[86:89], v[90:93], v[34:49]
	s_waitcnt lgkmcnt(0)
	v_mfma_f32_32x32x16_bf16 v[50:65], v[86:89], v[94:97], v[50:65]
	global_load_dwordx4 v[86:89], v[72:73], off offset:1024
	v_mfma_f32_32x32x16_bf16 v[2:17], v[98:101], v[90:93], v[2:17]
	global_load_dwordx4 v[90:93], v[78:79], off offset:1024
	v_mfma_f32_32x32x16_bf16 v[18:33], v[98:101], v[94:97], v[18:33]
	s_setprio 0
	s_barrier
; #define MFMA(a, b, c) __builtin_amdgcn_mfma_f32_32x32x16_bf16((a), (b), (c), 0, 0, 0)
; template <int TM, int TN>
; DI void gemm_mainloop(const u16* __restrict__ A, long lda, const u16* __restrict__ Bt, long ldb, int K, char* smem,
;                       f32x16 (&acc)[TM][TN]) {
;     ...
;   for (int kt = 0; kt < nk; kt++) {
;     const int buf = kt & 1;
;     const u16* cA = sA + buf * BM * LD + (wm * 32 * TM + r) * LD + h * 8;
;     const u16* cB = sB + buf * BN * LD + (wn * 32 * TN + r) * LD + h * 8;
;     bf16x8 af[TM], bfr[TN];
; #pragma unroll
;     for (int tm = 0; tm < TM; tm++) af[tm] = *(const bf16x8*)(cA + tm * 32 * LD);
; #pragma unroll
;     for (int tn = 0; tn < TN; tn++) bfr[tn] = *(const bf16x8*)(cB + tn * 32 * LD);
;     if (kt + 1 < nk) GEMM_SSTORE(buf ^ 1)
;     __builtin_amdgcn_sched_barrier(0);
;     __builtin_amdgcn_s_setprio(1);
; #pragma unroll
;     for (int tm = 0; tm < TM; tm++)
; #pragma unroll
;       for (int tn = 0; tn < TN; tn++) acc[tm][tn] = MFMA(af[tm], bfr[tn], acc[tm][tn]);
; #pragma unroll
;     for (int tm = 0; tm < TM; tm++) af[tm] = *(const bf16x8*)(cA + tm * 32 * LD + 16);
; #pragma unroll
;     for (int tn = 0; tn < TN; tn++) bfr[tn] = *(const bf16x8*)(cB + tn * 32 * LD + 16);
; #pragma unroll
;     for (int tm = 0; tm < TM; tm++)
; #pragma unroll
;       for (int tn = 0; tn < TN; tn++) acc[tm][tn] = MFMA(af[tm], bfr[tn], acc[tm][tn]);
;     __builtin_amdgcn_sched_group_barrier(0x8, 4, 0);
;     if (kt + 2 < nk) GEMM_GLOAD((kt + 2) * 64)
; #pragma unroll
;     for (int ks = 2; ks < 4; ks++) {
; #pragma unroll
;       for (int tm = 0; tm < TM; tm++) af[tm] = *(const bf16x8*)(cA + tm * 32 * LD + ks * 16);
; #pragma unroll
;       for (int tn = 0; tn < TN; tn++) bfr[tn] = *(const bf16x8*)(cB + tn * 32 * LD + ks * 16);
; #pragma unroll
;       for (int tm = 0; tm < TM; tm++)
; #pragma unroll
;         for (int tn = 0; tn < TN; tn++) acc[tm][tn] = MFMA(af[tm], bfr[tn], acc[tm][tn]);
;     }
;     __builtin_amdgcn_s_setprio(0);
;     __syncthreads();
	ds_read_b128 v[94:97], v68 offset:18432
	ds_read_b128 v[98:101], v68 offset:23040
	ds_read_b128 v[126:129], v1 offset:55296
	ds_read_b128 v[130:133], v1 offset:59904
	s_waitcnt vmcnt(1)
	ds_write_b128 v66, v[86:89]
	ds_write_b128 v66, v[102:105] offset:4608
	ds_write_b128 v66, v[106:109] offset:9216
	ds_write_b128 v66, v[110:113] offset:13824
	s_waitcnt vmcnt(0)
	ds_write_b128 v66, v[90:93] offset:36864
	ds_write_b128 v66, v[122:125] offset:41472
	ds_write_b128 v66, v[118:121] offset:46080
	ds_write_b128 v66, v[114:117] offset:50688
	s_setprio 1
	ds_read_b128 v[86:89], v68 offset:18464
	s_waitcnt lgkmcnt(10)
	v_mfma_f32_32x32x16_bf16 v[34:49], v[94:97], v[126:129], v[34:49]
	ds_read_b128 v[90:93], v1 offset:55328
	global_load_dwordx4 v[102:105], v[70:71], off offset:1152
	global_load_dwordx4 v[106:109], v[74:75], off offset:1152
	global_load_dwordx4 v[110:113], v[76:77], off offset:1152
	global_load_dwordx4 v[114:117], v[84:85], off offset:1152
	global_load_dwordx4 v[118:121], v[82:83], off offset:1152
	global_load_dwordx4 v[122:125], v[80:81], off offset:1152
	s_waitcnt lgkmcnt(10)
	v_mfma_f32_32x32x16_bf16 v[50:65], v[94:97], v[130:133], v[50:65]
	ds_read_b128 v[94:97], v1 offset:59936
	s_waitcnt lgkmcnt(1)
	v_mfma_f32_32x32x16_bf16 v[34:49], v[86:89], v[90:93], v[34:49]
	s_waitcnt lgkmcnt(0)
	v_mfma_f32_32x32x16_bf16 v[50:65], v[86:89], v[94:97], v[50:65]
	ds_read_b128 v[86:89], v68 offset:23072
	v_mfma_f32_32x32x16_bf16 v[2:17], v[98:101], v[126:129], v[2:17]
	v_mfma_f32_32x32x16_bf16 v[18:33], v[98:101], v[130:133], v[18:33]
	ds_read_b128 v[98:101], v68 offset:23136
	s_waitcnt lgkmcnt(1)
	v_mfma_f32_32x32x16_bf16 v[2:17], v[86:89], v[90:93], v[2:17]
	ds_read_b128 v[90:93], v1 offset:55360
	v_mfma_f32_32x32x16_bf16 v[18:33], v[86:89], v[94:97], v[18:33]
	ds_read_b128 v[86:89], v68 offset:18496
	ds_read_b128 v[94:97], v1 offset:59968
	s_waitcnt lgkmcnt(1)
	v_mfma_f32_32x32x16_bf16 v[34:49], v[86:89], v[90:93], v[34:49]
	s_waitcnt lgkmcnt(0)
	v_mfma_f32_32x32x16_bf16 v[50:65], v[86:89], v[94:97], v[50:65]
	ds_read_b128 v[86:89], v68 offset:23104
	s_waitcnt lgkmcnt(0)
	v_mfma_f32_32x32x16_bf16 v[2:17], v[86:89], v[90:93], v[2:17]
	ds_read_b128 v[90:93], v1 offset:55392
	v_mfma_f32_32x32x16_bf16 v[18:33], v[86:89], v[94:97], v[18:33]
	ds_read_b128 v[86:89], v68 offset:18528
	ds_read_b128 v[94:97], v1 offset:60000
	s_waitcnt lgkmcnt(1)
	v_mfma_f32_32x32x16_bf16 v[34:49], v[86:89], v[90:93], v[34:49]
	s_waitcnt lgkmcnt(0)
	v_mfma_f32_32x32x16_bf16 v[50:65], v[86:89], v[94:97], v[50:65]
	global_load_dwordx4 v[86:89], v[72:73], off offset:1152
	v_mfma_f32_32x32x16_bf16 v[2:17], v[98:101], v[90:93], v[2:17]
	global_load_dwordx4 v[90:93], v[78:79], off offset:1152
	v_mfma_f32_32x32x16_bf16 v[18:33], v[98:101], v[94:97], v[18:33]
	s_setprio 0
	s_barrier
	ds_read_b128 v[94:97], v68
	ds_read_b128 v[98:101], v68 offset:4608
	ds_read_b128 v[126:129], v1 offset:36864
	ds_read_b128 v[130:133], v1 offset:41472
	s_waitcnt vmcnt(1)
	ds_write_b128 v66, v[86:89] offset:18432
	ds_write_b128 v66, v[102:105] offset:23040
	ds_write_b128 v66, v[106:109] offset:27648
	ds_write_b128 v66, v[110:113] offset:32256
	s_waitcnt vmcnt(0)
	ds_write_b128 v66, v[90:93] offset:55296
	ds_write_b128 v66, v[122:125] offset:59904
	ds_write_b128 v66, v[118:121] offset:64512
	ds_write_b128 v69, v[114:117] offset:32256
	s_setprio 1
	ds_read_b128 v[86:89], v68 offset:32
	s_waitcnt lgkmcnt(10)
	v_mfma_f32_32x32x16_bf16 v[34:49], v[94:97], v[126:129], v[34:49]
	ds_read_b128 v[90:93], v1 offset:36896
	global_load_dwordx4 v[102:105], v[70:71], off offset:1280
	global_load_dwordx4 v[106:109], v[74:75], off offset:1280
	global_load_dwordx4 v[110:113], v[76:77], off offset:1280
	global_load_dwordx4 v[114:117], v[84:85], off offset:1280
	global_load_dwordx4 v[118:121], v[82:83], off offset:1280
	global_load_dwordx4 v[122:125], v[80:81], off offset:1280
	s_waitcnt lgkmcnt(10)
	v_mfma_f32_32x32x16_bf16 v[50:65], v[94:97], v[130:133], v[50:65]
	ds_read_b128 v[94:97], v1 offset:41504
	s_waitcnt lgkmcnt(1)
	v_mfma_f32_32x32x16_bf16 v[34:49], v[86:89], v[90:93], v[34:49]
	s_waitcnt lgkmcnt(0)
	v_mfma_f32_32x32x16_bf16 v[50:65], v[86:89], v[94:97], v[50:65]
	ds_read_b128 v[86:89], v68 offset:4640
	v_mfma_f32_32x32x16_bf16 v[2:17], v[98:101], v[126:129], v[2:17]
	v_mfma_f32_32x32x16_bf16 v[18:33], v[98:101], v[130:133], v[18:33]
	ds_read_b128 v[98:101], v68 offset:4704
	s_waitcnt lgkmcnt(1)
	v_mfma_f32_32x32x16_bf16 v[2:17], v[86:89], v[90:93], v[2:17]
	ds_read_b128 v[90:93], v1 offset:36928
	v_mfma_f32_32x32x16_bf16 v[18:33], v[86:89], v[94:97], v[18:33]
	ds_read_b128 v[86:89], v68 offset:64
	ds_read_b128 v[94:97], v1 offset:41536
	s_waitcnt lgkmcnt(1)
	v_mfma_f32_32x32x16_bf16 v[34:49], v[86:89], v[90:93], v[34:49]
	s_waitcnt lgkmcnt(0)
	v_mfma_f32_32x32x16_bf16 v[50:65], v[86:89], v[94:97], v[50:65]
	ds_read_b128 v[86:89], v68 offset:4672
	s_waitcnt lgkmcnt(0)
	v_mfma_f32_32x32x16_bf16 v[2:17], v[86:89], v[90:93], v[2:17]
	ds_read_b128 v[90:93], v1 offset:36960
	v_mfma_f32_32x32x16_bf16 v[18:33], v[86:89], v[94:97], v[18:33]
	ds_read_b128 v[86:89], v68 offset:96
	ds_read_b128 v[94:97], v1 offset:41568
	s_waitcnt lgkmcnt(1)
	v_mfma_f32_32x32x16_bf16 v[34:49], v[86:89], v[90:93], v[34:49]
	s_waitcnt lgkmcnt(0)
	v_mfma_f32_32x32x16_bf16 v[50:65], v[86:89], v[94:97], v[50:65]
	global_load_dwordx4 v[86:89], v[72:73], off offset:1280
	v_mfma_f32_32x32x16_bf16 v[2:17], v[98:101], v[90:93], v[2:17]
	global_load_dwordx4 v[90:93], v[78:79], off offset:1280
	v_mfma_f32_32x32x16_bf16 v[18:33], v[98:101], v[94:97], v[18:33]
	s_setprio 0
	s_barrier
; #define MFMA(a, b, c) __builtin_amdgcn_mfma_f32_32x32x16_bf16((a), (b), (c), 0, 0, 0)
; template <int TM, int TN>
; DI void gemm_mainloop(const u16* __restrict__ A, long lda, const u16* __restrict__ Bt, long ldb, int K, char* smem,
;                       f32x16 (&acc)[TM][TN]) {
;     ...
;   for (int kt = 0; kt < nk; kt++) {
;     const int buf = kt & 1;
;     const u16* cA = sA + buf * BM * LD + (wm * 32 * TM + r) * LD + h * 8;
;     const u16* cB = sB + buf * BN * LD + (wn * 32 * TN + r) * LD + h * 8;
;     bf16x8 af[TM], bfr[TN];
; #pragma unroll
;     for (int tm = 0; tm < TM; tm++) af[tm] = *(const bf16x8*)(cA + tm * 32 * LD);
; #pragma unroll
;     for (int tn = 0; tn < TN; tn++) bfr[tn] = *(const bf16x8*)(cB + tn * 32 * LD);
;     if (kt + 1 < nk) GEMM_SSTORE(buf ^ 1)
;     __builtin_amdgcn_sched_barrier(0);
;     __builtin_amdgcn_s_setprio(1);
; #pragma unroll
;     for (int tm = 0; tm < TM; tm++)
; #pragma unroll
;       for (int tn = 0; tn < TN; tn++) acc[tm][tn] = MFMA(af[tm], bfr[tn], acc[tm][tn]);
; #pragma unroll
;     for (int tm = 0; tm < TM; tm++) af[tm] = *(const bf16x8*)(cA + tm * 32 * LD + 16);
; #pragma unroll
;     for (int tn = 0; tn < TN; tn++) bfr[tn] = *(const bf16x8*)(cB + tn * 32 * LD + 16);
; #pragma unroll
;     for (int tm = 0; tm < TM; tm++)
; #pragma unroll
;       for (int tn = 0; tn < TN; tn++) acc[tm][tn] = MFMA(af[tm], bfr[tn], acc[tm][tn]);
;     __builtin_amdgcn_sched_group_barrier(0x8, 4, 0);
;     if (kt + 2 < nk) GEMM_GLOAD((kt + 2) * 64)
; #pragma unroll
;     for (int ks = 2; ks < 4; ks++) {
; #pragma unroll
;       for (int tm = 0; tm < TM; tm++) af[tm] = *(const bf16x8*)(cA + tm * 32 * LD + ks * 16);
; #pragma unroll
;       for (int tn = 0; tn < TN; tn++) bfr[tn] = *(const bf16x8*)(cB + tn * 32 * LD + ks * 16);
; #pragma unroll
;       for (int tm = 0; tm < TM; tm++)
; #pragma unroll
;         for (int tn = 0; tn < TN; tn++) acc[tm][tn] = MFMA(af[tm], bfr[tn], acc[tm][tn]);
;     }
;     __builtin_amdgcn_s_setprio(0);
;     __syncthreads();
	ds_read_b128 v[94:97], v68 offset:18432
	ds_read_b128 v[98:101], v68 offset:23040
	ds_read_b128 v[126:129], v1 offset:55296
	ds_read_b128 v[130:133], v1 offset:59904
	s_waitcnt vmcnt(1)
	ds_write_b128 v66, v[86:89]
	ds_write_b128 v66, v[102:105] offset:4608
	ds_write_b128 v66, v[106:109] offset:9216
	ds_write_b128 v66, v[110:113] offset:13824
	s_waitcnt vmcnt(0)
	ds_write_b128 v66, v[90:93] offset:36864
	ds_write_b128 v66, v[122:125] offset:41472
	ds_write_b128 v66, v[118:121] offset:46080
	ds_write_b128 v66, v[114:117] offset:50688
	s_setprio 1
	ds_read_b128 v[86:89], v68 offset:18464
	s_waitcnt lgkmcnt(10)
	v_mfma_f32_32x32x16_bf16 v[34:49], v[94:97], v[126:129], v[34:49]
	ds_read_b128 v[90:93], v1 offset:55328
	global_load_dwordx4 v[102:105], v[70:71], off offset:1408
	global_load_dwordx4 v[106:109], v[74:75], off offset:1408
	global_load_dwordx4 v[110:113], v[76:77], off offset:1408
	global_load_dwordx4 v[114:117], v[84:85], off offset:1408
	global_load_dwordx4 v[118:121], v[82:83], off offset:1408
	global_load_dwordx4 v[122:125], v[80:81], off offset:1408
	s_waitcnt lgkmcnt(10)
	v_mfma_f32_32x32x16_bf16 v[50:65], v[94:97], v[130:133], v[50:65]
	ds_read_b128 v[94:97], v1 offset:59936
	s_waitcnt lgkmcnt(1)
	v_mfma_f32_32x32x16_bf16 v[34:49], v[86:89], v[90:93], v[34:49]
	s_waitcnt lgkmcnt(0)
	v_mfma_f32_32x32x16_bf16 v[50:65], v[86:89], v[94:97], v[50:65]
	ds_read_b128 v[86:89], v68 offset:23072
	v_mfma_f32_32x32x16_bf16 v[2:17], v[98:101], v[126:129], v[2:17]
	v_mfma_f32_32x32x16_bf16 v[18:33], v[98:101], v[130:133], v[18:33]
	ds_read_b128 v[98:101], v68 offset:23136
	s_waitcnt lgkmcnt(1)
	v_mfma_f32_32x32x16_bf16 v[2:17], v[86:89], v[90:93], v[2:17]
	ds_read_b128 v[90:93], v1 offset:55360
	v_mfma_f32_32x32x16_bf16 v[18:33], v[86:89], v[94:97], v[18:33]
	ds_read_b128 v[86:89], v68 offset:18496
	ds_read_b128 v[94:97], v1 offset:59968
	s_waitcnt lgkmcnt(1)
	v_mfma_f32_32x32x16_bf16 v[34:49], v[86:89], v[90:93], v[34:49]
	s_waitcnt lgkmcnt(0)
	v_mfma_f32_32x32x16_bf16 v[50:65], v[86:89], v[94:97], v[50:65]
	ds_read_b128 v[86:89], v68 offset:23104
	s_waitcnt lgkmcnt(0)
	v_mfma_f32_32x32x16_bf16 v[2:17], v[86:89], v[90:93], v[2:17]
	ds_read_b128 v[90:93], v1 offset:55392
	v_mfma_f32_32x32x16_bf16 v[18:33], v[86:89], v[94:97], v[18:33]
	ds_read_b128 v[86:89], v68 offset:18528
	ds_read_b128 v[94:97], v1 offset:60000
	s_waitcnt lgkmcnt(1)
	v_mfma_f32_32x32x16_bf16 v[34:49], v[86:89], v[90:93], v[34:49]
	s_waitcnt lgkmcnt(0)
	v_mfma_f32_32x32x16_bf16 v[50:65], v[86:89], v[94:97], v[50:65]
	global_load_dwordx4 v[86:89], v[72:73], off offset:1408
	v_mfma_f32_32x32x16_bf16 v[2:17], v[98:101], v[90:93], v[2:17]
	global_load_dwordx4 v[90:93], v[78:79], off offset:1408
	v_mfma_f32_32x32x16_bf16 v[18:33], v[98:101], v[94:97], v[18:33]
	s_setprio 0
	s_barrier
	ds_read_b128 v[94:97], v68
	ds_read_b128 v[98:101], v68 offset:4608
	ds_read_b128 v[126:129], v1 offset:36864
	ds_read_b128 v[130:133], v1 offset:41472
	s_waitcnt vmcnt(1)
	ds_write_b128 v66, v[86:89] offset:18432
	ds_write_b128 v66, v[102:105] offset:23040
	ds_write_b128 v66, v[106:109] offset:27648
	ds_write_b128 v66, v[110:113] offset:32256
	s_waitcnt vmcnt(0)
	ds_write_b128 v66, v[90:93] offset:55296
	ds_write_b128 v66, v[122:125] offset:59904
	ds_write_b128 v66, v[118:121] offset:64512
	ds_write_b128 v69, v[114:117] offset:32256
	s_setprio 1
	ds_read_b128 v[86:89], v68 offset:32
	s_waitcnt lgkmcnt(10)
	v_mfma_f32_32x32x16_bf16 v[34:49], v[94:97], v[126:129], v[34:49]
	ds_read_b128 v[90:93], v1 offset:36896
	global_load_dwordx4 v[102:105], v[70:71], off offset:1536
	global_load_dwordx4 v[106:109], v[74:75], off offset:1536
	global_load_dwordx4 v[110:113], v[76:77], off offset:1536
	global_load_dwordx4 v[114:117], v[84:85], off offset:1536
	global_load_dwordx4 v[118:121], v[82:83], off offset:1536
	global_load_dwordx4 v[122:125], v[80:81], off offset:1536
	s_waitcnt lgkmcnt(10)
	v_mfma_f32_32x32x16_bf16 v[50:65], v[94:97], v[130:133], v[50:65]
	ds_read_b128 v[94:97], v1 offset:41504
	s_waitcnt lgkmcnt(1)
	v_mfma_f32_32x32x16_bf16 v[34:49], v[86:89], v[90:93], v[34:49]
	s_waitcnt lgkmcnt(0)
	v_mfma_f32_32x32x16_bf16 v[50:65], v[86:89], v[94:97], v[50:65]
	ds_read_b128 v[86:89], v68 offset:4640
	v_mfma_f32_32x32x16_bf16 v[2:17], v[98:101], v[126:129], v[2:17]
	v_mfma_f32_32x32x16_bf16 v[18:33], v[98:101], v[130:133], v[18:33]
	ds_read_b128 v[98:101], v68 offset:4704
	s_waitcnt lgkmcnt(1)
	v_mfma_f32_32x32x16_bf16 v[2:17], v[86:89], v[90:93], v[2:17]
	ds_read_b128 v[90:93], v1 offset:36928
	v_mfma_f32_32x32x16_bf16 v[18:33], v[86:89], v[94:97], v[18:33]
	ds_read_b128 v[86:89], v68 offset:64
	ds_read_b128 v[94:97], v1 offset:41536
	s_waitcnt lgkmcnt(1)
	v_mfma_f32_32x32x16_bf16 v[34:49], v[86:89], v[90:93], v[34:49]
	s_waitcnt lgkmcnt(0)
	v_mfma_f32_32x32x16_bf16 v[50:65], v[86:89], v[94:97], v[50:65]
	ds_read_b128 v[86:89], v68 offset:4672
	s_waitcnt lgkmcnt(0)
	v_mfma_f32_32x32x16_bf16 v[2:17], v[86:89], v[90:93], v[2:17]
	ds_read_b128 v[90:93], v1 offset:36960
	v_mfma_f32_32x32x16_bf16 v[18:33], v[86:89], v[94:97], v[18:33]
	ds_read_b128 v[86:89], v68 offset:96
	ds_read_b128 v[94:97], v1 offset:41568
	s_waitcnt lgkmcnt(1)
	v_mfma_f32_32x32x16_bf16 v[34:49], v[86:89], v[90:93], v[34:49]
	s_waitcnt lgkmcnt(0)
	v_mfma_f32_32x32x16_bf16 v[50:65], v[86:89], v[94:97], v[50:65]
	global_load_dwordx4 v[86:89], v[72:73], off offset:1536
	v_mfma_f32_32x32x16_bf16 v[2:17], v[98:101], v[90:93], v[2:17]
	global_load_dwordx4 v[90:93], v[78:79], off offset:1536
	v_mfma_f32_32x32x16_bf16 v[18:33], v[98:101], v[94:97], v[18:33]
	s_setprio 0
	s_barrier
; #define MFMA(a, b, c) __builtin_amdgcn_mfma_f32_32x32x16_bf16((a), (b), (c), 0, 0, 0)
; template <int TM, int TN>
; DI void gemm_mainloop(const u16* __restrict__ A, long lda, const u16* __restrict__ Bt, long ldb, int K, char* smem,
;                       f32x16 (&acc)[TM][TN]) {
;     ...
;   for (int kt = 0; kt < nk; kt++) {
;     const int buf = kt & 1;
;     const u16* cA = sA + buf * BM * LD + (wm * 32 * TM + r) * LD + h * 8;
;     const u16* cB = sB + buf * BN * LD + (wn * 32 * TN + r) * LD + h * 8;
;     bf16x8 af[TM], bfr[TN];
; #pragma unroll
;     for (int tm = 0; tm < TM; tm++) af[tm] = *(const bf16x8*)(cA + tm * 32 * LD);
; #pragma unroll
;     for (int tn = 0; tn < TN; tn++) bfr[tn] = *(const bf16x8*)(cB + tn * 32 * LD);
;     if (kt + 1 < nk) GEMM_SSTORE(buf ^ 1)
;     __builtin_amdgcn_sched_barrier(0);
;     __builtin_amdgcn_s_setprio(1);
; #pragma unroll
;     for (int tm = 0; tm < TM; tm++)
; #pragma unroll
;       for (int tn = 0; tn < TN; tn++) acc[tm][tn] = MFMA(af[tm], bfr[tn], acc[tm][tn]);
; #pragma unroll
;     for (int tm = 0; tm < TM; tm++) af[tm] = *(const bf16x8*)(cA + tm * 32 * LD + 16);
; #pragma unroll
;     for (int tn = 0; tn < TN; tn++) bfr[tn] = *(const bf16x8*)(cB + tn * 32 * LD + 16);
; #pragma unroll
;     for (int tm = 0; tm < TM; tm++)
; #pragma unroll
;       for (int tn = 0; tn < TN; tn++) acc[tm][tn] = MFMA(af[tm], bfr[tn], acc[tm][tn]);
;     __builtin_amdgcn_sched_group_barrier(0x8, 4, 0);
;     if (kt + 2 < nk) GEMM_GLOAD((kt + 2) * 64)
; #pragma unroll
;     for (int ks = 2; ks < 4; ks++) {
; #pragma unroll
;       for (int tm = 0; tm < TM; tm++) af[tm] = *(const bf16x8*)(cA + tm * 32 * LD + ks * 16);
; #pragma unroll
;       for (int tn = 0; tn < TN; tn++) bfr[tn] = *(const bf16x8*)(cB + tn * 32 * LD + ks * 16);
; #pragma unroll
;       for (int tm = 0; tm < TM; tm++)
; #pragma unroll
;         for (int tn = 0; tn < TN; tn++) acc[tm][tn] = MFMA(af[tm], bfr[tn], acc[tm][tn]);
;     }
;     __builtin_amdgcn_s_setprio(0);
;     __syncthreads();
	ds_read_b128 v[94:97], v68 offset:18432
	ds_read_b128 v[98:101], v68 offset:23040
	ds_read_b128 v[126:129], v1 offset:55296
	ds_read_b128 v[130:133], v1 offset:59904
	s_waitcnt vmcnt(1)
	ds_write_b128 v66, v[86:89]
	ds_write_b128 v66, v[102:105] offset:4608
	ds_write_b128 v66, v[106:109] offset:9216
	ds_write_b128 v66, v[110:113] offset:13824
	s_waitcnt vmcnt(0)
	ds_write_b128 v66, v[90:93] offset:36864
	ds_write_b128 v66, v[122:125] offset:41472
	ds_write_b128 v66, v[118:121] offset:46080
	ds_write_b128 v66, v[114:117] offset:50688
	s_setprio 1
	ds_read_b128 v[86:89], v68 offset:18464
	s_waitcnt lgkmcnt(10)
	v_mfma_f32_32x32x16_bf16 v[34:49], v[94:97], v[126:129], v[34:49]
	ds_read_b128 v[90:93], v1 offset:55328
	global_load_dwordx4 v[102:105], v[70:71], off offset:1664
	global_load_dwordx4 v[106:109], v[74:75], off offset:1664
	global_load_dwordx4 v[110:113], v[76:77], off offset:1664
	global_load_dwordx4 v[114:117], v[84:85], off offset:1664
	global_load_dwordx4 v[118:121], v[82:83], off offset:1664
	global_load_dwordx4 v[122:125], v[80:81], off offset:1664
	s_waitcnt lgkmcnt(10)
	v_mfma_f32_32x32x16_bf16 v[50:65], v[94:97], v[130:133], v[50:65]
	ds_read_b128 v[94:97], v1 offset:59936
	s_waitcnt lgkmcnt(1)
	v_mfma_f32_32x32x16_bf16 v[34:49], v[86:89], v[90:93], v[34:49]
	s_waitcnt lgkmcnt(0)
	v_mfma_f32_32x32x16_bf16 v[50:65], v[86:89], v[94:97], v[50:65]
	ds_read_b128 v[86:89], v68 offset:23072
	v_mfma_f32_32x32x16_bf16 v[2:17], v[98:101], v[126:129], v[2:17]
	v_mfma_f32_32x32x16_bf16 v[18:33], v[98:101], v[130:133], v[18:33]
	ds_read_b128 v[98:101], v68 offset:23136
	s_waitcnt lgkmcnt(1)
	v_mfma_f32_32x32x16_bf16 v[2:17], v[86:89], v[90:93], v[2:17]
	ds_read_b128 v[90:93], v1 offset:55360
	v_mfma_f32_32x32x16_bf16 v[18:33], v[86:89], v[94:97], v[18:33]
	ds_read_b128 v[86:89], v68 offset:18496
	ds_read_b128 v[94:97], v1 offset:59968
	s_waitcnt lgkmcnt(1)
	v_mfma_f32_32x32x16_bf16 v[34:49], v[86:89], v[90:93], v[34:49]
	s_waitcnt lgkmcnt(0)
	v_mfma_f32_32x32x16_bf16 v[50:65], v[86:89], v[94:97], v[50:65]
	ds_read_b128 v[86:89], v68 offset:23104
	s_waitcnt lgkmcnt(0)
	v_mfma_f32_32x32x16_bf16 v[2:17], v[86:89], v[90:93], v[2:17]
	ds_read_b128 v[90:93], v1 offset:55392
	v_mfma_f32_32x32x16_bf16 v[18:33], v[86:89], v[94:97], v[18:33]
	ds_read_b128 v[86:89], v68 offset:18528
	ds_read_b128 v[94:97], v1 offset:60000
	s_waitcnt lgkmcnt(1)
	v_mfma_f32_32x32x16_bf16 v[34:49], v[86:89], v[90:93], v[34:49]
	s_waitcnt lgkmcnt(0)
	v_mfma_f32_32x32x16_bf16 v[50:65], v[86:89], v[94:97], v[50:65]
	global_load_dwordx4 v[86:89], v[72:73], off offset:1664
	v_mfma_f32_32x32x16_bf16 v[2:17], v[98:101], v[90:93], v[2:17]
	global_load_dwordx4 v[90:93], v[78:79], off offset:1664
	v_mfma_f32_32x32x16_bf16 v[18:33], v[98:101], v[94:97], v[18:33]
	s_setprio 0
	s_barrier
	ds_read_b128 v[94:97], v68
	ds_read_b128 v[98:101], v68 offset:4608
	ds_read_b128 v[126:129], v1 offset:36864
	ds_read_b128 v[130:133], v1 offset:41472
	s_waitcnt vmcnt(1)
	ds_write_b128 v66, v[86:89] offset:18432
	ds_write_b128 v66, v[102:105] offset:23040
	ds_write_b128 v66, v[106:109] offset:27648
	ds_write_b128 v66, v[110:113] offset:32256
	s_waitcnt vmcnt(0)
	ds_write_b128 v66, v[90:93] offset:55296
	ds_write_b128 v66, v[122:125] offset:59904
	ds_write_b128 v66, v[118:121] offset:64512
	ds_write_b128 v69, v[114:117] offset:32256
	s_setprio 1
	ds_read_b128 v[86:89], v68 offset:32
	s_waitcnt lgkmcnt(10)
	v_mfma_f32_32x32x16_bf16 v[34:49], v[94:97], v[126:129], v[34:49]
	ds_read_b128 v[90:93], v1 offset:36896
	global_load_dwordx4 v[102:105], v[70:71], off offset:1792
	global_load_dwordx4 v[106:109], v[74:75], off offset:1792
	global_load_dwordx4 v[110:113], v[76:77], off offset:1792
	global_load_dwordx4 v[114:117], v[84:85], off offset:1792
	global_load_dwordx4 v[118:121], v[82:83], off offset:1792
	global_load_dwordx4 v[122:125], v[80:81], off offset:1792
	s_waitcnt lgkmcnt(10)
	v_mfma_f32_32x32x16_bf16 v[50:65], v[94:97], v[130:133], v[50:65]
	ds_read_b128 v[94:97], v1 offset:41504
	s_waitcnt lgkmcnt(1)
	v_mfma_f32_32x32x16_bf16 v[34:49], v[86:89], v[90:93], v[34:49]
	s_waitcnt lgkmcnt(0)
	v_mfma_f32_32x32x16_bf16 v[50:65], v[86:89], v[94:97], v[50:65]
	ds_read_b128 v[86:89], v68 offset:4640
	v_mfma_f32_32x32x16_bf16 v[2:17], v[98:101], v[126:129], v[2:17]
	v_mfma_f32_32x32x16_bf16 v[18:33], v[98:101], v[130:133], v[18:33]
	ds_read_b128 v[98:101], v68 offset:4704
	s_waitcnt lgkmcnt(1)
	v_mfma_f32_32x32x16_bf16 v[2:17], v[86:89], v[90:93], v[2:17]
	ds_read_b128 v[90:93], v1 offset:36928
	v_mfma_f32_32x32x16_bf16 v[18:33], v[86:89], v[94:97], v[18:33]
	ds_read_b128 v[86:89], v68 offset:64
	ds_read_b128 v[94:97], v1 offset:41536
	s_waitcnt lgkmcnt(1)
	v_mfma_f32_32x32x16_bf16 v[34:49], v[86:89], v[90:93], v[34:49]
	s_waitcnt lgkmcnt(0)
	v_mfma_f32_32x32x16_bf16 v[50:65], v[86:89], v[94:97], v[50:65]
	ds_read_b128 v[86:89], v68 offset:4672
	s_waitcnt lgkmcnt(0)
	v_mfma_f32_32x32x16_bf16 v[2:17], v[86:89], v[90:93], v[2:17]
	ds_read_b128 v[90:93], v1 offset:36960
	v_mfma_f32_32x32x16_bf16 v[18:33], v[86:89], v[94:97], v[18:33]
	ds_read_b128 v[86:89], v68 offset:96
	ds_read_b128 v[94:97], v1 offset:41568
	s_waitcnt lgkmcnt(1)
	v_mfma_f32_32x32x16_bf16 v[34:49], v[86:89], v[90:93], v[34:49]
	s_waitcnt lgkmcnt(0)
	v_mfma_f32_32x32x16_bf16 v[50:65], v[86:89], v[94:97], v[50:65]
	global_load_dwordx4 v[86:89], v[72:73], off offset:1792
	v_mfma_f32_32x32x16_bf16 v[2:17], v[98:101], v[90:93], v[2:17]
	global_load_dwordx4 v[90:93], v[78:79], off offset:1792
	v_mfma_f32_32x32x16_bf16 v[18:33], v[98:101], v[94:97], v[18:33]
	s_setprio 0
	s_barrier
; #define MFMA(a, b, c) __builtin_amdgcn_mfma_f32_32x32x16_bf16((a), (b), (c), 0, 0, 0)
; template <int TM, int TN>
; DI void gemm_mainloop(const u16* __restrict__ A, long lda, const u16* __restrict__ Bt, long ldb, int K, char* smem,
;                       f32x16 (&acc)[TM][TN]) {
;     ...
;   for (int kt = 0; kt < nk; kt++) {
;     const int buf = kt & 1;
;     const u16* cA = sA + buf * BM * LD + (wm * 32 * TM + r) * LD + h * 8;
;     const u16* cB = sB + buf * BN * LD + (wn * 32 * TN + r) * LD + h * 8;
;     bf16x8 af[TM], bfr[TN];
; #pragma unroll
;     for (int tm = 0; tm < TM; tm++) af[tm] = *(const bf16x8*)(cA + tm * 32 * LD);
; #pragma unroll
;     for (int tn = 0; tn < TN; tn++) bfr[tn] = *(const bf16x8*)(cB + tn * 32 * LD);
;     if (kt + 1 < nk) GEMM_SSTORE(buf ^ 1)
;     __builtin_amdgcn_sched_barrier(0);
;     __builtin_amdgcn_s_setprio(1);
; #pragma unroll
;     for (int tm = 0; tm < TM; tm++)
; #pragma unroll
;       for (int tn = 0; tn < TN; tn++) acc[tm][tn] = MFMA(af[tm], bfr[tn], acc[tm][tn]);
; #pragma unroll
;     for (int tm = 0; tm < TM; tm++) af[tm] = *(const bf16x8*)(cA + tm * 32 * LD + 16);
; #pragma unroll
;     for (int tn = 0; tn < TN; tn++) bfr[tn] = *(const bf16x8*)(cB + tn * 32 * LD + 16);
; #pragma unroll
;     for (int tm = 0; tm < TM; tm++)
; #pragma unroll
;       for (int tn = 0; tn < TN; tn++) acc[tm][tn] = MFMA(af[tm], bfr[tn], acc[tm][tn]);
;     __builtin_amdgcn_sched_group_barrier(0x8, 4, 0);
;     if (kt + 2 < nk) GEMM_GLOAD((kt + 2) * 64)
; #pragma unroll
;     for (int ks = 2; ks < 4; ks++) {
; #pragma unroll
;       for (int tm = 0; tm < TM; tm++) af[tm] = *(const bf16x8*)(cA + tm * 32 * LD + ks * 16);
; #pragma unroll
;       for (int tn = 0; tn < TN; tn++) bfr[tn] = *(const bf16x8*)(cB + tn * 32 * LD + ks * 16);
; #pragma unroll
;       for (int tm = 0; tm < TM; tm++)
; #pragma unroll
;         for (int tn = 0; tn < TN; tn++) acc[tm][tn] = MFMA(af[tm], bfr[tn], acc[tm][tn]);
;     }
;     __builtin_amdgcn_s_setprio(0);
;     __syncthreads();
	ds_read_b128 v[94:97], v68 offset:18432
	ds_read_b128 v[98:101], v68 offset:23040
	ds_read_b128 v[126:129], v1 offset:55296
	ds_read_b128 v[130:133], v1 offset:59904
	s_waitcnt vmcnt(1)
	ds_write_b128 v66, v[86:89]
	ds_write_b128 v66, v[102:105] offset:4608
	ds_write_b128 v66, v[106:109] offset:9216
	ds_write_b128 v66, v[110:113] offset:13824
	s_waitcnt vmcnt(0)
	ds_write_b128 v66, v[90:93] offset:36864
	ds_write_b128 v66, v[122:125] offset:41472
	ds_write_b128 v66, v[118:121] offset:46080
	ds_write_b128 v66, v[114:117] offset:50688
	s_setprio 1
	ds_read_b128 v[86:89], v68 offset:18464
	s_waitcnt lgkmcnt(10)
	v_mfma_f32_32x32x16_bf16 v[34:49], v[94:97], v[126:129], v[34:49]
	ds_read_b128 v[90:93], v1 offset:55328
	global_load_dwordx4 v[102:105], v[70:71], off offset:1920
	global_load_dwordx4 v[106:109], v[74:75], off offset:1920
	global_load_dwordx4 v[110:113], v[76:77], off offset:1920
	global_load_dwordx4 v[114:117], v[84:85], off offset:1920
	global_load_dwordx4 v[118:121], v[82:83], off offset:1920
	global_load_dwordx4 v[122:125], v[80:81], off offset:1920
	s_waitcnt lgkmcnt(10)
	v_mfma_f32_32x32x16_bf16 v[50:65], v[94:97], v[130:133], v[50:65]
	ds_read_b128 v[94:97], v1 offset:59936
	s_waitcnt lgkmcnt(1)
	v_mfma_f32_32x32x16_bf16 v[34:49], v[86:89], v[90:93], v[34:49]
	s_waitcnt lgkmcnt(0)
	v_mfma_f32_32x32x16_bf16 v[50:65], v[86:89], v[94:97], v[50:65]
	ds_read_b128 v[86:89], v68 offset:23072
	v_mfma_f32_32x32x16_bf16 v[2:17], v[98:101], v[126:129], v[2:17]
	v_mfma_f32_32x32x16_bf16 v[18:33], v[98:101], v[130:133], v[18:33]
	ds_read_b128 v[98:101], v68 offset:23136
	s_waitcnt lgkmcnt(1)
	v_mfma_f32_32x32x16_bf16 v[2:17], v[86:89], v[90:93], v[2:17]
	ds_read_b128 v[90:93], v1 offset:55360
	v_mfma_f32_32x32x16_bf16 v[18:33], v[86:89], v[94:97], v[18:33]
	ds_read_b128 v[86:89], v68 offset:18496
	ds_read_b128 v[94:97], v1 offset:59968
	s_waitcnt lgkmcnt(1)
	v_mfma_f32_32x32x16_bf16 v[34:49], v[86:89], v[90:93], v[34:49]
	s_waitcnt lgkmcnt(0)
	v_mfma_f32_32x32x16_bf16 v[50:65], v[86:89], v[94:97], v[50:65]
	ds_read_b128 v[86:89], v68 offset:23104
	s_waitcnt lgkmcnt(0)
	v_mfma_f32_32x32x16_bf16 v[2:17], v[86:89], v[90:93], v[2:17]
	ds_read_b128 v[90:93], v1 offset:55392
	v_mfma_f32_32x32x16_bf16 v[18:33], v[86:89], v[94:97], v[18:33]
	ds_read_b128 v[86:89], v68 offset:18528
	ds_read_b128 v[94:97], v1 offset:60000
	s_waitcnt lgkmcnt(1)
	v_mfma_f32_32x32x16_bf16 v[34:49], v[86:89], v[90:93], v[34:49]
	s_waitcnt lgkmcnt(0)
	v_mfma_f32_32x32x16_bf16 v[50:65], v[86:89], v[94:97], v[50:65]
	global_load_dwordx4 v[86:89], v[72:73], off offset:1920
	s_nop 0
	global_load_dwordx4 v[70:73], v[78:79], off offset:1920
	v_mfma_f32_32x32x16_bf16 v[2:17], v[98:101], v[90:93], v[2:17]
	v_mfma_f32_32x32x16_bf16 v[18:33], v[98:101], v[94:97], v[18:33]
	s_setprio 0
	s_barrier
	ds_read_b128 v[74:77], v68
	ds_read_b128 v[78:81], v68 offset:4608
	ds_read_b128 v[82:85], v1 offset:36864
	ds_read_b128 v[90:93], v1 offset:41472
	s_waitcnt vmcnt(1)
	ds_write_b128 v66, v[86:89] offset:18432
	ds_write_b128 v66, v[102:105] offset:23040
	ds_write_b128 v66, v[106:109] offset:27648
	ds_write_b128 v66, v[110:113] offset:32256
	s_waitcnt vmcnt(0)
	ds_write_b128 v66, v[70:73] offset:55296
	ds_write_b128 v66, v[122:125] offset:59904
	ds_write_b128 v66, v[118:121] offset:64512
	ds_write_b128 v69, v[114:117] offset:32256
	s_setprio 1
	ds_read_b128 v[70:73], v68 offset:32
	s_waitcnt lgkmcnt(10)
	v_mfma_f32_32x32x16_bf16 v[34:49], v[74:77], v[82:85], v[34:49]
	s_waitcnt lgkmcnt(9)
	v_mfma_f32_32x32x16_bf16 v[50:65], v[74:77], v[90:93], v[50:65]
	ds_read_b128 v[74:77], v1 offset:36896
	v_mfma_f32_32x32x16_bf16 v[2:17], v[78:81], v[82:85], v[2:17]
	v_mfma_f32_32x32x16_bf16 v[18:33], v[78:81], v[90:93], v[18:33]
	ds_read_b128 v[78:81], v1 offset:41504
	s_waitcnt lgkmcnt(1)
	v_mfma_f32_32x32x16_bf16 v[34:49], v[70:73], v[74:77], v[34:49]
	s_waitcnt lgkmcnt(0)
	v_mfma_f32_32x32x16_bf16 v[50:65], v[70:73], v[78:81], v[50:65]
	ds_read_b128 v[70:73], v68 offset:4640
	s_waitcnt lgkmcnt(0)
	v_mfma_f32_32x32x16_bf16 v[2:17], v[70:73], v[74:77], v[2:17]
	ds_read_b128 v[74:77], v1 offset:36928
	v_mfma_f32_32x32x16_bf16 v[18:33], v[70:73], v[78:81], v[18:33]
	ds_read_b128 v[70:73], v68 offset:64
	ds_read_b128 v[78:81], v1 offset:41536
	s_waitcnt lgkmcnt(1)
	v_mfma_f32_32x32x16_bf16 v[34:49], v[70:73], v[74:77], v[34:49]
	s_waitcnt lgkmcnt(0)
	v_mfma_f32_32x32x16_bf16 v[50:65], v[70:73], v[78:81], v[50:65]
	ds_read_b128 v[70:73], v68 offset:4672
	s_waitcnt lgkmcnt(0)
	v_mfma_f32_32x32x16_bf16 v[2:17], v[70:73], v[74:77], v[2:17]
	ds_read_b128 v[74:77], v1 offset:36960
	v_mfma_f32_32x32x16_bf16 v[18:33], v[70:73], v[78:81], v[18:33]
	ds_read_b128 v[70:73], v68 offset:96
	ds_read_b128 v[78:81], v1 offset:41568
	s_waitcnt lgkmcnt(1)
	v_mfma_f32_32x32x16_bf16 v[34:49], v[70:73], v[74:77], v[34:49]
	s_waitcnt lgkmcnt(0)
	v_mfma_f32_32x32x16_bf16 v[50:65], v[70:73], v[78:81], v[50:65]
	ds_read_b128 v[70:73], v68 offset:4704
	s_waitcnt lgkmcnt(0)
	v_mfma_f32_32x32x16_bf16 v[2:17], v[70:73], v[74:77], v[2:17]
	v_mfma_f32_32x32x16_bf16 v[18:33], v[70:73], v[78:81], v[18:33]
	s_setprio 0
	s_barrier
; #define MFMA(a, b, c) __builtin_amdgcn_mfma_f32_32x32x16_bf16((a), (b), (c), 0, 0, 0)
; DI unsigned pk2(float a, float b) { fv2 v = {a, b}; bfv2 r = __builtin_convertvector(v, bfv2); return __builtin_bit_cast(unsigned, r); }
; DI int crow(int i, int h) { return (i & 3) + 8 * (i >> 2) + 4 * h; }
; template <int TM, int TN>
; DI void gemm_mainloop(const u16* __restrict__ A, long lda, const u16* __restrict__ Bt, long ldb, int K, char* smem,
;                       f32x16 (&acc)[TM][TN]) {
;     ...
;     for (int tm = 0; tm < TM; tm++)
; #pragma unroll
;       for (int tn = 0; tn < TN; tn++) acc[tm][tn] = MFMA(af[tm], bfr[tn], acc[tm][tn]);
;     __builtin_amdgcn_sched_group_barrier(0x8, 4, 0);
;     if (kt + 2 < nk) GEMM_GLOAD((kt + 2) * 64)
; #pragma unroll
;     for (int ks = 2; ks < 4; ks++) {
; #pragma unroll
;       for (int tm = 0; tm < TM; tm++) af[tm] = *(const bf16x8*)(cA + tm * 32 * LD + ks * 16);
; #pragma unroll
;       for (int tn = 0; tn < TN; tn++) bfr[tn] = *(const bf16x8*)(cB + tn * 32 * LD + ks * 16);
; #pragma unroll
;       for (int tm = 0; tm < TM; tm++)
; #pragma unroll
;         for (int tn = 0; tn < TN; tn++) acc[tm][tn] = MFMA(af[tm], bfr[tn], acc[tm][tn]);
;     }
;     __builtin_amdgcn_s_setprio(0);
;     __syncthreads();
; template <int TM, int TN, class Epi>
; DI void gemm_tile(const u16* A, long lda, const u16* Bt, long ldb, int K, int m0, int n0, char* smem, const Epi& epi) {
;     ...
; #pragma unroll
;   for (int tm = 0; tm < TM; tm++)
; #pragma unroll
;     for (int tn = 0; tn < TN; tn++)
; #pragma unroll
;       for (int i = 0; i < 16; i++)
;         Ct[(wm * 32 * TM + tm * 32 + crow(i, h)) * LDC + wn * 32 * TN + tn * 32 + r] = acc[tm][tn][i];
;   __syncthreads();
;   epi(Ct, LDC, m0, n0, tid, BM);
;   __syncthreads();
;   (void)BM;
; }
;   DI void operator()(const float* Ct, int ldc, int m0, int n0, int tid, int bm) const {
; #pragma unroll 4
;     for (int it = 0; it < bm / 16; it++) {
;       int id = tid + 256 * it; int row = id >> 4, c8 = (id & 15) * 8;
;       int n = n0 + c8;
;       if (n < nmax) {
;         const float* c = Ct + row * ldc + c8;
;         float4 a = *(const float4*)c, b = *(const float4*)(c + 4);
;         uint4 v; v.x = pk2(a.x, a.y); v.y = pk2(a.z, a.w); v.z = pk2(b.x, b.y); v.w = pk2(b.z, b.w);
;         *(uint4*)(out + (long)(m0 + row) * ldo + n) = v;
;         if (gates != nullptr && n == 1952) {
	ds_read_b128 v[70:73], v68 offset:18432
	ds_read_b128 v[74:77], v68 offset:23040
	ds_read_b128 v[78:81], v1 offset:55296
	ds_read_b128 v[82:85], v1 offset:59904
	s_setprio 1
	s_waitcnt lgkmcnt(1)
	v_mfma_f32_32x32x16_bf16 v[34:49], v[70:73], v[78:81], v[34:49]
	s_waitcnt lgkmcnt(0)
	v_mfma_f32_32x32x16_bf16 v[50:65], v[70:73], v[82:85], v[50:65]
	ds_read_b128 v[70:73], v68 offset:18464
	v_mfma_f32_32x32x16_bf16 v[2:17], v[74:77], v[78:81], v[2:17]
	ds_read_b128 v[78:81], v1 offset:59936
	v_mfma_f32_32x32x16_bf16 v[18:33], v[74:77], v[82:85], v[18:33]
	ds_read_b128 v[74:77], v1 offset:55328
	s_waitcnt lgkmcnt(0)
	v_mfma_f32_32x32x16_bf16 v[34:49], v[70:73], v[74:77], v[34:49]
	v_mfma_f32_32x32x16_bf16 v[50:65], v[70:73], v[78:81], v[50:65]
	ds_read_b128 v[70:73], v68 offset:23072
	s_waitcnt lgkmcnt(0)
	v_mfma_f32_32x32x16_bf16 v[2:17], v[70:73], v[74:77], v[2:17]
	ds_read_b128 v[74:77], v1 offset:55360
	v_mfma_f32_32x32x16_bf16 v[18:33], v[70:73], v[78:81], v[18:33]
	ds_read_b128 v[70:73], v68 offset:18496
	ds_read_b128 v[78:81], v1 offset:59968
	s_waitcnt lgkmcnt(1)
	v_mfma_f32_32x32x16_bf16 v[34:49], v[70:73], v[74:77], v[34:49]
	s_waitcnt lgkmcnt(0)
	v_mfma_f32_32x32x16_bf16 v[50:65], v[70:73], v[78:81], v[50:65]
	ds_read_b128 v[70:73], v68 offset:23104
	s_waitcnt lgkmcnt(0)
	v_mfma_f32_32x32x16_bf16 v[2:17], v[70:73], v[74:77], v[2:17]
	ds_read_b128 v[74:77], v1 offset:55392
	v_mfma_f32_32x32x16_bf16 v[18:33], v[70:73], v[78:81], v[18:33]
	ds_read_b128 v[70:73], v68 offset:18528
	ds_read_b128 v[78:81], v1 offset:60000
	s_waitcnt lgkmcnt(1)
	v_mfma_f32_32x32x16_bf16 v[34:49], v[70:73], v[74:77], v[34:49]
	s_waitcnt lgkmcnt(0)
	v_mfma_f32_32x32x16_bf16 v[50:65], v[70:73], v[78:81], v[50:65]
	ds_read_b128 v[68:71], v68 offset:23136
	s_waitcnt lgkmcnt(0)
	v_mfma_f32_32x32x16_bf16 v[2:17], v[68:71], v[74:77], v[2:17]
	v_mfma_f32_32x32x16_bf16 v[18:33], v[68:71], v[78:81], v[18:33]
	s_setprio 0
	v_mov_b32_e32 v1, v0
	s_barrier
	s_mov_b32 s4, 0
	v_lshrrev_b32_e32 v66, 1, v1
	v_and_b32_e32 v66, 0xfffffc0, v66
	v_lshrrev_b32_e32 v68, 3, v1
	v_and_or_b32 v66, v68, 4, v66
	v_and_b32_e32 v68, 0x5f, v1
	v_mul_lo_u32 v66, v66, s28
	v_lshl_add_u32 v66, v68, 2, v66
	ds_write2_b32 v66, v34, v50 offset1:32
	v_add_u32_e32 v34, 0x400, v66
	ds_write2_b32 v34, v36, v52 offset0:8 offset1:40
	ds_write2_b32 v34, v37, v53 offset0:140 offset1:172
	v_add_u32_e32 v34, 0x1000, v66
	ds_write2_b32 v34, v38, v54 offset0:32 offset1:64
	ds_write2_b32 v34, v39, v55 offset0:164 offset1:196
	v_add_u32_e32 v34, 0x1400, v66
	ds_write2_b32 v34, v40, v56 offset0:40 offset1:72
	ds_write2_b32 v34, v41, v57 offset0:172 offset1:204
	v_add_u32_e32 v34, 0x2000, v66
	ds_write2_b32 v34, v42, v58 offset0:64 offset1:96
	ds_write2_b32 v34, v43, v59 offset0:196 offset1:228
	v_add_u32_e32 v34, 0x2400, v66
	ds_write2_b32 v34, v44, v60 offset0:72 offset1:104
	ds_write2_b32 v34, v45, v61 offset0:204 offset1:236
	v_add_u32_e32 v34, 0x3000, v66
	ds_write2_b32 v34, v46, v62 offset0:96 offset1:128
	v_add_u32_e32 v34, 0x3200, v66
	ds_write2_b32 v34, v47, v63 offset0:100 offset1:132
	v_add_u32_e32 v34, 0x3400, v66
	ds_write2_b32 v34, v48, v64 offset0:104 offset1:136
	v_add_u32_e32 v34, 0x3600, v66
	ds_write2_b32 v34, v49, v65 offset0:108 offset1:140
	v_add_u32_e32 v34, 0x4000, v66
	ds_write2_b32 v34, v2, v18 offset0:128 offset1:160
	v_add_u32_e32 v2, 0x4400, v66
	ds_write2_b32 v2, v3, v19 offset0:4 offset1:36
	ds_write2_b32 v2, v4, v20 offset0:136 offset1:168
	v_add_u32_e32 v2, 0x4800, v66
	ds_write2_b32 v2, v5, v21 offset0:12 offset1:44
	v_add_u32_e32 v2, 0x5000, v66
	ds_write2_b32 v2, v6, v22 offset0:160 offset1:192
	v_add_u32_e32 v2, 0x5400, v66
	ds_write2_b32 v2, v7, v23 offset0:36 offset1:68
	ds_write2_b32 v2, v8, v24 offset0:168 offset1:200
	v_add_u32_e32 v2, 0x5800, v66
	ds_write2_b32 v2, v9, v25 offset0:44 offset1:76
	v_add_u32_e32 v2, 0x6000, v66
	ds_write2_b32 v2, v10, v26 offset0:192 offset1:224
	v_add_u32_e32 v2, 0x6400, v66
	ds_write2_b32 v2, v11, v27 offset0:68 offset1:100
	ds_write2_b32 v2, v12, v28 offset0:200 offset1:232
	v_add_u32_e32 v2, 0x6800, v66
	ds_write2_b32 v2, v13, v29 offset0:76 offset1:108
	v_add_u32_e32 v2, 0x7200, v66
	ds_write2_b32 v2, v14, v30 offset0:96 offset1:128
	v_add_u32_e32 v2, 0x7400, v66
	ds_write2_b32 v2, v15, v31 offset0:100 offset1:132
	v_add_u32_e32 v2, 0x7600, v66
	ds_write2_b32 v2, v16, v32 offset0:104 offset1:136
	v_add_u32_e32 v2, 0x7800, v66
	ds_write2_b32 v2, v17, v33 offset0:108 offset1:140
	v_lshlrev_b32_e32 v2, 3, v1
	v_and_b32_e32 v3, 0x78, v2
	v_lshl_or_b32 v2, s6, 7, v3
	v_lshlrev_b32_e32 v10, 2, v3
	v_ashrrev_i32_e32 v3, 31, v2
	v_cmp_eq_u32_e32 vcc, s29, v2
	v_cmp_gt_i32_e64 s[6:7], s30, v2
	v_lshl_add_u64 v[12:13], v[2:3], 1, s[14:15]
	ds_write2_b32 v66, v35, v51 offset0:132 offset1:164
	s_waitcnt lgkmcnt(0)
	s_barrier
	s_branch .LBB0_1540

; #define MFMA(a, b, c) __builtin_amdgcn_mfma_f32_32x32x16_bf16((a), (b), (c), 0, 0, 0)
; template <int TM, int TN>
; DI void gemm_mainloop(const u16* __restrict__ A, long lda, const u16* __restrict__ Bt, long ldb, int K, char* smem,
;                       f32x16 (&acc)[TM][TN]) {
;     ...
;   const int nk = K / 64;
;   const int lrow = tid >> 3, lch = (tid & 7) * 8;
;   const u16* gA = A + (long)lrow * lda + lch;
;   const u16* gB = Bt + (long)lrow * ldb + lch;
;   const int soff = lrow * LD + lch;
;     ...
;   GEMM_GLOAD(0)
;   __syncthreads();
;   GEMM_SSTORE(0)
;   if (nk > 1) GEMM_GLOAD(64)
;   __syncthreads();
;   for (int kt = 0; kt < nk; kt++) {
;     const int buf = kt & 1;
;     const u16* cA = sA + buf * BM * LD + (wm * 32 * TM + r) * LD + h * 8;
;     const u16* cB = sB + buf * BN * LD + (wn * 32 * TN + r) * LD + h * 8;
;     bf16x8 af[TM], bfr[TN];
; #pragma unroll
;     for (int tm = 0; tm < TM; tm++) af[tm] = *(const bf16x8*)(cA + tm * 32 * LD);
; #pragma unroll
;     for (int tn = 0; tn < TN; tn++) bfr[tn] = *(const bf16x8*)(cB + tn * 32 * LD);
;     if (kt + 1 < nk) GEMM_SSTORE(buf ^ 1)
;     __builtin_amdgcn_sched_barrier(0);
;     __builtin_amdgcn_s_setprio(1);
; #pragma unroll
;     for (int tm = 0; tm < TM; tm++)
; #pragma unroll
;       for (int tn = 0; tn < TN; tn++) acc[tm][tn] = MFMA(af[tm], bfr[tn], acc[tm][tn]);
; #pragma unroll
;     for (int tm = 0; tm < TM; tm++) af[tm] = *(const bf16x8*)(cA + tm * 32 * LD + 16);
; #pragma unroll
;     for (int tn = 0; tn < TN; tn++) bfr[tn] = *(const bf16x8*)(cB + tn * 32 * LD + 16);
; #pragma unroll
;     for (int tm = 0; tm < TM; tm++)
; #pragma unroll
;       for (int tn = 0; tn < TN; tn++) acc[tm][tn] = MFMA(af[tm], bfr[tn], acc[tm][tn]);
;     __builtin_amdgcn_sched_group_barrier(0x8, 4, 0);
;     if (kt + 2 < nk) GEMM_GLOAD((kt + 2) * 64)
.LBB0_2466:
	s_ashr_i32 s6, s22, 31
	s_lshr_b32 s6, s6, 29
	s_add_i32 s7, s22, s6
	s_and_b32 s6, s7, -8
	s_lshl_b32 s7, s7, 4
	s_and_b32 s23, s7, 0xffffff80
	s_sub_i32 s6, s22, s6
	s_mul_i32 s24, s23, 0x880
	s_mul_hi_i32 s7, s23, 0x880
	s_add_u32 s24, s4, s24
	v_mov_b32_e32 v1, v0
	s_addc_u32 s25, s5, s7
	s_mul_i32 s7, s6, 0x44000
	v_lshlrev_b32_e32 v2, 3, v1
	v_ashrrev_i32_e32 v68, 3, v1
	v_and_b32_e32 v69, 56, v2
	v_mov_b64_e32 v[2:3], s[24:25]
	v_mad_i64_i32 v[2:3], s[24:25], v68, s10, v[2:3]
	v_lshlrev_b32_e32 v66, 1, v69
	v_lshl_add_u64 v[72:73], v[2:3], 0, v[66:67]
	s_ashr_i32 s27, s7, 31
	v_add_co_u32_e32 v70, vcc, s15, v72
	s_add_u32 s26, s3, s7
	s_nop 0
	v_addc_co_u32_e32 v71, vcc, 0, v73, vcc
	s_addc_u32 s27, s14, s27
	v_add_co_u32_e32 v74, vcc, s16, v72
	v_mov_b64_e32 v[2:3], s[26:27]
	s_nop 0
	v_addc_co_u32_e32 v75, vcc, 0, v73, vcc
	v_mad_i64_i32 v[18:19], s[24:25], v68, s10, v[2:3]
	v_add_co_u32_e32 v78, vcc, s17, v72
	v_lshl_add_u64 v[76:77], v[18:19], 0, v[66:67]
	s_nop 0
	v_addc_co_u32_e32 v79, vcc, 0, v73, vcc
	v_add_co_u32_e32 v80, vcc, s15, v76
	global_load_dwordx4 v[2:5], v[72:73], off
	s_nop 0
	v_addc_co_u32_e32 v81, vcc, 0, v77, vcc
	v_add_co_u32_e32 v82, vcc, s16, v76
	global_load_dwordx4 v[6:9], v[70:71], off
	s_nop 0
	v_addc_co_u32_e32 v83, vcc, 0, v77, vcc
	v_add_co_u32_e32 v84, vcc, s17, v76
	global_load_dwordx4 v[10:13], v[74:75], off
	s_nop 0
	v_addc_co_u32_e32 v85, vcc, 0, v77, vcc
	global_load_dwordx4 v[14:17], v[78:79], off
	global_load_dwordx4 v[18:21], v[76:77], off
	global_load_dwordx4 v[22:25], v[80:81], off
	global_load_dwordx4 v[26:29], v[82:83], off
	global_load_dwordx4 v[30:33], v[84:85], off
	s_barrier
	global_load_dwordx4 v[34:37], v[72:73], off offset:128
	global_load_dwordx4 v[38:41], v[70:71], off offset:128
	global_load_dwordx4 v[42:45], v[74:75], off offset:128
	global_load_dwordx4 v[46:49], v[78:79], off offset:128
	global_load_dwordx4 v[50:53], v[76:77], off offset:128
	global_load_dwordx4 v[54:57], v[80:81], off offset:128
	global_load_dwordx4 v[58:61], v[82:83], off offset:128
	global_load_dwordx4 v[62:65], v[84:85], off offset:128
	v_and_b32_e32 v66, 31, v1
	v_lshrrev_b32_e32 v86, 1, v1
	v_mul_lo_u32 v68, v68, s11
	v_and_or_b32 v87, v86, s18, v66
	v_and_b32_e32 v86, 16, v86
	v_and_b32_e32 v1, 0x5f, v1
	v_add_lshl_u32 v66, v68, v69, 1
	v_mad_u64_u32 v[68:69], s[24:25], v87, s19, v[86:87]
	v_mad_u32_u24 v1, v1, s19, v86
	v_add_u32_e32 v69, 0x9000, v66
	s_waitcnt vmcnt(15)
	ds_write_b128 v66, v[2:5]
	s_waitcnt vmcnt(14)
	ds_write_b128 v66, v[6:9] offset:4608
	s_waitcnt vmcnt(13)
	ds_write_b128 v66, v[10:13] offset:9216
	s_waitcnt vmcnt(12)
	ds_write_b128 v66, v[14:17] offset:13824
	s_waitcnt vmcnt(11)
	ds_write_b128 v66, v[18:21] offset:36864
	s_waitcnt vmcnt(10)
	ds_write_b128 v66, v[22:25] offset:41472
	s_waitcnt vmcnt(9)
	ds_write_b128 v66, v[26:29] offset:46080
	s_waitcnt vmcnt(8)
	ds_write_b128 v66, v[30:33] offset:50688
	s_waitcnt lgkmcnt(0)
	s_barrier
	ds_read_b128 v[2:5], v68
	ds_read_b128 v[18:21], v68 offset:4608
	ds_read_b128 v[6:9], v1 offset:36864
	ds_read_b128 v[22:25], v1 offset:41472
	s_waitcnt vmcnt(7)
	ds_write_b128 v66, v[34:37] offset:18432
	s_waitcnt vmcnt(6)
	ds_write_b128 v66, v[38:41] offset:23040
	s_waitcnt vmcnt(5)
	ds_write_b128 v66, v[42:45] offset:27648
	s_waitcnt vmcnt(4)
	ds_write_b128 v66, v[46:49] offset:32256
	s_waitcnt vmcnt(3)
	ds_write_b128 v66, v[50:53] offset:55296
	s_waitcnt vmcnt(2)
	ds_write_b128 v66, v[54:57] offset:59904
	s_waitcnt vmcnt(1)
	ds_write_b128 v66, v[58:61] offset:64512
	s_waitcnt vmcnt(0)
	ds_write_b128 v69, v[62:65] offset:32256
	s_setprio 1
	ds_read_b128 v[86:89], v68 offset:32
	s_waitcnt lgkmcnt(10)
	v_mfma_f32_32x32x16_bf16 v[34:49], v[2:5], v[6:9], 0
	ds_read_b128 v[90:93], v1 offset:36896
	ds_read_b128 v[94:97], v1 offset:41504
	ds_read_b128 v[98:101], v68 offset:4704
	global_load_dwordx4 v[102:105], v[70:71], off offset:256
	global_load_dwordx4 v[106:109], v[74:75], off offset:256
	global_load_dwordx4 v[110:113], v[78:79], off offset:256
	global_load_dwordx4 v[114:117], v[84:85], off offset:256
	s_waitcnt lgkmcnt(12)
	v_mfma_f32_32x32x16_bf16 v[50:65], v[2:5], v[22:25], 0
	global_load_dwordx4 v[118:121], v[82:83], off offset:256
	global_load_dwordx4 v[122:125], v[80:81], off offset:256
	s_waitcnt lgkmcnt(2)
	v_mfma_f32_32x32x16_bf16 v[34:49], v[86:89], v[90:93], v[34:49]
	s_waitcnt lgkmcnt(1)
	v_mfma_f32_32x32x16_bf16 v[50:65], v[86:89], v[94:97], v[50:65]
	ds_read_b128 v[86:89], v68 offset:4640
	v_mfma_f32_32x32x16_bf16 v[2:17], v[18:21], v[6:9], 0
	v_mfma_f32_32x32x16_bf16 v[18:33], v[18:21], v[22:25], 0
	s_waitcnt lgkmcnt(0)
	v_mfma_f32_32x32x16_bf16 v[2:17], v[86:89], v[90:93], v[2:17]
	ds_read_b128 v[90:93], v1 offset:36928
	v_mfma_f32_32x32x16_bf16 v[18:33], v[86:89], v[94:97], v[18:33]
	ds_read_b128 v[86:89], v68 offset:64
	ds_read_b128 v[94:97], v1 offset:41536
	s_waitcnt lgkmcnt(1)
	v_mfma_f32_32x32x16_bf16 v[34:49], v[86:89], v[90:93], v[34:49]
	s_waitcnt lgkmcnt(0)
	v_mfma_f32_32x32x16_bf16 v[50:65], v[86:89], v[94:97], v[50:65]
	ds_read_b128 v[86:89], v68 offset:4672
	s_waitcnt lgkmcnt(0)
	v_mfma_f32_32x32x16_bf16 v[2:17], v[86:89], v[90:93], v[2:17]
	ds_read_b128 v[90:93], v1 offset:36960
	v_mfma_f32_32x32x16_bf16 v[18:33], v[86:89], v[94:97], v[18:33]
	ds_read_b128 v[86:89], v68 offset:96
	ds_read_b128 v[94:97], v1 offset:41568
	s_waitcnt lgkmcnt(1)
	v_mfma_f32_32x32x16_bf16 v[34:49], v[86:89], v[90:93], v[34:49]
	s_waitcnt lgkmcnt(0)
	v_mfma_f32_32x32x16_bf16 v[50:65], v[86:89], v[94:97], v[50:65]
	global_load_dwordx4 v[86:89], v[72:73], off offset:256
	v_mfma_f32_32x32x16_bf16 v[2:17], v[98:101], v[90:93], v[2:17]
	global_load_dwordx4 v[90:93], v[76:77], off offset:256
	v_mfma_f32_32x32x16_bf16 v[18:33], v[98:101], v[94:97], v[18:33]
	s_setprio 0
	s_barrier
; #define MFMA(a, b, c) __builtin_amdgcn_mfma_f32_32x32x16_bf16((a), (b), (c), 0, 0, 0)
; template <int TM, int TN>
; DI void gemm_mainloop(const u16* __restrict__ A, long lda, const u16* __restrict__ Bt, long ldb, int K, char* smem,
;                       f32x16 (&acc)[TM][TN]) {
;     ...
;   for (int kt = 0; kt < nk; kt++) {
;     const int buf = kt & 1;
;     const u16* cA = sA + buf * BM * LD + (wm * 32 * TM + r) * LD + h * 8;
;     const u16* cB = sB + buf * BN * LD + (wn * 32 * TN + r) * LD + h * 8;
;     bf16x8 af[TM], bfr[TN];
; #pragma unroll
;     for (int tm = 0; tm < TM; tm++) af[tm] = *(const bf16x8*)(cA + tm * 32 * LD);
; #pragma unroll
;     for (int tn = 0; tn < TN; tn++) bfr[tn] = *(const bf16x8*)(cB + tn * 32 * LD);
;     if (kt + 1 < nk) GEMM_SSTORE(buf ^ 1)
;     __builtin_amdgcn_sched_barrier(0);
;     __builtin_amdgcn_s_setprio(1);
; #pragma unroll
;     for (int tm = 0; tm < TM; tm++)
; #pragma unroll
;       for (int tn = 0; tn < TN; tn++) acc[tm][tn] = MFMA(af[tm], bfr[tn], acc[tm][tn]);
; #pragma unroll
;     for (int tm = 0; tm < TM; tm++) af[tm] = *(const bf16x8*)(cA + tm * 32 * LD + 16);
; #pragma unroll
;     for (int tn = 0; tn < TN; tn++) bfr[tn] = *(const bf16x8*)(cB + tn * 32 * LD + 16);
; #pragma unroll
;     for (int tm = 0; tm < TM; tm++)
; #pragma unroll
;       for (int tn = 0; tn < TN; tn++) acc[tm][tn] = MFMA(af[tm], bfr[tn], acc[tm][tn]);
;     __builtin_amdgcn_sched_group_barrier(0x8, 4, 0);
;     if (kt + 2 < nk) GEMM_GLOAD((kt + 2) * 64)
; #pragma unroll
;     for (int ks = 2; ks < 4; ks++) {
; #pragma unroll
;       for (int tm = 0; tm < TM; tm++) af[tm] = *(const bf16x8*)(cA + tm * 32 * LD + ks * 16);
; #pragma unroll
;       for (int tn = 0; tn < TN; tn++) bfr[tn] = *(const bf16x8*)(cB + tn * 32 * LD + ks * 16);
; #pragma unroll
;       for (int tm = 0; tm < TM; tm++)
; #pragma unroll
;         for (int tn = 0; tn < TN; tn++) acc[tm][tn] = MFMA(af[tm], bfr[tn], acc[tm][tn]);
;     }
;     __builtin_amdgcn_s_setprio(0);
;     __syncthreads();
	ds_read_b128 v[94:97], v68 offset:18432
	ds_read_b128 v[98:101], v68 offset:23040
	ds_read_b128 v[126:129], v1 offset:55296
	ds_read_b128 v[130:133], v1 offset:59904
	s_waitcnt vmcnt(1)
	ds_write_b128 v66, v[86:89]
	ds_write_b128 v66, v[102:105] offset:4608
	ds_write_b128 v66, v[106:109] offset:9216
	ds_write_b128 v66, v[110:113] offset:13824
	s_waitcnt vmcnt(0)
	ds_write_b128 v66, v[90:93] offset:36864
	ds_write_b128 v66, v[122:125] offset:41472
	ds_write_b128 v66, v[118:121] offset:46080
	ds_write_b128 v66, v[114:117] offset:50688
	s_setprio 1
	ds_read_b128 v[86:89], v68 offset:18464
	s_waitcnt lgkmcnt(10)
	v_mfma_f32_32x32x16_bf16 v[34:49], v[94:97], v[126:129], v[34:49]
	ds_read_b128 v[90:93], v1 offset:55328
	global_load_dwordx4 v[102:105], v[70:71], off offset:384
	global_load_dwordx4 v[106:109], v[74:75], off offset:384
	global_load_dwordx4 v[110:113], v[78:79], off offset:384
	global_load_dwordx4 v[114:117], v[84:85], off offset:384
	global_load_dwordx4 v[118:121], v[82:83], off offset:384
	global_load_dwordx4 v[122:125], v[80:81], off offset:384
	s_waitcnt lgkmcnt(10)
	v_mfma_f32_32x32x16_bf16 v[50:65], v[94:97], v[130:133], v[50:65]
	ds_read_b128 v[94:97], v1 offset:59936
	s_waitcnt lgkmcnt(1)
	v_mfma_f32_32x32x16_bf16 v[34:49], v[86:89], v[90:93], v[34:49]
	s_waitcnt lgkmcnt(0)
	v_mfma_f32_32x32x16_bf16 v[50:65], v[86:89], v[94:97], v[50:65]
	ds_read_b128 v[86:89], v68 offset:23072
	v_mfma_f32_32x32x16_bf16 v[2:17], v[98:101], v[126:129], v[2:17]
	v_mfma_f32_32x32x16_bf16 v[18:33], v[98:101], v[130:133], v[18:33]
	ds_read_b128 v[98:101], v68 offset:23136
	s_waitcnt lgkmcnt(1)
	v_mfma_f32_32x32x16_bf16 v[2:17], v[86:89], v[90:93], v[2:17]
	ds_read_b128 v[90:93], v1 offset:55360
	v_mfma_f32_32x32x16_bf16 v[18:33], v[86:89], v[94:97], v[18:33]
	ds_read_b128 v[86:89], v68 offset:18496
	ds_read_b128 v[94:97], v1 offset:59968
	s_waitcnt lgkmcnt(1)
	v_mfma_f32_32x32x16_bf16 v[34:49], v[86:89], v[90:93], v[34:49]
	s_waitcnt lgkmcnt(0)
	v_mfma_f32_32x32x16_bf16 v[50:65], v[86:89], v[94:97], v[50:65]
	ds_read_b128 v[86:89], v68 offset:23104
	s_waitcnt lgkmcnt(0)
	v_mfma_f32_32x32x16_bf16 v[2:17], v[86:89], v[90:93], v[2:17]
	ds_read_b128 v[90:93], v1 offset:55392
	v_mfma_f32_32x32x16_bf16 v[18:33], v[86:89], v[94:97], v[18:33]
	ds_read_b128 v[86:89], v68 offset:18528
	ds_read_b128 v[94:97], v1 offset:60000
	s_waitcnt lgkmcnt(1)
	v_mfma_f32_32x32x16_bf16 v[34:49], v[86:89], v[90:93], v[34:49]
	s_waitcnt lgkmcnt(0)
	v_mfma_f32_32x32x16_bf16 v[50:65], v[86:89], v[94:97], v[50:65]
	global_load_dwordx4 v[86:89], v[72:73], off offset:384
	v_mfma_f32_32x32x16_bf16 v[2:17], v[98:101], v[90:93], v[2:17]
	global_load_dwordx4 v[90:93], v[76:77], off offset:384
	v_mfma_f32_32x32x16_bf16 v[18:33], v[98:101], v[94:97], v[18:33]
	s_setprio 0
	s_barrier
	ds_read_b128 v[94:97], v68
	ds_read_b128 v[98:101], v68 offset:4608
	ds_read_b128 v[126:129], v1 offset:36864
	ds_read_b128 v[130:133], v1 offset:41472
	s_waitcnt vmcnt(1)
	ds_write_b128 v66, v[86:89] offset:18432
	ds_write_b128 v66, v[102:105] offset:23040
	ds_write_b128 v66, v[106:109] offset:27648
	ds_write_b128 v66, v[110:113] offset:32256
	s_waitcnt vmcnt(0)
	ds_write_b128 v66, v[90:93] offset:55296
	ds_write_b128 v66, v[122:125] offset:59904
	ds_write_b128 v66, v[118:121] offset:64512
	ds_write_b128 v69, v[114:117] offset:32256
	s_setprio 1
	ds_read_b128 v[86:89], v68 offset:32
	s_waitcnt lgkmcnt(10)
	v_mfma_f32_32x32x16_bf16 v[34:49], v[94:97], v[126:129], v[34:49]
	ds_read_b128 v[90:93], v1 offset:36896
	global_load_dwordx4 v[102:105], v[70:71], off offset:512
	global_load_dwordx4 v[106:109], v[74:75], off offset:512
	global_load_dwordx4 v[110:113], v[78:79], off offset:512
	global_load_dwordx4 v[114:117], v[84:85], off offset:512
	global_load_dwordx4 v[118:121], v[82:83], off offset:512
	global_load_dwordx4 v[122:125], v[80:81], off offset:512
	s_waitcnt lgkmcnt(10)
	v_mfma_f32_32x32x16_bf16 v[50:65], v[94:97], v[130:133], v[50:65]
	ds_read_b128 v[94:97], v1 offset:41504
	s_waitcnt lgkmcnt(1)
	v_mfma_f32_32x32x16_bf16 v[34:49], v[86:89], v[90:93], v[34:49]
	s_waitcnt lgkmcnt(0)
	v_mfma_f32_32x32x16_bf16 v[50:65], v[86:89], v[94:97], v[50:65]
	ds_read_b128 v[86:89], v68 offset:4640
	v_mfma_f32_32x32x16_bf16 v[2:17], v[98:101], v[126:129], v[2:17]
	v_mfma_f32_32x32x16_bf16 v[18:33], v[98:101], v[130:133], v[18:33]
	ds_read_b128 v[98:101], v68 offset:4704
	s_waitcnt lgkmcnt(1)
	v_mfma_f32_32x32x16_bf16 v[2:17], v[86:89], v[90:93], v[2:17]
	ds_read_b128 v[90:93], v1 offset:36928
	v_mfma_f32_32x32x16_bf16 v[18:33], v[86:89], v[94:97], v[18:33]
	ds_read_b128 v[86:89], v68 offset:64
	ds_read_b128 v[94:97], v1 offset:41536
	s_waitcnt lgkmcnt(1)
	v_mfma_f32_32x32x16_bf16 v[34:49], v[86:89], v[90:93], v[34:49]
	s_waitcnt lgkmcnt(0)
	v_mfma_f32_32x32x16_bf16 v[50:65], v[86:89], v[94:97], v[50:65]
	ds_read_b128 v[86:89], v68 offset:4672
	s_waitcnt lgkmcnt(0)
	v_mfma_f32_32x32x16_bf16 v[2:17], v[86:89], v[90:93], v[2:17]
	ds_read_b128 v[90:93], v1 offset:36960
	v_mfma_f32_32x32x16_bf16 v[18:33], v[86:89], v[94:97], v[18:33]
	ds_read_b128 v[86:89], v68 offset:96
	ds_read_b128 v[94:97], v1 offset:41568
	s_waitcnt lgkmcnt(1)
	v_mfma_f32_32x32x16_bf16 v[34:49], v[86:89], v[90:93], v[34:49]
	s_waitcnt lgkmcnt(0)
	v_mfma_f32_32x32x16_bf16 v[50:65], v[86:89], v[94:97], v[50:65]
	global_load_dwordx4 v[86:89], v[72:73], off offset:512
	v_mfma_f32_32x32x16_bf16 v[2:17], v[98:101], v[90:93], v[2:17]
	global_load_dwordx4 v[90:93], v[76:77], off offset:512
	v_mfma_f32_32x32x16_bf16 v[18:33], v[98:101], v[94:97], v[18:33]
	s_setprio 0
	s_barrier
; #define MFMA(a, b, c) __builtin_amdgcn_mfma_f32_32x32x16_bf16((a), (b), (c), 0, 0, 0)
; template <int TM, int TN>
; DI void gemm_mainloop(const u16* __restrict__ A, long lda, const u16* __restrict__ Bt, long ldb, int K, char* smem,
;                       f32x16 (&acc)[TM][TN]) {
;     ...
;   for (int kt = 0; kt < nk; kt++) {
;     const int buf = kt & 1;
;     const u16* cA = sA + buf * BM * LD + (wm * 32 * TM + r) * LD + h * 8;
;     const u16* cB = sB + buf * BN * LD + (wn * 32 * TN + r) * LD + h * 8;
;     bf16x8 af[TM], bfr[TN];
; #pragma unroll
;     for (int tm = 0; tm < TM; tm++) af[tm] = *(const bf16x8*)(cA + tm * 32 * LD);
; #pragma unroll
;     for (int tn = 0; tn < TN; tn++) bfr[tn] = *(const bf16x8*)(cB + tn * 32 * LD);
;     if (kt + 1 < nk) GEMM_SSTORE(buf ^ 1)
;     __builtin_amdgcn_sched_barrier(0);
;     __builtin_amdgcn_s_setprio(1);
; #pragma unroll
;     for (int tm = 0; tm < TM; tm++)
; #pragma unroll
;       for (int tn = 0; tn < TN; tn++) acc[tm][tn] = MFMA(af[tm], bfr[tn], acc[tm][tn]);
; #pragma unroll
;     for (int tm = 0; tm < TM; tm++) af[tm] = *(const bf16x8*)(cA + tm * 32 * LD + 16);
; #pragma unroll
;     for (int tn = 0; tn < TN; tn++) bfr[tn] = *(const bf16x8*)(cB + tn * 32 * LD + 16);
; #pragma unroll
;     for (int tm = 0; tm < TM; tm++)
; #pragma unroll
;       for (int tn = 0; tn < TN; tn++) acc[tm][tn] = MFMA(af[tm], bfr[tn], acc[tm][tn]);
;     __builtin_amdgcn_sched_group_barrier(0x8, 4, 0);
;     if (kt + 2 < nk) GEMM_GLOAD((kt + 2) * 64)
; #pragma unroll
;     for (int ks = 2; ks < 4; ks++) {
; #pragma unroll
;       for (int tm = 0; tm < TM; tm++) af[tm] = *(const bf16x8*)(cA + tm * 32 * LD + ks * 16);
; #pragma unroll
;       for (int tn = 0; tn < TN; tn++) bfr[tn] = *(const bf16x8*)(cB + tn * 32 * LD + ks * 16);
; #pragma unroll
;       for (int tm = 0; tm < TM; tm++)
; #pragma unroll
;         for (int tn = 0; tn < TN; tn++) acc[tm][tn] = MFMA(af[tm], bfr[tn], acc[tm][tn]);
;     }
;     __builtin_amdgcn_s_setprio(0);
;     __syncthreads();
	ds_read_b128 v[94:97], v68 offset:18432
	ds_read_b128 v[98:101], v68 offset:23040
	ds_read_b128 v[126:129], v1 offset:55296
	ds_read_b128 v[130:133], v1 offset:59904
	s_waitcnt vmcnt(1)
	ds_write_b128 v66, v[86:89]
	ds_write_b128 v66, v[102:105] offset:4608
	ds_write_b128 v66, v[106:109] offset:9216
	ds_write_b128 v66, v[110:113] offset:13824
	s_waitcnt vmcnt(0)
	ds_write_b128 v66, v[90:93] offset:36864
	ds_write_b128 v66, v[122:125] offset:41472
	ds_write_b128 v66, v[118:121] offset:46080
	ds_write_b128 v66, v[114:117] offset:50688
	s_setprio 1
	ds_read_b128 v[86:89], v68 offset:18464
	s_waitcnt lgkmcnt(10)
	v_mfma_f32_32x32x16_bf16 v[34:49], v[94:97], v[126:129], v[34:49]
	ds_read_b128 v[90:93], v1 offset:55328
	global_load_dwordx4 v[102:105], v[70:71], off offset:640
	global_load_dwordx4 v[106:109], v[74:75], off offset:640
	global_load_dwordx4 v[110:113], v[78:79], off offset:640
	global_load_dwordx4 v[114:117], v[84:85], off offset:640
	global_load_dwordx4 v[118:121], v[82:83], off offset:640
	global_load_dwordx4 v[122:125], v[80:81], off offset:640
	s_waitcnt lgkmcnt(10)
	v_mfma_f32_32x32x16_bf16 v[50:65], v[94:97], v[130:133], v[50:65]
	ds_read_b128 v[94:97], v1 offset:59936
	s_waitcnt lgkmcnt(1)
	v_mfma_f32_32x32x16_bf16 v[34:49], v[86:89], v[90:93], v[34:49]
	s_waitcnt lgkmcnt(0)
	v_mfma_f32_32x32x16_bf16 v[50:65], v[86:89], v[94:97], v[50:65]
	ds_read_b128 v[86:89], v68 offset:23072
	v_mfma_f32_32x32x16_bf16 v[2:17], v[98:101], v[126:129], v[2:17]
	v_mfma_f32_32x32x16_bf16 v[18:33], v[98:101], v[130:133], v[18:33]
	ds_read_b128 v[98:101], v68 offset:23136
	s_waitcnt lgkmcnt(1)
	v_mfma_f32_32x32x16_bf16 v[2:17], v[86:89], v[90:93], v[2:17]
	ds_read_b128 v[90:93], v1 offset:55360
	v_mfma_f32_32x32x16_bf16 v[18:33], v[86:89], v[94:97], v[18:33]
	ds_read_b128 v[86:89], v68 offset:18496
	ds_read_b128 v[94:97], v1 offset:59968
	s_waitcnt lgkmcnt(1)
	v_mfma_f32_32x32x16_bf16 v[34:49], v[86:89], v[90:93], v[34:49]
	s_waitcnt lgkmcnt(0)
	v_mfma_f32_32x32x16_bf16 v[50:65], v[86:89], v[94:97], v[50:65]
	ds_read_b128 v[86:89], v68 offset:23104
	s_waitcnt lgkmcnt(0)
	v_mfma_f32_32x32x16_bf16 v[2:17], v[86:89], v[90:93], v[2:17]
	ds_read_b128 v[90:93], v1 offset:55392
	v_mfma_f32_32x32x16_bf16 v[18:33], v[86:89], v[94:97], v[18:33]
	ds_read_b128 v[86:89], v68 offset:18528
	ds_read_b128 v[94:97], v1 offset:60000
	s_waitcnt lgkmcnt(1)
	v_mfma_f32_32x32x16_bf16 v[34:49], v[86:89], v[90:93], v[34:49]
	s_waitcnt lgkmcnt(0)
	v_mfma_f32_32x32x16_bf16 v[50:65], v[86:89], v[94:97], v[50:65]
	global_load_dwordx4 v[86:89], v[72:73], off offset:640
	v_mfma_f32_32x32x16_bf16 v[2:17], v[98:101], v[90:93], v[2:17]
	global_load_dwordx4 v[90:93], v[76:77], off offset:640
	v_mfma_f32_32x32x16_bf16 v[18:33], v[98:101], v[94:97], v[18:33]
	s_setprio 0
	s_barrier
	ds_read_b128 v[94:97], v68
	ds_read_b128 v[98:101], v68 offset:4608
	ds_read_b128 v[126:129], v1 offset:36864
	ds_read_b128 v[130:133], v1 offset:41472
	s_waitcnt vmcnt(1)
	ds_write_b128 v66, v[86:89] offset:18432
	ds_write_b128 v66, v[102:105] offset:23040
	ds_write_b128 v66, v[106:109] offset:27648
	ds_write_b128 v66, v[110:113] offset:32256
	s_waitcnt vmcnt(0)
	ds_write_b128 v66, v[90:93] offset:55296
	ds_write_b128 v66, v[122:125] offset:59904
	ds_write_b128 v66, v[118:121] offset:64512
	ds_write_b128 v69, v[114:117] offset:32256
	s_setprio 1
	ds_read_b128 v[86:89], v68 offset:32
	s_waitcnt lgkmcnt(10)
	v_mfma_f32_32x32x16_bf16 v[34:49], v[94:97], v[126:129], v[34:49]
	ds_read_b128 v[90:93], v1 offset:36896
	global_load_dwordx4 v[102:105], v[70:71], off offset:768
	global_load_dwordx4 v[106:109], v[74:75], off offset:768
	global_load_dwordx4 v[110:113], v[78:79], off offset:768
	global_load_dwordx4 v[114:117], v[84:85], off offset:768
	global_load_dwordx4 v[118:121], v[82:83], off offset:768
	global_load_dwordx4 v[122:125], v[80:81], off offset:768
	s_waitcnt lgkmcnt(10)
	v_mfma_f32_32x32x16_bf16 v[50:65], v[94:97], v[130:133], v[50:65]
	ds_read_b128 v[94:97], v1 offset:41504
	s_waitcnt lgkmcnt(1)
	v_mfma_f32_32x32x16_bf16 v[34:49], v[86:89], v[90:93], v[34:49]
	s_waitcnt lgkmcnt(0)
	v_mfma_f32_32x32x16_bf16 v[50:65], v[86:89], v[94:97], v[50:65]
	ds_read_b128 v[86:89], v68 offset:4640
	v_mfma_f32_32x32x16_bf16 v[2:17], v[98:101], v[126:129], v[2:17]
	v_mfma_f32_32x32x16_bf16 v[18:33], v[98:101], v[130:133], v[18:33]
	ds_read_b128 v[98:101], v68 offset:4704
	s_waitcnt lgkmcnt(1)
	v_mfma_f32_32x32x16_bf16 v[2:17], v[86:89], v[90:93], v[2:17]
	ds_read_b128 v[90:93], v1 offset:36928
	v_mfma_f32_32x32x16_bf16 v[18:33], v[86:89], v[94:97], v[18:33]
	ds_read_b128 v[86:89], v68 offset:64
	ds_read_b128 v[94:97], v1 offset:41536
	s_waitcnt lgkmcnt(1)
	v_mfma_f32_32x32x16_bf16 v[34:49], v[86:89], v[90:93], v[34:49]
	s_waitcnt lgkmcnt(0)
	v_mfma_f32_32x32x16_bf16 v[50:65], v[86:89], v[94:97], v[50:65]
	ds_read_b128 v[86:89], v68 offset:4672
	s_waitcnt lgkmcnt(0)
	v_mfma_f32_32x32x16_bf16 v[2:17], v[86:89], v[90:93], v[2:17]
	ds_read_b128 v[90:93], v1 offset:36960
	v_mfma_f32_32x32x16_bf16 v[18:33], v[86:89], v[94:97], v[18:33]
	ds_read_b128 v[86:89], v68 offset:96
	ds_read_b128 v[94:97], v1 offset:41568
	s_waitcnt lgkmcnt(1)
	v_mfma_f32_32x32x16_bf16 v[34:49], v[86:89], v[90:93], v[34:49]
	s_waitcnt lgkmcnt(0)
	v_mfma_f32_32x32x16_bf16 v[50:65], v[86:89], v[94:97], v[50:65]
	global_load_dwordx4 v[86:89], v[72:73], off offset:768
	v_mfma_f32_32x32x16_bf16 v[2:17], v[98:101], v[90:93], v[2:17]
	global_load_dwordx4 v[90:93], v[76:77], off offset:768
	v_mfma_f32_32x32x16_bf16 v[18:33], v[98:101], v[94:97], v[18:33]
	s_setprio 0
	s_barrier
; #define MFMA(a, b, c) __builtin_amdgcn_mfma_f32_32x32x16_bf16((a), (b), (c), 0, 0, 0)
; template <int TM, int TN>
; DI void gemm_mainloop(const u16* __restrict__ A, long lda, const u16* __restrict__ Bt, long ldb, int K, char* smem,
;                       f32x16 (&acc)[TM][TN]) {
;     ...
;   for (int kt = 0; kt < nk; kt++) {
;     const int buf = kt & 1;
;     const u16* cA = sA + buf * BM * LD + (wm * 32 * TM + r) * LD + h * 8;
;     const u16* cB = sB + buf * BN * LD + (wn * 32 * TN + r) * LD + h * 8;
;     bf16x8 af[TM], bfr[TN];
; #pragma unroll
;     for (int tm = 0; tm < TM; tm++) af[tm] = *(const bf16x8*)(cA + tm * 32 * LD);
; #pragma unroll
;     for (int tn = 0; tn < TN; tn++) bfr[tn] = *(const bf16x8*)(cB + tn * 32 * LD);
;     if (kt + 1 < nk) GEMM_SSTORE(buf ^ 1)
;     __builtin_amdgcn_sched_barrier(0);
;     __builtin_amdgcn_s_setprio(1);
; #pragma unroll
;     for (int tm = 0; tm < TM; tm++)
; #pragma unroll
;       for (int tn = 0; tn < TN; tn++) acc[tm][tn] = MFMA(af[tm], bfr[tn], acc[tm][tn]);
; #pragma unroll
;     for (int tm = 0; tm < TM; tm++) af[tm] = *(const bf16x8*)(cA + tm * 32 * LD + 16);
; #pragma unroll
;     for (int tn = 0; tn < TN; tn++) bfr[tn] = *(const bf16x8*)(cB + tn * 32 * LD + 16);
; #pragma unroll
;     for (int tm = 0; tm < TM; tm++)
; #pragma unroll
;       for (int tn = 0; tn < TN; tn++) acc[tm][tn] = MFMA(af[tm], bfr[tn], acc[tm][tn]);
;     __builtin_amdgcn_sched_group_barrier(0x8, 4, 0);
;     if (kt + 2 < nk) GEMM_GLOAD((kt + 2) * 64)
; #pragma unroll
;     for (int ks = 2; ks < 4; ks++) {
; #pragma unroll
;       for (int tm = 0; tm < TM; tm++) af[tm] = *(const bf16x8*)(cA + tm * 32 * LD + ks * 16);
; #pragma unroll
;       for (int tn = 0; tn < TN; tn++) bfr[tn] = *(const bf16x8*)(cB + tn * 32 * LD + ks * 16);
; #pragma unroll
;       for (int tm = 0; tm < TM; tm++)
; #pragma unroll
;         for (int tn = 0; tn < TN; tn++) acc[tm][tn] = MFMA(af[tm], bfr[tn], acc[tm][tn]);
;     }
;     __builtin_amdgcn_s_setprio(0);
;     __syncthreads();
	ds_read_b128 v[94:97], v68 offset:18432
	ds_read_b128 v[98:101], v68 offset:23040
	ds_read_b128 v[126:129], v1 offset:55296
	ds_read_b128 v[130:133], v1 offset:59904
	s_waitcnt vmcnt(1)
	ds_write_b128 v66, v[86:89]
	ds_write_b128 v66, v[102:105] offset:4608
	ds_write_b128 v66, v[106:109] offset:9216
	ds_write_b128 v66, v[110:113] offset:13824
	s_waitcnt vmcnt(0)
	ds_write_b128 v66, v[90:93] offset:36864
	ds_write_b128 v66, v[122:125] offset:41472
	ds_write_b128 v66, v[118:121] offset:46080
	ds_write_b128 v66, v[114:117] offset:50688
	s_setprio 1
	ds_read_b128 v[86:89], v68 offset:18464
	s_waitcnt lgkmcnt(10)
	v_mfma_f32_32x32x16_bf16 v[34:49], v[94:97], v[126:129], v[34:49]
	ds_read_b128 v[90:93], v1 offset:55328
	global_load_dwordx4 v[102:105], v[70:71], off offset:896
	global_load_dwordx4 v[106:109], v[74:75], off offset:896
	global_load_dwordx4 v[110:113], v[78:79], off offset:896
	global_load_dwordx4 v[114:117], v[84:85], off offset:896
	global_load_dwordx4 v[118:121], v[82:83], off offset:896
	global_load_dwordx4 v[122:125], v[80:81], off offset:896
	s_waitcnt lgkmcnt(10)
	v_mfma_f32_32x32x16_bf16 v[50:65], v[94:97], v[130:133], v[50:65]
	ds_read_b128 v[94:97], v1 offset:59936
	s_waitcnt lgkmcnt(1)
	v_mfma_f32_32x32x16_bf16 v[34:49], v[86:89], v[90:93], v[34:49]
	s_waitcnt lgkmcnt(0)
	v_mfma_f32_32x32x16_bf16 v[50:65], v[86:89], v[94:97], v[50:65]
	ds_read_b128 v[86:89], v68 offset:23072
	v_mfma_f32_32x32x16_bf16 v[2:17], v[98:101], v[126:129], v[2:17]
	v_mfma_f32_32x32x16_bf16 v[18:33], v[98:101], v[130:133], v[18:33]
	ds_read_b128 v[98:101], v68 offset:23136
	s_waitcnt lgkmcnt(1)
	v_mfma_f32_32x32x16_bf16 v[2:17], v[86:89], v[90:93], v[2:17]
	ds_read_b128 v[90:93], v1 offset:55360
	v_mfma_f32_32x32x16_bf16 v[18:33], v[86:89], v[94:97], v[18:33]
	ds_read_b128 v[86:89], v68 offset:18496
	ds_read_b128 v[94:97], v1 offset:59968
	s_waitcnt lgkmcnt(1)
	v_mfma_f32_32x32x16_bf16 v[34:49], v[86:89], v[90:93], v[34:49]
	s_waitcnt lgkmcnt(0)
	v_mfma_f32_32x32x16_bf16 v[50:65], v[86:89], v[94:97], v[50:65]
	ds_read_b128 v[86:89], v68 offset:23104
	s_waitcnt lgkmcnt(0)
	v_mfma_f32_32x32x16_bf16 v[2:17], v[86:89], v[90:93], v[2:17]
	ds_read_b128 v[90:93], v1 offset:55392
	v_mfma_f32_32x32x16_bf16 v[18:33], v[86:89], v[94:97], v[18:33]
	ds_read_b128 v[86:89], v68 offset:18528
	ds_read_b128 v[94:97], v1 offset:60000
	s_waitcnt lgkmcnt(1)
	v_mfma_f32_32x32x16_bf16 v[34:49], v[86:89], v[90:93], v[34:49]
	s_waitcnt lgkmcnt(0)
	v_mfma_f32_32x32x16_bf16 v[50:65], v[86:89], v[94:97], v[50:65]
	global_load_dwordx4 v[86:89], v[72:73], off offset:896
	v_mfma_f32_32x32x16_bf16 v[2:17], v[98:101], v[90:93], v[2:17]
	global_load_dwordx4 v[90:93], v[76:77], off offset:896
	v_mfma_f32_32x32x16_bf16 v[18:33], v[98:101], v[94:97], v[18:33]
	s_setprio 0
	s_barrier
	ds_read_b128 v[94:97], v68
	ds_read_b128 v[98:101], v68 offset:4608
	ds_read_b128 v[126:129], v1 offset:36864
	ds_read_b128 v[130:133], v1 offset:41472
	s_waitcnt vmcnt(1)
	ds_write_b128 v66, v[86:89] offset:18432
	ds_write_b128 v66, v[102:105] offset:23040
	ds_write_b128 v66, v[106:109] offset:27648
	ds_write_b128 v66, v[110:113] offset:32256
	s_waitcnt vmcnt(0)
	ds_write_b128 v66, v[90:93] offset:55296
	ds_write_b128 v66, v[122:125] offset:59904
	ds_write_b128 v66, v[118:121] offset:64512
	ds_write_b128 v69, v[114:117] offset:32256
	s_setprio 1
	ds_read_b128 v[86:89], v68 offset:32
	s_waitcnt lgkmcnt(10)
	v_mfma_f32_32x32x16_bf16 v[34:49], v[94:97], v[126:129], v[34:49]
	ds_read_b128 v[90:93], v1 offset:36896
	global_load_dwordx4 v[102:105], v[70:71], off offset:1024
	global_load_dwordx4 v[106:109], v[74:75], off offset:1024
	global_load_dwordx4 v[110:113], v[78:79], off offset:1024
	global_load_dwordx4 v[114:117], v[84:85], off offset:1024
	global_load_dwordx4 v[118:121], v[82:83], off offset:1024
	global_load_dwordx4 v[122:125], v[80:81], off offset:1024
	s_waitcnt lgkmcnt(10)
	v_mfma_f32_32x32x16_bf16 v[50:65], v[94:97], v[130:133], v[50:65]
	ds_read_b128 v[94:97], v1 offset:41504
	s_waitcnt lgkmcnt(1)
	v_mfma_f32_32x32x16_bf16 v[34:49], v[86:89], v[90:93], v[34:49]
	s_waitcnt lgkmcnt(0)
	v_mfma_f32_32x32x16_bf16 v[50:65], v[86:89], v[94:97], v[50:65]
	ds_read_b128 v[86:89], v68 offset:4640
	v_mfma_f32_32x32x16_bf16 v[2:17], v[98:101], v[126:129], v[2:17]
	v_mfma_f32_32x32x16_bf16 v[18:33], v[98:101], v[130:133], v[18:33]
	ds_read_b128 v[98:101], v68 offset:4704
	s_waitcnt lgkmcnt(1)
	v_mfma_f32_32x32x16_bf16 v[2:17], v[86:89], v[90:93], v[2:17]
	ds_read_b128 v[90:93], v1 offset:36928
	v_mfma_f32_32x32x16_bf16 v[18:33], v[86:89], v[94:97], v[18:33]
	ds_read_b128 v[86:89], v68 offset:64
	ds_read_b128 v[94:97], v1 offset:41536
	s_waitcnt lgkmcnt(1)
	v_mfma_f32_32x32x16_bf16 v[34:49], v[86:89], v[90:93], v[34:49]
	s_waitcnt lgkmcnt(0)
	v_mfma_f32_32x32x16_bf16 v[50:65], v[86:89], v[94:97], v[50:65]
	ds_read_b128 v[86:89], v68 offset:4672
	s_waitcnt lgkmcnt(0)
	v_mfma_f32_32x32x16_bf16 v[2:17], v[86:89], v[90:93], v[2:17]
	ds_read_b128 v[90:93], v1 offset:36960
	v_mfma_f32_32x32x16_bf16 v[18:33], v[86:89], v[94:97], v[18:33]
	ds_read_b128 v[86:89], v68 offset:96
	ds_read_b128 v[94:97], v1 offset:41568
	s_waitcnt lgkmcnt(1)
	v_mfma_f32_32x32x16_bf16 v[34:49], v[86:89], v[90:93], v[34:49]
	s_waitcnt lgkmcnt(0)
	v_mfma_f32_32x32x16_bf16 v[50:65], v[86:89], v[94:97], v[50:65]
	global_load_dwordx4 v[86:89], v[72:73], off offset:1024
	v_mfma_f32_32x32x16_bf16 v[2:17], v[98:101], v[90:93], v[2:17]
	global_load_dwordx4 v[90:93], v[76:77], off offset:1024
	v_mfma_f32_32x32x16_bf16 v[18:33], v[98:101], v[94:97], v[18:33]
	s_setprio 0
	s_barrier
; #define MFMA(a, b, c) __builtin_amdgcn_mfma_f32_32x32x16_bf16((a), (b), (c), 0, 0, 0)
; template <int TM, int TN>
; DI void gemm_mainloop(const u16* __restrict__ A, long lda, const u16* __restrict__ Bt, long ldb, int K, char* smem,
;                       f32x16 (&acc)[TM][TN]) {
;     ...
;   for (int kt = 0; kt < nk; kt++) {
;     const int buf = kt & 1;
;     const u16* cA = sA + buf * BM * LD + (wm * 32 * TM + r) * LD + h * 8;
;     const u16* cB = sB + buf * BN * LD + (wn * 32 * TN + r) * LD + h * 8;
;     bf16x8 af[TM], bfr[TN];
; #pragma unroll
;     for (int tm = 0; tm < TM; tm++) af[tm] = *(const bf16x8*)(cA + tm * 32 * LD);
; #pragma unroll
;     for (int tn = 0; tn < TN; tn++) bfr[tn] = *(const bf16x8*)(cB + tn * 32 * LD);
;     if (kt + 1 < nk) GEMM_SSTORE(buf ^ 1)
;     __builtin_amdgcn_sched_barrier(0);
;     __builtin_amdgcn_s_setprio(1);
; #pragma unroll
;     for (int tm = 0; tm < TM; tm++)
; #pragma unroll
;       for (int tn = 0; tn < TN; tn++) acc[tm][tn] = MFMA(af[tm], bfr[tn], acc[tm][tn]);
; #pragma unroll
;     for (int tm = 0; tm < TM; tm++) af[tm] = *(const bf16x8*)(cA + tm * 32 * LD + 16);
; #pragma unroll
;     for (int tn = 0; tn < TN; tn++) bfr[tn] = *(const bf16x8*)(cB + tn * 32 * LD + 16);
; #pragma unroll
;     for (int tm = 0; tm < TM; tm++)
; #pragma unroll
;       for (int tn = 0; tn < TN; tn++) acc[tm][tn] = MFMA(af[tm], bfr[tn], acc[tm][tn]);
;     __builtin_amdgcn_sched_group_barrier(0x8, 4, 0);
;     if (kt + 2 < nk) GEMM_GLOAD((kt + 2) * 64)
; #pragma unroll
;     for (int ks = 2; ks < 4; ks++) {
; #pragma unroll
;       for (int tm = 0; tm < TM; tm++) af[tm] = *(const bf16x8*)(cA + tm * 32 * LD + ks * 16);
; #pragma unroll
;       for (int tn = 0; tn < TN; tn++) bfr[tn] = *(const bf16x8*)(cB + tn * 32 * LD + ks * 16);
; #pragma unroll
;       for (int tm = 0; tm < TM; tm++)
; #pragma unroll
;         for (int tn = 0; tn < TN; tn++) acc[tm][tn] = MFMA(af[tm], bfr[tn], acc[tm][tn]);
;     }
;     __builtin_amdgcn_s_setprio(0);
;     __syncthreads();
	ds_read_b128 v[94:97], v68 offset:18432
	ds_read_b128 v[98:101], v68 offset:23040
	ds_read_b128 v[126:129], v1 offset:55296
	ds_read_b128 v[130:133], v1 offset:59904
	s_waitcnt vmcnt(1)
	ds_write_b128 v66, v[86:89]
	ds_write_b128 v66, v[102:105] offset:4608
	ds_write_b128 v66, v[106:109] offset:9216
	ds_write_b128 v66, v[110:113] offset:13824
	s_waitcnt vmcnt(0)
	ds_write_b128 v66, v[90:93] offset:36864
	ds_write_b128 v66, v[122:125] offset:41472
	ds_write_b128 v66, v[118:121] offset:46080
	ds_write_b128 v66, v[114:117] offset:50688
	s_setprio 1
	ds_read_b128 v[86:89], v68 offset:18464
	s_waitcnt lgkmcnt(10)
	v_mfma_f32_32x32x16_bf16 v[34:49], v[94:97], v[126:129], v[34:49]
	ds_read_b128 v[90:93], v1 offset:55328
	global_load_dwordx4 v[102:105], v[70:71], off offset:1152
	global_load_dwordx4 v[106:109], v[74:75], off offset:1152
	global_load_dwordx4 v[110:113], v[78:79], off offset:1152
	global_load_dwordx4 v[114:117], v[84:85], off offset:1152
	global_load_dwordx4 v[118:121], v[82:83], off offset:1152
	global_load_dwordx4 v[122:125], v[80:81], off offset:1152
	s_waitcnt lgkmcnt(10)
	v_mfma_f32_32x32x16_bf16 v[50:65], v[94:97], v[130:133], v[50:65]
	ds_read_b128 v[94:97], v1 offset:59936
	s_waitcnt lgkmcnt(1)
	v_mfma_f32_32x32x16_bf16 v[34:49], v[86:89], v[90:93], v[34:49]
	s_waitcnt lgkmcnt(0)
	v_mfma_f32_32x32x16_bf16 v[50:65], v[86:89], v[94:97], v[50:65]
	ds_read_b128 v[86:89], v68 offset:23072
	v_mfma_f32_32x32x16_bf16 v[2:17], v[98:101], v[126:129], v[2:17]
	v_mfma_f32_32x32x16_bf16 v[18:33], v[98:101], v[130:133], v[18:33]
	ds_read_b128 v[98:101], v68 offset:23136
	s_waitcnt lgkmcnt(1)
	v_mfma_f32_32x32x16_bf16 v[2:17], v[86:89], v[90:93], v[2:17]
	ds_read_b128 v[90:93], v1 offset:55360
	v_mfma_f32_32x32x16_bf16 v[18:33], v[86:89], v[94:97], v[18:33]
	ds_read_b128 v[86:89], v68 offset:18496
	ds_read_b128 v[94:97], v1 offset:59968
	s_waitcnt lgkmcnt(1)
	v_mfma_f32_32x32x16_bf16 v[34:49], v[86:89], v[90:93], v[34:49]
	s_waitcnt lgkmcnt(0)
	v_mfma_f32_32x32x16_bf16 v[50:65], v[86:89], v[94:97], v[50:65]
	ds_read_b128 v[86:89], v68 offset:23104
	s_waitcnt lgkmcnt(0)
	v_mfma_f32_32x32x16_bf16 v[2:17], v[86:89], v[90:93], v[2:17]
	ds_read_b128 v[90:93], v1 offset:55392
	v_mfma_f32_32x32x16_bf16 v[18:33], v[86:89], v[94:97], v[18:33]
	ds_read_b128 v[86:89], v68 offset:18528
	ds_read_b128 v[94:97], v1 offset:60000
	s_waitcnt lgkmcnt(1)
	v_mfma_f32_32x32x16_bf16 v[34:49], v[86:89], v[90:93], v[34:49]
	s_waitcnt lgkmcnt(0)
	v_mfma_f32_32x32x16_bf16 v[50:65], v[86:89], v[94:97], v[50:65]
	global_load_dwordx4 v[86:89], v[72:73], off offset:1152
	v_mfma_f32_32x32x16_bf16 v[2:17], v[98:101], v[90:93], v[2:17]
	global_load_dwordx4 v[90:93], v[76:77], off offset:1152
	v_mfma_f32_32x32x16_bf16 v[18:33], v[98:101], v[94:97], v[18:33]
	s_setprio 0
	s_barrier
	ds_read_b128 v[94:97], v68
	ds_read_b128 v[98:101], v68 offset:4608
	ds_read_b128 v[126:129], v1 offset:36864
	ds_read_b128 v[130:133], v1 offset:41472
	s_waitcnt vmcnt(1)
	ds_write_b128 v66, v[86:89] offset:18432
	ds_write_b128 v66, v[102:105] offset:23040
	ds_write_b128 v66, v[106:109] offset:27648
	ds_write_b128 v66, v[110:113] offset:32256
	s_waitcnt vmcnt(0)
	ds_write_b128 v66, v[90:93] offset:55296
	ds_write_b128 v66, v[122:125] offset:59904
	ds_write_b128 v66, v[118:121] offset:64512
	ds_write_b128 v69, v[114:117] offset:32256
	s_setprio 1
	ds_read_b128 v[86:89], v68 offset:32
	s_waitcnt lgkmcnt(10)
	v_mfma_f32_32x32x16_bf16 v[34:49], v[94:97], v[126:129], v[34:49]
	ds_read_b128 v[90:93], v1 offset:36896
	global_load_dwordx4 v[102:105], v[70:71], off offset:1280
	global_load_dwordx4 v[106:109], v[74:75], off offset:1280
	global_load_dwordx4 v[110:113], v[78:79], off offset:1280
	global_load_dwordx4 v[114:117], v[84:85], off offset:1280
	global_load_dwordx4 v[118:121], v[82:83], off offset:1280
	global_load_dwordx4 v[122:125], v[80:81], off offset:1280
	s_waitcnt lgkmcnt(10)
	v_mfma_f32_32x32x16_bf16 v[50:65], v[94:97], v[130:133], v[50:65]
	ds_read_b128 v[94:97], v1 offset:41504
	s_waitcnt lgkmcnt(1)
	v_mfma_f32_32x32x16_bf16 v[34:49], v[86:89], v[90:93], v[34:49]
	s_waitcnt lgkmcnt(0)
	v_mfma_f32_32x32x16_bf16 v[50:65], v[86:89], v[94:97], v[50:65]
	ds_read_b128 v[86:89], v68 offset:4640
	v_mfma_f32_32x32x16_bf16 v[2:17], v[98:101], v[126:129], v[2:17]
	v_mfma_f32_32x32x16_bf16 v[18:33], v[98:101], v[130:133], v[18:33]
	ds_read_b128 v[98:101], v68 offset:4704
	s_waitcnt lgkmcnt(1)
	v_mfma_f32_32x32x16_bf16 v[2:17], v[86:89], v[90:93], v[2:17]
	ds_read_b128 v[90:93], v1 offset:36928
	v_mfma_f32_32x32x16_bf16 v[18:33], v[86:89], v[94:97], v[18:33]
	ds_read_b128 v[86:89], v68 offset:64
	ds_read_b128 v[94:97], v1 offset:41536
	s_waitcnt lgkmcnt(1)
	v_mfma_f32_32x32x16_bf16 v[34:49], v[86:89], v[90:93], v[34:49]
	s_waitcnt lgkmcnt(0)
	v_mfma_f32_32x32x16_bf16 v[50:65], v[86:89], v[94:97], v[50:65]
	ds_read_b128 v[86:89], v68 offset:4672
	s_waitcnt lgkmcnt(0)
	v_mfma_f32_32x32x16_bf16 v[2:17], v[86:89], v[90:93], v[2:17]
	ds_read_b128 v[90:93], v1 offset:36960
	v_mfma_f32_32x32x16_bf16 v[18:33], v[86:89], v[94:97], v[18:33]
	ds_read_b128 v[86:89], v68 offset:96
	ds_read_b128 v[94:97], v1 offset:41568
	s_waitcnt lgkmcnt(1)
	v_mfma_f32_32x32x16_bf16 v[34:49], v[86:89], v[90:93], v[34:49]
	s_waitcnt lgkmcnt(0)
	v_mfma_f32_32x32x16_bf16 v[50:65], v[86:89], v[94:97], v[50:65]
	global_load_dwordx4 v[86:89], v[72:73], off offset:1280
	v_mfma_f32_32x32x16_bf16 v[2:17], v[98:101], v[90:93], v[2:17]
	global_load_dwordx4 v[90:93], v[76:77], off offset:1280
	v_mfma_f32_32x32x16_bf16 v[18:33], v[98:101], v[94:97], v[18:33]
	s_setprio 0
	s_barrier
; #define MFMA(a, b, c) __builtin_amdgcn_mfma_f32_32x32x16_bf16((a), (b), (c), 0, 0, 0)
; template <int TM, int TN>
; DI void gemm_mainloop(const u16* __restrict__ A, long lda, const u16* __restrict__ Bt, long ldb, int K, char* smem,
;                       f32x16 (&acc)[TM][TN]) {
;     ...
;   for (int kt = 0; kt < nk; kt++) {
;     const int buf = kt & 1;
;     const u16* cA = sA + buf * BM * LD + (wm * 32 * TM + r) * LD + h * 8;
;     const u16* cB = sB + buf * BN * LD + (wn * 32 * TN + r) * LD + h * 8;
;     bf16x8 af[TM], bfr[TN];
; #pragma unroll
;     for (int tm = 0; tm < TM; tm++) af[tm] = *(const bf16x8*)(cA + tm * 32 * LD);
; #pragma unroll
;     for (int tn = 0; tn < TN; tn++) bfr[tn] = *(const bf16x8*)(cB + tn * 32 * LD);
;     if (kt + 1 < nk) GEMM_SSTORE(buf ^ 1)
;     __builtin_amdgcn_sched_barrier(0);
;     __builtin_amdgcn_s_setprio(1);
; #pragma unroll
;     for (int tm = 0; tm < TM; tm++)
; #pragma unroll
;       for (int tn = 0; tn < TN; tn++) acc[tm][tn] = MFMA(af[tm], bfr[tn], acc[tm][tn]);
; #pragma unroll
;     for (int tm = 0; tm < TM; tm++) af[tm] = *(const bf16x8*)(cA + tm * 32 * LD + 16);
; #pragma unroll
;     for (int tn = 0; tn < TN; tn++) bfr[tn] = *(const bf16x8*)(cB + tn * 32 * LD + 16);
; #pragma unroll
;     for (int tm = 0; tm < TM; tm++)
; #pragma unroll
;       for (int tn = 0; tn < TN; tn++) acc[tm][tn] = MFMA(af[tm], bfr[tn], acc[tm][tn]);
;     __builtin_amdgcn_sched_group_barrier(0x8, 4, 0);
;     if (kt + 2 < nk) GEMM_GLOAD((kt + 2) * 64)
; #pragma unroll
;     for (int ks = 2; ks < 4; ks++) {
; #pragma unroll
;       for (int tm = 0; tm < TM; tm++) af[tm] = *(const bf16x8*)(cA + tm * 32 * LD + ks * 16);
; #pragma unroll
;       for (int tn = 0; tn < TN; tn++) bfr[tn] = *(const bf16x8*)(cB + tn * 32 * LD + ks * 16);
; #pragma unroll
;       for (int tm = 0; tm < TM; tm++)
; #pragma unroll
;         for (int tn = 0; tn < TN; tn++) acc[tm][tn] = MFMA(af[tm], bfr[tn], acc[tm][tn]);
;     }
;     __builtin_amdgcn_s_setprio(0);
;     __syncthreads();
	ds_read_b128 v[94:97], v68 offset:18432
	ds_read_b128 v[98:101], v68 offset:23040
	ds_read_b128 v[126:129], v1 offset:55296
	ds_read_b128 v[130:133], v1 offset:59904
	s_waitcnt vmcnt(1)
	ds_write_b128 v66, v[86:89]
	ds_write_b128 v66, v[102:105] offset:4608
	ds_write_b128 v66, v[106:109] offset:9216
	ds_write_b128 v66, v[110:113] offset:13824
	s_waitcnt vmcnt(0)
	ds_write_b128 v66, v[90:93] offset:36864
	ds_write_b128 v66, v[122:125] offset:41472
	ds_write_b128 v66, v[118:121] offset:46080
	ds_write_b128 v66, v[114:117] offset:50688
	s_setprio 1
	ds_read_b128 v[86:89], v68 offset:18464
	s_waitcnt lgkmcnt(10)
	v_mfma_f32_32x32x16_bf16 v[34:49], v[94:97], v[126:129], v[34:49]
	ds_read_b128 v[90:93], v1 offset:55328
	global_load_dwordx4 v[102:105], v[70:71], off offset:1408
	global_load_dwordx4 v[106:109], v[74:75], off offset:1408
	global_load_dwordx4 v[110:113], v[78:79], off offset:1408
	global_load_dwordx4 v[114:117], v[84:85], off offset:1408
	global_load_dwordx4 v[118:121], v[82:83], off offset:1408
	global_load_dwordx4 v[122:125], v[80:81], off offset:1408
	s_waitcnt lgkmcnt(10)
	v_mfma_f32_32x32x16_bf16 v[50:65], v[94:97], v[130:133], v[50:65]
	ds_read_b128 v[94:97], v1 offset:59936
	s_waitcnt lgkmcnt(1)
	v_mfma_f32_32x32x16_bf16 v[34:49], v[86:89], v[90:93], v[34:49]
	s_waitcnt lgkmcnt(0)
	v_mfma_f32_32x32x16_bf16 v[50:65], v[86:89], v[94:97], v[50:65]
	ds_read_b128 v[86:89], v68 offset:23072
	v_mfma_f32_32x32x16_bf16 v[2:17], v[98:101], v[126:129], v[2:17]
	v_mfma_f32_32x32x16_bf16 v[18:33], v[98:101], v[130:133], v[18:33]
	ds_read_b128 v[98:101], v68 offset:23136
	s_waitcnt lgkmcnt(1)
	v_mfma_f32_32x32x16_bf16 v[2:17], v[86:89], v[90:93], v[2:17]
	ds_read_b128 v[90:93], v1 offset:55360
	v_mfma_f32_32x32x16_bf16 v[18:33], v[86:89], v[94:97], v[18:33]
	ds_read_b128 v[86:89], v68 offset:18496
	ds_read_b128 v[94:97], v1 offset:59968
	s_waitcnt lgkmcnt(1)
	v_mfma_f32_32x32x16_bf16 v[34:49], v[86:89], v[90:93], v[34:49]
	s_waitcnt lgkmcnt(0)
	v_mfma_f32_32x32x16_bf16 v[50:65], v[86:89], v[94:97], v[50:65]
	ds_read_b128 v[86:89], v68 offset:23104
	s_waitcnt lgkmcnt(0)
	v_mfma_f32_32x32x16_bf16 v[2:17], v[86:89], v[90:93], v[2:17]
	ds_read_b128 v[90:93], v1 offset:55392
	v_mfma_f32_32x32x16_bf16 v[18:33], v[86:89], v[94:97], v[18:33]
	ds_read_b128 v[86:89], v68 offset:18528
	ds_read_b128 v[94:97], v1 offset:60000
	s_waitcnt lgkmcnt(1)
	v_mfma_f32_32x32x16_bf16 v[34:49], v[86:89], v[90:93], v[34:49]
	s_waitcnt lgkmcnt(0)
	v_mfma_f32_32x32x16_bf16 v[50:65], v[86:89], v[94:97], v[50:65]
	global_load_dwordx4 v[86:89], v[72:73], off offset:1408
	v_mfma_f32_32x32x16_bf16 v[2:17], v[98:101], v[90:93], v[2:17]
	global_load_dwordx4 v[90:93], v[76:77], off offset:1408
	v_mfma_f32_32x32x16_bf16 v[18:33], v[98:101], v[94:97], v[18:33]
	s_setprio 0
	s_barrier
	ds_read_b128 v[94:97], v68
	ds_read_b128 v[98:101], v68 offset:4608
	ds_read_b128 v[126:129], v1 offset:36864
	ds_read_b128 v[130:133], v1 offset:41472
	s_waitcnt vmcnt(1)
	ds_write_b128 v66, v[86:89] offset:18432
	ds_write_b128 v66, v[102:105] offset:23040
	ds_write_b128 v66, v[106:109] offset:27648
	ds_write_b128 v66, v[110:113] offset:32256
	s_waitcnt vmcnt(0)
	ds_write_b128 v66, v[90:93] offset:55296
	ds_write_b128 v66, v[122:125] offset:59904
	ds_write_b128 v66, v[118:121] offset:64512
	ds_write_b128 v69, v[114:117] offset:32256
	s_setprio 1
	ds_read_b128 v[86:89], v68 offset:32
	s_waitcnt lgkmcnt(10)
	v_mfma_f32_32x32x16_bf16 v[34:49], v[94:97], v[126:129], v[34:49]
	ds_read_b128 v[90:93], v1 offset:36896
	global_load_dwordx4 v[102:105], v[70:71], off offset:1536
	global_load_dwordx4 v[106:109], v[74:75], off offset:1536
	global_load_dwordx4 v[110:113], v[78:79], off offset:1536
	global_load_dwordx4 v[114:117], v[84:85], off offset:1536
	global_load_dwordx4 v[118:121], v[82:83], off offset:1536
	global_load_dwordx4 v[122:125], v[80:81], off offset:1536
	s_waitcnt lgkmcnt(10)
	v_mfma_f32_32x32x16_bf16 v[50:65], v[94:97], v[130:133], v[50:65]
	ds_read_b128 v[94:97], v1 offset:41504
	s_waitcnt lgkmcnt(1)
	v_mfma_f32_32x32x16_bf16 v[34:49], v[86:89], v[90:93], v[34:49]
	s_waitcnt lgkmcnt(0)
	v_mfma_f32_32x32x16_bf16 v[50:65], v[86:89], v[94:97], v[50:65]
	ds_read_b128 v[86:89], v68 offset:4640
	v_mfma_f32_32x32x16_bf16 v[2:17], v[98:101], v[126:129], v[2:17]
	v_mfma_f32_32x32x16_bf16 v[18:33], v[98:101], v[130:133], v[18:33]
	ds_read_b128 v[98:101], v68 offset:4704
	s_waitcnt lgkmcnt(1)
	v_mfma_f32_32x32x16_bf16 v[2:17], v[86:89], v[90:93], v[2:17]
	ds_read_b128 v[90:93], v1 offset:36928
	v_mfma_f32_32x32x16_bf16 v[18:33], v[86:89], v[94:97], v[18:33]
	ds_read_b128 v[86:89], v68 offset:64
	ds_read_b128 v[94:97], v1 offset:41536
	s_waitcnt lgkmcnt(1)
	v_mfma_f32_32x32x16_bf16 v[34:49], v[86:89], v[90:93], v[34:49]
	s_waitcnt lgkmcnt(0)
	v_mfma_f32_32x32x16_bf16 v[50:65], v[86:89], v[94:97], v[50:65]
	ds_read_b128 v[86:89], v68 offset:4672
	s_waitcnt lgkmcnt(0)
	v_mfma_f32_32x32x16_bf16 v[2:17], v[86:89], v[90:93], v[2:17]
	ds_read_b128 v[90:93], v1 offset:36960
	v_mfma_f32_32x32x16_bf16 v[18:33], v[86:89], v[94:97], v[18:33]
	ds_read_b128 v[86:89], v68 offset:96
	ds_read_b128 v[94:97], v1 offset:41568
	s_waitcnt lgkmcnt(1)
	v_mfma_f32_32x32x16_bf16 v[34:49], v[86:89], v[90:93], v[34:49]
	s_waitcnt lgkmcnt(0)
	v_mfma_f32_32x32x16_bf16 v[50:65], v[86:89], v[94:97], v[50:65]
	global_load_dwordx4 v[86:89], v[72:73], off offset:1536
	v_mfma_f32_32x32x16_bf16 v[2:17], v[98:101], v[90:93], v[2:17]
	global_load_dwordx4 v[90:93], v[76:77], off offset:1536
	v_mfma_f32_32x32x16_bf16 v[18:33], v[98:101], v[94:97], v[18:33]
	s_setprio 0
	s_barrier
; #define MFMA(a, b, c) __builtin_amdgcn_mfma_f32_32x32x16_bf16((a), (b), (c), 0, 0, 0)
; template <int TM, int TN>
; DI void gemm_mainloop(const u16* __restrict__ A, long lda, const u16* __restrict__ Bt, long ldb, int K, char* smem,
;                       f32x16 (&acc)[TM][TN]) {
;     ...
;   for (int kt = 0; kt < nk; kt++) {
;     const int buf = kt & 1;
;     const u16* cA = sA + buf * BM * LD + (wm * 32 * TM + r) * LD + h * 8;
;     const u16* cB = sB + buf * BN * LD + (wn * 32 * TN + r) * LD + h * 8;
;     bf16x8 af[TM], bfr[TN];
; #pragma unroll
;     for (int tm = 0; tm < TM; tm++) af[tm] = *(const bf16x8*)(cA + tm * 32 * LD);
; #pragma unroll
;     for (int tn = 0; tn < TN; tn++) bfr[tn] = *(const bf16x8*)(cB + tn * 32 * LD);
;     if (kt + 1 < nk) GEMM_SSTORE(buf ^ 1)
;     __builtin_amdgcn_sched_barrier(0);
;     __builtin_amdgcn_s_setprio(1);
; #pragma unroll
;     for (int tm = 0; tm < TM; tm++)
; #pragma unroll
;       for (int tn = 0; tn < TN; tn++) acc[tm][tn] = MFMA(af[tm], bfr[tn], acc[tm][tn]);
; #pragma unroll
;     for (int tm = 0; tm < TM; tm++) af[tm] = *(const bf16x8*)(cA + tm * 32 * LD + 16);
; #pragma unroll
;     for (int tn = 0; tn < TN; tn++) bfr[tn] = *(const bf16x8*)(cB + tn * 32 * LD + 16);
; #pragma unroll
;     for (int tm = 0; tm < TM; tm++)
; #pragma unroll
;       for (int tn = 0; tn < TN; tn++) acc[tm][tn] = MFMA(af[tm], bfr[tn], acc[tm][tn]);
;     __builtin_amdgcn_sched_group_barrier(0x8, 4, 0);
;     if (kt + 2 < nk) GEMM_GLOAD((kt + 2) * 64)
; #pragma unroll
;     for (int ks = 2; ks < 4; ks++) {
; #pragma unroll
;       for (int tm = 0; tm < TM; tm++) af[tm] = *(const bf16x8*)(cA + tm * 32 * LD + ks * 16);
; #pragma unroll
;       for (int tn = 0; tn < TN; tn++) bfr[tn] = *(const bf16x8*)(cB + tn * 32 * LD + ks * 16);
; #pragma unroll
;       for (int tm = 0; tm < TM; tm++)
; #pragma unroll
;         for (int tn = 0; tn < TN; tn++) acc[tm][tn] = MFMA(af[tm], bfr[tn], acc[tm][tn]);
;     }
;     __builtin_amdgcn_s_setprio(0);
;     __syncthreads();
	ds_read_b128 v[94:97], v68 offset:18432
	ds_read_b128 v[98:101], v68 offset:23040
	ds_read_b128 v[126:129], v1 offset:55296
	ds_read_b128 v[130:133], v1 offset:59904
	s_waitcnt vmcnt(1)
	ds_write_b128 v66, v[86:89]
	ds_write_b128 v66, v[102:105] offset:4608
	ds_write_b128 v66, v[106:109] offset:9216
	ds_write_b128 v66, v[110:113] offset:13824
	s_waitcnt vmcnt(0)
	ds_write_b128 v66, v[90:93] offset:36864
	ds_write_b128 v66, v[122:125] offset:41472
	ds_write_b128 v66, v[118:121] offset:46080
	ds_write_b128 v66, v[114:117] offset:50688
	s_setprio 1
	ds_read_b128 v[86:89], v68 offset:18464
	s_waitcnt lgkmcnt(10)
	v_mfma_f32_32x32x16_bf16 v[34:49], v[94:97], v[126:129], v[34:49]
	ds_read_b128 v[90:93], v1 offset:55328
	global_load_dwordx4 v[102:105], v[70:71], off offset:1664
	global_load_dwordx4 v[106:109], v[74:75], off offset:1664
	global_load_dwordx4 v[110:113], v[78:79], off offset:1664
	global_load_dwordx4 v[114:117], v[84:85], off offset:1664
	global_load_dwordx4 v[118:121], v[82:83], off offset:1664
	global_load_dwordx4 v[122:125], v[80:81], off offset:1664
	s_waitcnt lgkmcnt(10)
	v_mfma_f32_32x32x16_bf16 v[50:65], v[94:97], v[130:133], v[50:65]
	ds_read_b128 v[94:97], v1 offset:59936
	s_waitcnt lgkmcnt(1)
	v_mfma_f32_32x32x16_bf16 v[34:49], v[86:89], v[90:93], v[34:49]
	s_waitcnt lgkmcnt(0)
	v_mfma_f32_32x32x16_bf16 v[50:65], v[86:89], v[94:97], v[50:65]
	ds_read_b128 v[86:89], v68 offset:23072
	v_mfma_f32_32x32x16_bf16 v[2:17], v[98:101], v[126:129], v[2:17]
	v_mfma_f32_32x32x16_bf16 v[18:33], v[98:101], v[130:133], v[18:33]
	ds_read_b128 v[98:101], v68 offset:23136
	s_waitcnt lgkmcnt(1)
	v_mfma_f32_32x32x16_bf16 v[2:17], v[86:89], v[90:93], v[2:17]
	ds_read_b128 v[90:93], v1 offset:55360
	v_mfma_f32_32x32x16_bf16 v[18:33], v[86:89], v[94:97], v[18:33]
	ds_read_b128 v[86:89], v68 offset:18496
	ds_read_b128 v[94:97], v1 offset:59968
	s_waitcnt lgkmcnt(1)
	v_mfma_f32_32x32x16_bf16 v[34:49], v[86:89], v[90:93], v[34:49]
	s_waitcnt lgkmcnt(0)
	v_mfma_f32_32x32x16_bf16 v[50:65], v[86:89], v[94:97], v[50:65]
	ds_read_b128 v[86:89], v68 offset:23104
	s_waitcnt lgkmcnt(0)
	v_mfma_f32_32x32x16_bf16 v[2:17], v[86:89], v[90:93], v[2:17]
	ds_read_b128 v[90:93], v1 offset:55392
	v_mfma_f32_32x32x16_bf16 v[18:33], v[86:89], v[94:97], v[18:33]
	ds_read_b128 v[86:89], v68 offset:18528
	ds_read_b128 v[94:97], v1 offset:60000
	s_waitcnt lgkmcnt(1)
	v_mfma_f32_32x32x16_bf16 v[34:49], v[86:89], v[90:93], v[34:49]
	s_waitcnt lgkmcnt(0)
	v_mfma_f32_32x32x16_bf16 v[50:65], v[86:89], v[94:97], v[50:65]
	global_load_dwordx4 v[86:89], v[72:73], off offset:1664
	v_mfma_f32_32x32x16_bf16 v[2:17], v[98:101], v[90:93], v[2:17]
	global_load_dwordx4 v[90:93], v[76:77], off offset:1664
	v_mfma_f32_32x32x16_bf16 v[18:33], v[98:101], v[94:97], v[18:33]
	s_setprio 0
	s_barrier
	ds_read_b128 v[94:97], v68
	ds_read_b128 v[98:101], v68 offset:4608
	ds_read_b128 v[126:129], v1 offset:36864
	ds_read_b128 v[130:133], v1 offset:41472
	s_waitcnt vmcnt(1)
	ds_write_b128 v66, v[86:89] offset:18432
	ds_write_b128 v66, v[102:105] offset:23040
	ds_write_b128 v66, v[106:109] offset:27648
	ds_write_b128 v66, v[110:113] offset:32256
	s_waitcnt vmcnt(0)
	ds_write_b128 v66, v[90:93] offset:55296
	ds_write_b128 v66, v[122:125] offset:59904
	ds_write_b128 v66, v[118:121] offset:64512
	ds_write_b128 v69, v[114:117] offset:32256
	s_setprio 1
	ds_read_b128 v[86:89], v68 offset:32
	s_waitcnt lgkmcnt(10)
	v_mfma_f32_32x32x16_bf16 v[34:49], v[94:97], v[126:129], v[34:49]
	ds_read_b128 v[90:93], v1 offset:36896
	global_load_dwordx4 v[102:105], v[70:71], off offset:1792
	global_load_dwordx4 v[106:109], v[74:75], off offset:1792
	global_load_dwordx4 v[110:113], v[78:79], off offset:1792
	global_load_dwordx4 v[114:117], v[84:85], off offset:1792
	global_load_dwordx4 v[118:121], v[82:83], off offset:1792
	global_load_dwordx4 v[122:125], v[80:81], off offset:1792
	s_waitcnt lgkmcnt(10)
	v_mfma_f32_32x32x16_bf16 v[50:65], v[94:97], v[130:133], v[50:65]
	ds_read_b128 v[94:97], v1 offset:41504
	s_waitcnt lgkmcnt(1)
	v_mfma_f32_32x32x16_bf16 v[34:49], v[86:89], v[90:93], v[34:49]
	s_waitcnt lgkmcnt(0)
	v_mfma_f32_32x32x16_bf16 v[50:65], v[86:89], v[94:97], v[50:65]
	ds_read_b128 v[86:89], v68 offset:4640
	v_mfma_f32_32x32x16_bf16 v[2:17], v[98:101], v[126:129], v[2:17]
	v_mfma_f32_32x32x16_bf16 v[18:33], v[98:101], v[130:133], v[18:33]
	ds_read_b128 v[98:101], v68 offset:4704
	s_waitcnt lgkmcnt(1)
	v_mfma_f32_32x32x16_bf16 v[2:17], v[86:89], v[90:93], v[2:17]
	ds_read_b128 v[90:93], v1 offset:36928
	v_mfma_f32_32x32x16_bf16 v[18:33], v[86:89], v[94:97], v[18:33]
	ds_read_b128 v[86:89], v68 offset:64
	ds_read_b128 v[94:97], v1 offset:41536
	s_waitcnt lgkmcnt(1)
	v_mfma_f32_32x32x16_bf16 v[34:49], v[86:89], v[90:93], v[34:49]
	s_waitcnt lgkmcnt(0)
	v_mfma_f32_32x32x16_bf16 v[50:65], v[86:89], v[94:97], v[50:65]
	ds_read_b128 v[86:89], v68 offset:4672
	s_waitcnt lgkmcnt(0)
	v_mfma_f32_32x32x16_bf16 v[2:17], v[86:89], v[90:93], v[2:17]
	ds_read_b128 v[90:93], v1 offset:36960
	v_mfma_f32_32x32x16_bf16 v[18:33], v[86:89], v[94:97], v[18:33]
	ds_read_b128 v[86:89], v68 offset:96
	ds_read_b128 v[94:97], v1 offset:41568
	s_waitcnt lgkmcnt(1)
	v_mfma_f32_32x32x16_bf16 v[34:49], v[86:89], v[90:93], v[34:49]
	s_waitcnt lgkmcnt(0)
	v_mfma_f32_32x32x16_bf16 v[50:65], v[86:89], v[94:97], v[50:65]
	global_load_dwordx4 v[86:89], v[72:73], off offset:1792
	v_mfma_f32_32x32x16_bf16 v[2:17], v[98:101], v[90:93], v[2:17]
	global_load_dwordx4 v[90:93], v[76:77], off offset:1792
	v_mfma_f32_32x32x16_bf16 v[18:33], v[98:101], v[94:97], v[18:33]
	s_setprio 0
	s_barrier
; #define MFMA(a, b, c) __builtin_amdgcn_mfma_f32_32x32x16_bf16((a), (b), (c), 0, 0, 0)
; template <int TM, int TN>
; DI void gemm_mainloop(const u16* __restrict__ A, long lda, const u16* __restrict__ Bt, long ldb, int K, char* smem,
;                       f32x16 (&acc)[TM][TN]) {
;     ...
;   for (int kt = 0; kt < nk; kt++) {
;     const int buf = kt & 1;
;     const u16* cA = sA + buf * BM * LD + (wm * 32 * TM + r) * LD + h * 8;
;     const u16* cB = sB + buf * BN * LD + (wn * 32 * TN + r) * LD + h * 8;
;     bf16x8 af[TM], bfr[TN];
; #pragma unroll
;     for (int tm = 0; tm < TM; tm++) af[tm] = *(const bf16x8*)(cA + tm * 32 * LD);
; #pragma unroll
;     for (int tn = 0; tn < TN; tn++) bfr[tn] = *(const bf16x8*)(cB + tn * 32 * LD);
;     if (kt + 1 < nk) GEMM_SSTORE(buf ^ 1)
;     __builtin_amdgcn_sched_barrier(0);
;     __builtin_amdgcn_s_setprio(1);
; #pragma unroll
;     for (int tm = 0; tm < TM; tm++)
; #pragma unroll
;       for (int tn = 0; tn < TN; tn++) acc[tm][tn] = MFMA(af[tm], bfr[tn], acc[tm][tn]);
; #pragma unroll
;     for (int tm = 0; tm < TM; tm++) af[tm] = *(const bf16x8*)(cA + tm * 32 * LD + 16);
; #pragma unroll
;     for (int tn = 0; tn < TN; tn++) bfr[tn] = *(const bf16x8*)(cB + tn * 32 * LD + 16);
; #pragma unroll
;     for (int tm = 0; tm < TM; tm++)
; #pragma unroll
;       for (int tn = 0; tn < TN; tn++) acc[tm][tn] = MFMA(af[tm], bfr[tn], acc[tm][tn]);
;     __builtin_amdgcn_sched_group_barrier(0x8, 4, 0);
;     if (kt + 2 < nk) GEMM_GLOAD((kt + 2) * 64)
; #pragma unroll
;     for (int ks = 2; ks < 4; ks++) {
; #pragma unroll
;       for (int tm = 0; tm < TM; tm++) af[tm] = *(const bf16x8*)(cA + tm * 32 * LD + ks * 16);
; #pragma unroll
;       for (int tn = 0; tn < TN; tn++) bfr[tn] = *(const bf16x8*)(cB + tn * 32 * LD + ks * 16);
; #pragma unroll
;       for (int tm = 0; tm < TM; tm++)
; #pragma unroll
;         for (int tn = 0; tn < TN; tn++) acc[tm][tn] = MFMA(af[tm], bfr[tn], acc[tm][tn]);
;     }
;     __builtin_amdgcn_s_setprio(0);
;     __syncthreads();
	ds_read_b128 v[94:97], v68 offset:18432
	ds_read_b128 v[98:101], v68 offset:23040
	ds_read_b128 v[126:129], v1 offset:55296
	ds_read_b128 v[130:133], v1 offset:59904
	s_waitcnt vmcnt(1)
	ds_write_b128 v66, v[86:89]
	ds_write_b128 v66, v[102:105] offset:4608
	ds_write_b128 v66, v[106:109] offset:9216
	ds_write_b128 v66, v[110:113] offset:13824
	s_waitcnt vmcnt(0)
	ds_write_b128 v66, v[90:93] offset:36864
	ds_write_b128 v66, v[122:125] offset:41472
	ds_write_b128 v66, v[118:121] offset:46080
	ds_write_b128 v66, v[114:117] offset:50688
	s_setprio 1
	ds_read_b128 v[86:89], v68 offset:18464
	s_waitcnt lgkmcnt(10)
	v_mfma_f32_32x32x16_bf16 v[34:49], v[94:97], v[126:129], v[34:49]
	ds_read_b128 v[90:93], v1 offset:55328
	global_load_dwordx4 v[102:105], v[70:71], off offset:1920
	global_load_dwordx4 v[106:109], v[74:75], off offset:1920
	global_load_dwordx4 v[110:113], v[78:79], off offset:1920
	global_load_dwordx4 v[114:117], v[84:85], off offset:1920
	global_load_dwordx4 v[118:121], v[82:83], off offset:1920
	global_load_dwordx4 v[122:125], v[80:81], off offset:1920
	s_waitcnt lgkmcnt(10)
	v_mfma_f32_32x32x16_bf16 v[50:65], v[94:97], v[130:133], v[50:65]
	ds_read_b128 v[94:97], v1 offset:59936
	s_waitcnt lgkmcnt(1)
	v_mfma_f32_32x32x16_bf16 v[34:49], v[86:89], v[90:93], v[34:49]
	s_waitcnt lgkmcnt(0)
	v_mfma_f32_32x32x16_bf16 v[50:65], v[86:89], v[94:97], v[50:65]
	ds_read_b128 v[86:89], v68 offset:23072
	v_mfma_f32_32x32x16_bf16 v[2:17], v[98:101], v[126:129], v[2:17]
	v_mfma_f32_32x32x16_bf16 v[18:33], v[98:101], v[130:133], v[18:33]
	ds_read_b128 v[98:101], v68 offset:23136
	s_waitcnt lgkmcnt(1)
	v_mfma_f32_32x32x16_bf16 v[2:17], v[86:89], v[90:93], v[2:17]
	ds_read_b128 v[90:93], v1 offset:55360
	v_mfma_f32_32x32x16_bf16 v[18:33], v[86:89], v[94:97], v[18:33]
	ds_read_b128 v[86:89], v68 offset:18496
	ds_read_b128 v[94:97], v1 offset:59968
	s_waitcnt lgkmcnt(1)
	v_mfma_f32_32x32x16_bf16 v[34:49], v[86:89], v[90:93], v[34:49]
	s_waitcnt lgkmcnt(0)
	v_mfma_f32_32x32x16_bf16 v[50:65], v[86:89], v[94:97], v[50:65]
	ds_read_b128 v[86:89], v68 offset:23104
	s_waitcnt lgkmcnt(0)
	v_mfma_f32_32x32x16_bf16 v[2:17], v[86:89], v[90:93], v[2:17]
	ds_read_b128 v[90:93], v1 offset:55392
	v_mfma_f32_32x32x16_bf16 v[18:33], v[86:89], v[94:97], v[18:33]
	ds_read_b128 v[86:89], v68 offset:18528
	ds_read_b128 v[94:97], v1 offset:60000
	s_waitcnt lgkmcnt(1)
	v_mfma_f32_32x32x16_bf16 v[34:49], v[86:89], v[90:93], v[34:49]
	s_waitcnt lgkmcnt(0)
	v_mfma_f32_32x32x16_bf16 v[50:65], v[86:89], v[94:97], v[50:65]
	global_load_dwordx4 v[86:89], v[72:73], off offset:1920
	s_nop 0
	global_load_dwordx4 v[70:73], v[76:77], off offset:1920
	v_mfma_f32_32x32x16_bf16 v[2:17], v[98:101], v[90:93], v[2:17]
	v_mfma_f32_32x32x16_bf16 v[18:33], v[98:101], v[94:97], v[18:33]
	s_setprio 0
	s_barrier
	ds_read_b128 v[74:77], v68
	ds_read_b128 v[78:81], v68 offset:4608
	ds_read_b128 v[82:85], v1 offset:36864
	ds_read_b128 v[90:93], v1 offset:41472
	s_waitcnt vmcnt(1)
	ds_write_b128 v66, v[86:89] offset:18432
	ds_write_b128 v66, v[102:105] offset:23040
	ds_write_b128 v66, v[106:109] offset:27648
	ds_write_b128 v66, v[110:113] offset:32256
	s_waitcnt vmcnt(0)
	ds_write_b128 v66, v[70:73] offset:55296
	ds_write_b128 v66, v[122:125] offset:59904
	ds_write_b128 v66, v[118:121] offset:64512
	ds_write_b128 v69, v[114:117] offset:32256
	s_setprio 1
	ds_read_b128 v[70:73], v68 offset:32
	s_waitcnt lgkmcnt(10)
	v_mfma_f32_32x32x16_bf16 v[34:49], v[74:77], v[82:85], v[34:49]
	s_waitcnt lgkmcnt(9)
	v_mfma_f32_32x32x16_bf16 v[50:65], v[74:77], v[90:93], v[50:65]
	ds_read_b128 v[74:77], v1 offset:36896
	v_mfma_f32_32x32x16_bf16 v[2:17], v[78:81], v[82:85], v[2:17]
	v_mfma_f32_32x32x16_bf16 v[18:33], v[78:81], v[90:93], v[18:33]
	ds_read_b128 v[78:81], v1 offset:41504
	s_waitcnt lgkmcnt(1)
	v_mfma_f32_32x32x16_bf16 v[34:49], v[70:73], v[74:77], v[34:49]
	s_waitcnt lgkmcnt(0)
	v_mfma_f32_32x32x16_bf16 v[50:65], v[70:73], v[78:81], v[50:65]
	ds_read_b128 v[70:73], v68 offset:4640
	s_waitcnt lgkmcnt(0)
	v_mfma_f32_32x32x16_bf16 v[2:17], v[70:73], v[74:77], v[2:17]
	ds_read_b128 v[74:77], v1 offset:36928
	v_mfma_f32_32x32x16_bf16 v[18:33], v[70:73], v[78:81], v[18:33]
	ds_read_b128 v[70:73], v68 offset:64
	ds_read_b128 v[78:81], v1 offset:41536
	s_waitcnt lgkmcnt(1)
	v_mfma_f32_32x32x16_bf16 v[34:49], v[70:73], v[74:77], v[34:49]
	s_waitcnt lgkmcnt(0)
	v_mfma_f32_32x32x16_bf16 v[50:65], v[70:73], v[78:81], v[50:65]
	ds_read_b128 v[70:73], v68 offset:4672
	s_waitcnt lgkmcnt(0)
	v_mfma_f32_32x32x16_bf16 v[2:17], v[70:73], v[74:77], v[2:17]
	ds_read_b128 v[74:77], v1 offset:36960
	v_mfma_f32_32x32x16_bf16 v[18:33], v[70:73], v[78:81], v[18:33]
	ds_read_b128 v[70:73], v68 offset:96
	ds_read_b128 v[78:81], v1 offset:41568
	s_waitcnt lgkmcnt(1)
	v_mfma_f32_32x32x16_bf16 v[34:49], v[70:73], v[74:77], v[34:49]
	s_waitcnt lgkmcnt(0)
	v_mfma_f32_32x32x16_bf16 v[50:65], v[70:73], v[78:81], v[50:65]
	ds_read_b128 v[70:73], v68 offset:4704
	s_waitcnt lgkmcnt(0)
	v_mfma_f32_32x32x16_bf16 v[2:17], v[70:73], v[74:77], v[2:17]
	v_mfma_f32_32x32x16_bf16 v[18:33], v[70:73], v[78:81], v[18:33]
	s_setprio 0
	s_barrier
; #define MFMA(a, b, c) __builtin_amdgcn_mfma_f32_32x32x16_bf16((a), (b), (c), 0, 0, 0)
; DI unsigned pk2(float a, float b) { fv2 v = {a, b}; bfv2 r = __builtin_convertvector(v, bfv2); return __builtin_bit_cast(unsigned, r); }
; DI int crow(int i, int h) { return (i & 3) + 8 * (i >> 2) + 4 * h; }
; template <int TM, int TN>
; DI void gemm_mainloop(const u16* __restrict__ A, long lda, const u16* __restrict__ Bt, long ldb, int K, char* smem,
;                       f32x16 (&acc)[TM][TN]) {
;     ...
;     for (int tm = 0; tm < TM; tm++)
; #pragma unroll
;       for (int tn = 0; tn < TN; tn++) acc[tm][tn] = MFMA(af[tm], bfr[tn], acc[tm][tn]);
;     __builtin_amdgcn_sched_group_barrier(0x8, 4, 0);
;     if (kt + 2 < nk) GEMM_GLOAD((kt + 2) * 64)
; #pragma unroll
;     for (int ks = 2; ks < 4; ks++) {
; #pragma unroll
;       for (int tm = 0; tm < TM; tm++) af[tm] = *(const bf16x8*)(cA + tm * 32 * LD + ks * 16);
; #pragma unroll
;       for (int tn = 0; tn < TN; tn++) bfr[tn] = *(const bf16x8*)(cB + tn * 32 * LD + ks * 16);
; #pragma unroll
;       for (int tm = 0; tm < TM; tm++)
; #pragma unroll
;         for (int tn = 0; tn < TN; tn++) acc[tm][tn] = MFMA(af[tm], bfr[tn], acc[tm][tn]);
;     }
;     __builtin_amdgcn_s_setprio(0);
;     __syncthreads();
; template <int TM, int TN, class Epi>
; DI void gemm_tile(const u16* A, long lda, const u16* Bt, long ldb, int K, int m0, int n0, char* smem, const Epi& epi) {
;     ...
; #pragma unroll
;   for (int tm = 0; tm < TM; tm++)
; #pragma unroll
;     for (int tn = 0; tn < TN; tn++)
; #pragma unroll
;       for (int i = 0; i < 16; i++)
;         Ct[(wm * 32 * TM + tm * 32 + crow(i, h)) * LDC + wn * 32 * TN + tn * 32 + r] = acc[tm][tn][i];
;   __syncthreads();
;   epi(Ct, LDC, m0, n0, tid, BM);
;   __syncthreads();
;   (void)BM;
; }
;   DI void operator()(const float* Ct, int ldc, int m0, int n0, int tid, int bm) const {
; #pragma unroll 4
;     for (int it = 0; it < bm / 16; it++) {
;       int id = tid + 256 * it; int row = id >> 4, c8 = (id & 15) * 8;
;       int n = n0 + c8;
;       if (n < nmax) {
;         const float* c = Ct + row * ldc + c8;
;         float4 a = *(const float4*)c, b = *(const float4*)(c + 4);
;         uint4 v; v.x = pk2(a.x, a.y); v.y = pk2(a.z, a.w); v.z = pk2(b.x, b.y); v.w = pk2(b.z, b.w);
;         *(uint4*)(out + (long)(m0 + row) * ldo + n) = v;
;         if (gates != nullptr && n == 1952) {
	ds_read_b128 v[70:73], v68 offset:18432
	ds_read_b128 v[74:77], v68 offset:23040
	ds_read_b128 v[78:81], v1 offset:55296
	ds_read_b128 v[82:85], v1 offset:59904
	s_setprio 1
	s_waitcnt lgkmcnt(1)
	v_mfma_f32_32x32x16_bf16 v[34:49], v[70:73], v[78:81], v[34:49]
	s_waitcnt lgkmcnt(0)
	v_mfma_f32_32x32x16_bf16 v[50:65], v[70:73], v[82:85], v[50:65]
	ds_read_b128 v[70:73], v68 offset:18464
	v_mfma_f32_32x32x16_bf16 v[2:17], v[74:77], v[78:81], v[2:17]
	ds_read_b128 v[78:81], v1 offset:59936
	v_mfma_f32_32x32x16_bf16 v[18:33], v[74:77], v[82:85], v[18:33]
	ds_read_b128 v[74:77], v1 offset:55328
	s_waitcnt lgkmcnt(0)
	v_mfma_f32_32x32x16_bf16 v[34:49], v[70:73], v[74:77], v[34:49]
	v_mfma_f32_32x32x16_bf16 v[50:65], v[70:73], v[78:81], v[50:65]
	ds_read_b128 v[70:73], v68 offset:23072
	s_waitcnt lgkmcnt(0)
	v_mfma_f32_32x32x16_bf16 v[2:17], v[70:73], v[74:77], v[2:17]
	ds_read_b128 v[74:77], v1 offset:55360
	v_mfma_f32_32x32x16_bf16 v[18:33], v[70:73], v[78:81], v[18:33]
	ds_read_b128 v[70:73], v68 offset:18496
	ds_read_b128 v[78:81], v1 offset:59968
	s_waitcnt lgkmcnt(1)
	v_mfma_f32_32x32x16_bf16 v[34:49], v[70:73], v[74:77], v[34:49]
	s_waitcnt lgkmcnt(0)
	v_mfma_f32_32x32x16_bf16 v[50:65], v[70:73], v[78:81], v[50:65]
	ds_read_b128 v[70:73], v68 offset:23104
	s_waitcnt lgkmcnt(0)
	v_mfma_f32_32x32x16_bf16 v[2:17], v[70:73], v[74:77], v[2:17]
	ds_read_b128 v[74:77], v1 offset:55392
	v_mfma_f32_32x32x16_bf16 v[18:33], v[70:73], v[78:81], v[18:33]
	ds_read_b128 v[70:73], v68 offset:18528
	ds_read_b128 v[78:81], v1 offset:60000
	s_waitcnt lgkmcnt(1)
	v_mfma_f32_32x32x16_bf16 v[34:49], v[70:73], v[74:77], v[34:49]
	s_waitcnt lgkmcnt(0)
	v_mfma_f32_32x32x16_bf16 v[50:65], v[70:73], v[78:81], v[50:65]
	ds_read_b128 v[68:71], v68 offset:23136
	s_waitcnt lgkmcnt(0)
	v_mfma_f32_32x32x16_bf16 v[2:17], v[68:71], v[74:77], v[2:17]
	v_mfma_f32_32x32x16_bf16 v[18:33], v[68:71], v[78:81], v[18:33]
	s_setprio 0
	v_mov_b32_e32 v1, v0
	s_barrier
	s_mov_b32 s24, 0
	v_lshrrev_b32_e32 v66, 1, v1
	v_and_b32_e32 v66, 0xfffffc0, v66
	v_lshrrev_b32_e32 v68, 3, v1
	v_and_or_b32 v66, v68, 4, v66
	v_and_b32_e32 v68, 0x5f, v1
	v_mul_lo_u32 v66, v66, s20
	v_lshl_add_u32 v66, v68, 2, v66
	ds_write2_b32 v66, v34, v50 offset1:32
	v_add_u32_e32 v34, 0x400, v66
	ds_write2_b32 v34, v36, v52 offset0:8 offset1:40
	ds_write2_b32 v34, v37, v53 offset0:140 offset1:172
	v_add_u32_e32 v34, 0x1000, v66
	ds_write2_b32 v34, v38, v54 offset0:32 offset1:64
	ds_write2_b32 v34, v39, v55 offset0:164 offset1:196
	v_add_u32_e32 v34, 0x1400, v66
	ds_write2_b32 v34, v40, v56 offset0:40 offset1:72
	ds_write2_b32 v34, v41, v57 offset0:172 offset1:204
	v_add_u32_e32 v34, 0x2000, v66
	ds_write2_b32 v34, v42, v58 offset0:64 offset1:96
	ds_write2_b32 v34, v43, v59 offset0:196 offset1:228
	v_add_u32_e32 v34, 0x2400, v66
	ds_write2_b32 v34, v44, v60 offset0:72 offset1:104
	ds_write2_b32 v34, v45, v61 offset0:204 offset1:236
	v_add_u32_e32 v34, 0x3000, v66
	ds_write2_b32 v34, v46, v62 offset0:96 offset1:128
	v_add_u32_e32 v34, 0x3200, v66
	ds_write2_b32 v34, v47, v63 offset0:100 offset1:132
	v_add_u32_e32 v34, 0x3400, v66
	ds_write2_b32 v34, v48, v64 offset0:104 offset1:136
	v_add_u32_e32 v34, 0x3600, v66
	ds_write2_b32 v34, v49, v65 offset0:108 offset1:140
	v_add_u32_e32 v34, 0x4000, v66
	ds_write2_b32 v34, v2, v18 offset0:128 offset1:160
	v_add_u32_e32 v2, 0x4400, v66
	ds_write2_b32 v2, v3, v19 offset0:4 offset1:36
	ds_write2_b32 v2, v4, v20 offset0:136 offset1:168
	v_add_u32_e32 v2, 0x4800, v66
	ds_write2_b32 v2, v5, v21 offset0:12 offset1:44
	v_add_u32_e32 v2, 0x5000, v66
	ds_write2_b32 v2, v6, v22 offset0:160 offset1:192
	v_add_u32_e32 v2, 0x5400, v66
	ds_write2_b32 v2, v7, v23 offset0:36 offset1:68
	ds_write2_b32 v2, v8, v24 offset0:168 offset1:200
	v_add_u32_e32 v2, 0x5800, v66
	ds_write2_b32 v2, v9, v25 offset0:44 offset1:76
	v_add_u32_e32 v2, 0x6000, v66
	ds_write2_b32 v2, v10, v26 offset0:192 offset1:224
	v_add_u32_e32 v2, 0x6400, v66
	ds_write2_b32 v2, v11, v27 offset0:68 offset1:100
	ds_write2_b32 v2, v12, v28 offset0:200 offset1:232
	v_add_u32_e32 v2, 0x6800, v66
	ds_write2_b32 v2, v13, v29 offset0:76 offset1:108
	v_add_u32_e32 v2, 0x7200, v66
	ds_write2_b32 v2, v14, v30 offset0:96 offset1:128
	v_add_u32_e32 v2, 0x7400, v66
	ds_write2_b32 v2, v15, v31 offset0:100 offset1:132
	v_add_u32_e32 v2, 0x7600, v66
	ds_write2_b32 v2, v16, v32 offset0:104 offset1:136
	v_add_u32_e32 v2, 0x7800, v66
	ds_write2_b32 v2, v17, v33 offset0:108 offset1:140
	v_lshlrev_b32_e32 v2, 3, v1
	v_and_b32_e32 v2, 0x78, v2
	v_lshl_or_b32 v4, s6, 7, v2
	v_ashrrev_i32_e32 v5, 31, v4
	v_lshlrev_b32_e32 v2, 2, v2
	v_cmp_gt_i32_e32 vcc, s21, v4
	v_lshl_add_u64 v[4:5], v[4:5], 1, s[8:9]
	ds_write2_b32 v66, v35, v51 offset0:132 offset1:164
	s_waitcnt lgkmcnt(0)
	s_barrier
	s_branch .LBB0_2468

; #define MFMA(a, b, c) __builtin_amdgcn_mfma_f32_32x32x16_bf16((a), (b), (c), 0, 0, 0)
; template <int TM, int TN>
; DI void gemm_mainloop(const u16* __restrict__ A, long lda, const u16* __restrict__ Bt, long ldb, int K, char* smem,
;                       f32x16 (&acc)[TM][TN]) {
;     ...
;   const int nk = K / 64;
;   const int lrow = tid >> 3, lch = (tid & 7) * 8;
;   const u16* gA = A + (long)lrow * lda + lch;
;   const u16* gB = Bt + (long)lrow * ldb + lch;
;   const int soff = lrow * LD + lch;
;     ...
;   GEMM_GLOAD(0)
;   __syncthreads();
;   GEMM_SSTORE(0)
;   if (nk > 1) GEMM_GLOAD(64)
;   __syncthreads();
;   for (int kt = 0; kt < nk; kt++) {
;     const int buf = kt & 1;
;     const u16* cA = sA + buf * BM * LD + (wm * 32 * TM + r) * LD + h * 8;
;     const u16* cB = sB + buf * BN * LD + (wn * 32 * TN + r) * LD + h * 8;
;     bf16x8 af[TM], bfr[TN];
; #pragma unroll
;     for (int tm = 0; tm < TM; tm++) af[tm] = *(const bf16x8*)(cA + tm * 32 * LD);
; #pragma unroll
;     for (int tn = 0; tn < TN; tn++) bfr[tn] = *(const bf16x8*)(cB + tn * 32 * LD);
;     if (kt + 1 < nk) GEMM_SSTORE(buf ^ 1)
;     __builtin_amdgcn_sched_barrier(0);
;     __builtin_amdgcn_s_setprio(1);
; #pragma unroll
;     for (int tm = 0; tm < TM; tm++)
; #pragma unroll
;       for (int tn = 0; tn < TN; tn++) acc[tm][tn] = MFMA(af[tm], bfr[tn], acc[tm][tn]);
; #pragma unroll
;     for (int tm = 0; tm < TM; tm++) af[tm] = *(const bf16x8*)(cA + tm * 32 * LD + 16);
; #pragma unroll
;     for (int tn = 0; tn < TN; tn++) bfr[tn] = *(const bf16x8*)(cB + tn * 32 * LD + 16);
; #pragma unroll
;     for (int tm = 0; tm < TM; tm++)
; #pragma unroll
;       for (int tn = 0; tn < TN; tn++) acc[tm][tn] = MFMA(af[tm], bfr[tn], acc[tm][tn]);
;     __builtin_amdgcn_sched_group_barrier(0x8, 4, 0);
;     if (kt + 2 < nk) GEMM_GLOAD((kt + 2) * 64)
.LBB0_2739:
	s_ashr_i32 s6, s22, 31
	s_lshr_b32 s6, s6, 27
	s_add_i32 s6, s22, s6
	s_and_b32 s7, s6, 0xffffffe0
	s_lshl_b32 s6, s6, 2
	s_sub_i32 s26, s22, s7
	s_and_b32 s23, s6, 0xffffff80
	s_lshl_b32 s6, s26, 7
	s_mul_i32 s24, s23, 0x880
	s_mul_hi_i32 s7, s23, 0x880
	s_add_u32 s24, s4, s24
	v_mov_b32_e32 v1, v0
	s_addc_u32 s25, s5, s7
	s_ashr_i32 s7, s6, 31
	v_lshlrev_b32_e32 v2, 3, v1
	v_ashrrev_i32_e32 v68, 3, v1
	v_and_b32_e32 v69, 56, v2
	v_mov_b64_e32 v[2:3], s[24:25]
	v_mad_i64_i32 v[2:3], s[24:25], v68, s8, v[2:3]
	v_lshlrev_b32_e32 v66, 1, v69
	v_lshl_add_u64 v[72:73], v[2:3], 0, v[66:67]
	s_mul_i32 s26, s26, 0x44000
	v_add_co_u32_e32 v70, vcc, s15, v72
	s_mul_hi_i32 s27, s6, 0x880
	s_add_u32 s26, s11, s26
	v_addc_co_u32_e32 v71, vcc, 0, v73, vcc
	s_addc_u32 s27, s14, s27
	v_add_co_u32_e32 v74, vcc, s16, v72
	v_mov_b64_e32 v[2:3], s[26:27]
	s_nop 0
	v_addc_co_u32_e32 v75, vcc, 0, v73, vcc
	v_mad_i64_i32 v[18:19], s[24:25], v68, s8, v[2:3]
	v_add_co_u32_e32 v78, vcc, s17, v72
	v_lshl_add_u64 v[76:77], v[18:19], 0, v[66:67]
	s_nop 0
	v_addc_co_u32_e32 v79, vcc, 0, v73, vcc
	v_add_co_u32_e32 v80, vcc, s15, v76
	global_load_dwordx4 v[2:5], v[72:73], off
	s_nop 0
	v_addc_co_u32_e32 v81, vcc, 0, v77, vcc
	v_add_co_u32_e32 v82, vcc, s16, v76
	global_load_dwordx4 v[6:9], v[70:71], off
	s_nop 0
	v_addc_co_u32_e32 v83, vcc, 0, v77, vcc
	v_add_co_u32_e32 v84, vcc, s17, v76
	global_load_dwordx4 v[10:13], v[74:75], off
	s_nop 0
	v_addc_co_u32_e32 v85, vcc, 0, v77, vcc
	global_load_dwordx4 v[14:17], v[78:79], off
	global_load_dwordx4 v[18:21], v[76:77], off
	global_load_dwordx4 v[22:25], v[80:81], off
	global_load_dwordx4 v[26:29], v[82:83], off
	global_load_dwordx4 v[30:33], v[84:85], off
	s_barrier
	global_load_dwordx4 v[34:37], v[72:73], off offset:128
	global_load_dwordx4 v[38:41], v[70:71], off offset:128
	global_load_dwordx4 v[42:45], v[74:75], off offset:128
	global_load_dwordx4 v[46:49], v[78:79], off offset:128
	global_load_dwordx4 v[50:53], v[76:77], off offset:128
	global_load_dwordx4 v[54:57], v[80:81], off offset:128
	global_load_dwordx4 v[58:61], v[82:83], off offset:128
	global_load_dwordx4 v[62:65], v[84:85], off offset:128
	v_and_b32_e32 v66, 31, v1
	v_lshrrev_b32_e32 v86, 1, v1
	v_mul_lo_u32 v68, v68, s9
	v_and_or_b32 v87, v86, s18, v66
	v_and_b32_e32 v86, 16, v86
	v_and_b32_e32 v1, 0x5f, v1
	v_add_lshl_u32 v66, v68, v69, 1
	v_mad_u64_u32 v[68:69], s[24:25], v87, s19, v[86:87]
	v_mad_u32_u24 v1, v1, s19, v86
	v_add_u32_e32 v69, 0x9000, v66
	s_waitcnt vmcnt(15)
	ds_write_b128 v66, v[2:5]
	s_waitcnt vmcnt(14)
	ds_write_b128 v66, v[6:9] offset:4608
	s_waitcnt vmcnt(13)
	ds_write_b128 v66, v[10:13] offset:9216
	s_waitcnt vmcnt(12)
	ds_write_b128 v66, v[14:17] offset:13824
	s_waitcnt vmcnt(11)
	ds_write_b128 v66, v[18:21] offset:36864
	s_waitcnt vmcnt(10)
	ds_write_b128 v66, v[22:25] offset:41472
	s_waitcnt vmcnt(9)
	ds_write_b128 v66, v[26:29] offset:46080
	s_waitcnt vmcnt(8)
	ds_write_b128 v66, v[30:33] offset:50688
	s_waitcnt lgkmcnt(0)
	s_barrier
	ds_read_b128 v[2:5], v68
	ds_read_b128 v[18:21], v68 offset:4608
	ds_read_b128 v[6:9], v1 offset:36864
	ds_read_b128 v[22:25], v1 offset:41472
	s_waitcnt vmcnt(7)
	ds_write_b128 v66, v[34:37] offset:18432
	s_waitcnt vmcnt(6)
	ds_write_b128 v66, v[38:41] offset:23040
	s_waitcnt vmcnt(5)
	ds_write_b128 v66, v[42:45] offset:27648
	s_waitcnt vmcnt(4)
	ds_write_b128 v66, v[46:49] offset:32256
	s_waitcnt vmcnt(3)
	ds_write_b128 v66, v[50:53] offset:55296
	s_waitcnt vmcnt(2)
	ds_write_b128 v66, v[54:57] offset:59904
	s_waitcnt vmcnt(1)
	ds_write_b128 v66, v[58:61] offset:64512
	s_waitcnt vmcnt(0)
	ds_write_b128 v69, v[62:65] offset:32256
	s_setprio 1
	ds_read_b128 v[86:89], v68 offset:32
	s_waitcnt lgkmcnt(10)
	v_mfma_f32_32x32x16_bf16 v[34:49], v[2:5], v[6:9], 0
	ds_read_b128 v[90:93], v1 offset:36896
	ds_read_b128 v[94:97], v1 offset:41504
	ds_read_b128 v[98:101], v68 offset:4704
	global_load_dwordx4 v[102:105], v[70:71], off offset:256
	global_load_dwordx4 v[106:109], v[74:75], off offset:256
	global_load_dwordx4 v[110:113], v[78:79], off offset:256
	global_load_dwordx4 v[114:117], v[84:85], off offset:256
	s_waitcnt lgkmcnt(12)
	v_mfma_f32_32x32x16_bf16 v[50:65], v[2:5], v[22:25], 0
	global_load_dwordx4 v[118:121], v[82:83], off offset:256
	global_load_dwordx4 v[122:125], v[80:81], off offset:256
	s_waitcnt lgkmcnt(2)
	v_mfma_f32_32x32x16_bf16 v[34:49], v[86:89], v[90:93], v[34:49]
	s_waitcnt lgkmcnt(1)
	v_mfma_f32_32x32x16_bf16 v[50:65], v[86:89], v[94:97], v[50:65]
	ds_read_b128 v[86:89], v68 offset:4640
	v_mfma_f32_32x32x16_bf16 v[2:17], v[18:21], v[6:9], 0
	v_mfma_f32_32x32x16_bf16 v[18:33], v[18:21], v[22:25], 0
	s_waitcnt lgkmcnt(0)
	v_mfma_f32_32x32x16_bf16 v[2:17], v[86:89], v[90:93], v[2:17]
	ds_read_b128 v[90:93], v1 offset:36928
	v_mfma_f32_32x32x16_bf16 v[18:33], v[86:89], v[94:97], v[18:33]
	ds_read_b128 v[86:89], v68 offset:64
	ds_read_b128 v[94:97], v1 offset:41536
	s_waitcnt lgkmcnt(1)
	v_mfma_f32_32x32x16_bf16 v[34:49], v[86:89], v[90:93], v[34:49]
	s_waitcnt lgkmcnt(0)
	v_mfma_f32_32x32x16_bf16 v[50:65], v[86:89], v[94:97], v[50:65]
	ds_read_b128 v[86:89], v68 offset:4672
	s_waitcnt lgkmcnt(0)
	v_mfma_f32_32x32x16_bf16 v[2:17], v[86:89], v[90:93], v[2:17]
	ds_read_b128 v[90:93], v1 offset:36960
	v_mfma_f32_32x32x16_bf16 v[18:33], v[86:89], v[94:97], v[18:33]
	ds_read_b128 v[86:89], v68 offset:96
	ds_read_b128 v[94:97], v1 offset:41568
	s_waitcnt lgkmcnt(1)
	v_mfma_f32_32x32x16_bf16 v[34:49], v[86:89], v[90:93], v[34:49]
	s_waitcnt lgkmcnt(0)
	v_mfma_f32_32x32x16_bf16 v[50:65], v[86:89], v[94:97], v[50:65]
	global_load_dwordx4 v[86:89], v[72:73], off offset:256
	v_mfma_f32_32x32x16_bf16 v[2:17], v[98:101], v[90:93], v[2:17]
	global_load_dwordx4 v[90:93], v[76:77], off offset:256
	v_mfma_f32_32x32x16_bf16 v[18:33], v[98:101], v[94:97], v[18:33]
	s_setprio 0
	s_barrier
; #define MFMA(a, b, c) __builtin_amdgcn_mfma_f32_32x32x16_bf16((a), (b), (c), 0, 0, 0)
; template <int TM, int TN>
; DI void gemm_mainloop(const u16* __restrict__ A, long lda, const u16* __restrict__ Bt, long ldb, int K, char* smem,
;                       f32x16 (&acc)[TM][TN]) {
;     ...
;   for (int kt = 0; kt < nk; kt++) {
;     const int buf = kt & 1;
;     const u16* cA = sA + buf * BM * LD + (wm * 32 * TM + r) * LD + h * 8;
;     const u16* cB = sB + buf * BN * LD + (wn * 32 * TN + r) * LD + h * 8;
;     bf16x8 af[TM], bfr[TN];
; #pragma unroll
;     for (int tm = 0; tm < TM; tm++) af[tm] = *(const bf16x8*)(cA + tm * 32 * LD);
; #pragma unroll
;     for (int tn = 0; tn < TN; tn++) bfr[tn] = *(const bf16x8*)(cB + tn * 32 * LD);
;     if (kt + 1 < nk) GEMM_SSTORE(buf ^ 1)
;     __builtin_amdgcn_sched_barrier(0);
;     __builtin_amdgcn_s_setprio(1);
; #pragma unroll
;     for (int tm = 0; tm < TM; tm++)
; #pragma unroll
;       for (int tn = 0; tn < TN; tn++) acc[tm][tn] = MFMA(af[tm], bfr[tn], acc[tm][tn]);
; #pragma unroll
;     for (int tm = 0; tm < TM; tm++) af[tm] = *(const bf16x8*)(cA + tm * 32 * LD + 16);
; #pragma unroll
;     for (int tn = 0; tn < TN; tn++) bfr[tn] = *(const bf16x8*)(cB + tn * 32 * LD + 16);
; #pragma unroll
;     for (int tm = 0; tm < TM; tm++)
; #pragma unroll
;       for (int tn = 0; tn < TN; tn++) acc[tm][tn] = MFMA(af[tm], bfr[tn], acc[tm][tn]);
;     __builtin_amdgcn_sched_group_barrier(0x8, 4, 0);
;     if (kt + 2 < nk) GEMM_GLOAD((kt + 2) * 64)
; #pragma unroll
;     for (int ks = 2; ks < 4; ks++) {
; #pragma unroll
;       for (int tm = 0; tm < TM; tm++) af[tm] = *(const bf16x8*)(cA + tm * 32 * LD + ks * 16);
; #pragma unroll
;       for (int tn = 0; tn < TN; tn++) bfr[tn] = *(const bf16x8*)(cB + tn * 32 * LD + ks * 16);
; #pragma unroll
;       for (int tm = 0; tm < TM; tm++)
; #pragma unroll
;         for (int tn = 0; tn < TN; tn++) acc[tm][tn] = MFMA(af[tm], bfr[tn], acc[tm][tn]);
;     }
;     __builtin_amdgcn_s_setprio(0);
;     __syncthreads();
	ds_read_b128 v[94:97], v68 offset:18432
	ds_read_b128 v[98:101], v68 offset:23040
	ds_read_b128 v[126:129], v1 offset:55296
	ds_read_b128 v[130:133], v1 offset:59904
	s_waitcnt vmcnt(1)
	ds_write_b128 v66, v[86:89]
	ds_write_b128 v66, v[102:105] offset:4608
	ds_write_b128 v66, v[106:109] offset:9216
	ds_write_b128 v66, v[110:113] offset:13824
	s_waitcnt vmcnt(0)
	ds_write_b128 v66, v[90:93] offset:36864
	ds_write_b128 v66, v[122:125] offset:41472
	ds_write_b128 v66, v[118:121] offset:46080
	ds_write_b128 v66, v[114:117] offset:50688
	s_setprio 1
	ds_read_b128 v[86:89], v68 offset:18464
	s_waitcnt lgkmcnt(10)
	v_mfma_f32_32x32x16_bf16 v[34:49], v[94:97], v[126:129], v[34:49]
	ds_read_b128 v[90:93], v1 offset:55328
	global_load_dwordx4 v[102:105], v[70:71], off offset:384
	global_load_dwordx4 v[106:109], v[74:75], off offset:384
	global_load_dwordx4 v[110:113], v[78:79], off offset:384
	global_load_dwordx4 v[114:117], v[84:85], off offset:384
	global_load_dwordx4 v[118:121], v[82:83], off offset:384
	global_load_dwordx4 v[122:125], v[80:81], off offset:384
	s_waitcnt lgkmcnt(10)
	v_mfma_f32_32x32x16_bf16 v[50:65], v[94:97], v[130:133], v[50:65]
	ds_read_b128 v[94:97], v1 offset:59936
	s_waitcnt lgkmcnt(1)
	v_mfma_f32_32x32x16_bf16 v[34:49], v[86:89], v[90:93], v[34:49]
	s_waitcnt lgkmcnt(0)
	v_mfma_f32_32x32x16_bf16 v[50:65], v[86:89], v[94:97], v[50:65]
	ds_read_b128 v[86:89], v68 offset:23072
	v_mfma_f32_32x32x16_bf16 v[2:17], v[98:101], v[126:129], v[2:17]
	v_mfma_f32_32x32x16_bf16 v[18:33], v[98:101], v[130:133], v[18:33]
	ds_read_b128 v[98:101], v68 offset:23136
	s_waitcnt lgkmcnt(1)
	v_mfma_f32_32x32x16_bf16 v[2:17], v[86:89], v[90:93], v[2:17]
	ds_read_b128 v[90:93], v1 offset:55360
	v_mfma_f32_32x32x16_bf16 v[18:33], v[86:89], v[94:97], v[18:33]
	ds_read_b128 v[86:89], v68 offset:18496
	ds_read_b128 v[94:97], v1 offset:59968
	s_waitcnt lgkmcnt(1)
	v_mfma_f32_32x32x16_bf16 v[34:49], v[86:89], v[90:93], v[34:49]
	s_waitcnt lgkmcnt(0)
	v_mfma_f32_32x32x16_bf16 v[50:65], v[86:89], v[94:97], v[50:65]
	ds_read_b128 v[86:89], v68 offset:23104
	s_waitcnt lgkmcnt(0)
	v_mfma_f32_32x32x16_bf16 v[2:17], v[86:89], v[90:93], v[2:17]
	ds_read_b128 v[90:93], v1 offset:55392
	v_mfma_f32_32x32x16_bf16 v[18:33], v[86:89], v[94:97], v[18:33]
	ds_read_b128 v[86:89], v68 offset:18528
	ds_read_b128 v[94:97], v1 offset:60000
	s_waitcnt lgkmcnt(1)
	v_mfma_f32_32x32x16_bf16 v[34:49], v[86:89], v[90:93], v[34:49]
	s_waitcnt lgkmcnt(0)
	v_mfma_f32_32x32x16_bf16 v[50:65], v[86:89], v[94:97], v[50:65]
	global_load_dwordx4 v[86:89], v[72:73], off offset:384
	v_mfma_f32_32x32x16_bf16 v[2:17], v[98:101], v[90:93], v[2:17]
	global_load_dwordx4 v[90:93], v[76:77], off offset:384
	v_mfma_f32_32x32x16_bf16 v[18:33], v[98:101], v[94:97], v[18:33]
	s_setprio 0
	s_barrier
	ds_read_b128 v[94:97], v68
	ds_read_b128 v[98:101], v68 offset:4608
	ds_read_b128 v[126:129], v1 offset:36864
	ds_read_b128 v[130:133], v1 offset:41472
	s_waitcnt vmcnt(1)
	ds_write_b128 v66, v[86:89] offset:18432
	ds_write_b128 v66, v[102:105] offset:23040
	ds_write_b128 v66, v[106:109] offset:27648
	ds_write_b128 v66, v[110:113] offset:32256
	s_waitcnt vmcnt(0)
	ds_write_b128 v66, v[90:93] offset:55296
	ds_write_b128 v66, v[122:125] offset:59904
	ds_write_b128 v66, v[118:121] offset:64512
	ds_write_b128 v69, v[114:117] offset:32256
	s_setprio 1
	ds_read_b128 v[86:89], v68 offset:32
	s_waitcnt lgkmcnt(10)
	v_mfma_f32_32x32x16_bf16 v[34:49], v[94:97], v[126:129], v[34:49]
	ds_read_b128 v[90:93], v1 offset:36896
	global_load_dwordx4 v[102:105], v[70:71], off offset:512
	global_load_dwordx4 v[106:109], v[74:75], off offset:512
	global_load_dwordx4 v[110:113], v[78:79], off offset:512
	global_load_dwordx4 v[114:117], v[84:85], off offset:512
	global_load_dwordx4 v[118:121], v[82:83], off offset:512
	global_load_dwordx4 v[122:125], v[80:81], off offset:512
	s_waitcnt lgkmcnt(10)
	v_mfma_f32_32x32x16_bf16 v[50:65], v[94:97], v[130:133], v[50:65]
	ds_read_b128 v[94:97], v1 offset:41504
	s_waitcnt lgkmcnt(1)
	v_mfma_f32_32x32x16_bf16 v[34:49], v[86:89], v[90:93], v[34:49]
	s_waitcnt lgkmcnt(0)
	v_mfma_f32_32x32x16_bf16 v[50:65], v[86:89], v[94:97], v[50:65]
	ds_read_b128 v[86:89], v68 offset:4640
	v_mfma_f32_32x32x16_bf16 v[2:17], v[98:101], v[126:129], v[2:17]
	v_mfma_f32_32x32x16_bf16 v[18:33], v[98:101], v[130:133], v[18:33]
	ds_read_b128 v[98:101], v68 offset:4704
	s_waitcnt lgkmcnt(1)
	v_mfma_f32_32x32x16_bf16 v[2:17], v[86:89], v[90:93], v[2:17]
	ds_read_b128 v[90:93], v1 offset:36928
	v_mfma_f32_32x32x16_bf16 v[18:33], v[86:89], v[94:97], v[18:33]
	ds_read_b128 v[86:89], v68 offset:64
	ds_read_b128 v[94:97], v1 offset:41536
	s_waitcnt lgkmcnt(1)
	v_mfma_f32_32x32x16_bf16 v[34:49], v[86:89], v[90:93], v[34:49]
	s_waitcnt lgkmcnt(0)
	v_mfma_f32_32x32x16_bf16 v[50:65], v[86:89], v[94:97], v[50:65]
	ds_read_b128 v[86:89], v68 offset:4672
	s_waitcnt lgkmcnt(0)
	v_mfma_f32_32x32x16_bf16 v[2:17], v[86:89], v[90:93], v[2:17]
	ds_read_b128 v[90:93], v1 offset:36960
	v_mfma_f32_32x32x16_bf16 v[18:33], v[86:89], v[94:97], v[18:33]
	ds_read_b128 v[86:89], v68 offset:96
	ds_read_b128 v[94:97], v1 offset:41568
	s_waitcnt lgkmcnt(1)
	v_mfma_f32_32x32x16_bf16 v[34:49], v[86:89], v[90:93], v[34:49]
	s_waitcnt lgkmcnt(0)
	v_mfma_f32_32x32x16_bf16 v[50:65], v[86:89], v[94:97], v[50:65]
	global_load_dwordx4 v[86:89], v[72:73], off offset:512
	v_mfma_f32_32x32x16_bf16 v[2:17], v[98:101], v[90:93], v[2:17]
	global_load_dwordx4 v[90:93], v[76:77], off offset:512
	v_mfma_f32_32x32x16_bf16 v[18:33], v[98:101], v[94:97], v[18:33]
	s_setprio 0
	s_barrier
; #define MFMA(a, b, c) __builtin_amdgcn_mfma_f32_32x32x16_bf16((a), (b), (c), 0, 0, 0)
; template <int TM, int TN>
; DI void gemm_mainloop(const u16* __restrict__ A, long lda, const u16* __restrict__ Bt, long ldb, int K, char* smem,
;                       f32x16 (&acc)[TM][TN]) {
;     ...
;   for (int kt = 0; kt < nk; kt++) {
;     const int buf = kt & 1;
;     const u16* cA = sA + buf * BM * LD + (wm * 32 * TM + r) * LD + h * 8;
;     const u16* cB = sB + buf * BN * LD + (wn * 32 * TN + r) * LD + h * 8;
;     bf16x8 af[TM], bfr[TN];
; #pragma unroll
;     for (int tm = 0; tm < TM; tm++) af[tm] = *(const bf16x8*)(cA + tm * 32 * LD);
; #pragma unroll
;     for (int tn = 0; tn < TN; tn++) bfr[tn] = *(const bf16x8*)(cB + tn * 32 * LD);
;     if (kt + 1 < nk) GEMM_SSTORE(buf ^ 1)
;     __builtin_amdgcn_sched_barrier(0);
;     __builtin_amdgcn_s_setprio(1);
; #pragma unroll
;     for (int tm = 0; tm < TM; tm++)
; #pragma unroll
;       for (int tn = 0; tn < TN; tn++) acc[tm][tn] = MFMA(af[tm], bfr[tn], acc[tm][tn]);
; #pragma unroll
;     for (int tm = 0; tm < TM; tm++) af[tm] = *(const bf16x8*)(cA + tm * 32 * LD + 16);
; #pragma unroll
;     for (int tn = 0; tn < TN; tn++) bfr[tn] = *(const bf16x8*)(cB + tn * 32 * LD + 16);
; #pragma unroll
;     for (int tm = 0; tm < TM; tm++)
; #pragma unroll
;       for (int tn = 0; tn < TN; tn++) acc[tm][tn] = MFMA(af[tm], bfr[tn], acc[tm][tn]);
;     __builtin_amdgcn_sched_group_barrier(0x8, 4, 0);
;     if (kt + 2 < nk) GEMM_GLOAD((kt + 2) * 64)
; #pragma unroll
;     for (int ks = 2; ks < 4; ks++) {
; #pragma unroll
;       for (int tm = 0; tm < TM; tm++) af[tm] = *(const bf16x8*)(cA + tm * 32 * LD + ks * 16);
; #pragma unroll
;       for (int tn = 0; tn < TN; tn++) bfr[tn] = *(const bf16x8*)(cB + tn * 32 * LD + ks * 16);
; #pragma unroll
;       for (int tm = 0; tm < TM; tm++)
; #pragma unroll
;         for (int tn = 0; tn < TN; tn++) acc[tm][tn] = MFMA(af[tm], bfr[tn], acc[tm][tn]);
;     }
;     __builtin_amdgcn_s_setprio(0);
;     __syncthreads();
	ds_read_b128 v[94:97], v68 offset:18432
	ds_read_b128 v[98:101], v68 offset:23040
	ds_read_b128 v[126:129], v1 offset:55296
	ds_read_b128 v[130:133], v1 offset:59904
	s_waitcnt vmcnt(1)
	ds_write_b128 v66, v[86:89]
	ds_write_b128 v66, v[102:105] offset:4608
	ds_write_b128 v66, v[106:109] offset:9216
	ds_write_b128 v66, v[110:113] offset:13824
	s_waitcnt vmcnt(0)
	ds_write_b128 v66, v[90:93] offset:36864
	ds_write_b128 v66, v[122:125] offset:41472
	ds_write_b128 v66, v[118:121] offset:46080
	ds_write_b128 v66, v[114:117] offset:50688
	s_setprio 1
	ds_read_b128 v[86:89], v68 offset:18464
	s_waitcnt lgkmcnt(10)
	v_mfma_f32_32x32x16_bf16 v[34:49], v[94:97], v[126:129], v[34:49]
	ds_read_b128 v[90:93], v1 offset:55328
	global_load_dwordx4 v[102:105], v[70:71], off offset:640
	global_load_dwordx4 v[106:109], v[74:75], off offset:640
	global_load_dwordx4 v[110:113], v[78:79], off offset:640
	global_load_dwordx4 v[114:117], v[84:85], off offset:640
	global_load_dwordx4 v[118:121], v[82:83], off offset:640
	global_load_dwordx4 v[122:125], v[80:81], off offset:640
	s_waitcnt lgkmcnt(10)
	v_mfma_f32_32x32x16_bf16 v[50:65], v[94:97], v[130:133], v[50:65]
	ds_read_b128 v[94:97], v1 offset:59936
	s_waitcnt lgkmcnt(1)
	v_mfma_f32_32x32x16_bf16 v[34:49], v[86:89], v[90:93], v[34:49]
	s_waitcnt lgkmcnt(0)
	v_mfma_f32_32x32x16_bf16 v[50:65], v[86:89], v[94:97], v[50:65]
	ds_read_b128 v[86:89], v68 offset:23072
	v_mfma_f32_32x32x16_bf16 v[2:17], v[98:101], v[126:129], v[2:17]
	v_mfma_f32_32x32x16_bf16 v[18:33], v[98:101], v[130:133], v[18:33]
	ds_read_b128 v[98:101], v68 offset:23136
	s_waitcnt lgkmcnt(1)
	v_mfma_f32_32x32x16_bf16 v[2:17], v[86:89], v[90:93], v[2:17]
	ds_read_b128 v[90:93], v1 offset:55360
	v_mfma_f32_32x32x16_bf16 v[18:33], v[86:89], v[94:97], v[18:33]
	ds_read_b128 v[86:89], v68 offset:18496
	ds_read_b128 v[94:97], v1 offset:59968
	s_waitcnt lgkmcnt(1)
	v_mfma_f32_32x32x16_bf16 v[34:49], v[86:89], v[90:93], v[34:49]
	s_waitcnt lgkmcnt(0)
	v_mfma_f32_32x32x16_bf16 v[50:65], v[86:89], v[94:97], v[50:65]
	ds_read_b128 v[86:89], v68 offset:23104
	s_waitcnt lgkmcnt(0)
	v_mfma_f32_32x32x16_bf16 v[2:17], v[86:89], v[90:93], v[2:17]
	ds_read_b128 v[90:93], v1 offset:55392
	v_mfma_f32_32x32x16_bf16 v[18:33], v[86:89], v[94:97], v[18:33]
	ds_read_b128 v[86:89], v68 offset:18528
	ds_read_b128 v[94:97], v1 offset:60000
	s_waitcnt lgkmcnt(1)
	v_mfma_f32_32x32x16_bf16 v[34:49], v[86:89], v[90:93], v[34:49]
	s_waitcnt lgkmcnt(0)
	v_mfma_f32_32x32x16_bf16 v[50:65], v[86:89], v[94:97], v[50:65]
	global_load_dwordx4 v[86:89], v[72:73], off offset:640
	v_mfma_f32_32x32x16_bf16 v[2:17], v[98:101], v[90:93], v[2:17]
	global_load_dwordx4 v[90:93], v[76:77], off offset:640
	v_mfma_f32_32x32x16_bf16 v[18:33], v[98:101], v[94:97], v[18:33]
	s_setprio 0
	s_barrier
	ds_read_b128 v[94:97], v68
	ds_read_b128 v[98:101], v68 offset:4608
	ds_read_b128 v[126:129], v1 offset:36864
	ds_read_b128 v[130:133], v1 offset:41472
	s_waitcnt vmcnt(1)
	ds_write_b128 v66, v[86:89] offset:18432
	ds_write_b128 v66, v[102:105] offset:23040
	ds_write_b128 v66, v[106:109] offset:27648
	ds_write_b128 v66, v[110:113] offset:32256
	s_waitcnt vmcnt(0)
	ds_write_b128 v66, v[90:93] offset:55296
	ds_write_b128 v66, v[122:125] offset:59904
	ds_write_b128 v66, v[118:121] offset:64512
	ds_write_b128 v69, v[114:117] offset:32256
	s_setprio 1
	ds_read_b128 v[86:89], v68 offset:32
	s_waitcnt lgkmcnt(10)
	v_mfma_f32_32x32x16_bf16 v[34:49], v[94:97], v[126:129], v[34:49]
	ds_read_b128 v[90:93], v1 offset:36896
	global_load_dwordx4 v[102:105], v[70:71], off offset:768
	global_load_dwordx4 v[106:109], v[74:75], off offset:768
	global_load_dwordx4 v[110:113], v[78:79], off offset:768
	global_load_dwordx4 v[114:117], v[84:85], off offset:768
	global_load_dwordx4 v[118:121], v[82:83], off offset:768
	global_load_dwordx4 v[122:125], v[80:81], off offset:768
	s_waitcnt lgkmcnt(10)
	v_mfma_f32_32x32x16_bf16 v[50:65], v[94:97], v[130:133], v[50:65]
	ds_read_b128 v[94:97], v1 offset:41504
	s_waitcnt lgkmcnt(1)
	v_mfma_f32_32x32x16_bf16 v[34:49], v[86:89], v[90:93], v[34:49]
	s_waitcnt lgkmcnt(0)
	v_mfma_f32_32x32x16_bf16 v[50:65], v[86:89], v[94:97], v[50:65]
	ds_read_b128 v[86:89], v68 offset:4640
	v_mfma_f32_32x32x16_bf16 v[2:17], v[98:101], v[126:129], v[2:17]
	v_mfma_f32_32x32x16_bf16 v[18:33], v[98:101], v[130:133], v[18:33]
	ds_read_b128 v[98:101], v68 offset:4704
	s_waitcnt lgkmcnt(1)
	v_mfma_f32_32x32x16_bf16 v[2:17], v[86:89], v[90:93], v[2:17]
	ds_read_b128 v[90:93], v1 offset:36928
	v_mfma_f32_32x32x16_bf16 v[18:33], v[86:89], v[94:97], v[18:33]
	ds_read_b128 v[86:89], v68 offset:64
	ds_read_b128 v[94:97], v1 offset:41536
	s_waitcnt lgkmcnt(1)
	v_mfma_f32_32x32x16_bf16 v[34:49], v[86:89], v[90:93], v[34:49]
	s_waitcnt lgkmcnt(0)
	v_mfma_f32_32x32x16_bf16 v[50:65], v[86:89], v[94:97], v[50:65]
	ds_read_b128 v[86:89], v68 offset:4672
	s_waitcnt lgkmcnt(0)
	v_mfma_f32_32x32x16_bf16 v[2:17], v[86:89], v[90:93], v[2:17]
	ds_read_b128 v[90:93], v1 offset:36960
	v_mfma_f32_32x32x16_bf16 v[18:33], v[86:89], v[94:97], v[18:33]
	ds_read_b128 v[86:89], v68 offset:96
	ds_read_b128 v[94:97], v1 offset:41568
	s_waitcnt lgkmcnt(1)
	v_mfma_f32_32x32x16_bf16 v[34:49], v[86:89], v[90:93], v[34:49]
	s_waitcnt lgkmcnt(0)
	v_mfma_f32_32x32x16_bf16 v[50:65], v[86:89], v[94:97], v[50:65]
	global_load_dwordx4 v[86:89], v[72:73], off offset:768
	v_mfma_f32_32x32x16_bf16 v[2:17], v[98:101], v[90:93], v[2:17]
	global_load_dwordx4 v[90:93], v[76:77], off offset:768
	v_mfma_f32_32x32x16_bf16 v[18:33], v[98:101], v[94:97], v[18:33]
	s_setprio 0
	s_barrier
; #define MFMA(a, b, c) __builtin_amdgcn_mfma_f32_32x32x16_bf16((a), (b), (c), 0, 0, 0)
; template <int TM, int TN>
; DI void gemm_mainloop(const u16* __restrict__ A, long lda, const u16* __restrict__ Bt, long ldb, int K, char* smem,
;                       f32x16 (&acc)[TM][TN]) {
;     ...
;   for (int kt = 0; kt < nk; kt++) {
;     const int buf = kt & 1;
;     const u16* cA = sA + buf * BM * LD + (wm * 32 * TM + r) * LD + h * 8;
;     const u16* cB = sB + buf * BN * LD + (wn * 32 * TN + r) * LD + h * 8;
;     bf16x8 af[TM], bfr[TN];
; #pragma unroll
;     for (int tm = 0; tm < TM; tm++) af[tm] = *(const bf16x8*)(cA + tm * 32 * LD);
; #pragma unroll
;     for (int tn = 0; tn < TN; tn++) bfr[tn] = *(const bf16x8*)(cB + tn * 32 * LD);
;     if (kt + 1 < nk) GEMM_SSTORE(buf ^ 1)
;     __builtin_amdgcn_sched_barrier(0);
;     __builtin_amdgcn_s_setprio(1);
; #pragma unroll
;     for (int tm = 0; tm < TM; tm++)
; #pragma unroll
;       for (int tn = 0; tn < TN; tn++) acc[tm][tn] = MFMA(af[tm], bfr[tn], acc[tm][tn]);
; #pragma unroll
;     for (int tm = 0; tm < TM; tm++) af[tm] = *(const bf16x8*)(cA + tm * 32 * LD + 16);
; #pragma unroll
;     for (int tn = 0; tn < TN; tn++) bfr[tn] = *(const bf16x8*)(cB + tn * 32 * LD + 16);
; #pragma unroll
;     for (int tm = 0; tm < TM; tm++)
; #pragma unroll
;       for (int tn = 0; tn < TN; tn++) acc[tm][tn] = MFMA(af[tm], bfr[tn], acc[tm][tn]);
;     __builtin_amdgcn_sched_group_barrier(0x8, 4, 0);
;     if (kt + 2 < nk) GEMM_GLOAD((kt + 2) * 64)
; #pragma unroll
;     for (int ks = 2; ks < 4; ks++) {
; #pragma unroll
;       for (int tm = 0; tm < TM; tm++) af[tm] = *(const bf16x8*)(cA + tm * 32 * LD + ks * 16);
; #pragma unroll
;       for (int tn = 0; tn < TN; tn++) bfr[tn] = *(const bf16x8*)(cB + tn * 32 * LD + ks * 16);
; #pragma unroll
;       for (int tm = 0; tm < TM; tm++)
; #pragma unroll
;         for (int tn = 0; tn < TN; tn++) acc[tm][tn] = MFMA(af[tm], bfr[tn], acc[tm][tn]);
;     }
;     __builtin_amdgcn_s_setprio(0);
;     __syncthreads();
	ds_read_b128 v[94:97], v68 offset:18432
	ds_read_b128 v[98:101], v68 offset:23040
	ds_read_b128 v[126:129], v1 offset:55296
	ds_read_b128 v[130:133], v1 offset:59904
	s_waitcnt vmcnt(1)
	ds_write_b128 v66, v[86:89]
	ds_write_b128 v66, v[102:105] offset:4608
	ds_write_b128 v66, v[106:109] offset:9216
	ds_write_b128 v66, v[110:113] offset:13824
	s_waitcnt vmcnt(0)
	ds_write_b128 v66, v[90:93] offset:36864
	ds_write_b128 v66, v[122:125] offset:41472
	ds_write_b128 v66, v[118:121] offset:46080
	ds_write_b128 v66, v[114:117] offset:50688
	s_setprio 1
	ds_read_b128 v[86:89], v68 offset:18464
	s_waitcnt lgkmcnt(10)
	v_mfma_f32_32x32x16_bf16 v[34:49], v[94:97], v[126:129], v[34:49]
	ds_read_b128 v[90:93], v1 offset:55328
	global_load_dwordx4 v[102:105], v[70:71], off offset:896
	global_load_dwordx4 v[106:109], v[74:75], off offset:896
	global_load_dwordx4 v[110:113], v[78:79], off offset:896
	global_load_dwordx4 v[114:117], v[84:85], off offset:896
	global_load_dwordx4 v[118:121], v[82:83], off offset:896
	global_load_dwordx4 v[122:125], v[80:81], off offset:896
	s_waitcnt lgkmcnt(10)
	v_mfma_f32_32x32x16_bf16 v[50:65], v[94:97], v[130:133], v[50:65]
	ds_read_b128 v[94:97], v1 offset:59936
	s_waitcnt lgkmcnt(1)
	v_mfma_f32_32x32x16_bf16 v[34:49], v[86:89], v[90:93], v[34:49]
	s_waitcnt lgkmcnt(0)
	v_mfma_f32_32x32x16_bf16 v[50:65], v[86:89], v[94:97], v[50:65]
	ds_read_b128 v[86:89], v68 offset:23072
	v_mfma_f32_32x32x16_bf16 v[2:17], v[98:101], v[126:129], v[2:17]
	v_mfma_f32_32x32x16_bf16 v[18:33], v[98:101], v[130:133], v[18:33]
	ds_read_b128 v[98:101], v68 offset:23136
	s_waitcnt lgkmcnt(1)
	v_mfma_f32_32x32x16_bf16 v[2:17], v[86:89], v[90:93], v[2:17]
	ds_read_b128 v[90:93], v1 offset:55360
	v_mfma_f32_32x32x16_bf16 v[18:33], v[86:89], v[94:97], v[18:33]
	ds_read_b128 v[86:89], v68 offset:18496
	ds_read_b128 v[94:97], v1 offset:59968
	s_waitcnt lgkmcnt(1)
	v_mfma_f32_32x32x16_bf16 v[34:49], v[86:89], v[90:93], v[34:49]
	s_waitcnt lgkmcnt(0)
	v_mfma_f32_32x32x16_bf16 v[50:65], v[86:89], v[94:97], v[50:65]
	ds_read_b128 v[86:89], v68 offset:23104
	s_waitcnt lgkmcnt(0)
	v_mfma_f32_32x32x16_bf16 v[2:17], v[86:89], v[90:93], v[2:17]
	ds_read_b128 v[90:93], v1 offset:55392
	v_mfma_f32_32x32x16_bf16 v[18:33], v[86:89], v[94:97], v[18:33]
	ds_read_b128 v[86:89], v68 offset:18528
	ds_read_b128 v[94:97], v1 offset:60000
	s_waitcnt lgkmcnt(1)
	v_mfma_f32_32x32x16_bf16 v[34:49], v[86:89], v[90:93], v[34:49]
	s_waitcnt lgkmcnt(0)
	v_mfma_f32_32x32x16_bf16 v[50:65], v[86:89], v[94:97], v[50:65]
	global_load_dwordx4 v[86:89], v[72:73], off offset:896
	v_mfma_f32_32x32x16_bf16 v[2:17], v[98:101], v[90:93], v[2:17]
	global_load_dwordx4 v[90:93], v[76:77], off offset:896
	v_mfma_f32_32x32x16_bf16 v[18:33], v[98:101], v[94:97], v[18:33]
	s_setprio 0
	s_barrier
	ds_read_b128 v[94:97], v68
	ds_read_b128 v[98:101], v68 offset:4608
	ds_read_b128 v[126:129], v1 offset:36864
	ds_read_b128 v[130:133], v1 offset:41472
	s_waitcnt vmcnt(1)
	ds_write_b128 v66, v[86:89] offset:18432
	ds_write_b128 v66, v[102:105] offset:23040
	ds_write_b128 v66, v[106:109] offset:27648
	ds_write_b128 v66, v[110:113] offset:32256
	s_waitcnt vmcnt(0)
	ds_write_b128 v66, v[90:93] offset:55296
	ds_write_b128 v66, v[122:125] offset:59904
	ds_write_b128 v66, v[118:121] offset:64512
	ds_write_b128 v69, v[114:117] offset:32256
	s_setprio 1
	ds_read_b128 v[86:89], v68 offset:32
	s_waitcnt lgkmcnt(10)
	v_mfma_f32_32x32x16_bf16 v[34:49], v[94:97], v[126:129], v[34:49]
	ds_read_b128 v[90:93], v1 offset:36896
	global_load_dwordx4 v[102:105], v[70:71], off offset:1024
	global_load_dwordx4 v[106:109], v[74:75], off offset:1024
	global_load_dwordx4 v[110:113], v[78:79], off offset:1024
	global_load_dwordx4 v[114:117], v[84:85], off offset:1024
	global_load_dwordx4 v[118:121], v[82:83], off offset:1024
	global_load_dwordx4 v[122:125], v[80:81], off offset:1024
	s_waitcnt lgkmcnt(10)
	v_mfma_f32_32x32x16_bf16 v[50:65], v[94:97], v[130:133], v[50:65]
	ds_read_b128 v[94:97], v1 offset:41504
	s_waitcnt lgkmcnt(1)
	v_mfma_f32_32x32x16_bf16 v[34:49], v[86:89], v[90:93], v[34:49]
	s_waitcnt lgkmcnt(0)
	v_mfma_f32_32x32x16_bf16 v[50:65], v[86:89], v[94:97], v[50:65]
	ds_read_b128 v[86:89], v68 offset:4640
	v_mfma_f32_32x32x16_bf16 v[2:17], v[98:101], v[126:129], v[2:17]
	v_mfma_f32_32x32x16_bf16 v[18:33], v[98:101], v[130:133], v[18:33]
	ds_read_b128 v[98:101], v68 offset:4704
	s_waitcnt lgkmcnt(1)
	v_mfma_f32_32x32x16_bf16 v[2:17], v[86:89], v[90:93], v[2:17]
	ds_read_b128 v[90:93], v1 offset:36928
	v_mfma_f32_32x32x16_bf16 v[18:33], v[86:89], v[94:97], v[18:33]
	ds_read_b128 v[86:89], v68 offset:64
	ds_read_b128 v[94:97], v1 offset:41536
	s_waitcnt lgkmcnt(1)
	v_mfma_f32_32x32x16_bf16 v[34:49], v[86:89], v[90:93], v[34:49]
	s_waitcnt lgkmcnt(0)
	v_mfma_f32_32x32x16_bf16 v[50:65], v[86:89], v[94:97], v[50:65]
	ds_read_b128 v[86:89], v68 offset:4672
	s_waitcnt lgkmcnt(0)
	v_mfma_f32_32x32x16_bf16 v[2:17], v[86:89], v[90:93], v[2:17]
	ds_read_b128 v[90:93], v1 offset:36960
	v_mfma_f32_32x32x16_bf16 v[18:33], v[86:89], v[94:97], v[18:33]
	ds_read_b128 v[86:89], v68 offset:96
	ds_read_b128 v[94:97], v1 offset:41568
	s_waitcnt lgkmcnt(1)
	v_mfma_f32_32x32x16_bf16 v[34:49], v[86:89], v[90:93], v[34:49]
	s_waitcnt lgkmcnt(0)
	v_mfma_f32_32x32x16_bf16 v[50:65], v[86:89], v[94:97], v[50:65]
	global_load_dwordx4 v[86:89], v[72:73], off offset:1024
	v_mfma_f32_32x32x16_bf16 v[2:17], v[98:101], v[90:93], v[2:17]
	global_load_dwordx4 v[90:93], v[76:77], off offset:1024
	v_mfma_f32_32x32x16_bf16 v[18:33], v[98:101], v[94:97], v[18:33]
	s_setprio 0
	s_barrier
; #define MFMA(a, b, c) __builtin_amdgcn_mfma_f32_32x32x16_bf16((a), (b), (c), 0, 0, 0)
; template <int TM, int TN>
; DI void gemm_mainloop(const u16* __restrict__ A, long lda, const u16* __restrict__ Bt, long ldb, int K, char* smem,
;                       f32x16 (&acc)[TM][TN]) {
;     ...
;   for (int kt = 0; kt < nk; kt++) {
;     const int buf = kt & 1;
;     const u16* cA = sA + buf * BM * LD + (wm * 32 * TM + r) * LD + h * 8;
;     const u16* cB = sB + buf * BN * LD + (wn * 32 * TN + r) * LD + h * 8;
;     bf16x8 af[TM], bfr[TN];
; #pragma unroll
;     for (int tm = 0; tm < TM; tm++) af[tm] = *(const bf16x8*)(cA + tm * 32 * LD);
; #pragma unroll
;     for (int tn = 0; tn < TN; tn++) bfr[tn] = *(const bf16x8*)(cB + tn * 32 * LD);
;     if (kt + 1 < nk) GEMM_SSTORE(buf ^ 1)
;     __builtin_amdgcn_sched_barrier(0);
;     __builtin_amdgcn_s_setprio(1);
; #pragma unroll
;     for (int tm = 0; tm < TM; tm++)
; #pragma unroll
;       for (int tn = 0; tn < TN; tn++) acc[tm][tn] = MFMA(af[tm], bfr[tn], acc[tm][tn]);
; #pragma unroll
;     for (int tm = 0; tm < TM; tm++) af[tm] = *(const bf16x8*)(cA + tm * 32 * LD + 16);
; #pragma unroll
;     for (int tn = 0; tn < TN; tn++) bfr[tn] = *(const bf16x8*)(cB + tn * 32 * LD + 16);
; #pragma unroll
;     for (int tm = 0; tm < TM; tm++)
; #pragma unroll
;       for (int tn = 0; tn < TN; tn++) acc[tm][tn] = MFMA(af[tm], bfr[tn], acc[tm][tn]);
;     __builtin_amdgcn_sched_group_barrier(0x8, 4, 0);
;     if (kt + 2 < nk) GEMM_GLOAD((kt + 2) * 64)
; #pragma unroll
;     for (int ks = 2; ks < 4; ks++) {
; #pragma unroll
;       for (int tm = 0; tm < TM; tm++) af[tm] = *(const bf16x8*)(cA + tm * 32 * LD + ks * 16);
; #pragma unroll
;       for (int tn = 0; tn < TN; tn++) bfr[tn] = *(const bf16x8*)(cB + tn * 32 * LD + ks * 16);
; #pragma unroll
;       for (int tm = 0; tm < TM; tm++)
; #pragma unroll
;         for (int tn = 0; tn < TN; tn++) acc[tm][tn] = MFMA(af[tm], bfr[tn], acc[tm][tn]);
;     }
;     __builtin_amdgcn_s_setprio(0);
;     __syncthreads();
	ds_read_b128 v[94:97], v68 offset:18432
	ds_read_b128 v[98:101], v68 offset:23040
	ds_read_b128 v[126:129], v1 offset:55296
	ds_read_b128 v[130:133], v1 offset:59904
	s_waitcnt vmcnt(1)
	ds_write_b128 v66, v[86:89]
	ds_write_b128 v66, v[102:105] offset:4608
	ds_write_b128 v66, v[106:109] offset:9216
	ds_write_b128 v66, v[110:113] offset:13824
	s_waitcnt vmcnt(0)
	ds_write_b128 v66, v[90:93] offset:36864
	ds_write_b128 v66, v[122:125] offset:41472
	ds_write_b128 v66, v[118:121] offset:46080
	ds_write_b128 v66, v[114:117] offset:50688
	s_setprio 1
	ds_read_b128 v[86:89], v68 offset:18464
	s_waitcnt lgkmcnt(10)
	v_mfma_f32_32x32x16_bf16 v[34:49], v[94:97], v[126:129], v[34:49]
	ds_read_b128 v[90:93], v1 offset:55328
	global_load_dwordx4 v[102:105], v[70:71], off offset:1152
	global_load_dwordx4 v[106:109], v[74:75], off offset:1152
	global_load_dwordx4 v[110:113], v[78:79], off offset:1152
	global_load_dwordx4 v[114:117], v[84:85], off offset:1152
	global_load_dwordx4 v[118:121], v[82:83], off offset:1152
	global_load_dwordx4 v[122:125], v[80:81], off offset:1152
	s_waitcnt lgkmcnt(10)
	v_mfma_f32_32x32x16_bf16 v[50:65], v[94:97], v[130:133], v[50:65]
	ds_read_b128 v[94:97], v1 offset:59936
	s_waitcnt lgkmcnt(1)
	v_mfma_f32_32x32x16_bf16 v[34:49], v[86:89], v[90:93], v[34:49]
	s_waitcnt lgkmcnt(0)
	v_mfma_f32_32x32x16_bf16 v[50:65], v[86:89], v[94:97], v[50:65]
	ds_read_b128 v[86:89], v68 offset:23072
	v_mfma_f32_32x32x16_bf16 v[2:17], v[98:101], v[126:129], v[2:17]
	v_mfma_f32_32x32x16_bf16 v[18:33], v[98:101], v[130:133], v[18:33]
	ds_read_b128 v[98:101], v68 offset:23136
	s_waitcnt lgkmcnt(1)
	v_mfma_f32_32x32x16_bf16 v[2:17], v[86:89], v[90:93], v[2:17]
	ds_read_b128 v[90:93], v1 offset:55360
	v_mfma_f32_32x32x16_bf16 v[18:33], v[86:89], v[94:97], v[18:33]
	ds_read_b128 v[86:89], v68 offset:18496
	ds_read_b128 v[94:97], v1 offset:59968
	s_waitcnt lgkmcnt(1)
	v_mfma_f32_32x32x16_bf16 v[34:49], v[86:89], v[90:93], v[34:49]
	s_waitcnt lgkmcnt(0)
	v_mfma_f32_32x32x16_bf16 v[50:65], v[86:89], v[94:97], v[50:65]
	ds_read_b128 v[86:89], v68 offset:23104
	s_waitcnt lgkmcnt(0)
	v_mfma_f32_32x32x16_bf16 v[2:17], v[86:89], v[90:93], v[2:17]
	ds_read_b128 v[90:93], v1 offset:55392
	v_mfma_f32_32x32x16_bf16 v[18:33], v[86:89], v[94:97], v[18:33]
	ds_read_b128 v[86:89], v68 offset:18528
	ds_read_b128 v[94:97], v1 offset:60000
	s_waitcnt lgkmcnt(1)
	v_mfma_f32_32x32x16_bf16 v[34:49], v[86:89], v[90:93], v[34:49]
	s_waitcnt lgkmcnt(0)
	v_mfma_f32_32x32x16_bf16 v[50:65], v[86:89], v[94:97], v[50:65]
	global_load_dwordx4 v[86:89], v[72:73], off offset:1152
	v_mfma_f32_32x32x16_bf16 v[2:17], v[98:101], v[90:93], v[2:17]
	global_load_dwordx4 v[90:93], v[76:77], off offset:1152
	v_mfma_f32_32x32x16_bf16 v[18:33], v[98:101], v[94:97], v[18:33]
	s_setprio 0
	s_barrier
	ds_read_b128 v[94:97], v68
	ds_read_b128 v[98:101], v68 offset:4608
	ds_read_b128 v[126:129], v1 offset:36864
	ds_read_b128 v[130:133], v1 offset:41472
	s_waitcnt vmcnt(1)
	ds_write_b128 v66, v[86:89] offset:18432
	ds_write_b128 v66, v[102:105] offset:23040
	ds_write_b128 v66, v[106:109] offset:27648
	ds_write_b128 v66, v[110:113] offset:32256
	s_waitcnt vmcnt(0)
	ds_write_b128 v66, v[90:93] offset:55296
	ds_write_b128 v66, v[122:125] offset:59904
	ds_write_b128 v66, v[118:121] offset:64512
	ds_write_b128 v69, v[114:117] offset:32256
	s_setprio 1
	ds_read_b128 v[86:89], v68 offset:32
	s_waitcnt lgkmcnt(10)
	v_mfma_f32_32x32x16_bf16 v[34:49], v[94:97], v[126:129], v[34:49]
	ds_read_b128 v[90:93], v1 offset:36896
	global_load_dwordx4 v[102:105], v[70:71], off offset:1280
	global_load_dwordx4 v[106:109], v[74:75], off offset:1280
	global_load_dwordx4 v[110:113], v[78:79], off offset:1280
	global_load_dwordx4 v[114:117], v[84:85], off offset:1280
	global_load_dwordx4 v[118:121], v[82:83], off offset:1280
	global_load_dwordx4 v[122:125], v[80:81], off offset:1280
	s_waitcnt lgkmcnt(10)
	v_mfma_f32_32x32x16_bf16 v[50:65], v[94:97], v[130:133], v[50:65]
	ds_read_b128 v[94:97], v1 offset:41504
	s_waitcnt lgkmcnt(1)
	v_mfma_f32_32x32x16_bf16 v[34:49], v[86:89], v[90:93], v[34:49]
	s_waitcnt lgkmcnt(0)
	v_mfma_f32_32x32x16_bf16 v[50:65], v[86:89], v[94:97], v[50:65]
	ds_read_b128 v[86:89], v68 offset:4640
	v_mfma_f32_32x32x16_bf16 v[2:17], v[98:101], v[126:129], v[2:17]
	v_mfma_f32_32x32x16_bf16 v[18:33], v[98:101], v[130:133], v[18:33]
	ds_read_b128 v[98:101], v68 offset:4704
	s_waitcnt lgkmcnt(1)
	v_mfma_f32_32x32x16_bf16 v[2:17], v[86:89], v[90:93], v[2:17]
	ds_read_b128 v[90:93], v1 offset:36928
	v_mfma_f32_32x32x16_bf16 v[18:33], v[86:89], v[94:97], v[18:33]
	ds_read_b128 v[86:89], v68 offset:64
	ds_read_b128 v[94:97], v1 offset:41536
	s_waitcnt lgkmcnt(1)
	v_mfma_f32_32x32x16_bf16 v[34:49], v[86:89], v[90:93], v[34:49]
	s_waitcnt lgkmcnt(0)
	v_mfma_f32_32x32x16_bf16 v[50:65], v[86:89], v[94:97], v[50:65]
	ds_read_b128 v[86:89], v68 offset:4672
	s_waitcnt lgkmcnt(0)
	v_mfma_f32_32x32x16_bf16 v[2:17], v[86:89], v[90:93], v[2:17]
	ds_read_b128 v[90:93], v1 offset:36960
	v_mfma_f32_32x32x16_bf16 v[18:33], v[86:89], v[94:97], v[18:33]
	ds_read_b128 v[86:89], v68 offset:96
	ds_read_b128 v[94:97], v1 offset:41568
	s_waitcnt lgkmcnt(1)
	v_mfma_f32_32x32x16_bf16 v[34:49], v[86:89], v[90:93], v[34:49]
	s_waitcnt lgkmcnt(0)
	v_mfma_f32_32x32x16_bf16 v[50:65], v[86:89], v[94:97], v[50:65]
	global_load_dwordx4 v[86:89], v[72:73], off offset:1280
	v_mfma_f32_32x32x16_bf16 v[2:17], v[98:101], v[90:93], v[2:17]
	global_load_dwordx4 v[90:93], v[76:77], off offset:1280
	v_mfma_f32_32x32x16_bf16 v[18:33], v[98:101], v[94:97], v[18:33]
	s_setprio 0
	s_barrier
; #define MFMA(a, b, c) __builtin_amdgcn_mfma_f32_32x32x16_bf16((a), (b), (c), 0, 0, 0)
; template <int TM, int TN>
; DI void gemm_mainloop(const u16* __restrict__ A, long lda, const u16* __restrict__ Bt, long ldb, int K, char* smem,
;                       f32x16 (&acc)[TM][TN]) {
;     ...
;   for (int kt = 0; kt < nk; kt++) {
;     const int buf = kt & 1;
;     const u16* cA = sA + buf * BM * LD + (wm * 32 * TM + r) * LD + h * 8;
;     const u16* cB = sB + buf * BN * LD + (wn * 32 * TN + r) * LD + h * 8;
;     bf16x8 af[TM], bfr[TN];
; #pragma unroll
;     for (int tm = 0; tm < TM; tm++) af[tm] = *(const bf16x8*)(cA + tm * 32 * LD);
; #pragma unroll
;     for (int tn = 0; tn < TN; tn++) bfr[tn] = *(const bf16x8*)(cB + tn * 32 * LD);
;     if (kt + 1 < nk) GEMM_SSTORE(buf ^ 1)
;     __builtin_amdgcn_sched_barrier(0);
;     __builtin_amdgcn_s_setprio(1);
; #pragma unroll
;     for (int tm = 0; tm < TM; tm++)
; #pragma unroll
;       for (int tn = 0; tn < TN; tn++) acc[tm][tn] = MFMA(af[tm], bfr[tn], acc[tm][tn]);
; #pragma unroll
;     for (int tm = 0; tm < TM; tm++) af[tm] = *(const bf16x8*)(cA + tm * 32 * LD + 16);
; #pragma unroll
;     for (int tn = 0; tn < TN; tn++) bfr[tn] = *(const bf16x8*)(cB + tn * 32 * LD + 16);
; #pragma unroll
;     for (int tm = 0; tm < TM; tm++)
; #pragma unroll
;       for (int tn = 0; tn < TN; tn++) acc[tm][tn] = MFMA(af[tm], bfr[tn], acc[tm][tn]);
;     __builtin_amdgcn_sched_group_barrier(0x8, 4, 0);
;     if (kt + 2 < nk) GEMM_GLOAD((kt + 2) * 64)
; #pragma unroll
;     for (int ks = 2; ks < 4; ks++) {
; #pragma unroll
;       for (int tm = 0; tm < TM; tm++) af[tm] = *(const bf16x8*)(cA + tm * 32 * LD + ks * 16);
; #pragma unroll
;       for (int tn = 0; tn < TN; tn++) bfr[tn] = *(const bf16x8*)(cB + tn * 32 * LD + ks * 16);
; #pragma unroll
;       for (int tm = 0; tm < TM; tm++)
; #pragma unroll
;         for (int tn = 0; tn < TN; tn++) acc[tm][tn] = MFMA(af[tm], bfr[tn], acc[tm][tn]);
;     }
;     __builtin_amdgcn_s_setprio(0);
;     __syncthreads();
	ds_read_b128 v[94:97], v68 offset:18432
	ds_read_b128 v[98:101], v68 offset:23040
	ds_read_b128 v[126:129], v1 offset:55296
	ds_read_b128 v[130:133], v1 offset:59904
	s_waitcnt vmcnt(1)
	ds_write_b128 v66, v[86:89]
	ds_write_b128 v66, v[102:105] offset:4608
	ds_write_b128 v66, v[106:109] offset:9216
	ds_write_b128 v66, v[110:113] offset:13824
	s_waitcnt vmcnt(0)
	ds_write_b128 v66, v[90:93] offset:36864
	ds_write_b128 v66, v[122:125] offset:41472
	ds_write_b128 v66, v[118:121] offset:46080
	ds_write_b128 v66, v[114:117] offset:50688
	s_setprio 1
	ds_read_b128 v[86:89], v68 offset:18464
	s_waitcnt lgkmcnt(10)
	v_mfma_f32_32x32x16_bf16 v[34:49], v[94:97], v[126:129], v[34:49]
	ds_read_b128 v[90:93], v1 offset:55328
	global_load_dwordx4 v[102:105], v[70:71], off offset:1408
	global_load_dwordx4 v[106:109], v[74:75], off offset:1408
	global_load_dwordx4 v[110:113], v[78:79], off offset:1408
	global_load_dwordx4 v[114:117], v[84:85], off offset:1408
	global_load_dwordx4 v[118:121], v[82:83], off offset:1408
	global_load_dwordx4 v[122:125], v[80:81], off offset:1408
	s_waitcnt lgkmcnt(10)
	v_mfma_f32_32x32x16_bf16 v[50:65], v[94:97], v[130:133], v[50:65]
	ds_read_b128 v[94:97], v1 offset:59936
	s_waitcnt lgkmcnt(1)
	v_mfma_f32_32x32x16_bf16 v[34:49], v[86:89], v[90:93], v[34:49]
	s_waitcnt lgkmcnt(0)
	v_mfma_f32_32x32x16_bf16 v[50:65], v[86:89], v[94:97], v[50:65]
	ds_read_b128 v[86:89], v68 offset:23072
	v_mfma_f32_32x32x16_bf16 v[2:17], v[98:101], v[126:129], v[2:17]
	v_mfma_f32_32x32x16_bf16 v[18:33], v[98:101], v[130:133], v[18:33]
	ds_read_b128 v[98:101], v68 offset:23136
	s_waitcnt lgkmcnt(1)
	v_mfma_f32_32x32x16_bf16 v[2:17], v[86:89], v[90:93], v[2:17]
	ds_read_b128 v[90:93], v1 offset:55360
	v_mfma_f32_32x32x16_bf16 v[18:33], v[86:89], v[94:97], v[18:33]
	ds_read_b128 v[86:89], v68 offset:18496
	ds_read_b128 v[94:97], v1 offset:59968
	s_waitcnt lgkmcnt(1)
	v_mfma_f32_32x32x16_bf16 v[34:49], v[86:89], v[90:93], v[34:49]
	s_waitcnt lgkmcnt(0)
	v_mfma_f32_32x32x16_bf16 v[50:65], v[86:89], v[94:97], v[50:65]
	ds_read_b128 v[86:89], v68 offset:23104
	s_waitcnt lgkmcnt(0)
	v_mfma_f32_32x32x16_bf16 v[2:17], v[86:89], v[90:93], v[2:17]
	ds_read_b128 v[90:93], v1 offset:55392
	v_mfma_f32_32x32x16_bf16 v[18:33], v[86:89], v[94:97], v[18:33]
	ds_read_b128 v[86:89], v68 offset:18528
	ds_read_b128 v[94:97], v1 offset:60000
	s_waitcnt lgkmcnt(1)
	v_mfma_f32_32x32x16_bf16 v[34:49], v[86:89], v[90:93], v[34:49]
	s_waitcnt lgkmcnt(0)
	v_mfma_f32_32x32x16_bf16 v[50:65], v[86:89], v[94:97], v[50:65]
	global_load_dwordx4 v[86:89], v[72:73], off offset:1408
	v_mfma_f32_32x32x16_bf16 v[2:17], v[98:101], v[90:93], v[2:17]
	global_load_dwordx4 v[90:93], v[76:77], off offset:1408
	v_mfma_f32_32x32x16_bf16 v[18:33], v[98:101], v[94:97], v[18:33]
	s_setprio 0
	s_barrier
	ds_read_b128 v[94:97], v68
	ds_read_b128 v[98:101], v68 offset:4608
	ds_read_b128 v[126:129], v1 offset:36864
	ds_read_b128 v[130:133], v1 offset:41472
	s_waitcnt vmcnt(1)
	ds_write_b128 v66, v[86:89] offset:18432
	ds_write_b128 v66, v[102:105] offset:23040
	ds_write_b128 v66, v[106:109] offset:27648
	ds_write_b128 v66, v[110:113] offset:32256
	s_waitcnt vmcnt(0)
	ds_write_b128 v66, v[90:93] offset:55296
	ds_write_b128 v66, v[122:125] offset:59904
	ds_write_b128 v66, v[118:121] offset:64512
	ds_write_b128 v69, v[114:117] offset:32256
	s_setprio 1
	ds_read_b128 v[86:89], v68 offset:32
	s_waitcnt lgkmcnt(10)
	v_mfma_f32_32x32x16_bf16 v[34:49], v[94:97], v[126:129], v[34:49]
	ds_read_b128 v[90:93], v1 offset:36896
	global_load_dwordx4 v[102:105], v[70:71], off offset:1536
	global_load_dwordx4 v[106:109], v[74:75], off offset:1536
	global_load_dwordx4 v[110:113], v[78:79], off offset:1536
	global_load_dwordx4 v[114:117], v[84:85], off offset:1536
	global_load_dwordx4 v[118:121], v[82:83], off offset:1536
	global_load_dwordx4 v[122:125], v[80:81], off offset:1536
	s_waitcnt lgkmcnt(10)
	v_mfma_f32_32x32x16_bf16 v[50:65], v[94:97], v[130:133], v[50:65]
	ds_read_b128 v[94:97], v1 offset:41504
	s_waitcnt lgkmcnt(1)
	v_mfma_f32_32x32x16_bf16 v[34:49], v[86:89], v[90:93], v[34:49]
	s_waitcnt lgkmcnt(0)
	v_mfma_f32_32x32x16_bf16 v[50:65], v[86:89], v[94:97], v[50:65]
	ds_read_b128 v[86:89], v68 offset:4640
	v_mfma_f32_32x32x16_bf16 v[2:17], v[98:101], v[126:129], v[2:17]
	v_mfma_f32_32x32x16_bf16 v[18:33], v[98:101], v[130:133], v[18:33]
	ds_read_b128 v[98:101], v68 offset:4704
	s_waitcnt lgkmcnt(1)
	v_mfma_f32_32x32x16_bf16 v[2:17], v[86:89], v[90:93], v[2:17]
	ds_read_b128 v[90:93], v1 offset:36928
	v_mfma_f32_32x32x16_bf16 v[18:33], v[86:89], v[94:97], v[18:33]
	ds_read_b128 v[86:89], v68 offset:64
	ds_read_b128 v[94:97], v1 offset:41536
	s_waitcnt lgkmcnt(1)
	v_mfma_f32_32x32x16_bf16 v[34:49], v[86:89], v[90:93], v[34:49]
	s_waitcnt lgkmcnt(0)
	v_mfma_f32_32x32x16_bf16 v[50:65], v[86:89], v[94:97], v[50:65]
	ds_read_b128 v[86:89], v68 offset:4672
	s_waitcnt lgkmcnt(0)
	v_mfma_f32_32x32x16_bf16 v[2:17], v[86:89], v[90:93], v[2:17]
	ds_read_b128 v[90:93], v1 offset:36960
	v_mfma_f32_32x32x16_bf16 v[18:33], v[86:89], v[94:97], v[18:33]
	ds_read_b128 v[86:89], v68 offset:96
	ds_read_b128 v[94:97], v1 offset:41568
	s_waitcnt lgkmcnt(1)
	v_mfma_f32_32x32x16_bf16 v[34:49], v[86:89], v[90:93], v[34:49]
	s_waitcnt lgkmcnt(0)
	v_mfma_f32_32x32x16_bf16 v[50:65], v[86:89], v[94:97], v[50:65]
	global_load_dwordx4 v[86:89], v[72:73], off offset:1536
	v_mfma_f32_32x32x16_bf16 v[2:17], v[98:101], v[90:93], v[2:17]
	global_load_dwordx4 v[90:93], v[76:77], off offset:1536
	v_mfma_f32_32x32x16_bf16 v[18:33], v[98:101], v[94:97], v[18:33]
	s_setprio 0
	s_barrier
; #define MFMA(a, b, c) __builtin_amdgcn_mfma_f32_32x32x16_bf16((a), (b), (c), 0, 0, 0)
; template <int TM, int TN>
; DI void gemm_mainloop(const u16* __restrict__ A, long lda, const u16* __restrict__ Bt, long ldb, int K, char* smem,
;                       f32x16 (&acc)[TM][TN]) {
;     ...
;   for (int kt = 0; kt < nk; kt++) {
;     const int buf = kt & 1;
;     const u16* cA = sA + buf * BM * LD + (wm * 32 * TM + r) * LD + h * 8;
;     const u16* cB = sB + buf * BN * LD + (wn * 32 * TN + r) * LD + h * 8;
;     bf16x8 af[TM], bfr[TN];
; #pragma unroll
;     for (int tm = 0; tm < TM; tm++) af[tm] = *(const bf16x8*)(cA + tm * 32 * LD);
; #pragma unroll
;     for (int tn = 0; tn < TN; tn++) bfr[tn] = *(const bf16x8*)(cB + tn * 32 * LD);
;     if (kt + 1 < nk) GEMM_SSTORE(buf ^ 1)
;     __builtin_amdgcn_sched_barrier(0);
;     __builtin_amdgcn_s_setprio(1);
; #pragma unroll
;     for (int tm = 0; tm < TM; tm++)
; #pragma unroll
;       for (int tn = 0; tn < TN; tn++) acc[tm][tn] = MFMA(af[tm], bfr[tn], acc[tm][tn]);
; #pragma unroll
;     for (int tm = 0; tm < TM; tm++) af[tm] = *(const bf16x8*)(cA + tm * 32 * LD + 16);
; #pragma unroll
;     for (int tn = 0; tn < TN; tn++) bfr[tn] = *(const bf16x8*)(cB + tn * 32 * LD + 16);
; #pragma unroll
;     for (int tm = 0; tm < TM; tm++)
; #pragma unroll
;       for (int tn = 0; tn < TN; tn++) acc[tm][tn] = MFMA(af[tm], bfr[tn], acc[tm][tn]);
;     __builtin_amdgcn_sched_group_barrier(0x8, 4, 0);
;     if (kt + 2 < nk) GEMM_GLOAD((kt + 2) * 64)
; #pragma unroll
;     for (int ks = 2; ks < 4; ks++) {
; #pragma unroll
;       for (int tm = 0; tm < TM; tm++) af[tm] = *(const bf16x8*)(cA + tm * 32 * LD + ks * 16);
; #pragma unroll
;       for (int tn = 0; tn < TN; tn++) bfr[tn] = *(const bf16x8*)(cB + tn * 32 * LD + ks * 16);
; #pragma unroll
;       for (int tm = 0; tm < TM; tm++)
; #pragma unroll
;         for (int tn = 0; tn < TN; tn++) acc[tm][tn] = MFMA(af[tm], bfr[tn], acc[tm][tn]);
;     }
;     __builtin_amdgcn_s_setprio(0);
;     __syncthreads();
	ds_read_b128 v[94:97], v68 offset:18432
	ds_read_b128 v[98:101], v68 offset:23040
	ds_read_b128 v[126:129], v1 offset:55296
	ds_read_b128 v[130:133], v1 offset:59904
	s_waitcnt vmcnt(1)
	ds_write_b128 v66, v[86:89]
	ds_write_b128 v66, v[102:105] offset:4608
	ds_write_b128 v66, v[106:109] offset:9216
	ds_write_b128 v66, v[110:113] offset:13824
	s_waitcnt vmcnt(0)
	ds_write_b128 v66, v[90:93] offset:36864
	ds_write_b128 v66, v[122:125] offset:41472
	ds_write_b128 v66, v[118:121] offset:46080
	ds_write_b128 v66, v[114:117] offset:50688
	s_setprio 1
	ds_read_b128 v[86:89], v68 offset:18464
	s_waitcnt lgkmcnt(10)
	v_mfma_f32_32x32x16_bf16 v[34:49], v[94:97], v[126:129], v[34:49]
	ds_read_b128 v[90:93], v1 offset:55328
	global_load_dwordx4 v[102:105], v[70:71], off offset:1664
	global_load_dwordx4 v[106:109], v[74:75], off offset:1664
	global_load_dwordx4 v[110:113], v[78:79], off offset:1664
	global_load_dwordx4 v[114:117], v[84:85], off offset:1664
	global_load_dwordx4 v[118:121], v[82:83], off offset:1664
	global_load_dwordx4 v[122:125], v[80:81], off offset:1664
	s_waitcnt lgkmcnt(10)
	v_mfma_f32_32x32x16_bf16 v[50:65], v[94:97], v[130:133], v[50:65]
	ds_read_b128 v[94:97], v1 offset:59936
	s_waitcnt lgkmcnt(1)
	v_mfma_f32_32x32x16_bf16 v[34:49], v[86:89], v[90:93], v[34:49]
	s_waitcnt lgkmcnt(0)
	v_mfma_f32_32x32x16_bf16 v[50:65], v[86:89], v[94:97], v[50:65]
	ds_read_b128 v[86:89], v68 offset:23072
	v_mfma_f32_32x32x16_bf16 v[2:17], v[98:101], v[126:129], v[2:17]
	v_mfma_f32_32x32x16_bf16 v[18:33], v[98:101], v[130:133], v[18:33]
	ds_read_b128 v[98:101], v68 offset:23136
	s_waitcnt lgkmcnt(1)
	v_mfma_f32_32x32x16_bf16 v[2:17], v[86:89], v[90:93], v[2:17]
	ds_read_b128 v[90:93], v1 offset:55360
	v_mfma_f32_32x32x16_bf16 v[18:33], v[86:89], v[94:97], v[18:33]
	ds_read_b128 v[86:89], v68 offset:18496
	ds_read_b128 v[94:97], v1 offset:59968
	s_waitcnt lgkmcnt(1)
	v_mfma_f32_32x32x16_bf16 v[34:49], v[86:89], v[90:93], v[34:49]
	s_waitcnt lgkmcnt(0)
	v_mfma_f32_32x32x16_bf16 v[50:65], v[86:89], v[94:97], v[50:65]
	ds_read_b128 v[86:89], v68 offset:23104
	s_waitcnt lgkmcnt(0)
	v_mfma_f32_32x32x16_bf16 v[2:17], v[86:89], v[90:93], v[2:17]
	ds_read_b128 v[90:93], v1 offset:55392
	v_mfma_f32_32x32x16_bf16 v[18:33], v[86:89], v[94:97], v[18:33]
	ds_read_b128 v[86:89], v68 offset:18528
	ds_read_b128 v[94:97], v1 offset:60000
	s_waitcnt lgkmcnt(1)
	v_mfma_f32_32x32x16_bf16 v[34:49], v[86:89], v[90:93], v[34:49]
	s_waitcnt lgkmcnt(0)
	v_mfma_f32_32x32x16_bf16 v[50:65], v[86:89], v[94:97], v[50:65]
	global_load_dwordx4 v[86:89], v[72:73], off offset:1664
	v_mfma_f32_32x32x16_bf16 v[2:17], v[98:101], v[90:93], v[2:17]
	global_load_dwordx4 v[90:93], v[76:77], off offset:1664
	v_mfma_f32_32x32x16_bf16 v[18:33], v[98:101], v[94:97], v[18:33]
	s_setprio 0
	s_barrier
	ds_read_b128 v[94:97], v68
	ds_read_b128 v[98:101], v68 offset:4608
	ds_read_b128 v[126:129], v1 offset:36864
	ds_read_b128 v[130:133], v1 offset:41472
	s_waitcnt vmcnt(1)
	ds_write_b128 v66, v[86:89] offset:18432
	ds_write_b128 v66, v[102:105] offset:23040
	ds_write_b128 v66, v[106:109] offset:27648
	ds_write_b128 v66, v[110:113] offset:32256
	s_waitcnt vmcnt(0)
	ds_write_b128 v66, v[90:93] offset:55296
	ds_write_b128 v66, v[122:125] offset:59904
	ds_write_b128 v66, v[118:121] offset:64512
	ds_write_b128 v69, v[114:117] offset:32256
	s_setprio 1
	ds_read_b128 v[86:89], v68 offset:32
	s_waitcnt lgkmcnt(10)
	v_mfma_f32_32x32x16_bf16 v[34:49], v[94:97], v[126:129], v[34:49]
	ds_read_b128 v[90:93], v1 offset:36896
	global_load_dwordx4 v[102:105], v[70:71], off offset:1792
	global_load_dwordx4 v[106:109], v[74:75], off offset:1792
	global_load_dwordx4 v[110:113], v[78:79], off offset:1792
	global_load_dwordx4 v[114:117], v[84:85], off offset:1792
	global_load_dwordx4 v[118:121], v[82:83], off offset:1792
	global_load_dwordx4 v[122:125], v[80:81], off offset:1792
	s_waitcnt lgkmcnt(10)
	v_mfma_f32_32x32x16_bf16 v[50:65], v[94:97], v[130:133], v[50:65]
	ds_read_b128 v[94:97], v1 offset:41504
	s_waitcnt lgkmcnt(1)
	v_mfma_f32_32x32x16_bf16 v[34:49], v[86:89], v[90:93], v[34:49]
	s_waitcnt lgkmcnt(0)
	v_mfma_f32_32x32x16_bf16 v[50:65], v[86:89], v[94:97], v[50:65]
	ds_read_b128 v[86:89], v68 offset:4640
	v_mfma_f32_32x32x16_bf16 v[2:17], v[98:101], v[126:129], v[2:17]
	v_mfma_f32_32x32x16_bf16 v[18:33], v[98:101], v[130:133], v[18:33]
	ds_read_b128 v[98:101], v68 offset:4704
	s_waitcnt lgkmcnt(1)
	v_mfma_f32_32x32x16_bf16 v[2:17], v[86:89], v[90:93], v[2:17]
	ds_read_b128 v[90:93], v1 offset:36928
	v_mfma_f32_32x32x16_bf16 v[18:33], v[86:89], v[94:97], v[18:33]
	ds_read_b128 v[86:89], v68 offset:64
	ds_read_b128 v[94:97], v1 offset:41536
	s_waitcnt lgkmcnt(1)
	v_mfma_f32_32x32x16_bf16 v[34:49], v[86:89], v[90:93], v[34:49]
	s_waitcnt lgkmcnt(0)
	v_mfma_f32_32x32x16_bf16 v[50:65], v[86:89], v[94:97], v[50:65]
	ds_read_b128 v[86:89], v68 offset:4672
	s_waitcnt lgkmcnt(0)
	v_mfma_f32_32x32x16_bf16 v[2:17], v[86:89], v[90:93], v[2:17]
	ds_read_b128 v[90:93], v1 offset:36960
	v_mfma_f32_32x32x16_bf16 v[18:33], v[86:89], v[94:97], v[18:33]
	ds_read_b128 v[86:89], v68 offset:96
	ds_read_b128 v[94:97], v1 offset:41568
	s_waitcnt lgkmcnt(1)
	v_mfma_f32_32x32x16_bf16 v[34:49], v[86:89], v[90:93], v[34:49]
	s_waitcnt lgkmcnt(0)
	v_mfma_f32_32x32x16_bf16 v[50:65], v[86:89], v[94:97], v[50:65]
	global_load_dwordx4 v[86:89], v[72:73], off offset:1792
	v_mfma_f32_32x32x16_bf16 v[2:17], v[98:101], v[90:93], v[2:17]
	global_load_dwordx4 v[90:93], v[76:77], off offset:1792
	v_mfma_f32_32x32x16_bf16 v[18:33], v[98:101], v[94:97], v[18:33]
	s_setprio 0
	s_barrier
; #define MFMA(a, b, c) __builtin_amdgcn_mfma_f32_32x32x16_bf16((a), (b), (c), 0, 0, 0)
; template <int TM, int TN>
; DI void gemm_mainloop(const u16* __restrict__ A, long lda, const u16* __restrict__ Bt, long ldb, int K, char* smem,
;                       f32x16 (&acc)[TM][TN]) {
;     ...
;   for (int kt = 0; kt < nk; kt++) {
;     const int buf = kt & 1;
;     const u16* cA = sA + buf * BM * LD + (wm * 32 * TM + r) * LD + h * 8;
;     const u16* cB = sB + buf * BN * LD + (wn * 32 * TN + r) * LD + h * 8;
;     bf16x8 af[TM], bfr[TN];
; #pragma unroll
;     for (int tm = 0; tm < TM; tm++) af[tm] = *(const bf16x8*)(cA + tm * 32 * LD);
; #pragma unroll
;     for (int tn = 0; tn < TN; tn++) bfr[tn] = *(const bf16x8*)(cB + tn * 32 * LD);
;     if (kt + 1 < nk) GEMM_SSTORE(buf ^ 1)
;     __builtin_amdgcn_sched_barrier(0);
;     __builtin_amdgcn_s_setprio(1);
; #pragma unroll
;     for (int tm = 0; tm < TM; tm++)
; #pragma unroll
;       for (int tn = 0; tn < TN; tn++) acc[tm][tn] = MFMA(af[tm], bfr[tn], acc[tm][tn]);
; #pragma unroll
;     for (int tm = 0; tm < TM; tm++) af[tm] = *(const bf16x8*)(cA + tm * 32 * LD + 16);
; #pragma unroll
;     for (int tn = 0; tn < TN; tn++) bfr[tn] = *(const bf16x8*)(cB + tn * 32 * LD + 16);
; #pragma unroll
;     for (int tm = 0; tm < TM; tm++)
; #pragma unroll
;       for (int tn = 0; tn < TN; tn++) acc[tm][tn] = MFMA(af[tm], bfr[tn], acc[tm][tn]);
;     __builtin_amdgcn_sched_group_barrier(0x8, 4, 0);
;     if (kt + 2 < nk) GEMM_GLOAD((kt + 2) * 64)
; #pragma unroll
;     for (int ks = 2; ks < 4; ks++) {
; #pragma unroll
;       for (int tm = 0; tm < TM; tm++) af[tm] = *(const bf16x8*)(cA + tm * 32 * LD + ks * 16);
; #pragma unroll
;       for (int tn = 0; tn < TN; tn++) bfr[tn] = *(const bf16x8*)(cB + tn * 32 * LD + ks * 16);
; #pragma unroll
;       for (int tm = 0; tm < TM; tm++)
; #pragma unroll
;         for (int tn = 0; tn < TN; tn++) acc[tm][tn] = MFMA(af[tm], bfr[tn], acc[tm][tn]);
;     }
;     __builtin_amdgcn_s_setprio(0);
;     __syncthreads();
;   }
	ds_read_b128 v[94:97], v68 offset:18432
	ds_read_b128 v[98:101], v68 offset:23040
	ds_read_b128 v[126:129], v1 offset:55296
	ds_read_b128 v[130:133], v1 offset:59904
	s_waitcnt vmcnt(1)
	ds_write_b128 v66, v[86:89]
	ds_write_b128 v66, v[102:105] offset:4608
	ds_write_b128 v66, v[106:109] offset:9216
	ds_write_b128 v66, v[110:113] offset:13824
	s_waitcnt vmcnt(0)
	ds_write_b128 v66, v[90:93] offset:36864
	ds_write_b128 v66, v[122:125] offset:41472
	ds_write_b128 v66, v[118:121] offset:46080
	ds_write_b128 v66, v[114:117] offset:50688
	s_setprio 1
	ds_read_b128 v[86:89], v68 offset:18464
	s_waitcnt lgkmcnt(10)
	v_mfma_f32_32x32x16_bf16 v[34:49], v[94:97], v[126:129], v[34:49]
	ds_read_b128 v[90:93], v1 offset:55328
	global_load_dwordx4 v[102:105], v[70:71], off offset:1920
	global_load_dwordx4 v[106:109], v[74:75], off offset:1920
	global_load_dwordx4 v[110:113], v[78:79], off offset:1920
	global_load_dwordx4 v[114:117], v[84:85], off offset:1920
	global_load_dwordx4 v[118:121], v[82:83], off offset:1920
	global_load_dwordx4 v[122:125], v[80:81], off offset:1920
	s_waitcnt lgkmcnt(10)
	v_mfma_f32_32x32x16_bf16 v[50:65], v[94:97], v[130:133], v[50:65]
	ds_read_b128 v[94:97], v1 offset:59936
	s_waitcnt lgkmcnt(1)
	v_mfma_f32_32x32x16_bf16 v[34:49], v[86:89], v[90:93], v[34:49]
	s_waitcnt lgkmcnt(0)
	v_mfma_f32_32x32x16_bf16 v[50:65], v[86:89], v[94:97], v[50:65]
	ds_read_b128 v[86:89], v68 offset:23072
	v_mfma_f32_32x32x16_bf16 v[2:17], v[98:101], v[126:129], v[2:17]
	v_mfma_f32_32x32x16_bf16 v[18:33], v[98:101], v[130:133], v[18:33]
	ds_read_b128 v[98:101], v68 offset:23136
	s_waitcnt lgkmcnt(1)
	v_mfma_f32_32x32x16_bf16 v[2:17], v[86:89], v[90:93], v[2:17]
	ds_read_b128 v[90:93], v1 offset:55360
	v_mfma_f32_32x32x16_bf16 v[18:33], v[86:89], v[94:97], v[18:33]
	ds_read_b128 v[86:89], v68 offset:18496
	ds_read_b128 v[94:97], v1 offset:59968
	s_waitcnt lgkmcnt(1)
	v_mfma_f32_32x32x16_bf16 v[34:49], v[86:89], v[90:93], v[34:49]
	s_waitcnt lgkmcnt(0)
	v_mfma_f32_32x32x16_bf16 v[50:65], v[86:89], v[94:97], v[50:65]
	ds_read_b128 v[86:89], v68 offset:23104
	s_waitcnt lgkmcnt(0)
	v_mfma_f32_32x32x16_bf16 v[2:17], v[86:89], v[90:93], v[2:17]
	ds_read_b128 v[90:93], v1 offset:55392
	v_mfma_f32_32x32x16_bf16 v[18:33], v[86:89], v[94:97], v[18:33]
	ds_read_b128 v[86:89], v68 offset:18528
	ds_read_b128 v[94:97], v1 offset:60000
	s_waitcnt lgkmcnt(1)
	v_mfma_f32_32x32x16_bf16 v[34:49], v[86:89], v[90:93], v[34:49]
	s_waitcnt lgkmcnt(0)
	v_mfma_f32_32x32x16_bf16 v[50:65], v[86:89], v[94:97], v[50:65]
	global_load_dwordx4 v[86:89], v[72:73], off offset:1920
	s_nop 0
	global_load_dwordx4 v[70:73], v[76:77], off offset:1920
	v_mfma_f32_32x32x16_bf16 v[2:17], v[98:101], v[90:93], v[2:17]
	v_mfma_f32_32x32x16_bf16 v[18:33], v[98:101], v[94:97], v[18:33]
	s_setprio 0
	s_barrier
	ds_read_b128 v[74:77], v68
	ds_read_b128 v[78:81], v68 offset:4608
	ds_read_b128 v[82:85], v1 offset:36864
	ds_read_b128 v[90:93], v1 offset:41472
	s_waitcnt vmcnt(1)
	ds_write_b128 v66, v[86:89] offset:18432
	ds_write_b128 v66, v[102:105] offset:23040
	ds_write_b128 v66, v[106:109] offset:27648
	ds_write_b128 v66, v[110:113] offset:32256
	s_waitcnt vmcnt(0)
	ds_write_b128 v66, v[70:73] offset:55296
	ds_write_b128 v66, v[122:125] offset:59904
	ds_write_b128 v66, v[118:121] offset:64512
	ds_write_b128 v69, v[114:117] offset:32256
	s_setprio 1
	ds_read_b128 v[70:73], v68 offset:32
	s_waitcnt lgkmcnt(10)
	v_mfma_f32_32x32x16_bf16 v[34:49], v[74:77], v[82:85], v[34:49]
	s_waitcnt lgkmcnt(9)
	v_mfma_f32_32x32x16_bf16 v[50:65], v[74:77], v[90:93], v[50:65]
	ds_read_b128 v[74:77], v1 offset:36896
	v_mfma_f32_32x32x16_bf16 v[2:17], v[78:81], v[82:85], v[2:17]
	v_mfma_f32_32x32x16_bf16 v[18:33], v[78:81], v[90:93], v[18:33]
	ds_read_b128 v[78:81], v1 offset:41504
	s_waitcnt lgkmcnt(1)
	v_mfma_f32_32x32x16_bf16 v[34:49], v[70:73], v[74:77], v[34:49]
	s_waitcnt lgkmcnt(0)
	v_mfma_f32_32x32x16_bf16 v[50:65], v[70:73], v[78:81], v[50:65]
	ds_read_b128 v[70:73], v68 offset:4640
	s_waitcnt lgkmcnt(0)
	v_mfma_f32_32x32x16_bf16 v[2:17], v[70:73], v[74:77], v[2:17]
	ds_read_b128 v[74:77], v1 offset:36928
	v_mfma_f32_32x32x16_bf16 v[18:33], v[70:73], v[78:81], v[18:33]
	ds_read_b128 v[70:73], v68 offset:64
	ds_read_b128 v[78:81], v1 offset:41536
	s_waitcnt lgkmcnt(1)
	v_mfma_f32_32x32x16_bf16 v[34:49], v[70:73], v[74:77], v[34:49]
	s_waitcnt lgkmcnt(0)
	v_mfma_f32_32x32x16_bf16 v[50:65], v[70:73], v[78:81], v[50:65]
	ds_read_b128 v[70:73], v68 offset:4672
	s_waitcnt lgkmcnt(0)
	v_mfma_f32_32x32x16_bf16 v[2:17], v[70:73], v[74:77], v[2:17]
	ds_read_b128 v[74:77], v1 offset:36960
	v_mfma_f32_32x32x16_bf16 v[18:33], v[70:73], v[78:81], v[18:33]
	ds_read_b128 v[70:73], v68 offset:96
	ds_read_b128 v[78:81], v1 offset:41568
	s_waitcnt lgkmcnt(1)
	v_mfma_f32_32x32x16_bf16 v[34:49], v[70:73], v[74:77], v[34:49]
	s_waitcnt lgkmcnt(0)
	v_mfma_f32_32x32x16_bf16 v[50:65], v[70:73], v[78:81], v[50:65]
	ds_read_b128 v[70:73], v68 offset:4704
	s_waitcnt lgkmcnt(0)
	v_mfma_f32_32x32x16_bf16 v[2:17], v[70:73], v[74:77], v[2:17]
	v_mfma_f32_32x32x16_bf16 v[18:33], v[70:73], v[78:81], v[18:33]
	s_setprio 0
	s_barrier
; #define MFMA(a, b, c) __builtin_amdgcn_mfma_f32_32x32x16_bf16((a), (b), (c), 0, 0, 0)
; DI int crow(int i, int h) { return (i & 3) + 8 * (i >> 2) + 4 * h; }
; template <int TM, int TN>
; DI void gemm_mainloop(const u16* __restrict__ A, long lda, const u16* __restrict__ Bt, long ldb, int K, char* smem,
;                       f32x16 (&acc)[TM][TN]) {
;     ...
;     for (int tm = 0; tm < TM; tm++) af[tm] = *(const bf16x8*)(cA + tm * 32 * LD + 16);
; #pragma unroll
;     for (int tn = 0; tn < TN; tn++) bfr[tn] = *(const bf16x8*)(cB + tn * 32 * LD + 16);
; #pragma unroll
;     for (int tm = 0; tm < TM; tm++)
; #pragma unroll
;       for (int tn = 0; tn < TN; tn++) acc[tm][tn] = MFMA(af[tm], bfr[tn], acc[tm][tn]);
;     __builtin_amdgcn_sched_group_barrier(0x8, 4, 0);
;     if (kt + 2 < nk) GEMM_GLOAD((kt + 2) * 64)
; #pragma unroll
;     for (int ks = 2; ks < 4; ks++) {
; #pragma unroll
;       for (int tm = 0; tm < TM; tm++) af[tm] = *(const bf16x8*)(cA + tm * 32 * LD + ks * 16);
; #pragma unroll
;       for (int tn = 0; tn < TN; tn++) bfr[tn] = *(const bf16x8*)(cB + tn * 32 * LD + ks * 16);
; #pragma unroll
;       for (int tm = 0; tm < TM; tm++)
; #pragma unroll
;         for (int tn = 0; tn < TN; tn++) acc[tm][tn] = MFMA(af[tm], bfr[tn], acc[tm][tn]);
;     }
;     __builtin_amdgcn_s_setprio(0);
;     __syncthreads();
;   }
; template <int TM, int TN, class Epi>
; DI void gemm_tile(const u16* A, long lda, const u16* Bt, long ldb, int K, int m0, int n0, char* smem, const Epi& epi) {
;     ...
; #pragma unroll
;   for (int tm = 0; tm < TM; tm++)
; #pragma unroll
;     for (int tn = 0; tn < TN; tn++)
; #pragma unroll
;       for (int i = 0; i < 16; i++)
;         Ct[(wm * 32 * TM + tm * 32 + crow(i, h)) * LDC + wn * 32 * TN + tn * 32 + r] = acc[tm][tn][i];
;   __syncthreads();
	ds_read_b128 v[70:73], v68 offset:18432
	ds_read_b128 v[74:77], v68 offset:23040
	ds_read_b128 v[78:81], v1 offset:55296
	ds_read_b128 v[82:85], v1 offset:59904
	s_setprio 1
	s_waitcnt lgkmcnt(1)
	v_mfma_f32_32x32x16_bf16 v[34:49], v[70:73], v[78:81], v[34:49]
	s_waitcnt lgkmcnt(0)
	v_mfma_f32_32x32x16_bf16 v[50:65], v[70:73], v[82:85], v[50:65]
	ds_read_b128 v[70:73], v68 offset:18464
	v_mfma_f32_32x32x16_bf16 v[2:17], v[74:77], v[78:81], v[2:17]
	ds_read_b128 v[78:81], v1 offset:59936
	v_mfma_f32_32x32x16_bf16 v[18:33], v[74:77], v[82:85], v[18:33]
	ds_read_b128 v[74:77], v1 offset:55328
	s_waitcnt lgkmcnt(0)
	v_mfma_f32_32x32x16_bf16 v[34:49], v[70:73], v[74:77], v[34:49]
	v_mfma_f32_32x32x16_bf16 v[50:65], v[70:73], v[78:81], v[50:65]
	ds_read_b128 v[70:73], v68 offset:23072
	s_waitcnt lgkmcnt(0)
	v_mfma_f32_32x32x16_bf16 v[2:17], v[70:73], v[74:77], v[2:17]
	ds_read_b128 v[74:77], v1 offset:55360
	v_mfma_f32_32x32x16_bf16 v[18:33], v[70:73], v[78:81], v[18:33]
	ds_read_b128 v[70:73], v68 offset:18496
	ds_read_b128 v[78:81], v1 offset:59968
	s_waitcnt lgkmcnt(1)
	v_mfma_f32_32x32x16_bf16 v[34:49], v[70:73], v[74:77], v[34:49]
	s_waitcnt lgkmcnt(0)
	v_mfma_f32_32x32x16_bf16 v[50:65], v[70:73], v[78:81], v[50:65]
	ds_read_b128 v[70:73], v68 offset:23104
	s_waitcnt lgkmcnt(0)
	v_mfma_f32_32x32x16_bf16 v[2:17], v[70:73], v[74:77], v[2:17]
	ds_read_b128 v[74:77], v1 offset:55392
	v_mfma_f32_32x32x16_bf16 v[18:33], v[70:73], v[78:81], v[18:33]
	ds_read_b128 v[70:73], v68 offset:18528
	ds_read_b128 v[78:81], v1 offset:60000
	s_waitcnt lgkmcnt(1)
	v_mfma_f32_32x32x16_bf16 v[34:49], v[70:73], v[74:77], v[34:49]
	s_waitcnt lgkmcnt(0)
	v_mfma_f32_32x32x16_bf16 v[50:65], v[70:73], v[78:81], v[50:65]
	ds_read_b128 v[68:71], v68 offset:23136
	s_waitcnt lgkmcnt(0)
	v_mfma_f32_32x32x16_bf16 v[2:17], v[68:71], v[74:77], v[2:17]
	v_mfma_f32_32x32x16_bf16 v[18:33], v[68:71], v[78:81], v[18:33]
	s_setprio 0
	v_mov_b32_e32 v1, v0
	s_barrier
	s_lshl_b64 s[6:7], s[6:7], 1
	v_lshrrev_b32_e32 v66, 1, v1
	v_and_b32_e32 v66, 0xfffffc0, v66
	v_lshrrev_b32_e32 v68, 3, v1
	v_and_or_b32 v66, v68, 4, v66
	v_and_b32_e32 v68, 0x5f, v1
	v_mul_lo_u32 v66, v66, s20
	v_lshl_add_u32 v66, v68, 2, v66
	ds_write2_b32 v66, v34, v50 offset1:32
	v_add_u32_e32 v34, 0x400, v66
	ds_write2_b32 v34, v36, v52 offset0:8 offset1:40
	ds_write2_b32 v34, v37, v53 offset0:140 offset1:172
	v_add_u32_e32 v34, 0x1000, v66
	ds_write2_b32 v34, v38, v54 offset0:32 offset1:64
	ds_write2_b32 v34, v39, v55 offset0:164 offset1:196
	v_add_u32_e32 v34, 0x1400, v66
	ds_write2_b32 v34, v40, v56 offset0:40 offset1:72
	ds_write2_b32 v34, v41, v57 offset0:172 offset1:204
	v_add_u32_e32 v34, 0x2000, v66
	ds_write2_b32 v34, v42, v58 offset0:64 offset1:96
	ds_write2_b32 v34, v43, v59 offset0:196 offset1:228
	v_add_u32_e32 v34, 0x2400, v66
	ds_write2_b32 v34, v44, v60 offset0:72 offset1:104
	ds_write2_b32 v34, v45, v61 offset0:204 offset1:236
	v_add_u32_e32 v34, 0x3000, v66
	ds_write2_b32 v34, v46, v62 offset0:96 offset1:128
	v_add_u32_e32 v34, 0x3200, v66
	ds_write2_b32 v34, v47, v63 offset0:100 offset1:132
	v_add_u32_e32 v34, 0x3400, v66
	ds_write2_b32 v34, v48, v64 offset0:104 offset1:136
	v_add_u32_e32 v34, 0x3600, v66
	ds_write2_b32 v34, v49, v65 offset0:108 offset1:140
	v_add_u32_e32 v34, 0x4000, v66
	ds_write2_b32 v34, v2, v18 offset0:128 offset1:160
	v_add_u32_e32 v2, 0x4400, v66
	ds_write2_b32 v2, v3, v19 offset0:4 offset1:36
	ds_write2_b32 v2, v4, v20 offset0:136 offset1:168
	v_add_u32_e32 v2, 0x4800, v66
	ds_write2_b32 v2, v5, v21 offset0:12 offset1:44
	v_add_u32_e32 v2, 0x5000, v66
	ds_write2_b32 v2, v6, v22 offset0:160 offset1:192
	v_add_u32_e32 v2, 0x5400, v66
	ds_write2_b32 v2, v7, v23 offset0:36 offset1:68
	ds_write2_b32 v2, v8, v24 offset0:168 offset1:200
	v_add_u32_e32 v2, 0x5800, v66
	ds_write2_b32 v2, v9, v25 offset0:44 offset1:76
	v_add_u32_e32 v2, 0x6000, v66
	ds_write2_b32 v2, v10, v26 offset0:192 offset1:224
	v_add_u32_e32 v2, 0x6400, v66
	ds_write2_b32 v2, v11, v27 offset0:68 offset1:100
	ds_write2_b32 v2, v12, v28 offset0:200 offset1:232
	v_add_u32_e32 v2, 0x6800, v66
	ds_write2_b32 v2, v13, v29 offset0:76 offset1:108
	v_add_u32_e32 v2, 0x7200, v66
	ds_write2_b32 v2, v14, v30 offset0:96 offset1:128
	v_add_u32_e32 v2, 0x7400, v66
	ds_write2_b32 v2, v15, v31 offset0:100 offset1:132
	v_add_u32_e32 v2, 0x7600, v66
	ds_write2_b32 v2, v16, v32 offset0:104 offset1:136
	v_add_u32_e32 v2, 0x7800, v66
	ds_write2_b32 v2, v17, v33 offset0:108 offset1:140
	v_lshlrev_b32_e32 v2, 3, v1
	v_and_b32_e32 v3, 0x78, v2
	s_add_u32 s6, s3, s6
	ds_write2_b32 v66, v35, v51 offset0:132 offset1:164
	s_addc_u32 s7, s10, s7
	v_lshlrev_b32_e32 v66, 1, v3
	v_lshlrev_b32_e32 v2, 2, v3
	v_lshl_add_u64 v[4:5], s[6:7], 0, v[66:67]
	s_mov_b32 s6, 0
	s_waitcnt lgkmcnt(0)
	s_barrier
